# adds early issue of second-unit row-stat loads in P4/P7 (before first-unit epilogue stores) on top of P3 gate-load hoist, P3b wait relaxations, P6 epilogue repack
# speedup vs baseline: 1.0063x; 1.0063x over previous
.LBB0_543:
	s_lshl_b32 s8, s8, 5
	s_and_b32 s72, s8, 0x60
	s_mov_b64 s[8:9], 0x80
	s_add_i32 m0, s61, 0x18000
	v_lshl_add_u64 v[6:7], v[6:7], 0, s[8:9]
	s_lshl_b32 s69, s5, 6
	s_lshl_b32 s5, s5, 13
	s_lshl_b32 s11, s72, 7
	s_waitcnt vmcnt(2)
	s_barrier
	global_load_lds_dwordx4 v[6:7], off
	v_lshl_add_u64 v[4:5], v[4:5], 0, s[8:9]
	s_add_i32 m0, s61, 0x1a000
	s_add_i32 s73, s61, 0x8000
	s_add_i32 s74, s61, 0xa000
	global_load_lds_dwordx4 v[4:5], off
	v_lshl_add_u64 v[0:1], v[0:1], 0, s[8:9]
	s_mov_b32 m0, s73
	s_add_u32 s12, s62, 0x20080
	global_load_lds_dwordx4 v[0:1], off
	v_lshl_add_u64 v[0:1], v[2:3], 0, s[8:9]
	s_mov_b32 m0, s74
	s_addc_u32 s13, s63, 0
	global_load_lds_dwordx4 v[0:1], off
	s_add_i32 m0, s61, 0x1c000
	v_lshl_add_u64 v[0:1], s[12:13], 0, v[130:131]
	global_load_lds_dwordx4 v[0:1], off
	v_lshl_add_u64 v[0:1], s[12:13], 0, v[134:135]
	s_add_i32 m0, s61, 0x1e000
	v_bfe_u32 v151, v8, 4, 2
	global_load_lds_dwordx4 v[0:1], off
	v_and_b32_e32 v150, 15, v8
	v_lshlrev_b32_e32 v0, 4, v151
	v_lshlrev_b32_e32 v1, 2, v8
	v_lshl_or_b32 v0, v150, 6, v0
	v_and_b32_e32 v1, 32, v1
	v_bitop3_b32 v2, v0, s5, v1 bitop3:0xde
	v_bitop3_b32 v152, v0, s11, v1 bitop3:0xde
	v_lshlrev_b32_e32 v0, 13, v9
	v_and_b32_e32 v0, 0xffffc000, v0
	v_lshl_add_u32 v0, v10, 10, v0
	v_and_b32_e32 v1, 1, v9
	v_lshl_or_b32 v0, v1, 6, v0
	v_lshl_add_u32 v136, v11, 1, v0
	v_lshlrev_b32_e32 v0, 13, v12
	v_and_b32_e32 v0, 0xffffc000, v0
	s_waitcnt vmcnt(6)
	s_cmpk_lt_u32 s10, 0x100
	v_lshl_add_u32 v0, v13, 10, v0
	v_and_b32_e32 v1, 1, v12
	s_cselect_b64 s[10:11], -1, 0
	v_lshl_or_b32 v0, v1, 6, v0
	s_add_i32 s75, 0, 0x10000
	s_add_i32 s76, 0, 0x14000
	s_sext_i32_i8 s77, s4
	v_mov_b32_e32 v137, v131
	v_lshl_add_u32 v138, v14, 1, v0
	v_mov_b32_e32 v139, v131
	v_mov_b64_e32 v[140:141], 0x200
	v_mov_b64_e32 v[142:143], 0x1ff
	v_add_u32_e32 v153, s75, v152
	v_add_u32_e32 v154, s76, v152
	v_add_u32_e32 v155, 0, v2
	s_barrier
	s_mov_b32 s99, 0
	s_branch .LBB0_546

.Lrlx5p0b:
	s_waitcnt vmcnt(24)
	s_branch .Lrlx5p0b_done
.LBB0_544:
	s_mov_b64 s[4:5], 0

.LBB0_553:
	ds_read_b128 v[144:147], v153
	ds_read_b128 v[156:159], v153 offset:1024
	ds_read_b128 v[160:163], v153 offset:2048
	ds_read_b128 v[164:167], v153 offset:3072
	ds_read_b128 v[168:171], v154
	ds_read_b128 v[172:175], v154 offset:1024
	ds_read_b128 v[176:179], v154 offset:2048
	ds_read_b128 v[180:183], v154 offset:3072
	s_add_u32 s62, s46, 0xfffe0080
	s_addc_u32 s63, s47, -1
	s_cmp_eq_u32 s82, 4
	s_cselect_b32 s71, s15, s63
	s_cselect_b32 s70, s78, s62
	s_cselect_b32 s63, s13, s81
	s_cselect_b32 s62, s79, s80
	v_lshl_add_u64 v[148:149], s[46:47], 0, v[136:137]
	s_add_i32 m0, s61, 0xc000
	ds_read_b128 v[184:187], v155
	ds_read_b128 v[188:191], v155 offset:1024
	ds_read_b128 v[192:195], v155 offset:2048
	ds_read_b128 v[196:199], v155 offset:3072
	ds_read_b128 v[200:203], v155 offset:4096
	ds_read_b128 v[204:207], v155 offset:5120
	ds_read_b128 v[212:215], v155 offset:6144
	ds_read_b128 v[216:219], v155 offset:7168
	global_load_lds_dwordx4 v[148:149], off
	v_lshl_add_u64 v[148:149], s[46:47], 0, v[138:139]
	s_add_i32 m0, s61, 0xe000
	s_nop 0
	global_load_lds_dwordx4 v[148:149], off
	s_cmp_lg_u32 s99, 0
	s_cbranch_scc1 .Lrlx5p0a
	s_waitcnt vmcnt(8)
.Lrlx5p0a_done:
	s_waitcnt lgkmcnt(0)
	s_barrier
	s_setprio 1
	s_waitcnt lgkmcnt(0)
	v_mfma_f32_16x16x32_bf16 v[124:127], v[144:147], v[184:187], v[124:127]
	v_mfma_f32_16x16x32_bf16 v[120:123], v[160:163], v[184:187], v[120:123]
	v_mfma_f32_16x16x32_bf16 v[116:119], v[144:147], v[192:195], v[116:119]
	v_mfma_f32_16x16x32_bf16 v[108:111], v[160:163], v[192:195], v[108:111]
	v_mfma_f32_16x16x32_bf16 v[96:99], v[144:147], v[200:203], v[96:99]
	v_mfma_f32_16x16x32_bf16 v[88:91], v[160:163], v[200:203], v[88:91]
	v_mfma_f32_16x16x32_bf16 v[80:83], v[144:147], v[212:215], v[80:83]
	v_mfma_f32_16x16x32_bf16 v[72:75], v[160:163], v[212:215], v[72:75]
	v_mfma_f32_16x16x32_bf16 v[124:127], v[156:159], v[188:191], v[124:127]
	v_mfma_f32_16x16x32_bf16 v[120:123], v[164:167], v[188:191], v[120:123]
	v_mfma_f32_16x16x32_bf16 v[116:119], v[156:159], v[196:199], v[116:119]
	v_mfma_f32_16x16x32_bf16 v[108:111], v[164:167], v[196:199], v[108:111]
	v_mfma_f32_16x16x32_bf16 v[96:99], v[156:159], v[204:207], v[96:99]
	v_mfma_f32_16x16x32_bf16 v[88:91], v[164:167], v[204:207], v[88:91]
	v_mfma_f32_16x16x32_bf16 v[80:83], v[156:159], v[216:219], v[80:83]
	v_mfma_f32_16x16x32_bf16 v[72:75], v[164:167], v[216:219], v[72:75]
	s_setprio 0
	s_setprio 1
	v_mfma_f32_16x16x32_bf16 v[112:115], v[168:171], v[184:187], v[112:115]
	v_mfma_f32_16x16x32_bf16 v[104:107], v[176:179], v[184:187], v[104:107]
	v_mfma_f32_16x16x32_bf16 v[100:103], v[168:171], v[192:195], v[100:103]
	v_mfma_f32_16x16x32_bf16 v[92:95], v[176:179], v[192:195], v[92:95]
	v_mfma_f32_16x16x32_bf16 v[84:87], v[168:171], v[200:203], v[84:87]
	v_mfma_f32_16x16x32_bf16 v[76:79], v[176:179], v[200:203], v[76:79]
	v_mfma_f32_16x16x32_bf16 v[68:71], v[168:171], v[212:215], v[68:71]
	v_mfma_f32_16x16x32_bf16 v[64:67], v[176:179], v[212:215], v[64:67]
	v_mfma_f32_16x16x32_bf16 v[112:115], v[172:175], v[188:191], v[112:115]
	v_mfma_f32_16x16x32_bf16 v[104:107], v[180:183], v[188:191], v[104:107]
	v_mfma_f32_16x16x32_bf16 v[100:103], v[172:175], v[196:199], v[100:103]
	v_mfma_f32_16x16x32_bf16 v[92:95], v[180:183], v[196:199], v[92:95]
	v_mfma_f32_16x16x32_bf16 v[84:87], v[172:175], v[204:207], v[84:87]
	v_mfma_f32_16x16x32_bf16 v[76:79], v[180:183], v[204:207], v[76:79]
	v_mfma_f32_16x16x32_bf16 v[68:71], v[172:175], v[216:219], v[68:71]
	v_mfma_f32_16x16x32_bf16 v[64:67], v[180:183], v[216:219], v[64:67]
	s_setprio 0
	s_barrier
	s_add_i32 s83, s75, s64
	v_lshl_add_u64 v[148:149], s[62:63], 0, v[130:131]
	s_mov_b32 m0, s83
	ds_read_b128 v[184:187], v155 offset:16384
	ds_read_b128 v[188:191], v155 offset:17408
	ds_read_b128 v[192:195], v155 offset:18432
	ds_read_b128 v[196:199], v155 offset:19456
	ds_read_b128 v[200:203], v155 offset:20480
	ds_read_b128 v[204:207], v155 offset:21504
	ds_read_b128 v[212:215], v155 offset:22528
	ds_read_b128 v[216:219], v155 offset:23552
	global_load_lds_dwordx4 v[148:149], off
	s_add_i32 m0, s83, 0x2000
	s_add_u32 s84, s62, 0x20000
	v_lshl_add_u64 v[208:209], s[62:63], 0, v[134:135]
	s_addc_u32 s85, s63, 0
	s_add_i32 s83, s76, s64
	global_load_lds_dwordx4 v[208:209], off
	v_lshl_add_u64 v[220:221], s[84:85], 0, v[130:131]
	s_mov_b32 m0, s83
	v_lshl_add_u64 v[222:223], s[70:71], 0, v[132:133]
	global_load_lds_dwordx4 v[220:221], off
	v_lshl_add_u64 v[220:221], s[84:85], 0, v[134:135]
	s_add_i32 m0, s83, 0x2000
	s_nop 0
	global_load_lds_dwordx4 v[220:221], off
	v_lshl_add_u64 v[220:221], s[70:71], 0, v[128:129]
	s_mov_b32 m0, s61
	s_nop 0
	global_load_lds_dwordx4 v[220:221], off
	s_mov_b32 m0, s65
	s_nop 0
	global_load_lds_dwordx4 v[222:223], off
	s_cmp_lg_u32 s99, 0
	s_cbranch_scc1 .Lrlx5p0b
	s_waitcnt vmcnt(8)
.Lrlx5p0b_done:
	s_mov_b32 s99, 0
	s_waitcnt lgkmcnt(0)
	s_barrier
	s_setprio 1
	s_waitcnt lgkmcnt(0)
	v_mfma_f32_16x16x32_bf16 v[60:63], v[144:147], v[184:187], v[60:63]
	v_mfma_f32_16x16x32_bf16 v[56:59], v[160:163], v[184:187], v[56:59]
	v_mfma_f32_16x16x32_bf16 v[48:51], v[144:147], v[192:195], v[48:51]
	v_mfma_f32_16x16x32_bf16 v[40:43], v[160:163], v[192:195], v[40:43]
	v_mfma_f32_16x16x32_bf16 v[32:35], v[144:147], v[200:203], v[32:35]
	v_mfma_f32_16x16x32_bf16 v[24:27], v[160:163], v[200:203], v[24:27]
	v_mfma_f32_16x16x32_bf16 v[16:19], v[144:147], v[212:215], v[16:19]
	v_mfma_f32_16x16x32_bf16 v[8:11], v[160:163], v[212:215], v[8:11]
	v_mfma_f32_16x16x32_bf16 v[60:63], v[156:159], v[188:191], v[60:63]
	v_mfma_f32_16x16x32_bf16 v[56:59], v[164:167], v[188:191], v[56:59]
	v_mfma_f32_16x16x32_bf16 v[48:51], v[156:159], v[196:199], v[48:51]
	v_mfma_f32_16x16x32_bf16 v[40:43], v[164:167], v[196:199], v[40:43]
	v_mfma_f32_16x16x32_bf16 v[32:35], v[156:159], v[204:207], v[32:35]
	v_mfma_f32_16x16x32_bf16 v[24:27], v[164:167], v[204:207], v[24:27]
	v_mfma_f32_16x16x32_bf16 v[16:19], v[156:159], v[216:219], v[16:19]
	v_mfma_f32_16x16x32_bf16 v[8:11], v[164:167], v[216:219], v[8:11]
	s_setprio 0
	s_setprio 1
	v_mfma_f32_16x16x32_bf16 v[52:55], v[168:171], v[184:187], v[52:55]
	v_mfma_f32_16x16x32_bf16 v[44:47], v[176:179], v[184:187], v[44:47]
	v_mfma_f32_16x16x32_bf16 v[36:39], v[168:171], v[192:195], v[36:39]
	v_mfma_f32_16x16x32_bf16 v[28:31], v[176:179], v[192:195], v[28:31]
	v_mfma_f32_16x16x32_bf16 v[20:23], v[168:171], v[200:203], v[20:23]
	v_mfma_f32_16x16x32_bf16 v[12:15], v[176:179], v[200:203], v[12:15]
	v_mfma_f32_16x16x32_bf16 v[4:7], v[168:171], v[212:215], v[4:7]
	v_mfma_f32_16x16x32_bf16 v[0:3], v[176:179], v[212:215], v[0:3]
	v_mfma_f32_16x16x32_bf16 v[52:55], v[172:175], v[188:191], v[52:55]
	v_mfma_f32_16x16x32_bf16 v[44:47], v[180:183], v[188:191], v[44:47]
	v_mfma_f32_16x16x32_bf16 v[36:39], v[172:175], v[196:199], v[36:39]
	v_mfma_f32_16x16x32_bf16 v[28:31], v[180:183], v[196:199], v[28:31]
	v_mfma_f32_16x16x32_bf16 v[20:23], v[172:175], v[204:207], v[20:23]
	v_mfma_f32_16x16x32_bf16 v[12:15], v[180:183], v[204:207], v[12:15]
	v_mfma_f32_16x16x32_bf16 v[4:7], v[172:175], v[216:219], v[4:7]
	v_mfma_f32_16x16x32_bf16 v[0:3], v[180:183], v[216:219], v[0:3]
	s_setprio 0
	s_barrier
	s_add_i32 s83, 0, 0x18000
	s_add_i32 s84, 0, 0x1c000
	v_add_u32_e32 v164, s83, v152
	v_add_u32_e32 v180, s84, v152
	ds_read_b128 v[144:147], v164
	ds_read_b128 v[156:159], v164 offset:1024
	ds_read_b128 v[160:163], v164 offset:2048
	ds_read_b128 v[164:167], v164 offset:3072
	ds_read_b128 v[168:171], v180
	ds_read_b128 v[172:175], v180 offset:1024
	ds_read_b128 v[176:179], v180 offset:2048
	ds_read_b128 v[180:183], v180 offset:3072
	s_add_u32 s70, s70, 0x20000
	s_addc_u32 s71, s71, 0
	s_mov_b32 m0, s66
	v_lshl_add_u64 v[224:225], s[70:71], 0, v[128:129]
	ds_read_b128 v[184:187], v155 offset:32768
	ds_read_b128 v[188:191], v155 offset:33792
	ds_read_b128 v[192:195], v155 offset:34816
	ds_read_b128 v[196:199], v155 offset:35840
	ds_read_b128 v[200:203], v155 offset:36864
	ds_read_b128 v[204:207], v155 offset:37888
	ds_read_b128 v[212:215], v155 offset:38912
	ds_read_b128 v[216:219], v155 offset:39936
	global_load_lds_dwordx4 v[224:225], off
	v_lshl_add_u64 v[224:225], s[70:71], 0, v[132:133]
	s_mov_b32 m0, s67
	s_nop 0
	global_load_lds_dwordx4 v[224:225], off
	s_waitcnt vmcnt(8)
	s_waitcnt lgkmcnt(0)
	s_barrier
	s_setprio 1
	s_waitcnt lgkmcnt(0)
	v_mfma_f32_16x16x32_bf16 v[124:127], v[144:147], v[184:187], v[124:127]
	v_mfma_f32_16x16x32_bf16 v[120:123], v[160:163], v[184:187], v[120:123]
	v_mfma_f32_16x16x32_bf16 v[116:119], v[144:147], v[192:195], v[116:119]
	v_mfma_f32_16x16x32_bf16 v[108:111], v[160:163], v[192:195], v[108:111]
	v_mfma_f32_16x16x32_bf16 v[96:99], v[144:147], v[200:203], v[96:99]
	v_mfma_f32_16x16x32_bf16 v[88:91], v[160:163], v[200:203], v[88:91]
	v_mfma_f32_16x16x32_bf16 v[80:83], v[144:147], v[212:215], v[80:83]
	v_mfma_f32_16x16x32_bf16 v[72:75], v[160:163], v[212:215], v[72:75]
	v_mfma_f32_16x16x32_bf16 v[124:127], v[156:159], v[188:191], v[124:127]
	v_mfma_f32_16x16x32_bf16 v[120:123], v[164:167], v[188:191], v[120:123]
	v_mfma_f32_16x16x32_bf16 v[116:119], v[156:159], v[196:199], v[116:119]
	v_mfma_f32_16x16x32_bf16 v[108:111], v[164:167], v[196:199], v[108:111]
	v_mfma_f32_16x16x32_bf16 v[96:99], v[156:159], v[204:207], v[96:99]
	v_mfma_f32_16x16x32_bf16 v[88:91], v[164:167], v[204:207], v[88:91]
	v_mfma_f32_16x16x32_bf16 v[80:83], v[156:159], v[216:219], v[80:83]
	v_mfma_f32_16x16x32_bf16 v[72:75], v[164:167], v[216:219], v[72:75]
	s_setprio 0
	s_setprio 1
	v_mfma_f32_16x16x32_bf16 v[112:115], v[168:171], v[184:187], v[112:115]
	v_mfma_f32_16x16x32_bf16 v[104:107], v[176:179], v[184:187], v[104:107]
	v_mfma_f32_16x16x32_bf16 v[100:103], v[168:171], v[192:195], v[100:103]
	v_mfma_f32_16x16x32_bf16 v[92:95], v[176:179], v[192:195], v[92:95]
	v_mfma_f32_16x16x32_bf16 v[84:87], v[168:171], v[200:203], v[84:87]
	v_mfma_f32_16x16x32_bf16 v[76:79], v[176:179], v[200:203], v[76:79]
	v_mfma_f32_16x16x32_bf16 v[68:71], v[168:171], v[212:215], v[68:71]
	v_mfma_f32_16x16x32_bf16 v[64:67], v[176:179], v[212:215], v[64:67]
	v_mfma_f32_16x16x32_bf16 v[112:115], v[172:175], v[188:191], v[112:115]
	v_mfma_f32_16x16x32_bf16 v[104:107], v[180:183], v[188:191], v[104:107]
	v_mfma_f32_16x16x32_bf16 v[100:103], v[172:175], v[196:199], v[100:103]
	v_mfma_f32_16x16x32_bf16 v[92:95], v[180:183], v[196:199], v[92:95]
	v_mfma_f32_16x16x32_bf16 v[84:87], v[172:175], v[204:207], v[84:87]
	v_mfma_f32_16x16x32_bf16 v[76:79], v[180:183], v[204:207], v[76:79]
	v_mfma_f32_16x16x32_bf16 v[68:71], v[172:175], v[216:219], v[68:71]
	v_mfma_f32_16x16x32_bf16 v[64:67], v[180:183], v[216:219], v[64:67]
	s_setprio 0
	s_barrier
	s_add_i32 s70, s83, s64
	v_lshl_add_u64 v[148:149], v[148:149], 0, s[8:9]
	s_mov_b32 m0, s70
	ds_read_b128 v[184:187], v155 offset:49152
	ds_read_b128 v[188:191], v155 offset:50176
	ds_read_b128 v[192:195], v155 offset:51200
	ds_read_b128 v[196:199], v155 offset:52224
	ds_read_b128 v[200:203], v155 offset:53248
	ds_read_b128 v[204:207], v155 offset:54272
	ds_read_b128 v[212:215], v155 offset:55296
	ds_read_b128 v[216:219], v155 offset:56320
	global_load_lds_dwordx4 v[148:149], off
	s_add_i32 m0, s70, 0x2000
	s_add_u32 s62, s62, 0x20080
	v_lshl_add_u64 v[148:149], v[208:209], 0, s[8:9]
	s_addc_u32 s63, s63, 0
	s_add_i32 s70, s84, s64
	global_load_lds_dwordx4 v[148:149], off
	v_lshl_add_u64 v[148:149], s[62:63], 0, v[130:131]
	s_mov_b32 m0, s70
	s_nop 0
	global_load_lds_dwordx4 v[148:149], off
	v_lshl_add_u64 v[148:149], s[62:63], 0, v[134:135]
	s_add_i32 m0, s70, 0x2000
	s_nop 0
	global_load_lds_dwordx4 v[148:149], off
	v_lshl_add_u64 v[148:149], v[220:221], 0, s[8:9]
	s_mov_b32 m0, s73
	s_nop 0
	global_load_lds_dwordx4 v[148:149], off
	v_lshl_add_u64 v[148:149], v[222:223], 0, s[8:9]
	s_mov_b32 m0, s74
	s_nop 0
	global_load_lds_dwordx4 v[148:149], off
	s_waitcnt vmcnt(8)
	s_waitcnt lgkmcnt(0)
	s_barrier
	s_setprio 1
	s_waitcnt lgkmcnt(0)
	v_mfma_f32_16x16x32_bf16 v[60:63], v[144:147], v[184:187], v[60:63]
	v_mfma_f32_16x16x32_bf16 v[56:59], v[160:163], v[184:187], v[56:59]
	v_mfma_f32_16x16x32_bf16 v[48:51], v[144:147], v[192:195], v[48:51]
	v_mfma_f32_16x16x32_bf16 v[40:43], v[160:163], v[192:195], v[40:43]
	v_mfma_f32_16x16x32_bf16 v[32:35], v[144:147], v[200:203], v[32:35]
	v_mfma_f32_16x16x32_bf16 v[24:27], v[160:163], v[200:203], v[24:27]
	v_mfma_f32_16x16x32_bf16 v[16:19], v[144:147], v[212:215], v[16:19]
	v_mfma_f32_16x16x32_bf16 v[8:11], v[160:163], v[212:215], v[8:11]
	v_mfma_f32_16x16x32_bf16 v[60:63], v[156:159], v[188:191], v[60:63]
	v_mfma_f32_16x16x32_bf16 v[56:59], v[164:167], v[188:191], v[56:59]
	v_mfma_f32_16x16x32_bf16 v[48:51], v[156:159], v[196:199], v[48:51]
	v_mfma_f32_16x16x32_bf16 v[40:43], v[164:167], v[196:199], v[40:43]
	v_mfma_f32_16x16x32_bf16 v[32:35], v[156:159], v[204:207], v[32:35]
	v_mfma_f32_16x16x32_bf16 v[24:27], v[164:167], v[204:207], v[24:27]
	v_mfma_f32_16x16x32_bf16 v[16:19], v[156:159], v[216:219], v[16:19]
	v_mfma_f32_16x16x32_bf16 v[8:11], v[164:167], v[216:219], v[8:11]
	s_setprio 0
	s_setprio 1
	v_mfma_f32_16x16x32_bf16 v[52:55], v[168:171], v[184:187], v[52:55]
	v_mfma_f32_16x16x32_bf16 v[44:47], v[176:179], v[184:187], v[44:47]
	v_mfma_f32_16x16x32_bf16 v[36:39], v[168:171], v[192:195], v[36:39]
	v_mfma_f32_16x16x32_bf16 v[28:31], v[176:179], v[192:195], v[28:31]
	v_mfma_f32_16x16x32_bf16 v[20:23], v[168:171], v[200:203], v[20:23]
	v_mfma_f32_16x16x32_bf16 v[12:15], v[176:179], v[200:203], v[12:15]
	v_mfma_f32_16x16x32_bf16 v[4:7], v[168:171], v[212:215], v[4:7]
	v_mfma_f32_16x16x32_bf16 v[0:3], v[176:179], v[212:215], v[0:3]
	v_mfma_f32_16x16x32_bf16 v[52:55], v[172:175], v[188:191], v[52:55]
	v_mfma_f32_16x16x32_bf16 v[44:47], v[180:183], v[188:191], v[44:47]
	v_mfma_f32_16x16x32_bf16 v[36:39], v[172:175], v[196:199], v[36:39]
	v_mfma_f32_16x16x32_bf16 v[28:31], v[180:183], v[196:199], v[28:31]
	v_mfma_f32_16x16x32_bf16 v[20:23], v[172:175], v[204:207], v[20:23]
	v_mfma_f32_16x16x32_bf16 v[12:15], v[180:183], v[204:207], v[12:15]
	v_mfma_f32_16x16x32_bf16 v[4:7], v[172:175], v[216:219], v[4:7]
	v_mfma_f32_16x16x32_bf16 v[0:3], v[180:183], v[216:219], v[0:3]
	s_setprio 0
	s_barrier
	s_add_i32 s82, s82, 2
	s_add_u32 s46, s46, 0x100
	s_addc_u32 s47, s47, 0
	s_add_u32 s80, s80, 0x100
	s_addc_u32 s81, s81, 0
	s_cmp_gt_u32 s82, 5
	s_cbranch_scc0 .LBB0_553
	s_and_b64 vcc, exec, s[10:11]
	s_cbranch_vccz .LBB0_556
	s_barrier
.LBB0_556:
	s_lshl_b32 s13, s60, 8
	v_mov_b32_e32 v144, v151
	v_mov_b32_e32 v145, v150
	s_add_i32 s13, s13, s69
	s_andn2_b64 vcc, exec, s[4:5]
	v_add_u32_e32 v146, s13, v145
	s_lshl_b32 s13, s77, 8
	s_or_b32 s13, s13, s72
	v_lshl_add_u32 v144, v144, 3, s13
	v_ashrrev_i32_e32 v145, 31, v144
	v_lshlrev_b64 v[144:145], 1, v[144:145]
	v_ashrrev_i32_e32 v147, 31, v146
	v_lshl_add_u64 v[148:149], s[56:57], 0, v[144:145]
	v_lshlrev_b64 v[156:157], 12, v[146:147]
	v_lshl_add_u64 v[160:161], v[148:149], 0, v[156:157]
	v_add_u32_e32 v172, 16, v146
	global_load_dwordx4 v[156:159], v[160:161], off
	s_nop 0
	global_load_dwordx4 v[160:163], v[160:161], off offset:256
	v_ashrrev_i32_e32 v173, 31, v172
	v_lshlrev_b64 v[164:165], 12, v[172:173]
	v_lshl_add_u64 v[168:169], v[148:149], 0, v[164:165]
	global_load_dwordx4 v[164:167], v[168:169], off
	v_add_u32_e32 v188, 32, v146
	global_load_dwordx4 v[168:171], v[168:169], off offset:256
	v_add_u32_e32 v190, 48, v146
	v_ashrrev_i32_e32 v189, 31, v188
	v_ashrrev_i32_e32 v191, 31, v190
	v_lshlrev_b64 v[174:175], 11, v[146:147]
	v_lshlrev_b64 v[176:177], 12, v[188:189]
	v_lshlrev_b64 v[178:179], 12, v[190:191]
	v_lshl_add_u64 v[174:175], s[42:43], 0, v[174:175]
	v_lshlrev_b64 v[172:173], 11, v[172:173]
	v_lshl_add_u64 v[176:177], v[148:149], 0, v[176:177]
	v_lshl_add_u64 v[184:185], v[148:149], 0, v[178:179]
	v_lshl_add_u64 v[192:193], v[174:175], 0, v[144:145]
	v_lshl_add_u64 v[194:195], s[42:43], 0, v[172:173]
	global_load_dwordx4 v[172:175], v[176:177], off
	s_nop 0
	global_load_dwordx4 v[176:179], v[176:177], off offset:256
	s_nop 0
	global_load_dwordx4 v[180:183], v[184:185], off
	s_nop 0
	global_load_dwordx4 v[184:187], v[184:185], off offset:256
	v_lshl_add_u64 v[194:195], v[194:195], 0, v[144:145]
	s_mov_b64 s[4:5], -1
	v_add_u32_e32 v250, 0x80, v146
	v_ashrrev_i32_e32 v251, 31, v250
	v_lshlrev_b64 v[252:253], 12, v[250:251]
	v_lshl_add_u64 v[250:251], v[148:149], 0, v[252:253]
	global_load_dwordx4 v[206:209], v[250:251], off
	global_load_dwordx4 v[210:213], v[250:251], off offset:256
	v_add_u32_e32 v250, 0x90, v146
	v_ashrrev_i32_e32 v251, 31, v250
	v_lshlrev_b64 v[252:253], 12, v[250:251]
	v_lshl_add_u64 v[250:251], v[148:149], 0, v[252:253]
	global_load_dwordx4 v[214:217], v[250:251], off
	global_load_dwordx4 v[218:221], v[250:251], off offset:256
	v_add_u32_e32 v250, 0xa0, v146
	v_ashrrev_i32_e32 v251, 31, v250
	v_lshlrev_b64 v[252:253], 12, v[250:251]
	v_lshl_add_u64 v[250:251], v[148:149], 0, v[252:253]
	global_load_dwordx4 v[222:225], v[250:251], off
	global_load_dwordx4 v[226:229], v[250:251], off offset:256
	v_add_u32_e32 v250, 0xb0, v146
	v_ashrrev_i32_e32 v251, 31, v250
	v_lshlrev_b64 v[252:253], 12, v[250:251]
	v_lshl_add_u64 v[250:251], v[148:149], 0, v[252:253]
	global_load_dwordx4 v[230:233], v[250:251], off
	global_load_dwordx4 v[234:237], v[250:251], off offset:256
	s_waitcnt vmcnt(8)
	v_lshlrev_b32_e32 v147, 16, v156
	v_and_b32_e32 v156, 0xffff0000, v156
	v_lshlrev_b32_e32 v201, 16, v162
	v_lshlrev_b32_e32 v196, 16, v157
	v_and_b32_e32 v157, 0xffff0000, v157
	v_lshlrev_b32_e32 v197, 16, v158
	v_and_b32_e32 v158, 0xffff0000, v158
	v_lshlrev_b32_e32 v198, 16, v159
	v_and_b32_e32 v159, 0xffff0000, v159
	v_lshlrev_b32_e32 v199, 16, v160
	v_and_b32_e32 v160, 0xffff0000, v160
	v_and_b32_e32 v162, 0xffff0000, v162
	v_lshlrev_b32_e32 v202, 16, v163
	v_and_b32_e32 v163, 0xffff0000, v163
	v_mul_f32_e32 v124, v124, v147
	v_mul_f32_e32 v125, v125, v156
	v_mul_f32_e32 v147, v104, v201
	v_cvt_pk_bf16_f32 v104, v124, v125
	v_lshlrev_b32_e32 v200, 16, v161
	v_and_b32_e32 v161, 0xffff0000, v161
	v_mul_f32_e32 v126, v126, v196
	v_mul_f32_e32 v127, v127, v157
	v_mul_f32_e32 v120, v120, v197
	v_mul_f32_e32 v121, v121, v158
	v_mul_f32_e32 v122, v122, v198
	v_mul_f32_e32 v123, v123, v159
	v_mul_f32_e32 v112, v112, v199
	v_mul_f32_e32 v113, v113, v160
	v_mul_f32_e32 v156, v105, v162
	v_mul_f32_e32 v157, v106, v202
	v_mul_f32_e32 v158, v107, v163
	v_cvt_pk_bf16_f32 v105, v126, v127
	v_cvt_pk_bf16_f32 v106, v120, v121
	v_cvt_pk_bf16_f32 v107, v122, v123
	global_store_dwordx4 v[192:193], v[104:107], off
	v_mul_f32_e32 v114, v114, v200
	v_mul_f32_e32 v115, v115, v161
	v_cvt_pk_bf16_f32 v104, v112, v113
	v_cvt_pk_bf16_f32 v105, v114, v115
	v_cvt_pk_bf16_f32 v106, v147, v156
	v_cvt_pk_bf16_f32 v107, v157, v158
	global_store_dwordx4 v[192:193], v[104:107], off offset:256
	v_lshlrev_b32_e32 v205, 16, v166
	v_lshlrev_b32_e32 v203, 16, v164
	v_and_b32_e32 v104, 0xffff0000, v166
	v_mul_f32_e32 v107, v109, v104
	v_lshlrev_b32_e32 v104, 16, v167
	v_and_b32_e32 v164, 0xffff0000, v164
	v_mul_f32_e32 v106, v108, v205
	v_mul_f32_e32 v108, v110, v104
	v_and_b32_e32 v104, 0xffff0000, v167
	v_lshlrev_b32_e32 v204, 16, v165
	v_and_b32_e32 v165, 0xffff0000, v165
	v_mul_f32_e32 v116, v116, v203
	v_mul_f32_e32 v117, v117, v164
	v_mul_f32_e32 v109, v111, v104
	v_cvt_pk_bf16_f32 v104, v116, v117
	v_mul_f32_e32 v118, v118, v204
	v_mul_f32_e32 v119, v119, v165
	v_cvt_pk_bf16_f32 v105, v118, v119
	v_cvt_pk_bf16_f32 v106, v106, v107
	v_cvt_pk_bf16_f32 v107, v108, v109
	global_store_dwordx4 v[194:195], v[104:107], off
	s_nop 1
	v_lshlrev_b32_e32 v104, 16, v168
	v_mul_f32_e32 v100, v100, v104
	v_and_b32_e32 v104, 0xffff0000, v168
	v_mul_f32_e32 v101, v101, v104
	v_lshlrev_b32_e32 v104, 16, v169
	v_mul_f32_e32 v102, v102, v104
	v_and_b32_e32 v104, 0xffff0000, v169
	v_mul_f32_e32 v103, v103, v104
	v_lshlrev_b32_e32 v104, 16, v170
	v_mul_f32_e32 v104, v92, v104
	v_and_b32_e32 v92, 0xffff0000, v170
	v_mul_f32_e32 v105, v93, v92
	v_lshlrev_b32_e32 v92, 16, v171
	v_mul_f32_e32 v106, v94, v92
	v_and_b32_e32 v92, 0xffff0000, v171
	v_mul_f32_e32 v95, v95, v92
	v_cvt_pk_bf16_f32 v92, v100, v101
	v_cvt_pk_bf16_f32 v93, v102, v103
	v_cvt_pk_bf16_f32 v94, v104, v105
	v_cvt_pk_bf16_f32 v95, v106, v95
	global_store_dwordx4 v[194:195], v[92:95], off offset:256
	v_add_u32_e32 v102, 0xb0, v146
	v_ashrrev_i32_e32 v103, 31, v102
	v_lshlrev_b32_e32 v94, 16, v172
	v_mul_f32_e32 v94, v96, v94
	v_lshlrev_b32_e32 v96, 16, v173
	v_and_b32_e32 v95, 0xffff0000, v172
	v_mul_f32_e32 v96, v98, v96
	v_lshlrev_b32_e32 v98, 16, v174
	v_mul_f32_e32 v95, v97, v95
	v_and_b32_e32 v97, 0xffff0000, v173
	v_mul_f32_e32 v98, v88, v98
	v_and_b32_e32 v88, 0xffff0000, v174
	v_lshlrev_b64 v[92:93], 11, v[188:189]
	v_mul_f32_e32 v97, v99, v97
	v_mul_f32_e32 v99, v89, v88
	v_lshlrev_b32_e32 v88, 16, v175
	v_lshl_add_u64 v[92:93], s[42:43], 0, v[92:93]
	v_mul_f32_e32 v100, v90, v88
	v_and_b32_e32 v88, 0xffff0000, v175
	v_lshl_add_u64 v[92:93], v[92:93], 0, v[144:145]
	v_mul_f32_e32 v91, v91, v88
	v_cvt_pk_bf16_f32 v88, v94, v95
	v_cvt_pk_bf16_f32 v89, v96, v97
	v_cvt_pk_bf16_f32 v90, v98, v99
	v_cvt_pk_bf16_f32 v91, v100, v91
	global_store_dwordx4 v[92:93], v[88:91], off
	v_add_u32_e32 v96, 0x80, v146
	v_ashrrev_i32_e32 v97, 31, v96
	v_lshlrev_b32_e32 v88, 16, v176
	v_mul_f32_e32 v84, v84, v88
	v_and_b32_e32 v88, 0xffff0000, v176
	v_mul_f32_e32 v85, v85, v88
	v_lshlrev_b32_e32 v88, 16, v177
	v_mul_f32_e32 v86, v86, v88
	v_and_b32_e32 v88, 0xffff0000, v177
	v_mul_f32_e32 v87, v87, v88
	v_lshlrev_b32_e32 v88, 16, v178
	v_mul_f32_e32 v88, v76, v88
	v_and_b32_e32 v76, 0xffff0000, v178
	v_mul_f32_e32 v89, v77, v76
	v_lshlrev_b32_e32 v76, 16, v179
	v_mul_f32_e32 v90, v78, v76
	v_and_b32_e32 v76, 0xffff0000, v179
	v_mul_f32_e32 v79, v79, v76
	v_cvt_pk_bf16_f32 v76, v84, v85
	v_cvt_pk_bf16_f32 v77, v86, v87
	v_cvt_pk_bf16_f32 v78, v88, v89
	v_cvt_pk_bf16_f32 v79, v90, v79
	global_store_dwordx4 v[92:93], v[76:79], off offset:256
	v_add_u32_e32 v98, 0x90, v146
	v_ashrrev_i32_e32 v99, 31, v98
	v_lshlrev_b32_e32 v78, 16, v180
	v_mul_f32_e32 v78, v80, v78
	v_lshlrev_b32_e32 v80, 16, v181
	v_and_b32_e32 v79, 0xffff0000, v180
	v_mul_f32_e32 v80, v82, v80
	v_lshlrev_b32_e32 v82, 16, v182
	v_mul_f32_e32 v79, v81, v79
	v_and_b32_e32 v81, 0xffff0000, v181
	v_mul_f32_e32 v82, v72, v82
	v_and_b32_e32 v72, 0xffff0000, v182
	v_lshlrev_b64 v[76:77], 11, v[190:191]
	v_mul_f32_e32 v81, v83, v81
	v_mul_f32_e32 v83, v73, v72
	v_lshlrev_b32_e32 v72, 16, v183
	v_lshl_add_u64 v[76:77], s[42:43], 0, v[76:77]
	v_mul_f32_e32 v84, v74, v72
	v_and_b32_e32 v72, 0xffff0000, v183
	v_lshl_add_u64 v[76:77], v[76:77], 0, v[144:145]
	v_mul_f32_e32 v75, v75, v72
	v_cvt_pk_bf16_f32 v72, v78, v79
	v_cvt_pk_bf16_f32 v73, v80, v81
	v_cvt_pk_bf16_f32 v74, v82, v83
	v_cvt_pk_bf16_f32 v75, v84, v75
	global_store_dwordx4 v[76:77], v[72:75], off
	v_add_u32_e32 v100, 0xa0, v146
	v_ashrrev_i32_e32 v101, 31, v100
	v_lshlrev_b32_e32 v72, 16, v184
	v_mul_f32_e32 v68, v68, v72
	v_and_b32_e32 v72, 0xffff0000, v184
	v_mul_f32_e32 v69, v69, v72
	v_lshlrev_b32_e32 v72, 16, v185
	v_mul_f32_e32 v70, v70, v72
	v_and_b32_e32 v72, 0xffff0000, v185
	v_mul_f32_e32 v71, v71, v72
	v_lshlrev_b32_e32 v72, 16, v186
	v_mul_f32_e32 v72, v64, v72
	v_and_b32_e32 v64, 0xffff0000, v186
	v_mul_f32_e32 v73, v65, v64
	v_lshlrev_b32_e32 v64, 16, v187
	v_mul_f32_e32 v74, v66, v64
	v_and_b32_e32 v64, 0xffff0000, v187
	v_mul_f32_e32 v67, v67, v64
	v_cvt_pk_bf16_f32 v64, v68, v69
	v_cvt_pk_bf16_f32 v65, v70, v71
	v_cvt_pk_bf16_f32 v66, v72, v73
	v_cvt_pk_bf16_f32 v67, v74, v67
	global_store_dwordx4 v[76:77], v[64:67], off offset:256
	v_lshlrev_b64 v[72:73], 12, v[98:99]
	v_lshl_add_u64 v[76:77], v[148:149], 0, v[72:73]
	v_lshlrev_b64 v[64:65], 12, v[96:97]
	v_lshl_add_u64 v[68:69], v[148:149], 0, v[64:65]
	s_waitcnt vmcnt(8)
	v_mov_b32_e32 v64, v206
	v_mov_b32_e32 v65, v207
	v_mov_b32_e32 v66, v208
	v_mov_b32_e32 v67, v209
	s_nop 0
	v_mov_b32_e32 v68, v210
	v_mov_b32_e32 v69, v211
	v_mov_b32_e32 v70, v212
	v_mov_b32_e32 v71, v213
	s_nop 0
	v_mov_b32_e32 v72, v214
	v_mov_b32_e32 v73, v215
	v_mov_b32_e32 v74, v216
	v_mov_b32_e32 v75, v217
	s_nop 0
	v_mov_b32_e32 v76, v218
	v_mov_b32_e32 v77, v219
	v_mov_b32_e32 v78, v220
	v_mov_b32_e32 v79, v221
	v_lshlrev_b64 v[80:81], 12, v[100:101]
	v_lshl_add_u64 v[84:85], v[148:149], 0, v[80:81]
	v_mov_b32_e32 v80, v222
	v_mov_b32_e32 v81, v223
	v_mov_b32_e32 v82, v224
	v_mov_b32_e32 v83, v225
	s_nop 0
	v_mov_b32_e32 v84, v226
	v_mov_b32_e32 v85, v227
	v_mov_b32_e32 v86, v228
	v_mov_b32_e32 v87, v229
	v_lshlrev_b64 v[88:89], 12, v[102:103]
	v_lshl_add_u64 v[92:93], v[148:149], 0, v[88:89]
	v_mov_b32_e32 v88, v230
	v_mov_b32_e32 v89, v231
	v_mov_b32_e32 v90, v232
	v_mov_b32_e32 v91, v233
	s_nop 0
	v_mov_b32_e32 v92, v234
	v_mov_b32_e32 v93, v235
	v_mov_b32_e32 v94, v236
	v_mov_b32_e32 v95, v237
	v_lshlrev_b64 v[96:97], 11, v[96:97]
	v_lshl_add_u64 v[96:97], s[42:43], 0, v[96:97]
	v_lshl_add_u64 v[96:97], v[96:97], 0, v[144:145]
	v_lshlrev_b32_e32 v104, 16, v64
	v_and_b32_e32 v64, 0xffff0000, v64
	v_mul_f32_e32 v61, v61, v64
	v_lshlrev_b32_e32 v64, 16, v65
	v_mul_f32_e32 v62, v62, v64
	v_and_b32_e32 v64, 0xffff0000, v65
	v_mul_f32_e32 v63, v63, v64
	v_lshlrev_b32_e32 v64, 16, v66
	v_mul_f32_e32 v64, v56, v64
	v_and_b32_e32 v56, 0xffff0000, v66
	v_mul_f32_e32 v65, v57, v56
	v_lshlrev_b32_e32 v56, 16, v67
	v_mul_f32_e32 v66, v58, v56
	v_and_b32_e32 v56, 0xffff0000, v67
	v_mul_f32_e32 v60, v60, v104
	v_mul_f32_e32 v59, v59, v56
	v_cvt_pk_bf16_f32 v56, v60, v61
	v_cvt_pk_bf16_f32 v57, v62, v63
	v_cvt_pk_bf16_f32 v58, v64, v65
	v_cvt_pk_bf16_f32 v59, v66, v59
	global_store_dwordx4 v[96:97], v[56:59], off
	s_nop 0
	v_lshlrev_b32_e32 v56, 16, v68
	v_mul_f32_e32 v52, v52, v56
	v_and_b32_e32 v56, 0xffff0000, v68
	v_mul_f32_e32 v53, v53, v56
	v_lshlrev_b32_e32 v56, 16, v69
	v_mul_f32_e32 v54, v54, v56
	v_and_b32_e32 v56, 0xffff0000, v69
	v_mul_f32_e32 v55, v55, v56
	v_lshlrev_b32_e32 v56, 16, v70
	v_mul_f32_e32 v56, v44, v56
	v_and_b32_e32 v44, 0xffff0000, v70
	v_mul_f32_e32 v57, v45, v44
	v_lshlrev_b32_e32 v44, 16, v71
	v_mul_f32_e32 v58, v46, v44
	v_and_b32_e32 v44, 0xffff0000, v71
	v_mul_f32_e32 v47, v47, v44
	v_cvt_pk_bf16_f32 v44, v52, v53
	v_cvt_pk_bf16_f32 v45, v54, v55
	v_cvt_pk_bf16_f32 v46, v56, v57
	v_cvt_pk_bf16_f32 v47, v58, v47
	global_store_dwordx4 v[96:97], v[44:47], off offset:256
	s_nop 0
	v_lshlrev_b32_e32 v46, 16, v72
	v_mul_f32_e32 v46, v48, v46
	v_lshlrev_b32_e32 v48, 16, v73
	v_and_b32_e32 v47, 0xffff0000, v72
	v_mul_f32_e32 v48, v50, v48
	v_lshlrev_b32_e32 v50, 16, v74
	v_mul_f32_e32 v47, v49, v47
	v_and_b32_e32 v49, 0xffff0000, v73
	v_mul_f32_e32 v50, v40, v50
	v_and_b32_e32 v40, 0xffff0000, v74
	v_lshlrev_b64 v[44:45], 11, v[98:99]
	v_mul_f32_e32 v49, v51, v49
	v_mul_f32_e32 v51, v41, v40
	v_lshlrev_b32_e32 v40, 16, v75
	v_lshl_add_u64 v[44:45], s[42:43], 0, v[44:45]
	v_mul_f32_e32 v52, v42, v40
	v_and_b32_e32 v40, 0xffff0000, v75
	v_lshl_add_u64 v[44:45], v[44:45], 0, v[144:145]
	v_mul_f32_e32 v43, v43, v40
	v_cvt_pk_bf16_f32 v40, v46, v47
	v_cvt_pk_bf16_f32 v41, v48, v49
	v_cvt_pk_bf16_f32 v42, v50, v51
	v_cvt_pk_bf16_f32 v43, v52, v43
	global_store_dwordx4 v[44:45], v[40:43], off
	s_nop 0
	v_lshlrev_b32_e32 v40, 16, v76
	v_mul_f32_e32 v36, v36, v40
	v_and_b32_e32 v40, 0xffff0000, v76
	v_mul_f32_e32 v37, v37, v40
	v_lshlrev_b32_e32 v40, 16, v77
	v_mul_f32_e32 v38, v38, v40
	v_and_b32_e32 v40, 0xffff0000, v77
	v_mul_f32_e32 v39, v39, v40
	v_lshlrev_b32_e32 v40, 16, v78
	v_mul_f32_e32 v40, v28, v40
	v_and_b32_e32 v28, 0xffff0000, v78
	v_mul_f32_e32 v41, v29, v28
	v_lshlrev_b32_e32 v28, 16, v79
	v_mul_f32_e32 v42, v30, v28
	v_and_b32_e32 v28, 0xffff0000, v79
	v_mul_f32_e32 v31, v31, v28
	v_cvt_pk_bf16_f32 v28, v36, v37
	v_cvt_pk_bf16_f32 v29, v38, v39
	v_cvt_pk_bf16_f32 v30, v40, v41
	v_cvt_pk_bf16_f32 v31, v42, v31
	global_store_dwordx4 v[44:45], v[28:31], off offset:256
	s_nop 0
	v_lshlrev_b32_e32 v30, 16, v80
	v_mul_f32_e32 v30, v32, v30
	v_lshlrev_b32_e32 v32, 16, v81
	v_and_b32_e32 v31, 0xffff0000, v80
	v_mul_f32_e32 v32, v34, v32
	v_lshlrev_b32_e32 v34, 16, v82
	v_mul_f32_e32 v31, v33, v31
	v_and_b32_e32 v33, 0xffff0000, v81
	v_mul_f32_e32 v34, v24, v34
	v_and_b32_e32 v24, 0xffff0000, v82
	v_lshlrev_b64 v[28:29], 11, v[100:101]
	v_mul_f32_e32 v33, v35, v33
	v_mul_f32_e32 v35, v25, v24
	v_lshlrev_b32_e32 v24, 16, v83
	v_lshl_add_u64 v[28:29], s[42:43], 0, v[28:29]
	v_mul_f32_e32 v36, v26, v24
	v_and_b32_e32 v24, 0xffff0000, v83
	v_lshl_add_u64 v[28:29], v[28:29], 0, v[144:145]
	v_mul_f32_e32 v27, v27, v24
	v_cvt_pk_bf16_f32 v24, v30, v31
	v_cvt_pk_bf16_f32 v25, v32, v33
	v_cvt_pk_bf16_f32 v26, v34, v35
	v_cvt_pk_bf16_f32 v27, v36, v27
	global_store_dwordx4 v[28:29], v[24:27], off
	s_nop 0
	v_lshlrev_b32_e32 v24, 16, v84
	v_mul_f32_e32 v20, v20, v24
	v_and_b32_e32 v24, 0xffff0000, v84
	v_mul_f32_e32 v21, v21, v24
	v_lshlrev_b32_e32 v24, 16, v85
	v_mul_f32_e32 v22, v22, v24
	v_and_b32_e32 v24, 0xffff0000, v85
	v_mul_f32_e32 v23, v23, v24
	v_lshlrev_b32_e32 v24, 16, v86
	v_mul_f32_e32 v24, v12, v24
	v_and_b32_e32 v12, 0xffff0000, v86
	v_mul_f32_e32 v25, v13, v12
	v_lshlrev_b32_e32 v12, 16, v87
	v_mul_f32_e32 v26, v14, v12
	v_and_b32_e32 v12, 0xffff0000, v87
	v_mul_f32_e32 v15, v15, v12
	v_cvt_pk_bf16_f32 v12, v20, v21
	v_cvt_pk_bf16_f32 v13, v22, v23
	v_cvt_pk_bf16_f32 v14, v24, v25
	v_cvt_pk_bf16_f32 v15, v26, v15
	global_store_dwordx4 v[28:29], v[12:15], off offset:256
	s_nop 0
	v_lshlrev_b32_e32 v14, 16, v88
	v_mul_f32_e32 v14, v16, v14
	v_lshlrev_b32_e32 v16, 16, v89
	v_and_b32_e32 v15, 0xffff0000, v88
	v_mul_f32_e32 v16, v18, v16
	v_lshlrev_b32_e32 v18, 16, v90
	v_mul_f32_e32 v15, v17, v15
	v_and_b32_e32 v17, 0xffff0000, v89
	v_mul_f32_e32 v18, v8, v18
	v_and_b32_e32 v8, 0xffff0000, v90
	v_lshlrev_b64 v[12:13], 11, v[102:103]
	v_mul_f32_e32 v17, v19, v17
	v_mul_f32_e32 v19, v9, v8
	v_lshlrev_b32_e32 v8, 16, v91
	v_lshl_add_u64 v[12:13], s[42:43], 0, v[12:13]
	v_mul_f32_e32 v20, v10, v8
	v_and_b32_e32 v8, 0xffff0000, v91
	v_lshl_add_u64 v[12:13], v[12:13], 0, v[144:145]
	v_mul_f32_e32 v11, v11, v8
	v_cvt_pk_bf16_f32 v8, v14, v15
	v_cvt_pk_bf16_f32 v9, v16, v17
	v_cvt_pk_bf16_f32 v10, v18, v19
	v_cvt_pk_bf16_f32 v11, v20, v11
	global_store_dwordx4 v[12:13], v[8:11], off
	s_nop 0
	v_lshlrev_b32_e32 v8, 16, v92
	v_mul_f32_e32 v4, v4, v8
	v_and_b32_e32 v8, 0xffff0000, v92
	v_mul_f32_e32 v5, v5, v8
	v_lshlrev_b32_e32 v8, 16, v93
	v_mul_f32_e32 v6, v6, v8
	v_and_b32_e32 v8, 0xffff0000, v93
	v_mul_f32_e32 v7, v7, v8
	v_lshlrev_b32_e32 v8, 16, v94
	v_mul_f32_e32 v8, v0, v8
	v_and_b32_e32 v0, 0xffff0000, v94
	v_mul_f32_e32 v9, v1, v0
	v_lshlrev_b32_e32 v0, 16, v95
	v_mul_f32_e32 v10, v2, v0
	v_and_b32_e32 v0, 0xffff0000, v95
	v_mul_f32_e32 v3, v3, v0
	v_cvt_pk_bf16_f32 v0, v4, v5
	v_cvt_pk_bf16_f32 v1, v6, v7
	v_cvt_pk_bf16_f32 v2, v8, v9
	v_cvt_pk_bf16_f32 v3, v10, v3
	global_store_dwordx4 v[12:13], v[0:3], off offset:256
	s_mov_b32 s99, 1
	s_cbranch_vccnz .LBB0_545
	s_andn2_b64 vcc, exec, s[6:7]
	s_cbranch_vccnz .LBB0_544
	s_barrier
	s_branch .LBB0_544

.LBB0_567:
	v_bfe_u32 v213, v8, 4, 2
	v_and_b32_e32 v212, 15, v8
	v_lshlrev_b32_e32 v9, 4, v213
	v_lshlrev_b32_e32 v8, 2, v8
	s_sext_i32_i8 s47, s4
	v_lshl_or_b32 v9, v212, 6, v9
	s_lshl_b32 s4, s5, 13
	v_and_b32_e32 v8, 32, v8
	v_bitop3_b32 v10, v9, s4, v8 bitop3:0xde
	s_lshl_b32 s4, s7, 5
	s_and_b32 s78, s4, 0x60
	s_lshl_b32 s4, s78, 7
	s_lshl_b32 s69, s5, 6
	v_bitop3_b32 v214, v9, s4, v8 bitop3:0xde
	s_mov_b64 s[4:5], 0x80
	s_add_i32 m0, s65, 0x18000
	v_lshl_add_u64 v[6:7], v[6:7], 0, s[4:5]
	s_waitcnt vmcnt(2)
	s_barrier
	global_load_lds_dwordx4 v[6:7], off
	v_lshl_add_u64 v[4:5], v[4:5], 0, s[4:5]
	s_add_i32 m0, s65, 0x1a000
	s_add_i32 s79, s65, 0x8000
	s_add_i32 s80, s65, 0xa000
	global_load_lds_dwordx4 v[4:5], off
	v_lshl_add_u64 v[0:1], v[0:1], 0, s[4:5]
	s_mov_b32 m0, s79
	s_add_u32 s8, s72, 0x10080
	global_load_lds_dwordx4 v[0:1], off
	v_lshl_add_u64 v[0:1], v[2:3], 0, s[4:5]
	s_mov_b32 m0, s80
	s_addc_u32 s9, s73, 0
	global_load_lds_dwordx4 v[0:1], off
	s_add_i32 m0, s65, 0x1c000
	v_lshl_add_u64 v[0:1], s[8:9], 0, v[186:187]
	global_load_lds_dwordx4 v[0:1], off
	v_lshl_add_u64 v[0:1], s[8:9], 0, v[190:191]
	s_add_i32 m0, s65, 0x1e000
	s_cmpk_lt_u32 s6, 0x100
	global_load_lds_dwordx4 v[0:1], off
	s_cselect_b64 s[6:7], -1, 0
	s_add_u32 s10, s38, s2
	s_waitcnt vmcnt(6)
	s_addc_u32 s11, s33, s3
	s_add_i32 s83, 0, 0x10000
	s_add_i32 s85, 0, 0x14000
	v_add_u32_e32 v215, s83, v214
	v_add_u32_e32 v216, s85, v214
	s_add_i32 s83, s83, s64
	s_add_i32 s85, s85, s64
	v_mov_b64_e32 v[192:193], 0x200
	v_mov_b64_e32 v[194:195], 0x1ff
	v_add_u32_e32 v217, 0, v10
	s_add_i32 s81, s65, 0xc000
	s_add_i32 s82, s65, 0xe000
	s_mov_b64 s[12:13], 0x100
	s_mov_b64 s[14:15], 0x180
	s_add_i32 s84, s83, 0x2000
	s_add_i32 s86, s85, 0x2000
	s_barrier
	s_mov_b32 s99, 0
	s_branch .LBB0_570

.Lrlx5p1b:
	s_waitcnt vmcnt(24)
	s_branch .Lrlx5p1b_done
.LBB0_568:
	s_add_u32 s10, s10, s38
	s_addc_u32 s11, s11, s33
	s_mov_b64 s[46:47], 0

.LBB0_576:
	ds_read_b128 v[0:3], v215
	ds_read_b128 v[4:7], v215 offset:1024
	ds_read_b128 v[8:11], v215 offset:2048
	ds_read_b128 v[12:15], v215 offset:3072
	ds_read_b128 v[16:19], v216
	ds_read_b128 v[20:23], v216 offset:1024
	ds_read_b128 v[24:27], v216 offset:2048
	ds_read_b128 v[28:31], v216 offset:3072
	s_ashr_i32 s37, s36, 31
	s_lshl_b64 s[60:61], s[36:37], 17
	v_readlane_b32 s62, v255, 24
	v_readlane_b32 s63, v255, 25
	s_add_u32 s60, s62, s60
	s_addc_u32 s61, s63, s61
	s_and_b64 s[62:63], s[8:9], exec
	s_cselect_b32 s77, s61, s71
	s_cselect_b32 s76, s60, s70
	s_ashr_i32 s35, s34, 31
	s_lshl_b64 s[62:63], s[34:35], 17
	v_readlane_b32 s74, v255, 30
	v_readlane_b32 s75, v255, 31
	s_add_u32 s62, s74, s62
	s_addc_u32 s63, s75, s63
	s_and_b64 s[74:75], s[8:9], exec
	s_cselect_b32 s75, s63, s73
	s_cselect_b32 s74, s62, s72
	s_add_u32 s88, s70, 0x10080
	s_addc_u32 s89, s71, 0
	s_mov_b32 m0, s81
	v_lshl_add_u64 v[64:65], s[88:89], 0, v[184:185]
	ds_read_b128 v[32:35], v217
	ds_read_b128 v[36:39], v217 offset:1024
	ds_read_b128 v[40:43], v217 offset:2048
	ds_read_b128 v[44:47], v217 offset:3072
	ds_read_b128 v[48:51], v217 offset:4096
	ds_read_b128 v[52:55], v217 offset:5120
	ds_read_b128 v[56:59], v217 offset:6144
	ds_read_b128 v[60:63], v217 offset:7168
	global_load_lds_dwordx4 v[64:65], off
	v_lshl_add_u64 v[64:65], s[88:89], 0, v[188:189]
	s_mov_b32 m0, s82
	s_nop 0
	global_load_lds_dwordx4 v[64:65], off
	s_cmp_lg_u32 s99, 0
	s_cbranch_scc1 .Lrlx5p1a
	s_waitcnt vmcnt(8)
.Lrlx5p1a_done:
	s_waitcnt lgkmcnt(0)
	s_barrier
	s_setprio 1
	s_waitcnt lgkmcnt(0)
	v_mfma_f32_16x16x32_bf16 v[64:67], v[0:3], v[32:35], 0
	v_mfma_f32_16x16x32_bf16 v[68:71], v[8:11], v[32:35], 0
	v_mfma_f32_16x16x32_bf16 v[72:75], v[0:3], v[40:43], 0
	v_mfma_f32_16x16x32_bf16 v[76:79], v[8:11], v[40:43], 0
	v_mfma_f32_16x16x32_bf16 v[80:83], v[0:3], v[48:51], 0
	v_mfma_f32_16x16x32_bf16 v[84:87], v[8:11], v[48:51], 0
	v_mfma_f32_16x16x32_bf16 v[88:91], v[0:3], v[56:59], 0
	v_mfma_f32_16x16x32_bf16 v[92:95], v[8:11], v[56:59], 0
	v_mfma_f32_16x16x32_bf16 v[64:67], v[4:7], v[36:39], v[64:67]
	v_mfma_f32_16x16x32_bf16 v[68:71], v[12:15], v[36:39], v[68:71]
	v_mfma_f32_16x16x32_bf16 v[72:75], v[4:7], v[44:47], v[72:75]
	v_mfma_f32_16x16x32_bf16 v[76:79], v[12:15], v[44:47], v[76:79]
	v_mfma_f32_16x16x32_bf16 v[80:83], v[4:7], v[52:55], v[80:83]
	v_mfma_f32_16x16x32_bf16 v[84:87], v[12:15], v[52:55], v[84:87]
	v_mfma_f32_16x16x32_bf16 v[88:91], v[4:7], v[60:63], v[88:91]
	v_mfma_f32_16x16x32_bf16 v[92:95], v[12:15], v[60:63], v[92:95]
	s_setprio 0
	s_setprio 1
	v_mfma_f32_16x16x32_bf16 v[96:99], v[16:19], v[32:35], 0
	v_mfma_f32_16x16x32_bf16 v[32:35], v[24:27], v[32:35], 0
	v_mfma_f32_16x16x32_bf16 v[96:99], v[20:23], v[36:39], v[96:99]
	v_mfma_f32_16x16x32_bf16 v[32:35], v[28:31], v[36:39], v[32:35]
	v_mfma_f32_16x16x32_bf16 v[36:39], v[16:19], v[40:43], 0
	v_mfma_f32_16x16x32_bf16 v[40:43], v[24:27], v[40:43], 0
	v_mfma_f32_16x16x32_bf16 v[36:39], v[20:23], v[44:47], v[36:39]
	v_mfma_f32_16x16x32_bf16 v[40:43], v[28:31], v[44:47], v[40:43]
	v_mfma_f32_16x16x32_bf16 v[44:47], v[16:19], v[48:51], 0
	v_mfma_f32_16x16x32_bf16 v[48:51], v[24:27], v[48:51], 0
	v_mfma_f32_16x16x32_bf16 v[44:47], v[20:23], v[52:55], v[44:47]
	v_mfma_f32_16x16x32_bf16 v[48:51], v[28:31], v[52:55], v[48:51]
	v_mfma_f32_16x16x32_bf16 v[52:55], v[16:19], v[56:59], 0
	v_mfma_f32_16x16x32_bf16 v[56:59], v[24:27], v[56:59], 0
	v_mfma_f32_16x16x32_bf16 v[52:55], v[20:23], v[60:63], v[52:55]
	v_mfma_f32_16x16x32_bf16 v[56:59], v[28:31], v[60:63], v[56:59]
	s_setprio 0
	s_barrier
	v_lshl_add_u64 v[204:205], s[72:73], 0, v[186:187]
	s_mov_b32 m0, s83
	v_lshl_add_u64 v[128:129], v[204:205], 0, s[12:13]
	v_lshl_add_u64 v[206:207], s[72:73], 0, v[190:191]
	s_add_u32 s88, s72, 0x10100
	ds_read_b128 v[60:63], v217 offset:16384
	ds_read_b128 v[100:103], v217 offset:17408
	ds_read_b128 v[104:107], v217 offset:18432
	ds_read_b128 v[108:111], v217 offset:19456
	ds_read_b128 v[112:115], v217 offset:20480
	ds_read_b128 v[116:119], v217 offset:21504
	ds_read_b128 v[120:123], v217 offset:22528
	ds_read_b128 v[124:127], v217 offset:23552
	global_load_lds_dwordx4 v[128:129], off
	v_lshl_add_u64 v[128:129], v[206:207], 0, s[12:13]
	s_mov_b32 m0, s84
	s_addc_u32 s89, s73, 0
	global_load_lds_dwordx4 v[128:129], off
	v_lshl_add_u64 v[128:129], s[88:89], 0, v[186:187]
	s_mov_b32 m0, s85
	v_lshl_add_u64 v[208:209], s[70:71], 0, v[184:185]
	global_load_lds_dwordx4 v[128:129], off
	v_lshl_add_u64 v[128:129], s[88:89], 0, v[190:191]
	s_mov_b32 m0, s86
	v_lshl_add_u64 v[218:219], s[70:71], 0, v[188:189]
	global_load_lds_dwordx4 v[128:129], off
	v_lshl_add_u64 v[128:129], v[208:209], 0, s[12:13]
	s_mov_b32 m0, s65
	s_nop 0
	global_load_lds_dwordx4 v[128:129], off
	v_lshl_add_u64 v[128:129], v[218:219], 0, s[12:13]
	s_mov_b32 m0, s66
	s_nop 0
	global_load_lds_dwordx4 v[128:129], off
	s_cmp_lg_u32 s99, 0
	s_cbranch_scc1 .Lrlx5p1b
	s_waitcnt vmcnt(8)
.Lrlx5p1b_done:
	s_mov_b32 s99, 0
	s_waitcnt lgkmcnt(0)
	s_barrier
	s_setprio 1
	s_waitcnt lgkmcnt(0)
	v_mfma_f32_16x16x32_bf16 v[128:131], v[0:3], v[60:63], 0
	v_mfma_f32_16x16x32_bf16 v[136:139], v[0:3], v[104:107], 0
	v_mfma_f32_16x16x32_bf16 v[144:147], v[0:3], v[112:115], 0
	v_mfma_f32_16x16x32_bf16 v[0:3], v[0:3], v[120:123], 0
	v_mfma_f32_16x16x32_bf16 v[128:131], v[4:7], v[100:103], v[128:131]
	v_mfma_f32_16x16x32_bf16 v[136:139], v[4:7], v[108:111], v[136:139]
	v_mfma_f32_16x16x32_bf16 v[144:147], v[4:7], v[116:119], v[144:147]
	v_mfma_f32_16x16x32_bf16 v[0:3], v[4:7], v[124:127], v[0:3]
	v_mfma_f32_16x16x32_bf16 v[4:7], v[8:11], v[120:123], 0
	v_mfma_f32_16x16x32_bf16 v[132:135], v[8:11], v[60:63], 0
	v_mfma_f32_16x16x32_bf16 v[140:143], v[8:11], v[104:107], 0
	v_mfma_f32_16x16x32_bf16 v[148:151], v[8:11], v[112:115], 0
	v_mfma_f32_16x16x32_bf16 v[4:7], v[12:15], v[124:127], v[4:7]
	v_mfma_f32_16x16x32_bf16 v[132:135], v[12:15], v[100:103], v[132:135]
	v_mfma_f32_16x16x32_bf16 v[140:143], v[12:15], v[108:111], v[140:143]
	v_mfma_f32_16x16x32_bf16 v[148:151], v[12:15], v[116:119], v[148:151]
	s_setprio 0
	s_setprio 1
	v_mfma_f32_16x16x32_bf16 v[8:11], v[16:19], v[60:63], 0
	v_mfma_f32_16x16x32_bf16 v[12:15], v[24:27], v[60:63], 0
	v_mfma_f32_16x16x32_bf16 v[8:11], v[20:23], v[100:103], v[8:11]
	v_mfma_f32_16x16x32_bf16 v[12:15], v[28:31], v[100:103], v[12:15]
	v_mfma_f32_16x16x32_bf16 v[60:63], v[16:19], v[104:107], 0
	v_mfma_f32_16x16x32_bf16 v[100:103], v[24:27], v[104:107], 0
	v_mfma_f32_16x16x32_bf16 v[104:107], v[16:19], v[112:115], 0
	v_mfma_f32_16x16x32_bf16 v[16:19], v[16:19], v[120:123], 0
	v_mfma_f32_16x16x32_bf16 v[60:63], v[20:23], v[108:111], v[60:63]
	v_mfma_f32_16x16x32_bf16 v[100:103], v[28:31], v[108:111], v[100:103]
	v_mfma_f32_16x16x32_bf16 v[104:107], v[20:23], v[116:119], v[104:107]
	v_mfma_f32_16x16x32_bf16 v[108:111], v[24:27], v[112:115], 0
	v_mfma_f32_16x16x32_bf16 v[16:19], v[20:23], v[124:127], v[16:19]
	v_mfma_f32_16x16x32_bf16 v[20:23], v[24:27], v[120:123], 0
	v_mfma_f32_16x16x32_bf16 v[108:111], v[28:31], v[116:119], v[108:111]
	v_mfma_f32_16x16x32_bf16 v[20:23], v[28:31], v[124:127], v[20:23]
	s_setprio 0
	s_barrier
	s_add_i32 s87, 0, 0x18000
	s_add_i32 s37, 0, 0x1c000
	v_add_u32_e32 v226, s87, v214
	v_add_u32_e32 v227, s37, v214
	ds_read_b128 v[24:27], v226
	ds_read_b128 v[28:31], v226 offset:1024
	ds_read_b128 v[112:115], v226 offset:2048
	ds_read_b128 v[116:119], v226 offset:3072
	ds_read_b128 v[120:123], v227
	ds_read_b128 v[124:127], v227 offset:1024
	ds_read_b128 v[152:155], v227 offset:2048
	ds_read_b128 v[156:159], v227 offset:3072
	s_add_u32 s88, s70, 0x10100
	s_addc_u32 s89, s71, 0
	s_mov_b32 m0, s67
	v_lshl_add_u64 v[220:221], s[88:89], 0, v[184:185]
	ds_read_b128 v[160:163], v217 offset:32768
	ds_read_b128 v[164:167], v217 offset:33792
	ds_read_b128 v[168:171], v217 offset:34816
	ds_read_b128 v[172:175], v217 offset:35840
	ds_read_b128 v[176:179], v217 offset:36864
	ds_read_b128 v[180:183], v217 offset:37888
	ds_read_b128 v[196:199], v217 offset:38912
	ds_read_b128 v[200:203], v217 offset:39936
	global_load_lds_dwordx4 v[220:221], off
	v_lshl_add_u64 v[220:221], s[88:89], 0, v[188:189]
	s_mov_b32 m0, s68
	s_nop 0
	global_load_lds_dwordx4 v[220:221], off
	s_waitcnt vmcnt(8)
	s_waitcnt lgkmcnt(0)
	s_barrier
	s_setprio 1
	s_waitcnt lgkmcnt(0)
	v_mfma_f32_16x16x32_bf16 v[64:67], v[24:27], v[160:163], v[64:67]
	v_mfma_f32_16x16x32_bf16 v[68:71], v[112:115], v[160:163], v[68:71]
	v_mfma_f32_16x16x32_bf16 v[72:75], v[24:27], v[168:171], v[72:75]
	v_mfma_f32_16x16x32_bf16 v[76:79], v[112:115], v[168:171], v[76:79]
	v_mfma_f32_16x16x32_bf16 v[80:83], v[24:27], v[176:179], v[80:83]
	v_mfma_f32_16x16x32_bf16 v[84:87], v[112:115], v[176:179], v[84:87]
	v_mfma_f32_16x16x32_bf16 v[88:91], v[24:27], v[196:199], v[88:91]
	v_mfma_f32_16x16x32_bf16 v[92:95], v[112:115], v[196:199], v[92:95]
	v_mfma_f32_16x16x32_bf16 v[64:67], v[28:31], v[164:167], v[64:67]
	v_mfma_f32_16x16x32_bf16 v[68:71], v[116:119], v[164:167], v[68:71]
	v_mfma_f32_16x16x32_bf16 v[72:75], v[28:31], v[172:175], v[72:75]
	v_mfma_f32_16x16x32_bf16 v[76:79], v[116:119], v[172:175], v[76:79]
	v_mfma_f32_16x16x32_bf16 v[80:83], v[28:31], v[180:183], v[80:83]
	v_mfma_f32_16x16x32_bf16 v[84:87], v[116:119], v[180:183], v[84:87]
	v_mfma_f32_16x16x32_bf16 v[88:91], v[28:31], v[200:203], v[88:91]
	v_mfma_f32_16x16x32_bf16 v[92:95], v[116:119], v[200:203], v[92:95]
	s_setprio 0
	s_setprio 1
	v_mfma_f32_16x16x32_bf16 v[96:99], v[120:123], v[160:163], v[96:99]
	v_mfma_f32_16x16x32_bf16 v[32:35], v[152:155], v[160:163], v[32:35]
	v_mfma_f32_16x16x32_bf16 v[36:39], v[120:123], v[168:171], v[36:39]
	v_mfma_f32_16x16x32_bf16 v[40:43], v[152:155], v[168:171], v[40:43]
	v_mfma_f32_16x16x32_bf16 v[44:47], v[120:123], v[176:179], v[44:47]
	v_mfma_f32_16x16x32_bf16 v[48:51], v[152:155], v[176:179], v[48:51]
	v_mfma_f32_16x16x32_bf16 v[52:55], v[120:123], v[196:199], v[52:55]
	v_mfma_f32_16x16x32_bf16 v[56:59], v[152:155], v[196:199], v[56:59]
	v_mfma_f32_16x16x32_bf16 v[96:99], v[124:127], v[164:167], v[96:99]
	v_mfma_f32_16x16x32_bf16 v[32:35], v[156:159], v[164:167], v[32:35]
	v_mfma_f32_16x16x32_bf16 v[36:39], v[124:127], v[172:175], v[36:39]
	v_mfma_f32_16x16x32_bf16 v[40:43], v[156:159], v[172:175], v[40:43]
	v_mfma_f32_16x16x32_bf16 v[44:47], v[124:127], v[180:183], v[44:47]
	v_mfma_f32_16x16x32_bf16 v[48:51], v[156:159], v[180:183], v[48:51]
	v_mfma_f32_16x16x32_bf16 v[52:55], v[124:127], v[200:203], v[52:55]
	v_mfma_f32_16x16x32_bf16 v[56:59], v[156:159], v[200:203], v[56:59]
	s_setprio 0
	s_barrier
	s_add_i32 s87, s87, s64
	s_add_i32 s35, s87, 0x2000
	v_lshl_add_u64 v[204:205], v[204:205], 0, s[14:15]
	s_mov_b32 m0, s87
	s_add_u32 s72, s72, 0x10180
	ds_read_b128 v[160:163], v217 offset:49152
	ds_read_b128 v[164:167], v217 offset:50176
	ds_read_b128 v[168:171], v217 offset:51200
	ds_read_b128 v[172:175], v217 offset:52224
	ds_read_b128 v[176:179], v217 offset:53248
	ds_read_b128 v[180:183], v217 offset:54272
	ds_read_b128 v[196:199], v217 offset:55296
	ds_read_b128 v[200:203], v217 offset:56320
	global_load_lds_dwordx4 v[204:205], off
	v_lshl_add_u64 v[204:205], v[206:207], 0, s[14:15]
	s_mov_b32 m0, s35
	s_addc_u32 s73, s73, 0
	s_add_i32 s37, s37, s64
	global_load_lds_dwordx4 v[204:205], off
	v_lshl_add_u64 v[204:205], s[72:73], 0, v[186:187]
	s_mov_b32 m0, s37
	s_nop 0
	global_load_lds_dwordx4 v[204:205], off
	v_lshl_add_u64 v[204:205], s[72:73], 0, v[190:191]
	s_add_i32 s72, s37, 0x2000
	s_mov_b32 m0, s72
	s_nop 0
	global_load_lds_dwordx4 v[204:205], off
	v_lshl_add_u64 v[204:205], v[208:209], 0, s[14:15]
	s_mov_b32 m0, s79
	s_nop 0
	global_load_lds_dwordx4 v[204:205], off
	v_lshl_add_u64 v[204:205], v[218:219], 0, s[14:15]
	s_mov_b32 m0, s80
	s_nop 0
	global_load_lds_dwordx4 v[204:205], off
	s_waitcnt vmcnt(8)
	s_waitcnt lgkmcnt(0)
	s_barrier
	s_setprio 1
	s_waitcnt lgkmcnt(0)
	v_mfma_f32_16x16x32_bf16 v[0:3], v[24:27], v[196:199], v[0:3]
	v_mfma_f32_16x16x32_bf16 v[4:7], v[112:115], v[196:199], v[4:7]
	v_mfma_f32_16x16x32_bf16 v[128:131], v[24:27], v[160:163], v[128:131]
	v_mfma_f32_16x16x32_bf16 v[132:135], v[112:115], v[160:163], v[132:135]
	v_mfma_f32_16x16x32_bf16 v[136:139], v[24:27], v[168:171], v[136:139]
	v_mfma_f32_16x16x32_bf16 v[140:143], v[112:115], v[168:171], v[140:143]
	v_mfma_f32_16x16x32_bf16 v[144:147], v[24:27], v[176:179], v[144:147]
	v_mfma_f32_16x16x32_bf16 v[148:151], v[112:115], v[176:179], v[148:151]
	v_mfma_f32_16x16x32_bf16 v[0:3], v[28:31], v[200:203], v[0:3]
	v_mfma_f32_16x16x32_bf16 v[4:7], v[116:119], v[200:203], v[4:7]
	v_mfma_f32_16x16x32_bf16 v[128:131], v[28:31], v[164:167], v[128:131]
	v_mfma_f32_16x16x32_bf16 v[132:135], v[116:119], v[164:167], v[132:135]
	v_mfma_f32_16x16x32_bf16 v[136:139], v[28:31], v[172:175], v[136:139]
	v_mfma_f32_16x16x32_bf16 v[140:143], v[116:119], v[172:175], v[140:143]
	v_mfma_f32_16x16x32_bf16 v[144:147], v[28:31], v[180:183], v[144:147]
	v_mfma_f32_16x16x32_bf16 v[148:151], v[116:119], v[180:183], v[148:151]
	s_setprio 0
	s_setprio 1
	v_mfma_f32_16x16x32_bf16 v[8:11], v[120:123], v[160:163], v[8:11]
	v_mfma_f32_16x16x32_bf16 v[12:15], v[152:155], v[160:163], v[12:15]
	v_mfma_f32_16x16x32_bf16 v[24:27], v[120:123], v[168:171], v[60:63]
	v_mfma_f32_16x16x32_bf16 v[28:31], v[152:155], v[168:171], v[100:103]
	v_mfma_f32_16x16x32_bf16 v[60:63], v[120:123], v[176:179], v[104:107]
	v_mfma_f32_16x16x32_bf16 v[100:103], v[152:155], v[176:179], v[108:111]
	v_mfma_f32_16x16x32_bf16 v[16:19], v[120:123], v[196:199], v[16:19]
	v_mfma_f32_16x16x32_bf16 v[20:23], v[152:155], v[196:199], v[20:23]
	v_mfma_f32_16x16x32_bf16 v[8:11], v[124:127], v[164:167], v[8:11]
	v_mfma_f32_16x16x32_bf16 v[12:15], v[156:159], v[164:167], v[12:15]
	v_mfma_f32_16x16x32_bf16 v[24:27], v[124:127], v[172:175], v[24:27]
	v_mfma_f32_16x16x32_bf16 v[28:31], v[156:159], v[172:175], v[28:31]
	v_mfma_f32_16x16x32_bf16 v[60:63], v[124:127], v[180:183], v[60:63]
	v_mfma_f32_16x16x32_bf16 v[100:103], v[156:159], v[180:183], v[100:103]
	v_mfma_f32_16x16x32_bf16 v[16:19], v[124:127], v[200:203], v[16:19]
	v_mfma_f32_16x16x32_bf16 v[20:23], v[156:159], v[200:203], v[20:23]
	s_setprio 0
	s_barrier
	ds_read_b128 v[104:107], v215
	ds_read_b128 v[108:111], v215 offset:1024
	ds_read_b128 v[112:115], v215 offset:2048
	ds_read_b128 v[116:119], v215 offset:3072
	ds_read_b128 v[120:123], v216
	ds_read_b128 v[124:127], v216 offset:1024
	ds_read_b128 v[152:155], v216 offset:2048
	ds_read_b128 v[156:159], v216 offset:3072
	s_add_u32 s70, s70, 0x10180
	s_addc_u32 s71, s71, 0
	s_mov_b32 m0, s81
	v_lshl_add_u64 v[204:205], s[70:71], 0, v[184:185]
	ds_read_b128 v[160:163], v217
	ds_read_b128 v[164:167], v217 offset:1024
	ds_read_b128 v[168:171], v217 offset:2048
	ds_read_b128 v[172:175], v217 offset:3072
	ds_read_b128 v[176:179], v217 offset:4096
	ds_read_b128 v[180:183], v217 offset:5120
	ds_read_b128 v[196:199], v217 offset:6144
	ds_read_b128 v[200:203], v217 offset:7168
	global_load_lds_dwordx4 v[204:205], off
	v_lshl_add_u64 v[204:205], s[70:71], 0, v[188:189]
	s_mov_b32 m0, s82
	s_nop 0
	global_load_lds_dwordx4 v[204:205], off
	s_waitcnt vmcnt(8)
	s_waitcnt lgkmcnt(0)
	s_barrier
	s_setprio 1
	s_waitcnt lgkmcnt(0)
	v_mfma_f32_16x16x32_bf16 v[64:67], v[104:107], v[160:163], v[64:67]
	v_mfma_f32_16x16x32_bf16 v[68:71], v[112:115], v[160:163], v[68:71]
	v_mfma_f32_16x16x32_bf16 v[72:75], v[104:107], v[168:171], v[72:75]
	v_mfma_f32_16x16x32_bf16 v[76:79], v[112:115], v[168:171], v[76:79]
	v_mfma_f32_16x16x32_bf16 v[80:83], v[104:107], v[176:179], v[80:83]
	v_mfma_f32_16x16x32_bf16 v[84:87], v[112:115], v[176:179], v[84:87]
	v_mfma_f32_16x16x32_bf16 v[88:91], v[104:107], v[196:199], v[88:91]
	v_mfma_f32_16x16x32_bf16 v[64:67], v[108:111], v[164:167], v[64:67]
	v_mfma_f32_16x16x32_bf16 v[68:71], v[116:119], v[164:167], v[68:71]
	v_mfma_f32_16x16x32_bf16 v[72:75], v[108:111], v[172:175], v[72:75]
	v_mfma_f32_16x16x32_bf16 v[76:79], v[116:119], v[172:175], v[76:79]
	v_mfma_f32_16x16x32_bf16 v[80:83], v[108:111], v[180:183], v[80:83]
	v_mfma_f32_16x16x32_bf16 v[84:87], v[116:119], v[180:183], v[84:87]
	v_mfma_f32_16x16x32_bf16 v[204:207], v[108:111], v[200:203], v[88:91]
	v_mfma_f32_16x16x32_bf16 v[88:91], v[112:115], v[196:199], v[92:95]
	v_mfma_f32_16x16x32_bf16 v[218:221], v[116:119], v[200:203], v[88:91]
	s_setprio 0
	s_setprio 1
	v_mfma_f32_16x16x32_bf16 v[88:91], v[120:123], v[160:163], v[96:99]
	v_mfma_f32_16x16x32_bf16 v[32:35], v[152:155], v[160:163], v[32:35]
	v_mfma_f32_16x16x32_bf16 v[36:39], v[120:123], v[168:171], v[36:39]
	v_mfma_f32_16x16x32_bf16 v[40:43], v[152:155], v[168:171], v[40:43]
	v_mfma_f32_16x16x32_bf16 v[44:47], v[120:123], v[176:179], v[44:47]
	v_mfma_f32_16x16x32_bf16 v[48:51], v[152:155], v[176:179], v[48:51]
	v_mfma_f32_16x16x32_bf16 v[52:55], v[120:123], v[196:199], v[52:55]
	v_mfma_f32_16x16x32_bf16 v[56:59], v[152:155], v[196:199], v[56:59]
	v_mfma_f32_16x16x32_bf16 v[96:99], v[124:127], v[164:167], v[88:91]
	v_mfma_f32_16x16x32_bf16 v[32:35], v[156:159], v[164:167], v[32:35]
	v_mfma_f32_16x16x32_bf16 v[36:39], v[124:127], v[172:175], v[36:39]
	v_mfma_f32_16x16x32_bf16 v[40:43], v[156:159], v[172:175], v[40:43]
	v_mfma_f32_16x16x32_bf16 v[44:47], v[124:127], v[180:183], v[44:47]
	v_mfma_f32_16x16x32_bf16 v[48:51], v[156:159], v[180:183], v[48:51]
	v_mfma_f32_16x16x32_bf16 v[52:55], v[124:127], v[200:203], v[52:55]
	v_mfma_f32_16x16x32_bf16 v[56:59], v[156:159], v[200:203], v[56:59]
	s_setprio 0
	s_barrier
	s_mov_b32 m0, s83
	v_lshl_add_u64 v[208:209], s[74:75], 0, v[186:187]
	s_add_u32 s70, s74, 0x10000
	ds_read_b128 v[88:91], v217 offset:16384
	ds_read_b128 v[92:95], v217 offset:17408
	ds_read_b128 v[160:163], v217 offset:18432
	ds_read_b128 v[164:167], v217 offset:19456
	ds_read_b128 v[168:171], v217 offset:20480
	ds_read_b128 v[172:175], v217 offset:21504
	ds_read_b128 v[176:179], v217 offset:22528
	ds_read_b128 v[180:183], v217 offset:23552
	global_load_lds_dwordx4 v[208:209], off
	v_lshl_add_u64 v[250:251], s[74:75], 0, v[190:191]
	s_mov_b32 m0, s84
	s_addc_u32 s71, s75, 0
	global_load_lds_dwordx4 v[250:251], off
	v_lshl_add_u64 v[196:197], s[70:71], 0, v[186:187]
	s_mov_b32 m0, s85
	v_lshl_add_u64 v[252:253], s[76:77], 0, v[184:185]
	global_load_lds_dwordx4 v[196:197], off
	v_lshl_add_u64 v[196:197], s[70:71], 0, v[190:191]
	s_mov_b32 m0, s86
	v_lshl_add_u64 v[210:211], s[76:77], 0, v[188:189]
	global_load_lds_dwordx4 v[196:197], off
	s_mov_b32 m0, s65
	s_nop 0
	global_load_lds_dwordx4 v[252:253], off
	s_mov_b32 m0, s66
	s_nop 0
	global_load_lds_dwordx4 v[210:211], off
	s_waitcnt vmcnt(8)
	s_waitcnt lgkmcnt(0)
	s_barrier
	s_setprio 1
	s_waitcnt lgkmcnt(0)
	v_mfma_f32_16x16x32_bf16 v[0:3], v[104:107], v[176:179], v[0:3]
	v_mfma_f32_16x16x32_bf16 v[4:7], v[112:115], v[176:179], v[4:7]
	v_mfma_f32_16x16x32_bf16 v[128:131], v[104:107], v[88:91], v[128:131]
	v_mfma_f32_16x16x32_bf16 v[132:135], v[112:115], v[88:91], v[132:135]
	v_mfma_f32_16x16x32_bf16 v[136:139], v[104:107], v[160:163], v[136:139]
	v_mfma_f32_16x16x32_bf16 v[140:143], v[112:115], v[160:163], v[140:143]
	v_mfma_f32_16x16x32_bf16 v[144:147], v[104:107], v[168:171], v[144:147]
	v_mfma_f32_16x16x32_bf16 v[148:151], v[112:115], v[168:171], v[148:151]
	v_mfma_f32_16x16x32_bf16 v[0:3], v[108:111], v[180:183], v[0:3]
	v_mfma_f32_16x16x32_bf16 v[4:7], v[116:119], v[180:183], v[4:7]
	v_mfma_f32_16x16x32_bf16 v[128:131], v[108:111], v[92:95], v[128:131]
	v_mfma_f32_16x16x32_bf16 v[132:135], v[116:119], v[92:95], v[132:135]
	v_mfma_f32_16x16x32_bf16 v[136:139], v[108:111], v[164:167], v[136:139]
	v_mfma_f32_16x16x32_bf16 v[140:143], v[116:119], v[164:167], v[140:143]
	v_mfma_f32_16x16x32_bf16 v[144:147], v[108:111], v[172:175], v[144:147]
	v_mfma_f32_16x16x32_bf16 v[148:151], v[116:119], v[172:175], v[148:151]
	s_setprio 0
	s_setprio 1
	v_mfma_f32_16x16x32_bf16 v[8:11], v[120:123], v[88:91], v[8:11]
	v_mfma_f32_16x16x32_bf16 v[116:119], v[124:127], v[92:95], v[8:11]
	v_mfma_f32_16x16x32_bf16 v[8:11], v[152:155], v[88:91], v[12:15]
	v_mfma_f32_16x16x32_bf16 v[196:199], v[156:159], v[92:95], v[8:11]
	v_mfma_f32_16x16x32_bf16 v[8:11], v[120:123], v[160:163], v[24:27]
	v_mfma_f32_16x16x32_bf16 v[200:203], v[124:127], v[164:167], v[8:11]
	v_mfma_f32_16x16x32_bf16 v[8:11], v[152:155], v[160:163], v[28:31]
	v_mfma_f32_16x16x32_bf16 v[160:163], v[156:159], v[164:167], v[8:11]
	v_mfma_f32_16x16x32_bf16 v[8:11], v[120:123], v[168:171], v[60:63]
	v_mfma_f32_16x16x32_bf16 v[222:225], v[124:127], v[172:175], v[8:11]
	v_mfma_f32_16x16x32_bf16 v[8:11], v[152:155], v[168:171], v[100:103]
	v_mfma_f32_16x16x32_bf16 v[168:171], v[156:159], v[172:175], v[8:11]
	v_mfma_f32_16x16x32_bf16 v[8:11], v[120:123], v[176:179], v[16:19]
	v_mfma_f32_16x16x32_bf16 v[124:127], v[124:127], v[180:183], v[8:11]
	v_mfma_f32_16x16x32_bf16 v[8:11], v[152:155], v[176:179], v[20:23]
	v_mfma_f32_16x16x32_bf16 v[156:159], v[156:159], v[180:183], v[8:11]
	s_setprio 0
	s_barrier
	s_nop 4
	ds_read_b128 v[8:11], v226
	ds_read_b128 v[12:15], v226 offset:1024
	ds_read_b128 v[16:19], v226 offset:2048
	ds_read_b128 v[20:23], v226 offset:3072
	ds_read_b128 v[172:175], v227
	ds_read_b128 v[176:179], v227 offset:1024
	ds_read_b128 v[180:183], v227 offset:2048
	ds_read_b128 v[226:229], v227 offset:3072
	s_add_u32 s70, s76, 0x10000
	s_addc_u32 s71, s77, 0
	s_mov_b32 m0, s67
	v_lshl_add_u64 v[88:89], s[70:71], 0, v[184:185]
	ds_read_b128 v[24:27], v217 offset:32768
	ds_read_b128 v[28:31], v217 offset:33792
	ds_read_b128 v[60:63], v217 offset:34816
	ds_read_b128 v[230:233], v217 offset:35840
	ds_read_b128 v[234:237], v217 offset:36864
	ds_read_b128 v[238:241], v217 offset:37888
	ds_read_b128 v[242:245], v217 offset:38912
	ds_read_b128 v[246:249], v217 offset:39936
	global_load_lds_dwordx4 v[88:89], off
	v_lshl_add_u64 v[88:89], s[70:71], 0, v[188:189]
	s_mov_b32 m0, s68
	s_nop 0
	global_load_lds_dwordx4 v[88:89], off
	s_waitcnt vmcnt(8)
	s_waitcnt lgkmcnt(0)
	s_barrier
	s_setprio 1
	s_waitcnt lgkmcnt(0)
	v_mfma_f32_16x16x32_bf16 v[64:67], v[8:11], v[24:27], v[64:67]
	v_mfma_f32_16x16x32_bf16 v[164:167], v[12:15], v[28:31], v[64:67]
	v_mfma_f32_16x16x32_bf16 v[64:67], v[16:19], v[24:27], v[68:71]
	v_mfma_f32_16x16x32_bf16 v[152:155], v[20:23], v[28:31], v[64:67]
	v_mfma_f32_16x16x32_bf16 v[64:67], v[8:11], v[60:63], v[72:75]
	v_mfma_f32_16x16x32_bf16 v[108:111], v[12:15], v[230:233], v[64:67]
	v_mfma_f32_16x16x32_bf16 v[64:67], v[16:19], v[60:63], v[76:79]
	v_mfma_f32_16x16x32_bf16 v[104:107], v[20:23], v[230:233], v[64:67]
	v_mfma_f32_16x16x32_bf16 v[64:67], v[8:11], v[234:237], v[80:83]
	v_mfma_f32_16x16x32_bf16 v[92:95], v[12:15], v[238:241], v[64:67]
	v_mfma_f32_16x16x32_bf16 v[64:67], v[16:19], v[234:237], v[84:87]
	v_mfma_f32_16x16x32_bf16 v[88:91], v[20:23], v[238:241], v[64:67]
	v_mfma_f32_16x16x32_bf16 v[64:67], v[8:11], v[242:245], v[204:207]
	v_mfma_f32_16x16x32_bf16 v[76:79], v[12:15], v[246:249], v[64:67]
	v_mfma_f32_16x16x32_bf16 v[64:67], v[16:19], v[242:245], v[218:221]
	v_mfma_f32_16x16x32_bf16 v[72:75], v[20:23], v[246:249], v[64:67]
	s_setprio 0
	s_setprio 1
	v_mfma_f32_16x16x32_bf16 v[64:67], v[172:175], v[24:27], v[96:99]
	v_mfma_f32_16x16x32_bf16 v[24:27], v[180:183], v[24:27], v[32:35]
	v_mfma_f32_16x16x32_bf16 v[112:115], v[226:229], v[28:31], v[24:27]
	v_mfma_f32_16x16x32_bf16 v[24:27], v[172:175], v[60:63], v[36:39]
	v_mfma_f32_16x16x32_bf16 v[100:103], v[176:179], v[230:233], v[24:27]
	v_mfma_f32_16x16x32_bf16 v[24:27], v[180:183], v[60:63], v[40:43]
	v_mfma_f32_16x16x32_bf16 v[96:99], v[226:229], v[230:233], v[24:27]
	v_mfma_f32_16x16x32_bf16 v[24:27], v[172:175], v[234:237], v[44:47]
	v_mfma_f32_16x16x32_bf16 v[84:87], v[176:179], v[238:241], v[24:27]
	v_mfma_f32_16x16x32_bf16 v[24:27], v[180:183], v[234:237], v[48:51]
	v_mfma_f32_16x16x32_bf16 v[80:83], v[226:229], v[238:241], v[24:27]
	v_mfma_f32_16x16x32_bf16 v[24:27], v[172:175], v[242:245], v[52:55]
	v_mfma_f32_16x16x32_bf16 v[68:71], v[176:179], v[246:249], v[24:27]
	v_mfma_f32_16x16x32_bf16 v[24:27], v[180:183], v[242:245], v[56:59]
	v_mfma_f32_16x16x32_bf16 v[120:123], v[176:179], v[28:31], v[64:67]
	v_mfma_f32_16x16x32_bf16 v[64:67], v[226:229], v[246:249], v[24:27]
	s_setprio 0
	s_barrier
	s_mov_b32 m0, s87
	s_nop 2
	v_lshl_add_u64 v[24:25], v[208:209], 0, s[4:5]
	s_add_u32 s70, s74, 0x10080
	ds_read_b128 v[32:35], v217 offset:49152
	ds_read_b128 v[36:39], v217 offset:50176
	ds_read_b128 v[204:207], v217 offset:51200
	ds_read_b128 v[218:221], v217 offset:52224
	ds_read_b128 v[230:233], v217 offset:53248
	ds_read_b128 v[234:237], v217 offset:54272
	ds_read_b128 v[238:241], v217 offset:55296
	ds_read_b128 v[242:245], v217 offset:56320
	global_load_lds_dwordx4 v[24:25], off
	v_lshl_add_u64 v[24:25], v[250:251], 0, s[4:5]
	s_mov_b32 m0, s35
	s_addc_u32 s71, s75, 0
	global_load_lds_dwordx4 v[24:25], off
	v_lshl_add_u64 v[24:25], s[70:71], 0, v[186:187]
	s_mov_b32 m0, s37
	s_nop 0
	global_load_lds_dwordx4 v[24:25], off
	v_lshl_add_u64 v[24:25], s[70:71], 0, v[190:191]
	s_mov_b32 m0, s72
	s_nop 0
	global_load_lds_dwordx4 v[24:25], off
	v_lshl_add_u64 v[24:25], v[252:253], 0, s[4:5]
	s_mov_b32 m0, s79
	s_nop 0
	global_load_lds_dwordx4 v[24:25], off
	v_lshl_add_u64 v[24:25], v[210:211], 0, s[4:5]
	s_mov_b32 m0, s80
	s_nop 0
	global_load_lds_dwordx4 v[24:25], off
	s_waitcnt vmcnt(8)
	s_waitcnt lgkmcnt(0)
	s_barrier
	s_setprio 1
	s_waitcnt lgkmcnt(0)
	v_mfma_f32_16x16x32_bf16 v[24:27], v[8:11], v[32:35], v[128:131]
	v_mfma_f32_16x16x32_bf16 v[60:63], v[12:15], v[36:39], v[24:27]
	v_mfma_f32_16x16x32_bf16 v[24:27], v[16:19], v[32:35], v[132:135]
	v_mfma_f32_16x16x32_bf16 v[56:59], v[20:23], v[36:39], v[24:27]
	v_mfma_f32_16x16x32_bf16 v[24:27], v[8:11], v[204:207], v[136:139]
	v_mfma_f32_16x16x32_bf16 v[44:47], v[12:15], v[218:221], v[24:27]
	v_mfma_f32_16x16x32_bf16 v[24:27], v[16:19], v[204:207], v[140:143]
	v_mfma_f32_16x16x32_bf16 v[40:43], v[20:23], v[218:221], v[24:27]
	v_mfma_f32_16x16x32_bf16 v[24:27], v[8:11], v[230:233], v[144:147]
	v_mfma_f32_16x16x32_bf16 v[0:3], v[8:11], v[238:241], v[0:3]
	v_mfma_f32_16x16x32_bf16 v[28:31], v[12:15], v[234:237], v[24:27]
	v_mfma_f32_16x16x32_bf16 v[24:27], v[16:19], v[230:233], v[148:151]
	v_mfma_f32_16x16x32_bf16 v[12:15], v[12:15], v[242:245], v[0:3]
	v_mfma_f32_16x16x32_bf16 v[0:3], v[16:19], v[238:241], v[4:7]
	v_mfma_f32_16x16x32_bf16 v[24:27], v[20:23], v[234:237], v[24:27]
	v_mfma_f32_16x16x32_bf16 v[8:11], v[20:23], v[242:245], v[0:3]
	s_setprio 0
	s_setprio 1
	v_mfma_f32_16x16x32_bf16 v[0:3], v[172:175], v[32:35], v[116:119]
	v_mfma_f32_16x16x32_bf16 v[52:55], v[176:179], v[36:39], v[0:3]
	v_mfma_f32_16x16x32_bf16 v[0:3], v[180:183], v[32:35], v[196:199]
	v_mfma_f32_16x16x32_bf16 v[48:51], v[226:229], v[36:39], v[0:3]
	v_mfma_f32_16x16x32_bf16 v[0:3], v[172:175], v[204:207], v[200:203]
	v_mfma_f32_16x16x32_bf16 v[36:39], v[176:179], v[218:221], v[0:3]
	v_mfma_f32_16x16x32_bf16 v[0:3], v[180:183], v[204:207], v[160:163]
	v_mfma_f32_16x16x32_bf16 v[32:35], v[226:229], v[218:221], v[0:3]
	v_mfma_f32_16x16x32_bf16 v[0:3], v[172:175], v[230:233], v[222:225]
	v_mfma_f32_16x16x32_bf16 v[20:23], v[176:179], v[234:237], v[0:3]
	v_mfma_f32_16x16x32_bf16 v[0:3], v[180:183], v[230:233], v[168:171]
	v_mfma_f32_16x16x32_bf16 v[16:19], v[226:229], v[234:237], v[0:3]
	v_mfma_f32_16x16x32_bf16 v[0:3], v[172:175], v[238:241], v[124:127]
	v_mfma_f32_16x16x32_bf16 v[4:7], v[176:179], v[242:245], v[0:3]
	v_mfma_f32_16x16x32_bf16 v[0:3], v[180:183], v[238:241], v[156:159]
	v_mfma_f32_16x16x32_bf16 v[0:3], v[226:229], v[242:245], v[0:3]
	s_setprio 0
	s_barrier
	s_andn2_b64 vcc, exec, s[6:7]
	s_cbranch_vccnz .LBB0_578
	s_barrier
.LBB0_578:
	s_lshl_b32 s35, s46, 8
	v_mov_b32_e32 v116, v212
	v_mov_b32_e32 v117, v213
	s_add_i32 s35, s35, s69
	s_andn2_b64 vcc, exec, s[8:9]
	v_add_u32_e32 v198, s35, v116
	s_lshl_b32 s35, s47, 8
	s_or_b32 s35, s35, s78
	v_lshl_add_u32 v116, v117, 3, s35
	v_ashrrev_i32_e32 v117, 31, v116
	v_lshlrev_b64 v[196:197], 1, v[116:117]
	v_ashrrev_i32_e32 v199, 31, v198
	v_lshl_add_u64 v[202:203], s[56:57], 0, v[196:197]
	v_lshlrev_b64 v[116:117], 12, v[198:199]
	v_lshl_add_u64 v[200:201], s[42:43], 0, v[196:197]
	v_lshl_add_u64 v[116:117], v[202:203], 0, v[116:117]
	v_lshlrev_b64 v[210:211], 11, v[198:199]
	v_lshl_add_u64 v[118:119], v[200:201], 0, v[210:211]
	global_load_dwordx4 v[218:221], v[116:117], off offset:2048
	global_load_dwordx4 v[222:225], v[118:119], off
	global_load_dwordx4 v[180:183], v[116:117], off offset:2304
	global_load_dwordx4 v[176:179], v[118:119], off offset:256
	v_add_u32_e32 v116, 16, v198
	v_ashrrev_i32_e32 v117, 31, v116
	v_lshlrev_b64 v[118:119], 12, v[116:117]
	v_lshl_add_u64 v[118:119], v[202:203], 0, v[118:119]
	v_lshlrev_b64 v[208:209], 11, v[116:117]
	v_lshl_add_u64 v[116:117], v[200:201], 0, v[208:209]
	global_load_dwordx4 v[172:175], v[118:119], off offset:2048
	global_load_dwordx4 v[168:171], v[116:117], off
	global_load_dwordx4 v[160:163], v[118:119], off offset:2304
	global_load_dwordx4 v[148:151], v[116:117], off offset:256
	v_add_u32_e32 v116, 32, v198
	v_ashrrev_i32_e32 v117, 31, v116
	v_lshlrev_b64 v[118:119], 12, v[116:117]
	v_lshl_add_u64 v[118:119], v[202:203], 0, v[118:119]
	v_lshlrev_b64 v[206:207], 11, v[116:117]
	v_lshl_add_u64 v[116:117], v[200:201], 0, v[206:207]
	global_load_dwordx4 v[156:159], v[118:119], off offset:2048
	global_load_dwordx4 v[140:143], v[116:117], off
	global_load_dwordx4 v[132:135], v[118:119], off offset:2304
	global_load_dwordx4 v[124:127], v[116:117], off offset:256
	v_add_u32_e32 v116, 48, v198
	v_ashrrev_i32_e32 v117, 31, v116
	v_lshlrev_b64 v[118:119], 12, v[116:117]
	v_lshlrev_b64 v[204:205], 11, v[116:117]
	v_lshl_add_u64 v[118:119], v[202:203], 0, v[118:119]
	v_lshl_add_u64 v[116:117], v[200:201], 0, v[204:205]
	global_load_dwordx4 v[144:147], v[118:119], off offset:2048
	global_load_dwordx4 v[136:139], v[116:117], off
	global_load_dwordx4 v[128:131], v[118:119], off offset:2304
	s_nop 0
	global_load_dwordx4 v[116:119], v[116:117], off offset:256
	v_lshl_add_u64 v[210:211], s[42:43], 0, v[210:211]
	v_lshl_add_u64 v[210:211], v[210:211], 0, v[196:197]
	s_mov_b64 s[46:47], -1
	s_waitcnt vmcnt(0)
	v_lshlrev_b32_e32 v199, 16, v218
	v_lshlrev_b32_e32 v229, 16, v222
	v_and_b32_e32 v218, 0xffff0000, v218
	v_fmac_f32_e32 v229, v164, v199
	v_and_b32_e32 v164, 0xffff0000, v222
	v_lshlrev_b32_e32 v226, 16, v219
	v_fmac_f32_e32 v164, v165, v218
	v_lshlrev_b32_e32 v165, 16, v223
	v_and_b32_e32 v219, 0xffff0000, v219
	v_fmac_f32_e32 v165, v166, v226
	v_and_b32_e32 v166, 0xffff0000, v223
	v_lshlrev_b32_e32 v227, 16, v220
	v_and_b32_e32 v220, 0xffff0000, v220
	v_fmac_f32_e32 v166, v167, v219
	v_lshlrev_b32_e32 v167, 16, v224
	v_and_b32_e32 v199, 0xffff0000, v224
	v_lshlrev_b32_e32 v228, 16, v221
	v_and_b32_e32 v221, 0xffff0000, v221
	v_fmac_f32_e32 v167, v152, v227
	v_fmac_f32_e32 v199, v153, v220
	v_lshlrev_b32_e32 v218, 16, v225
	v_and_b32_e32 v219, 0xffff0000, v225
	v_cvt_pk_bf16_f32 v152, v229, v164
	v_cvt_pk_bf16_f32 v153, v165, v166
	v_fmac_f32_e32 v218, v154, v228
	v_fmac_f32_e32 v219, v155, v221
	v_cvt_pk_bf16_f32 v154, v167, v199
	v_cvt_pk_bf16_f32 v155, v218, v219
	global_store_dwordx4 v[210:211], v[152:155], off
	v_lshlrev_b32_e32 v164, 16, v182
	v_and_b32_e32 v165, 0xffff0000, v182
	v_lshlrev_b32_e32 v152, 16, v180
	v_and_b32_e32 v153, 0xffff0000, v180
	v_lshlrev_b32_e32 v180, 16, v176
	v_fmac_f32_e32 v180, v120, v152
	v_and_b32_e32 v120, 0xffff0000, v176
	v_lshlrev_b32_e32 v154, 16, v181
	v_fmac_f32_e32 v120, v121, v153
	v_lshlrev_b32_e32 v121, 16, v177
	v_and_b32_e32 v155, 0xffff0000, v181
	v_fmac_f32_e32 v121, v122, v154
	v_and_b32_e32 v122, 0xffff0000, v177
	v_lshlrev_b32_e32 v166, 16, v183
	v_and_b32_e32 v167, 0xffff0000, v183
	v_fmac_f32_e32 v122, v123, v155
	v_lshlrev_b32_e32 v123, 16, v178
	v_and_b32_e32 v152, 0xffff0000, v178
	v_lshlrev_b32_e32 v153, 16, v179
	v_and_b32_e32 v154, 0xffff0000, v179
	v_fmac_f32_e32 v123, v112, v164
	v_fmac_f32_e32 v152, v113, v165
	v_fmac_f32_e32 v153, v114, v166
	v_fmac_f32_e32 v154, v115, v167
	v_cvt_pk_bf16_f32 v112, v180, v120
	v_cvt_pk_bf16_f32 v113, v121, v122
	v_cvt_pk_bf16_f32 v114, v123, v152
	v_cvt_pk_bf16_f32 v115, v153, v154
	global_store_dwordx4 v[210:211], v[112:115], off offset:256
	v_lshlrev_b32_e32 v154, 16, v168
	v_lshlrev_b32_e32 v120, 16, v173
	v_lshlrev_b32_e32 v114, 16, v172
	v_and_b32_e32 v115, 0xffff0000, v172
	v_fmac_f32_e32 v154, v108, v114
	v_and_b32_e32 v108, 0xffff0000, v168
	v_fmac_f32_e32 v108, v109, v115
	v_lshlrev_b32_e32 v109, 16, v169
	v_and_b32_e32 v121, 0xffff0000, v173
	v_fmac_f32_e32 v109, v110, v120
	v_and_b32_e32 v110, 0xffff0000, v169
	v_lshl_add_u64 v[112:113], s[42:43], 0, v[208:209]
	v_lshlrev_b32_e32 v122, 16, v174
	v_and_b32_e32 v123, 0xffff0000, v174
	v_fmac_f32_e32 v110, v111, v121
	v_lshlrev_b32_e32 v111, 16, v170
	v_and_b32_e32 v114, 0xffff0000, v170
	v_lshl_add_u64 v[112:113], v[112:113], 0, v[196:197]
	v_lshlrev_b32_e32 v152, 16, v175
	v_and_b32_e32 v153, 0xffff0000, v175
	v_fmac_f32_e32 v111, v104, v122
	v_fmac_f32_e32 v114, v105, v123
	v_lshlrev_b32_e32 v115, 16, v171
	v_and_b32_e32 v120, 0xffff0000, v171
	v_cvt_pk_bf16_f32 v104, v154, v108
	v_fmac_f32_e32 v115, v106, v152
	v_fmac_f32_e32 v120, v107, v153
	v_cvt_pk_bf16_f32 v105, v109, v110
	v_cvt_pk_bf16_f32 v106, v111, v114
	v_cvt_pk_bf16_f32 v107, v115, v120
	global_store_dwordx4 v[112:113], v[104:107], off
	v_lshlrev_b32_e32 v114, 16, v148
	v_lshlrev_b32_e32 v108, 16, v162
	v_lshlrev_b32_e32 v104, 16, v160
	v_and_b32_e32 v105, 0xffff0000, v160
	v_fmac_f32_e32 v114, v100, v104
	v_and_b32_e32 v100, 0xffff0000, v148
	v_lshlrev_b32_e32 v106, 16, v161
	v_fmac_f32_e32 v100, v101, v105
	v_lshlrev_b32_e32 v101, 16, v149
	v_and_b32_e32 v107, 0xffff0000, v161
	v_fmac_f32_e32 v101, v102, v106
	v_and_b32_e32 v102, 0xffff0000, v149
	v_and_b32_e32 v109, 0xffff0000, v162
	v_lshlrev_b32_e32 v110, 16, v163
	v_and_b32_e32 v111, 0xffff0000, v163
	v_fmac_f32_e32 v102, v103, v107
	v_lshlrev_b32_e32 v103, 16, v150
	v_and_b32_e32 v104, 0xffff0000, v150
	v_lshlrev_b32_e32 v105, 16, v151
	v_and_b32_e32 v106, 0xffff0000, v151
	v_fmac_f32_e32 v103, v96, v108
	v_fmac_f32_e32 v104, v97, v109
	v_fmac_f32_e32 v105, v98, v110
	v_fmac_f32_e32 v106, v99, v111
	v_cvt_pk_bf16_f32 v96, v114, v100
	v_cvt_pk_bf16_f32 v97, v101, v102
	v_cvt_pk_bf16_f32 v98, v103, v104
	v_cvt_pk_bf16_f32 v99, v105, v106
	global_store_dwordx4 v[112:113], v[96:99], off offset:256
	v_lshlrev_b32_e32 v106, 16, v140
	v_lshlrev_b32_e32 v100, 16, v157
	v_lshlrev_b32_e32 v98, 16, v156
	v_and_b32_e32 v99, 0xffff0000, v156
	v_fmac_f32_e32 v106, v92, v98
	v_and_b32_e32 v92, 0xffff0000, v140
	v_fmac_f32_e32 v92, v93, v99
	v_lshlrev_b32_e32 v93, 16, v141
	v_and_b32_e32 v101, 0xffff0000, v157
	v_fmac_f32_e32 v93, v94, v100
	v_and_b32_e32 v94, 0xffff0000, v141
	v_lshl_add_u64 v[96:97], s[42:43], 0, v[206:207]
	v_lshlrev_b32_e32 v102, 16, v158
	v_and_b32_e32 v103, 0xffff0000, v158
	v_fmac_f32_e32 v94, v95, v101
	v_lshlrev_b32_e32 v95, 16, v142
	v_and_b32_e32 v98, 0xffff0000, v142
	v_lshl_add_u64 v[96:97], v[96:97], 0, v[196:197]
	v_lshlrev_b32_e32 v104, 16, v159
	v_and_b32_e32 v105, 0xffff0000, v159
	v_fmac_f32_e32 v95, v88, v102
	v_fmac_f32_e32 v98, v89, v103
	v_lshlrev_b32_e32 v99, 16, v143
	v_and_b32_e32 v100, 0xffff0000, v143
	v_cvt_pk_bf16_f32 v88, v106, v92
	v_fmac_f32_e32 v99, v90, v104
	v_fmac_f32_e32 v100, v91, v105
	v_cvt_pk_bf16_f32 v89, v93, v94
	v_cvt_pk_bf16_f32 v90, v95, v98
	v_cvt_pk_bf16_f32 v91, v99, v100
	global_store_dwordx4 v[96:97], v[88:91], off
	v_lshlrev_b32_e32 v98, 16, v124
	v_lshlrev_b32_e32 v92, 16, v134
	v_lshlrev_b32_e32 v88, 16, v132
	v_and_b32_e32 v89, 0xffff0000, v132
	v_fmac_f32_e32 v98, v84, v88
	v_and_b32_e32 v84, 0xffff0000, v124
	v_lshlrev_b32_e32 v90, 16, v133
	v_fmac_f32_e32 v84, v85, v89
	v_lshlrev_b32_e32 v85, 16, v125
	v_and_b32_e32 v91, 0xffff0000, v133
	v_fmac_f32_e32 v85, v86, v90
	v_and_b32_e32 v86, 0xffff0000, v125
	v_and_b32_e32 v93, 0xffff0000, v134
	v_lshlrev_b32_e32 v94, 16, v135
	v_and_b32_e32 v95, 0xffff0000, v135
	v_fmac_f32_e32 v86, v87, v91
	v_lshlrev_b32_e32 v87, 16, v126
	v_and_b32_e32 v88, 0xffff0000, v126
	v_lshlrev_b32_e32 v89, 16, v127
	v_and_b32_e32 v90, 0xffff0000, v127
	v_fmac_f32_e32 v87, v80, v92
	v_fmac_f32_e32 v88, v81, v93
	v_fmac_f32_e32 v89, v82, v94
	v_fmac_f32_e32 v90, v83, v95
	v_cvt_pk_bf16_f32 v80, v98, v84
	v_cvt_pk_bf16_f32 v81, v85, v86
	v_cvt_pk_bf16_f32 v82, v87, v88
	v_cvt_pk_bf16_f32 v83, v89, v90
	global_store_dwordx4 v[96:97], v[80:83], off offset:256
	v_lshlrev_b32_e32 v90, 16, v136
	v_lshlrev_b32_e32 v84, 16, v145
	v_lshlrev_b32_e32 v82, 16, v144
	v_and_b32_e32 v83, 0xffff0000, v144
	v_fmac_f32_e32 v90, v76, v82
	v_and_b32_e32 v76, 0xffff0000, v136
	v_fmac_f32_e32 v76, v77, v83
	v_lshlrev_b32_e32 v77, 16, v137
	v_and_b32_e32 v85, 0xffff0000, v145
	v_fmac_f32_e32 v77, v78, v84
	v_and_b32_e32 v78, 0xffff0000, v137
	v_lshl_add_u64 v[80:81], s[42:43], 0, v[204:205]
	v_lshlrev_b32_e32 v86, 16, v146
	v_and_b32_e32 v87, 0xffff0000, v146
	v_fmac_f32_e32 v78, v79, v85
	v_lshlrev_b32_e32 v79, 16, v138
	v_and_b32_e32 v82, 0xffff0000, v138
	v_lshl_add_u64 v[80:81], v[80:81], 0, v[196:197]
	v_lshlrev_b32_e32 v88, 16, v147
	v_and_b32_e32 v89, 0xffff0000, v147
	v_fmac_f32_e32 v79, v72, v86
	v_fmac_f32_e32 v82, v73, v87
	v_lshlrev_b32_e32 v83, 16, v139
	v_and_b32_e32 v84, 0xffff0000, v139
	v_cvt_pk_bf16_f32 v72, v90, v76
	v_fmac_f32_e32 v83, v74, v88
	v_fmac_f32_e32 v84, v75, v89
	v_cvt_pk_bf16_f32 v73, v77, v78
	v_cvt_pk_bf16_f32 v74, v79, v82
	v_cvt_pk_bf16_f32 v75, v83, v84
	global_store_dwordx4 v[80:81], v[72:75], off
	v_lshlrev_b32_e32 v82, 16, v116
	v_lshlrev_b32_e32 v76, 16, v130
	v_lshlrev_b32_e32 v72, 16, v128
	v_and_b32_e32 v73, 0xffff0000, v128
	v_fmac_f32_e32 v82, v68, v72
	v_and_b32_e32 v68, 0xffff0000, v116
	v_lshlrev_b32_e32 v74, 16, v129
	v_fmac_f32_e32 v68, v69, v73
	v_lshlrev_b32_e32 v69, 16, v117
	v_and_b32_e32 v75, 0xffff0000, v129
	v_fmac_f32_e32 v69, v70, v74
	v_and_b32_e32 v70, 0xffff0000, v117
	v_fmac_f32_e32 v70, v71, v75
	v_lshlrev_b32_e32 v71, 16, v118
	v_and_b32_e32 v77, 0xffff0000, v130
	v_lshlrev_b32_e32 v78, 16, v131
	v_and_b32_e32 v79, 0xffff0000, v131
	v_fmac_f32_e32 v71, v64, v76
	v_and_b32_e32 v72, 0xffff0000, v118
	v_lshlrev_b32_e32 v73, 16, v119
	v_and_b32_e32 v74, 0xffff0000, v119
	v_cvt_pk_bf16_f32 v64, v82, v68
	v_fmac_f32_e32 v72, v65, v77
	v_fmac_f32_e32 v73, v66, v78
	v_fmac_f32_e32 v74, v67, v79
	v_cvt_pk_bf16_f32 v65, v69, v70
	v_cvt_pk_bf16_f32 v66, v71, v72
	v_cvt_pk_bf16_f32 v67, v73, v74
	global_store_dwordx4 v[80:81], v[64:67], off offset:256
	s_nop 1
	v_add_u32_e32 v64, 0x80, v198
	v_ashrrev_i32_e32 v65, 31, v64
	v_lshlrev_b64 v[66:67], 12, v[64:65]
	v_lshl_add_u64 v[66:67], v[202:203], 0, v[66:67]
	v_lshlrev_b64 v[130:131], 11, v[64:65]
	v_lshl_add_u64 v[64:65], v[200:201], 0, v[130:131]
	global_load_dwordx4 v[86:89], v[66:67], off offset:2048
	global_load_dwordx4 v[90:93], v[64:65], off
	global_load_dwordx4 v[94:97], v[66:67], off offset:2304
	global_load_dwordx4 v[98:101], v[64:65], off offset:256
	v_add_u32_e32 v64, 0x90, v198
	v_ashrrev_i32_e32 v65, 31, v64
	v_lshlrev_b64 v[66:67], 12, v[64:65]
	v_lshl_add_u64 v[66:67], v[202:203], 0, v[66:67]
	v_lshlrev_b64 v[132:133], 11, v[64:65]
	v_lshl_add_u64 v[64:65], v[200:201], 0, v[132:133]
	global_load_dwordx4 v[102:105], v[66:67], off offset:2048
	global_load_dwordx4 v[106:109], v[64:65], off
	global_load_dwordx4 v[110:113], v[66:67], off offset:2304
	global_load_dwordx4 v[114:117], v[64:65], off offset:256
	v_add_u32_e32 v64, 0xa0, v198
	v_ashrrev_i32_e32 v65, 31, v64
	v_lshlrev_b64 v[66:67], 12, v[64:65]
	v_lshl_add_u64 v[66:67], v[202:203], 0, v[66:67]
	v_lshlrev_b64 v[134:135], 11, v[64:65]
	v_lshl_add_u64 v[64:65], v[200:201], 0, v[134:135]
	global_load_dwordx4 v[118:121], v[66:67], off offset:2048
	global_load_dwordx4 v[122:125], v[64:65], off
	global_load_dwordx4 v[126:129], v[66:67], off offset:2304
	global_load_dwordx4 v[80:83], v[64:65], off offset:256
	v_add_u32_e32 v64, 0xb0, v198
	v_ashrrev_i32_e32 v65, 31, v64
	v_lshlrev_b64 v[66:67], 12, v[64:65]
	v_lshlrev_b64 v[84:85], 11, v[64:65]
	v_lshl_add_u64 v[66:67], v[202:203], 0, v[66:67]
	v_lshl_add_u64 v[64:65], v[200:201], 0, v[84:85]
	global_load_dwordx4 v[76:79], v[66:67], off offset:2048
	global_load_dwordx4 v[72:75], v[64:65], off
	global_load_dwordx4 v[68:71], v[66:67], off offset:2304
	s_nop 0
	global_load_dwordx4 v[64:67], v[64:65], off offset:256
	v_lshl_add_u64 v[130:131], s[42:43], 0, v[130:131]
	v_lshl_add_u64 v[130:131], v[130:131], 0, v[196:197]
	s_waitcnt vmcnt(15)
	v_lshlrev_b32_e32 v136, 16, v86
	s_waitcnt vmcnt(14)
	v_lshlrev_b32_e32 v140, 16, v90
	v_and_b32_e32 v86, 0xffff0000, v86
	v_fmac_f32_e32 v140, v60, v136
	v_and_b32_e32 v60, 0xffff0000, v90
	v_lshlrev_b32_e32 v137, 16, v87
	v_fmac_f32_e32 v60, v61, v86
	v_lshlrev_b32_e32 v61, 16, v91
	v_and_b32_e32 v87, 0xffff0000, v87
	v_fmac_f32_e32 v61, v62, v137
	v_and_b32_e32 v62, 0xffff0000, v91
	v_lshlrev_b32_e32 v138, 16, v88
	v_and_b32_e32 v88, 0xffff0000, v88
	v_fmac_f32_e32 v62, v63, v87
	v_lshlrev_b32_e32 v63, 16, v92
	v_and_b32_e32 v86, 0xffff0000, v92
	v_lshlrev_b32_e32 v139, 16, v89
	v_and_b32_e32 v89, 0xffff0000, v89
	v_fmac_f32_e32 v63, v56, v138
	v_fmac_f32_e32 v86, v57, v88
	v_lshlrev_b32_e32 v87, 16, v93
	v_and_b32_e32 v88, 0xffff0000, v93
	v_cvt_pk_bf16_f32 v56, v140, v60
	v_fmac_f32_e32 v87, v58, v139
	v_fmac_f32_e32 v88, v59, v89
	v_cvt_pk_bf16_f32 v57, v61, v62
	v_cvt_pk_bf16_f32 v58, v63, v86
	v_cvt_pk_bf16_f32 v59, v87, v88
	global_store_dwordx4 v[130:131], v[56:59], off
	s_waitcnt vmcnt(13)
	v_lshlrev_b32_e32 v86, 16, v98
	v_lshlrev_b32_e32 v60, 16, v96
	v_lshlrev_b32_e32 v56, 16, v94
	v_and_b32_e32 v57, 0xffff0000, v94
	v_fmac_f32_e32 v86, v52, v56
	v_and_b32_e32 v52, 0xffff0000, v98
	v_lshlrev_b32_e32 v58, 16, v95
	v_fmac_f32_e32 v52, v53, v57
	v_lshlrev_b32_e32 v53, 16, v99
	v_and_b32_e32 v59, 0xffff0000, v95
	v_fmac_f32_e32 v53, v54, v58
	v_and_b32_e32 v54, 0xffff0000, v99
	v_and_b32_e32 v61, 0xffff0000, v96
	v_lshlrev_b32_e32 v62, 16, v97
	v_and_b32_e32 v63, 0xffff0000, v97
	v_fmac_f32_e32 v54, v55, v59
	v_lshlrev_b32_e32 v55, 16, v100
	v_and_b32_e32 v56, 0xffff0000, v100
	v_lshlrev_b32_e32 v57, 16, v101
	v_and_b32_e32 v58, 0xffff0000, v101
	v_fmac_f32_e32 v55, v48, v60
	v_fmac_f32_e32 v56, v49, v61
	v_fmac_f32_e32 v57, v50, v62
	v_fmac_f32_e32 v58, v51, v63
	v_cvt_pk_bf16_f32 v48, v86, v52
	v_cvt_pk_bf16_f32 v49, v53, v54
	v_cvt_pk_bf16_f32 v50, v55, v56
	v_cvt_pk_bf16_f32 v51, v57, v58
	global_store_dwordx4 v[130:131], v[48:51], off offset:256
	s_waitcnt vmcnt(12)
	v_lshlrev_b32_e32 v58, 16, v106
	v_lshlrev_b32_e32 v52, 16, v103
	v_lshlrev_b32_e32 v50, 16, v102
	v_and_b32_e32 v51, 0xffff0000, v102
	v_fmac_f32_e32 v58, v44, v50
	v_and_b32_e32 v44, 0xffff0000, v106
	v_fmac_f32_e32 v44, v45, v51
	v_lshlrev_b32_e32 v45, 16, v107
	v_and_b32_e32 v53, 0xffff0000, v103
	v_fmac_f32_e32 v45, v46, v52
	v_and_b32_e32 v46, 0xffff0000, v107
	v_lshl_add_u64 v[48:49], s[42:43], 0, v[132:133]
	v_lshlrev_b32_e32 v54, 16, v104
	v_and_b32_e32 v55, 0xffff0000, v104
	v_fmac_f32_e32 v46, v47, v53
	v_lshlrev_b32_e32 v47, 16, v108
	v_and_b32_e32 v50, 0xffff0000, v108
	v_lshl_add_u64 v[48:49], v[48:49], 0, v[196:197]
	v_lshlrev_b32_e32 v56, 16, v105
	v_and_b32_e32 v57, 0xffff0000, v105
	v_fmac_f32_e32 v47, v40, v54
	v_fmac_f32_e32 v50, v41, v55
	v_lshlrev_b32_e32 v51, 16, v109
	v_and_b32_e32 v52, 0xffff0000, v109
	v_cvt_pk_bf16_f32 v40, v58, v44
	v_fmac_f32_e32 v51, v42, v56
	v_fmac_f32_e32 v52, v43, v57
	v_cvt_pk_bf16_f32 v41, v45, v46
	v_cvt_pk_bf16_f32 v42, v47, v50
	v_cvt_pk_bf16_f32 v43, v51, v52
	global_store_dwordx4 v[48:49], v[40:43], off
	s_waitcnt vmcnt(11)
	v_lshlrev_b32_e32 v50, 16, v114
	v_lshlrev_b32_e32 v44, 16, v112
	v_lshlrev_b32_e32 v40, 16, v110
	v_and_b32_e32 v41, 0xffff0000, v110
	v_fmac_f32_e32 v50, v36, v40
	v_and_b32_e32 v36, 0xffff0000, v114
	v_lshlrev_b32_e32 v42, 16, v111
	v_fmac_f32_e32 v36, v37, v41
	v_lshlrev_b32_e32 v37, 16, v115
	v_and_b32_e32 v43, 0xffff0000, v111
	v_fmac_f32_e32 v37, v38, v42
	v_and_b32_e32 v38, 0xffff0000, v115
	v_and_b32_e32 v45, 0xffff0000, v112
	v_lshlrev_b32_e32 v46, 16, v113
	v_and_b32_e32 v47, 0xffff0000, v113
	v_fmac_f32_e32 v38, v39, v43
	v_lshlrev_b32_e32 v39, 16, v116
	v_and_b32_e32 v40, 0xffff0000, v116
	v_lshlrev_b32_e32 v41, 16, v117
	v_and_b32_e32 v42, 0xffff0000, v117
	v_fmac_f32_e32 v39, v32, v44
	v_fmac_f32_e32 v40, v33, v45
	v_fmac_f32_e32 v41, v34, v46
	v_fmac_f32_e32 v42, v35, v47
	v_cvt_pk_bf16_f32 v32, v50, v36
	v_cvt_pk_bf16_f32 v33, v37, v38
	v_cvt_pk_bf16_f32 v34, v39, v40
	v_cvt_pk_bf16_f32 v35, v41, v42
	global_store_dwordx4 v[48:49], v[32:35], off offset:256
	s_waitcnt vmcnt(10)
	v_lshlrev_b32_e32 v42, 16, v122
	v_lshlrev_b32_e32 v36, 16, v119
	v_lshlrev_b32_e32 v34, 16, v118
	v_and_b32_e32 v35, 0xffff0000, v118
	v_fmac_f32_e32 v42, v28, v34
	v_and_b32_e32 v28, 0xffff0000, v122
	v_fmac_f32_e32 v28, v29, v35
	v_lshlrev_b32_e32 v29, 16, v123
	v_and_b32_e32 v37, 0xffff0000, v119
	v_fmac_f32_e32 v29, v30, v36
	v_and_b32_e32 v30, 0xffff0000, v123
	v_lshl_add_u64 v[32:33], s[42:43], 0, v[134:135]
	v_lshlrev_b32_e32 v38, 16, v120
	v_and_b32_e32 v39, 0xffff0000, v120
	v_fmac_f32_e32 v30, v31, v37
	v_lshlrev_b32_e32 v31, 16, v124
	v_and_b32_e32 v34, 0xffff0000, v124
	v_lshl_add_u64 v[32:33], v[32:33], 0, v[196:197]
	v_lshlrev_b32_e32 v40, 16, v121
	v_and_b32_e32 v41, 0xffff0000, v121
	v_fmac_f32_e32 v31, v24, v38
	v_fmac_f32_e32 v34, v25, v39
	v_lshlrev_b32_e32 v35, 16, v125
	v_and_b32_e32 v36, 0xffff0000, v125
	v_cvt_pk_bf16_f32 v24, v42, v28
	v_fmac_f32_e32 v35, v26, v40
	v_fmac_f32_e32 v36, v27, v41
	v_cvt_pk_bf16_f32 v25, v29, v30
	v_cvt_pk_bf16_f32 v26, v31, v34
	v_cvt_pk_bf16_f32 v27, v35, v36
	global_store_dwordx4 v[32:33], v[24:27], off
	s_waitcnt vmcnt(9)
	v_lshlrev_b32_e32 v34, 16, v80
	v_lshlrev_b32_e32 v28, 16, v128
	v_lshlrev_b32_e32 v24, 16, v126
	v_and_b32_e32 v25, 0xffff0000, v126
	v_fmac_f32_e32 v34, v20, v24
	v_and_b32_e32 v20, 0xffff0000, v80
	v_lshlrev_b32_e32 v26, 16, v127
	v_fmac_f32_e32 v20, v21, v25
	v_lshlrev_b32_e32 v21, 16, v81
	v_and_b32_e32 v27, 0xffff0000, v127
	v_fmac_f32_e32 v21, v22, v26
	v_and_b32_e32 v22, 0xffff0000, v81
	v_and_b32_e32 v29, 0xffff0000, v128
	v_lshlrev_b32_e32 v30, 16, v129
	v_and_b32_e32 v31, 0xffff0000, v129
	v_fmac_f32_e32 v22, v23, v27
	v_lshlrev_b32_e32 v23, 16, v82
	v_and_b32_e32 v24, 0xffff0000, v82
	v_lshlrev_b32_e32 v25, 16, v83
	v_and_b32_e32 v26, 0xffff0000, v83
	v_fmac_f32_e32 v23, v16, v28
	v_fmac_f32_e32 v24, v17, v29
	v_fmac_f32_e32 v25, v18, v30
	v_fmac_f32_e32 v26, v19, v31
	v_cvt_pk_bf16_f32 v16, v34, v20
	v_cvt_pk_bf16_f32 v17, v21, v22
	v_cvt_pk_bf16_f32 v18, v23, v24
	v_cvt_pk_bf16_f32 v19, v25, v26
	global_store_dwordx4 v[32:33], v[16:19], off offset:256
	s_waitcnt vmcnt(8)
	v_lshlrev_b32_e32 v26, 16, v72
	v_lshlrev_b32_e32 v20, 16, v77
	v_lshlrev_b32_e32 v18, 16, v76
	v_and_b32_e32 v19, 0xffff0000, v76
	v_fmac_f32_e32 v26, v12, v18
	v_and_b32_e32 v12, 0xffff0000, v72
	v_fmac_f32_e32 v12, v13, v19
	v_lshlrev_b32_e32 v13, 16, v73
	v_and_b32_e32 v21, 0xffff0000, v77
	v_fmac_f32_e32 v13, v14, v20
	v_and_b32_e32 v14, 0xffff0000, v73
	v_lshl_add_u64 v[16:17], s[42:43], 0, v[84:85]
	v_lshlrev_b32_e32 v22, 16, v78
	v_and_b32_e32 v23, 0xffff0000, v78
	v_fmac_f32_e32 v14, v15, v21
	v_lshlrev_b32_e32 v15, 16, v74
	v_and_b32_e32 v18, 0xffff0000, v74
	v_lshl_add_u64 v[16:17], v[16:17], 0, v[196:197]
	v_lshlrev_b32_e32 v24, 16, v79
	v_and_b32_e32 v25, 0xffff0000, v79
	v_fmac_f32_e32 v15, v8, v22
	v_fmac_f32_e32 v18, v9, v23
	v_lshlrev_b32_e32 v19, 16, v75
	v_and_b32_e32 v20, 0xffff0000, v75
	v_cvt_pk_bf16_f32 v8, v26, v12
	v_fmac_f32_e32 v19, v10, v24
	v_fmac_f32_e32 v20, v11, v25
	v_cvt_pk_bf16_f32 v9, v13, v14
	v_cvt_pk_bf16_f32 v10, v15, v18
	v_cvt_pk_bf16_f32 v11, v19, v20
	global_store_dwordx4 v[16:17], v[8:11], off
	s_waitcnt vmcnt(7)
	v_lshlrev_b32_e32 v18, 16, v64
	v_lshlrev_b32_e32 v12, 16, v70
	v_lshlrev_b32_e32 v8, 16, v68
	v_and_b32_e32 v9, 0xffff0000, v68
	v_fmac_f32_e32 v18, v4, v8
	v_and_b32_e32 v4, 0xffff0000, v64
	v_lshlrev_b32_e32 v10, 16, v69
	v_fmac_f32_e32 v4, v5, v9
	v_lshlrev_b32_e32 v5, 16, v65
	v_and_b32_e32 v11, 0xffff0000, v69
	v_fmac_f32_e32 v5, v6, v10
	v_and_b32_e32 v6, 0xffff0000, v65
	v_and_b32_e32 v13, 0xffff0000, v70
	v_lshlrev_b32_e32 v14, 16, v71
	v_and_b32_e32 v15, 0xffff0000, v71
	v_fmac_f32_e32 v6, v7, v11
	v_lshlrev_b32_e32 v7, 16, v66
	v_and_b32_e32 v8, 0xffff0000, v66
	v_lshlrev_b32_e32 v9, 16, v67
	v_and_b32_e32 v10, 0xffff0000, v67
	v_fmac_f32_e32 v7, v0, v12
	v_fmac_f32_e32 v8, v1, v13
	v_fmac_f32_e32 v9, v2, v14
	v_fmac_f32_e32 v10, v3, v15
	v_cvt_pk_bf16_f32 v0, v18, v4
	v_cvt_pk_bf16_f32 v1, v5, v6
	v_cvt_pk_bf16_f32 v2, v7, v8
	v_cvt_pk_bf16_f32 v3, v9, v10
	global_store_dwordx4 v[16:17], v[0:3], off offset:256
	s_mov_b32 s99, 1
	s_cbranch_vccnz .LBB0_569
	s_andn2_b64 vcc, exec, s[0:1]
	s_cbranch_vccnz .LBB0_568
	s_barrier
	s_branch .LBB0_568

.LBB0_833:
	s_cmp_lg_u64 s[8:9], 0
	s_cbranch_scc1 .Lrs3skip8
	s_lshl_b32 s98, s78, 8
	s_add_i32 s98, s98, s13
	v_add_u32_e32 v150, s98, v153
	v_lshlrev_b32_e32 v200, 3, v151
	v_ashrrev_i32_e32 v201, 31, v200
	v_lshl_add_u64 v[200:201], v[200:201], 2, s[62:63]
	v_mov_b32_e32 v252, v150
	v_ashrrev_i32_e32 v253, 31, v252
	v_lshlrev_b64 v[252:253], 7, v[252:253]
	v_lshl_add_u64 v[252:253], v[200:201], 0, v[252:253]
	global_load_dwordx4 v[184:187], v[252:253], off offset:16
	global_load_dwordx4 v[188:191], v[252:253], off
	v_add_u32_e32 v252, 0x10, v150
	v_ashrrev_i32_e32 v253, 31, v252
	v_lshlrev_b64 v[252:253], 7, v[252:253]
	v_lshl_add_u64 v[252:253], v[200:201], 0, v[252:253]
	global_load_dwordx4 v[192:195], v[252:253], off offset:16
	global_load_dwordx4 v[196:199], v[252:253], off
	v_add_u32_e32 v252, 0x20, v150
	v_ashrrev_i32_e32 v253, 31, v252
	v_lshlrev_b64 v[252:253], 7, v[252:253]
	v_lshl_add_u64 v[252:253], v[200:201], 0, v[252:253]
	global_load_dwordx4 v[204:207], v[252:253], off offset:16
	global_load_dwordx4 v[208:211], v[252:253], off
	v_add_u32_e32 v252, 0x30, v150
	v_ashrrev_i32_e32 v253, 31, v252
	v_lshlrev_b64 v[252:253], 7, v[252:253]
	v_lshl_add_u64 v[252:253], v[200:201], 0, v[252:253]
	global_load_dwordx4 v[212:215], v[252:253], off offset:16
	global_load_dwordx4 v[216:219], v[252:253], off
	v_add_u32_e32 v252, 0x80, v150
	v_ashrrev_i32_e32 v253, 31, v252
	v_lshlrev_b64 v[252:253], 7, v[252:253]
	v_lshl_add_u64 v[252:253], v[200:201], 0, v[252:253]
	global_load_dwordx4 v[220:223], v[252:253], off offset:16
	global_load_dwordx4 v[224:227], v[252:253], off
	v_add_u32_e32 v252, 0x90, v150
	v_ashrrev_i32_e32 v253, 31, v252
	v_lshlrev_b64 v[252:253], 7, v[252:253]
	v_lshl_add_u64 v[252:253], v[200:201], 0, v[252:253]
	global_load_dwordx4 v[228:231], v[252:253], off offset:16
	global_load_dwordx4 v[232:235], v[252:253], off
	v_add_u32_e32 v252, 0xa0, v150
	v_ashrrev_i32_e32 v253, 31, v252
	v_lshlrev_b64 v[252:253], 7, v[252:253]
	v_lshl_add_u64 v[252:253], v[200:201], 0, v[252:253]
	global_load_dwordx4 v[236:239], v[252:253], off offset:16
	global_load_dwordx4 v[240:243], v[252:253], off
	v_add_u32_e32 v252, 0xb0, v150
	v_ashrrev_i32_e32 v253, 31, v252
	v_lshlrev_b64 v[252:253], 7, v[252:253]
	v_lshl_add_u64 v[252:253], v[200:201], 0, v[252:253]
	global_load_dwordx4 v[244:247], v[252:253], off offset:16
	global_load_dwordx4 v[248:251], v[252:253], off

.LBB0_849:
	s_or_b64 exec, exec, s[46:47]
	s_and_b64 vcc, exec, s[8:9]
	s_mov_b64 s[8:9], -1
	s_cbranch_vccnz .LBB0_818
	v_mov_b32_e32 v0, v153
	v_mov_b32_e32 v1, v151
	s_lshl_b32 s8, s78, 8
	s_add_i32 s8, s8, s13
	v_add_u32_e32 v0, s8, v0
	s_waitcnt lgkmcnt(0)
	v_lshlrev_b32_e32 v2, 3, v1
	v_ashrrev_i32_e32 v3, 31, v2
	v_ashrrev_i32_e32 v1, 31, v0
	v_lshl_add_u64 v[6:7], v[2:3], 2, s[62:63]
	v_lshlrev_b64 v[4:5], 7, v[0:1]
	v_lshl_add_u64 v[4:5], v[6:7], 0, v[4:5]
	s_waitcnt vmcnt(16)
	v_mov_b32_e32 v8, v184
	v_mov_b32_e32 v9, v185
	v_mov_b32_e32 v10, v186
	v_mov_b32_e32 v11, v187
	v_mov_b32_e32 v12, v188
	v_mov_b32_e32 v13, v189
	v_mov_b32_e32 v14, v190
	v_mov_b32_e32 v15, v191
	v_add_u32_e32 v56, 0x90, v0
	v_ashrrev_i32_e32 v57, 31, v56
	v_add_u32_e32 v58, 0xa0, v0
	v_ashrrev_i32_e32 v59, 31, v58
	v_add_u32_e32 v60, 0xb0, v0
	v_ashrrev_i32_e32 v61, 31, v60
	s_lshl_b32 s8, s73, 8
	s_or_b32 s8, s8, s66
	v_add_u32_e32 v2, s8, v2
	v_ashrrev_i32_e32 v3, 31, v2
	s_andn2_b64 vcc, exec, s[4:5]
	v_mov_b32_e32 v5, v8
	v_mov_b32_e32 v4, v12
	v_mov_b32_e32 v16, v14
	v_mov_b32_e32 v17, v10
	v_pk_add_f32 v[4:5], v[4:5], v[16:17]
	v_add_f32_e32 v8, v13, v15
	v_add_f32_e32 v10, v9, v11
	v_mov_b32_e32 v9, v4
	v_mov_b32_e32 v11, v5
	v_pk_add_f32 v[4:5], v[8:9], v[10:11]
	ds_bpermute_b32 v9, v155, v5
	ds_bpermute_b32 v8, v155, v4
	s_waitcnt lgkmcnt(0)
	v_pk_add_f32 v[48:49], v[4:5], v[8:9]
	v_add_u32_e32 v4, 16, v0
	v_ashrrev_i32_e32 v5, 31, v4
	v_lshlrev_b64 v[8:9], 7, v[4:5]
	v_lshl_add_u64 v[12:13], v[6:7], 0, v[8:9]
	v_mov_b32_e32 v8, v192
	v_mov_b32_e32 v9, v193
	v_mov_b32_e32 v10, v194
	v_mov_b32_e32 v11, v195
	s_nop 0
	v_mov_b32_e32 v12, v196
	v_mov_b32_e32 v13, v197
	v_mov_b32_e32 v14, v198
	v_mov_b32_e32 v15, v199
	ds_bpermute_b32 v51, v157, v49
	ds_bpermute_b32 v50, v157, v48
	v_mov_b32_e32 v17, v8
	v_mov_b32_e32 v16, v12
	v_mov_b32_e32 v18, v14
	v_mov_b32_e32 v19, v10
	v_pk_add_f32 v[16:17], v[16:17], v[18:19]
	v_add_f32_e32 v8, v13, v15
	v_add_f32_e32 v10, v9, v11
	v_mov_b32_e32 v9, v16
	v_mov_b32_e32 v11, v17
	v_pk_add_f32 v[8:9], v[8:9], v[10:11]
	ds_bpermute_b32 v11, v155, v9
	ds_bpermute_b32 v10, v155, v8
	s_waitcnt lgkmcnt(0)
	v_pk_add_f32 v[52:53], v[8:9], v[10:11]
	v_add_u32_e32 v8, 32, v0
	v_ashrrev_i32_e32 v9, 31, v8
	v_lshlrev_b64 v[10:11], 7, v[8:9]
	v_lshl_add_u64 v[14:15], v[6:7], 0, v[10:11]
	v_mov_b32_e32 v10, v204
	v_mov_b32_e32 v11, v205
	v_mov_b32_e32 v12, v206
	v_mov_b32_e32 v13, v207
	s_nop 0
	v_mov_b32_e32 v14, v208
	v_mov_b32_e32 v15, v209
	v_mov_b32_e32 v16, v210
	v_mov_b32_e32 v17, v211
	ds_bpermute_b32 v55, v157, v53
	ds_bpermute_b32 v54, v157, v52
	v_mov_b32_e32 v19, v10
	v_mov_b32_e32 v18, v14
	v_mov_b32_e32 v20, v16
	v_mov_b32_e32 v21, v12
	v_pk_add_f32 v[18:19], v[18:19], v[20:21]
	v_add_f32_e32 v10, v15, v17
	v_add_f32_e32 v12, v11, v13
	v_mov_b32_e32 v11, v18
	v_mov_b32_e32 v13, v19
	v_pk_add_f32 v[10:11], v[10:11], v[12:13]
	ds_bpermute_b32 v13, v155, v11
	ds_bpermute_b32 v12, v155, v10
	s_waitcnt lgkmcnt(0)
	v_pk_add_f32 v[64:65], v[10:11], v[12:13]
	v_add_u32_e32 v10, 48, v0
	v_ashrrev_i32_e32 v11, 31, v10
	v_lshlrev_b64 v[12:13], 7, v[10:11]
	v_lshl_add_u64 v[16:17], v[6:7], 0, v[12:13]
	v_mov_b32_e32 v12, v212
	v_mov_b32_e32 v13, v213
	v_mov_b32_e32 v14, v214
	v_mov_b32_e32 v15, v215
	s_nop 0
	v_mov_b32_e32 v16, v216
	v_mov_b32_e32 v17, v217
	v_mov_b32_e32 v18, v218
	v_mov_b32_e32 v19, v219
	ds_bpermute_b32 v67, v157, v65
	ds_bpermute_b32 v66, v157, v64
	v_mov_b32_e32 v21, v12
	v_mov_b32_e32 v20, v16
	v_mov_b32_e32 v22, v18
	v_mov_b32_e32 v23, v14
	v_pk_add_f32 v[20:21], v[20:21], v[22:23]
	v_add_f32_e32 v12, v17, v19
	v_add_f32_e32 v14, v13, v15
	v_mov_b32_e32 v13, v20
	v_mov_b32_e32 v15, v21
	v_pk_add_f32 v[12:13], v[12:13], v[14:15]
	ds_bpermute_b32 v15, v155, v13
	ds_bpermute_b32 v14, v155, v12
	s_waitcnt lgkmcnt(0)
	v_pk_add_f32 v[68:69], v[12:13], v[14:15]
	v_add_u32_e32 v12, 0x80, v0
	v_ashrrev_i32_e32 v13, 31, v12
	v_lshlrev_b64 v[14:15], 7, v[12:13]
	v_lshl_add_u64 v[18:19], v[6:7], 0, v[14:15]
	v_mov_b32_e32 v14, v220
	v_mov_b32_e32 v15, v221
	v_mov_b32_e32 v16, v222
	v_mov_b32_e32 v17, v223
	s_nop 0
	v_mov_b32_e32 v18, v224
	v_mov_b32_e32 v19, v225
	v_mov_b32_e32 v20, v226
	v_mov_b32_e32 v21, v227
	v_lshlrev_b64 v[0:1], 11, v[0:1]
	v_lshl_add_u64 v[0:1], s[44:45], 0, v[0:1]
	ds_bpermute_b32 v71, v157, v69
	ds_bpermute_b32 v70, v157, v68
	v_mov_b32_e32 v23, v14
	v_mov_b32_e32 v22, v18
	v_mov_b32_e32 v24, v20
	v_mov_b32_e32 v25, v16
	v_pk_add_f32 v[22:23], v[22:23], v[24:25]
	v_add_f32_e32 v14, v19, v21
	v_add_f32_e32 v16, v15, v17
	v_mov_b32_e32 v15, v22
	v_mov_b32_e32 v17, v23
	v_pk_add_f32 v[14:15], v[14:15], v[16:17]
	ds_bpermute_b32 v17, v155, v15
	ds_bpermute_b32 v16, v155, v14
	s_waitcnt lgkmcnt(0)
	v_pk_add_f32 v[112:113], v[14:15], v[16:17]
	v_lshlrev_b64 v[14:15], 7, v[56:57]
	v_lshl_add_u64 v[18:19], v[6:7], 0, v[14:15]
	v_mov_b32_e32 v14, v228
	v_mov_b32_e32 v15, v229
	v_mov_b32_e32 v16, v230
	v_mov_b32_e32 v17, v231
	s_nop 0
	v_mov_b32_e32 v18, v232
	v_mov_b32_e32 v19, v233
	v_mov_b32_e32 v20, v234
	v_mov_b32_e32 v21, v235
	ds_bpermute_b32 v115, v157, v113
	ds_bpermute_b32 v114, v157, v112
	v_mov_b32_e32 v23, v14
	v_mov_b32_e32 v22, v18
	v_mov_b32_e32 v24, v20
	v_mov_b32_e32 v25, v16
	v_pk_add_f32 v[22:23], v[22:23], v[24:25]
	v_add_f32_e32 v14, v19, v21
	v_add_f32_e32 v16, v15, v17
	v_mov_b32_e32 v15, v22
	v_mov_b32_e32 v17, v23
	v_pk_add_f32 v[14:15], v[14:15], v[16:17]
	ds_bpermute_b32 v17, v155, v15
	ds_bpermute_b32 v16, v155, v14
	s_waitcnt lgkmcnt(0)
	v_pk_add_f32 v[116:117], v[14:15], v[16:17]
	v_lshlrev_b64 v[14:15], 7, v[58:59]
	v_lshl_add_u64 v[18:19], v[6:7], 0, v[14:15]
	v_mov_b32_e32 v14, v236
	v_mov_b32_e32 v15, v237
	v_mov_b32_e32 v16, v238
	v_mov_b32_e32 v17, v239
	s_nop 0
	v_mov_b32_e32 v18, v240
	v_mov_b32_e32 v19, v241
	v_mov_b32_e32 v20, v242
	v_mov_b32_e32 v21, v243
	ds_bpermute_b32 v119, v157, v117
	ds_bpermute_b32 v118, v157, v116
	v_mov_b32_e32 v23, v14
	v_mov_b32_e32 v22, v18
	v_mov_b32_e32 v24, v20
	v_mov_b32_e32 v25, v16
	v_pk_add_f32 v[22:23], v[22:23], v[24:25]
	v_add_f32_e32 v14, v19, v21
	v_add_f32_e32 v16, v15, v17
	v_mov_b32_e32 v15, v22
	v_mov_b32_e32 v17, v23
	v_pk_add_f32 v[14:15], v[14:15], v[16:17]
	ds_bpermute_b32 v17, v155, v15
	ds_bpermute_b32 v16, v155, v14
	s_waitcnt lgkmcnt(0)
	v_pk_add_f32 v[120:121], v[14:15], v[16:17]
	v_lshlrev_b64 v[14:15], 7, v[60:61]
	v_lshl_add_u64 v[6:7], v[6:7], 0, v[14:15]
	v_mov_b32_e32 v14, v244
	v_mov_b32_e32 v15, v245
	v_mov_b32_e32 v16, v246
	v_mov_b32_e32 v17, v247
	v_mov_b32_e32 v18, v248
	v_mov_b32_e32 v19, v249
	v_mov_b32_e32 v20, v250
	v_mov_b32_e32 v21, v251
	ds_bpermute_b32 v123, v157, v121
	ds_bpermute_b32 v122, v157, v120
	v_mov_b32_e32 v7, v14
	v_mov_b32_e32 v6, v18
	v_mov_b32_e32 v22, v20
	v_mov_b32_e32 v23, v16
	v_pk_add_f32 v[6:7], v[6:7], v[22:23]
	v_add_f32_e32 v14, v19, v21
	v_add_f32_e32 v16, v15, v17
	v_mov_b32_e32 v15, v6
	v_mov_b32_e32 v17, v7
	v_pk_add_f32 v[6:7], v[14:15], v[16:17]
	ds_bpermute_b32 v15, v155, v7
	ds_bpermute_b32 v14, v155, v6
	s_waitcnt lgkmcnt(0)
	v_pk_add_f32 v[124:125], v[6:7], v[14:15]
	v_lshlrev_b64 v[6:7], 2, v[2:3]
	v_lshlrev_b64 v[2:3], 1, v[2:3]
	v_lshl_add_u64 v[74:75], v[0:1], 0, v[2:3]
	v_lshlrev_b64 v[0:1], 11, v[4:5]
	v_lshl_add_u64 v[0:1], s[44:45], 0, v[0:1]
	v_lshl_add_u64 v[76:77], v[0:1], 0, v[2:3]
	v_lshlrev_b64 v[0:1], 11, v[8:9]
	v_lshl_add_u64 v[0:1], s[44:45], 0, v[0:1]
	v_lshl_add_u64 v[78:79], v[0:1], 0, v[2:3]
	v_lshlrev_b64 v[0:1], 11, v[10:11]
	v_lshl_add_u64 v[0:1], s[44:45], 0, v[0:1]
	v_lshl_add_u64 v[80:81], v[0:1], 0, v[2:3]
	v_lshlrev_b64 v[0:1], 11, v[12:13]
	v_lshl_add_u64 v[0:1], s[44:45], 0, v[0:1]
	v_lshl_add_u64 v[146:147], v[0:1], 0, v[2:3]
	v_lshlrev_b64 v[0:1], 11, v[56:57]
	v_lshl_add_u64 v[0:1], s[44:45], 0, v[0:1]
	v_lshl_add_u64 v[56:57], v[0:1], 0, v[2:3]
	v_lshlrev_b64 v[0:1], 11, v[58:59]
	v_lshl_add_u64 v[0:1], s[44:45], 0, v[0:1]
	v_lshl_add_u64 v[58:59], v[0:1], 0, v[2:3]
	v_lshlrev_b64 v[0:1], 11, v[60:61]
	v_lshl_add_u64 v[0:1], s[44:45], 0, v[0:1]
	v_lshl_add_u64 v[62:63], s[18:19], 0, v[6:7]
	v_lshl_add_u64 v[72:73], s[20:21], 0, v[6:7]
	v_lshl_add_u64 v[148:149], v[0:1], 0, v[2:3]
	global_load_dwordx4 v[36:39], v[62:63], off offset:16
	global_load_dwordx4 v[44:47], v[62:63], off
	global_load_dwordx4 v[32:35], v[72:73], off offset:16
	global_load_dwordx4 v[40:43], v[72:73], off
	global_load_dwordx4 v[28:31], v[74:75], off
	global_load_dwordx4 v[24:27], v[76:77], off
	global_load_dwordx4 v[20:23], v[78:79], off
	global_load_dwordx4 v[16:19], v[80:81], off
	global_load_dwordx4 v[12:15], v[146:147], off
	global_load_dwordx4 v[8:11], v[56:57], off
	global_load_dwordx4 v[4:7], v[58:59], off
	global_load_dwordx4 v[0:3], v[148:149], off
	global_load_dwordx4 v[104:107], v[62:63], off offset:528
	global_load_dwordx4 v[108:111], v[62:63], off offset:512
	global_load_dwordx4 v[96:99], v[72:73], off offset:528
	global_load_dwordx4 v[100:103], v[72:73], off offset:512
	global_load_dwordx4 v[92:95], v[74:75], off offset:256
	global_load_dwordx4 v[88:91], v[76:77], off offset:256
	global_load_dwordx4 v[84:87], v[78:79], off offset:256
	s_nop 0
	global_load_dwordx4 v[80:83], v[80:81], off offset:256
	s_nop 0
	global_load_dwordx4 v[76:79], v[146:147], off offset:256
	global_load_dwordx4 v[72:75], v[56:57], off offset:256
	global_load_dwordx4 v[60:63], v[58:59], off offset:256
	s_nop 0
	global_load_dwordx4 v[56:59], v[148:149], off offset:256
	ds_bpermute_b32 v127, v157, v125
	ds_bpermute_b32 v126, v157, v124
	s_cbranch_vccnz .LBB0_817
	s_barrier
	s_branch .LBB0_817

.LBB0_1403:
	v_bfe_u32 v179, v12, 4, 2
	v_and_b32_e32 v178, 15, v12
	v_lshlrev_b32_e32 v15, 4, v179
	v_lshlrev_b32_e32 v12, 2, v12
	s_sext_i32_i8 s37, s4
	v_lshl_or_b32 v15, v178, 6, v15
	s_lshl_b32 s4, s5, 13
	v_and_b32_e32 v12, 32, v12
	v_bitop3_b32 v16, v15, s4, v12 bitop3:0xde
	s_lshl_b32 s4, s7, 5
	s_and_b32 s71, s4, 0x60
	s_lshl_b32 s4, s71, 7
	s_lshl_b32 s70, s5, 6
	v_bitop3_b32 v180, v15, s4, v12 bitop3:0xde
	s_mov_b64 s[4:5], 0x80
	s_add_i32 m0, s65, 0x18000
	v_lshl_add_u64 v[6:7], v[6:7], 0, s[4:5]
	s_waitcnt vmcnt(2)
	s_barrier
	global_load_lds_dwordx4 v[6:7], off
	v_lshl_add_u64 v[4:5], v[4:5], 0, s[4:5]
	s_add_i32 m0, s65, 0x1a000
	s_add_i32 s72, s65, 0x8000
	s_add_i32 s73, s65, 0xa000
	global_load_lds_dwordx4 v[4:5], off
	v_lshl_add_u64 v[0:1], v[0:1], 0, s[4:5]
	s_mov_b32 m0, s72
	s_add_u32 s8, s46, 0x20080
	global_load_lds_dwordx4 v[0:1], off
	v_lshl_add_u64 v[0:1], v[2:3], 0, s[4:5]
	s_mov_b32 m0, s73
	s_addc_u32 s9, s47, 0
	global_load_lds_dwordx4 v[0:1], off
	s_add_i32 m0, s65, 0x1c000
	v_lshl_add_u64 v[0:1], s[8:9], 0, v[154:155]
	global_load_lds_dwordx4 v[0:1], off
	v_lshl_add_u64 v[0:1], s[8:9], 0, v[158:159]
	s_add_i32 m0, s65, 0x1e000
	s_cmpk_lt_u32 s6, 0x100
	global_load_lds_dwordx4 v[0:1], off
	v_lshlrev_b32_e32 v0, 13, v8
	v_and_b32_e32 v0, 0xffffc000, v0
	v_lshl_add_u32 v0, v9, 10, v0
	v_and_b32_e32 v1, 1, v8
	v_lshl_or_b32 v0, v1, 6, v0
	v_lshl_add_u32 v160, v10, 1, v0
	v_lshlrev_b32_e32 v0, 13, v11
	v_and_b32_e32 v0, 0xffffc000, v0
	s_waitcnt vmcnt(6)
	v_lshl_add_u32 v0, v13, 10, v0
	v_and_b32_e32 v1, 1, v11
	s_cselect_b64 s[6:7], -1, 0
	v_lshl_or_b32 v0, v1, 6, v0
	s_add_i32 s74, 0, 0x10000
	s_add_i32 s75, 0, 0x14000
	v_mov_b32_e32 v161, v155
	v_lshl_add_u32 v162, v14, 1, v0
	v_mov_b32_e32 v163, v155
	v_mov_b64_e32 v[164:165], 0x200
	v_mov_b64_e32 v[166:167], 0x1ff
	v_add_u32_e32 v181, s74, v180
	v_add_u32_e32 v182, s75, v180
	v_add_u32_e32 v183, 0, v16
	s_barrier
	s_mov_b32 s99, 0
	s_branch .LBB0_1406

.Lrlx13p0b:
	s_waitcnt vmcnt(24)
	s_branch .Lrlx13p0b_done
.LBB0_1404:
	s_mov_b64 s[36:37], 0

.LBB0_1413:
	ds_read_b128 v[128:131], v181
	ds_read_b128 v[132:135], v181 offset:1024
	ds_read_b128 v[136:139], v181 offset:2048
	ds_read_b128 v[140:143], v181 offset:3072
	ds_read_b128 v[144:147], v182
	ds_read_b128 v[148:151], v182 offset:1024
	ds_read_b128 v[168:171], v182 offset:2048
	ds_read_b128 v[172:175], v182 offset:3072
	s_add_u32 s46, s40, 0xfffe0080
	s_addc_u32 s47, s41, -1
	s_cmp_eq_u32 s82, 4
	s_cselect_b32 s61, s13, s47
	s_cselect_b32 s60, s78, s46
	s_cselect_b32 s47, s11, s81
	s_cselect_b32 s46, s79, s80
	v_lshl_add_u64 v[176:177], s[40:41], 0, v[160:161]
	s_add_i32 m0, s65, 0xc000
	ds_read_b128 v[184:187], v183
	ds_read_b128 v[188:191], v183 offset:1024
	ds_read_b128 v[192:195], v183 offset:2048
	ds_read_b128 v[196:199], v183 offset:3072
	ds_read_b128 v[200:203], v183 offset:4096
	ds_read_b128 v[204:207], v183 offset:5120
	ds_read_b128 v[212:215], v183 offset:6144
	ds_read_b128 v[216:219], v183 offset:7168
	global_load_lds_dwordx4 v[176:177], off
	v_lshl_add_u64 v[176:177], s[40:41], 0, v[162:163]
	s_add_i32 m0, s65, 0xe000
	s_nop 0
	global_load_lds_dwordx4 v[176:177], off
	s_cmp_lg_u32 s99, 0
	s_cbranch_scc1 .Lrlx13p0a
	s_waitcnt vmcnt(8)
.Lrlx13p0a_done:
	s_waitcnt lgkmcnt(0)
	s_barrier
	s_setprio 1
	s_waitcnt lgkmcnt(0)
	v_mfma_f32_16x16x32_bf16 v[124:127], v[128:131], v[184:187], v[124:127]
	v_mfma_f32_16x16x32_bf16 v[120:123], v[136:139], v[184:187], v[120:123]
	v_mfma_f32_16x16x32_bf16 v[108:111], v[128:131], v[192:195], v[108:111]
	v_mfma_f32_16x16x32_bf16 v[104:107], v[136:139], v[192:195], v[104:107]
	v_mfma_f32_16x16x32_bf16 v[96:99], v[128:131], v[200:203], v[96:99]
	v_mfma_f32_16x16x32_bf16 v[88:91], v[136:139], v[200:203], v[88:91]
	v_mfma_f32_16x16x32_bf16 v[80:83], v[128:131], v[212:215], v[80:83]
	v_mfma_f32_16x16x32_bf16 v[72:75], v[136:139], v[212:215], v[72:75]
	v_mfma_f32_16x16x32_bf16 v[124:127], v[132:135], v[188:191], v[124:127]
	v_mfma_f32_16x16x32_bf16 v[120:123], v[140:143], v[188:191], v[120:123]
	v_mfma_f32_16x16x32_bf16 v[108:111], v[132:135], v[196:199], v[108:111]
	v_mfma_f32_16x16x32_bf16 v[104:107], v[140:143], v[196:199], v[104:107]
	v_mfma_f32_16x16x32_bf16 v[96:99], v[132:135], v[204:207], v[96:99]
	v_mfma_f32_16x16x32_bf16 v[88:91], v[140:143], v[204:207], v[88:91]
	v_mfma_f32_16x16x32_bf16 v[80:83], v[132:135], v[216:219], v[80:83]
	v_mfma_f32_16x16x32_bf16 v[72:75], v[140:143], v[216:219], v[72:75]
	s_setprio 0
	s_setprio 1
	v_mfma_f32_16x16x32_bf16 v[116:119], v[144:147], v[184:187], v[116:119]
	v_mfma_f32_16x16x32_bf16 v[112:115], v[168:171], v[184:187], v[112:115]
	v_mfma_f32_16x16x32_bf16 v[100:103], v[144:147], v[192:195], v[100:103]
	v_mfma_f32_16x16x32_bf16 v[92:95], v[168:171], v[192:195], v[92:95]
	v_mfma_f32_16x16x32_bf16 v[84:87], v[144:147], v[200:203], v[84:87]
	v_mfma_f32_16x16x32_bf16 v[76:79], v[168:171], v[200:203], v[76:79]
	v_mfma_f32_16x16x32_bf16 v[68:71], v[144:147], v[212:215], v[68:71]
	v_mfma_f32_16x16x32_bf16 v[64:67], v[168:171], v[212:215], v[64:67]
	v_mfma_f32_16x16x32_bf16 v[116:119], v[148:151], v[188:191], v[116:119]
	v_mfma_f32_16x16x32_bf16 v[112:115], v[172:175], v[188:191], v[112:115]
	v_mfma_f32_16x16x32_bf16 v[100:103], v[148:151], v[196:199], v[100:103]
	v_mfma_f32_16x16x32_bf16 v[92:95], v[172:175], v[196:199], v[92:95]
	v_mfma_f32_16x16x32_bf16 v[84:87], v[148:151], v[204:207], v[84:87]
	v_mfma_f32_16x16x32_bf16 v[76:79], v[172:175], v[204:207], v[76:79]
	v_mfma_f32_16x16x32_bf16 v[68:71], v[148:151], v[216:219], v[68:71]
	v_mfma_f32_16x16x32_bf16 v[64:67], v[172:175], v[216:219], v[64:67]
	s_setprio 0
	s_barrier
	s_add_i32 s83, s74, s64
	v_lshl_add_u64 v[176:177], s[46:47], 0, v[154:155]
	s_mov_b32 m0, s83
	ds_read_b128 v[184:187], v183 offset:16384
	ds_read_b128 v[188:191], v183 offset:17408
	ds_read_b128 v[192:195], v183 offset:18432
	ds_read_b128 v[196:199], v183 offset:19456
	ds_read_b128 v[200:203], v183 offset:20480
	ds_read_b128 v[204:207], v183 offset:21504
	ds_read_b128 v[212:215], v183 offset:22528
	ds_read_b128 v[216:219], v183 offset:23552
	global_load_lds_dwordx4 v[176:177], off
	s_add_i32 m0, s83, 0x2000
	s_add_u32 s84, s46, 0x20000
	v_lshl_add_u64 v[208:209], s[46:47], 0, v[158:159]
	s_addc_u32 s85, s47, 0
	s_add_i32 s83, s75, s64
	global_load_lds_dwordx4 v[208:209], off
	v_lshl_add_u64 v[210:211], s[84:85], 0, v[154:155]
	s_mov_b32 m0, s83
	v_lshl_add_u64 v[220:221], s[60:61], 0, v[156:157]
	global_load_lds_dwordx4 v[210:211], off
	v_lshl_add_u64 v[210:211], s[84:85], 0, v[158:159]
	s_add_i32 m0, s83, 0x2000
	s_nop 0
	global_load_lds_dwordx4 v[210:211], off
	v_lshl_add_u64 v[210:211], s[60:61], 0, v[152:153]
	s_mov_b32 m0, s65
	s_nop 0
	global_load_lds_dwordx4 v[210:211], off
	s_mov_b32 m0, s66
	s_nop 0
	global_load_lds_dwordx4 v[220:221], off
	s_cmp_lg_u32 s99, 0
	s_cbranch_scc1 .Lrlx13p0b
	s_waitcnt vmcnt(8)
.Lrlx13p0b_done:
	s_mov_b32 s99, 0
	s_waitcnt lgkmcnt(0)
	s_barrier
	s_setprio 1
	s_waitcnt lgkmcnt(0)
	v_mfma_f32_16x16x32_bf16 v[60:63], v[128:131], v[184:187], v[60:63]
	v_mfma_f32_16x16x32_bf16 v[56:59], v[136:139], v[184:187], v[56:59]
	v_mfma_f32_16x16x32_bf16 v[48:51], v[128:131], v[192:195], v[48:51]
	v_mfma_f32_16x16x32_bf16 v[40:43], v[136:139], v[192:195], v[40:43]
	v_mfma_f32_16x16x32_bf16 v[32:35], v[128:131], v[200:203], v[32:35]
	v_mfma_f32_16x16x32_bf16 v[24:27], v[136:139], v[200:203], v[24:27]
	v_mfma_f32_16x16x32_bf16 v[16:19], v[128:131], v[212:215], v[16:19]
	v_mfma_f32_16x16x32_bf16 v[8:11], v[136:139], v[212:215], v[8:11]
	v_mfma_f32_16x16x32_bf16 v[60:63], v[132:135], v[188:191], v[60:63]
	v_mfma_f32_16x16x32_bf16 v[56:59], v[140:143], v[188:191], v[56:59]
	v_mfma_f32_16x16x32_bf16 v[48:51], v[132:135], v[196:199], v[48:51]
	v_mfma_f32_16x16x32_bf16 v[40:43], v[140:143], v[196:199], v[40:43]
	v_mfma_f32_16x16x32_bf16 v[32:35], v[132:135], v[204:207], v[32:35]
	v_mfma_f32_16x16x32_bf16 v[24:27], v[140:143], v[204:207], v[24:27]
	v_mfma_f32_16x16x32_bf16 v[16:19], v[132:135], v[216:219], v[16:19]
	v_mfma_f32_16x16x32_bf16 v[8:11], v[140:143], v[216:219], v[8:11]
	s_setprio 0
	s_setprio 1
	v_mfma_f32_16x16x32_bf16 v[52:55], v[144:147], v[184:187], v[52:55]
	v_mfma_f32_16x16x32_bf16 v[44:47], v[168:171], v[184:187], v[44:47]
	v_mfma_f32_16x16x32_bf16 v[36:39], v[144:147], v[192:195], v[36:39]
	v_mfma_f32_16x16x32_bf16 v[28:31], v[168:171], v[192:195], v[28:31]
	v_mfma_f32_16x16x32_bf16 v[20:23], v[144:147], v[200:203], v[20:23]
	v_mfma_f32_16x16x32_bf16 v[12:15], v[168:171], v[200:203], v[12:15]
	v_mfma_f32_16x16x32_bf16 v[4:7], v[144:147], v[212:215], v[4:7]
	v_mfma_f32_16x16x32_bf16 v[0:3], v[168:171], v[212:215], v[0:3]
	v_mfma_f32_16x16x32_bf16 v[52:55], v[148:151], v[188:191], v[52:55]
	v_mfma_f32_16x16x32_bf16 v[44:47], v[172:175], v[188:191], v[44:47]
	v_mfma_f32_16x16x32_bf16 v[36:39], v[148:151], v[196:199], v[36:39]
	v_mfma_f32_16x16x32_bf16 v[28:31], v[172:175], v[196:199], v[28:31]
	v_mfma_f32_16x16x32_bf16 v[20:23], v[148:151], v[204:207], v[20:23]
	v_mfma_f32_16x16x32_bf16 v[12:15], v[172:175], v[204:207], v[12:15]
	v_mfma_f32_16x16x32_bf16 v[4:7], v[148:151], v[216:219], v[4:7]
	v_mfma_f32_16x16x32_bf16 v[0:3], v[172:175], v[216:219], v[0:3]
	s_setprio 0
	s_barrier
	s_add_i32 s83, 0, 0x18000
	s_add_i32 s84, 0, 0x1c000
	v_add_u32_e32 v140, s83, v180
	v_add_u32_e32 v172, s84, v180
	ds_read_b128 v[128:131], v140
	ds_read_b128 v[132:135], v140 offset:1024
	ds_read_b128 v[136:139], v140 offset:2048
	ds_read_b128 v[140:143], v140 offset:3072
	ds_read_b128 v[144:147], v172
	ds_read_b128 v[148:151], v172 offset:1024
	ds_read_b128 v[168:171], v172 offset:2048
	ds_read_b128 v[172:175], v172 offset:3072
	s_add_u32 s60, s60, 0x20000
	s_addc_u32 s61, s61, 0
	s_mov_b32 m0, s67
	v_lshl_add_u64 v[222:223], s[60:61], 0, v[152:153]
	ds_read_b128 v[184:187], v183 offset:32768
	ds_read_b128 v[188:191], v183 offset:33792
	ds_read_b128 v[192:195], v183 offset:34816
	ds_read_b128 v[196:199], v183 offset:35840
	ds_read_b128 v[200:203], v183 offset:36864
	ds_read_b128 v[204:207], v183 offset:37888
	ds_read_b128 v[212:215], v183 offset:38912
	ds_read_b128 v[216:219], v183 offset:39936
	global_load_lds_dwordx4 v[222:223], off
	v_lshl_add_u64 v[222:223], s[60:61], 0, v[156:157]
	s_mov_b32 m0, s68
	s_nop 0
	global_load_lds_dwordx4 v[222:223], off
	s_waitcnt vmcnt(8)
	s_waitcnt lgkmcnt(0)
	s_barrier
	s_setprio 1
	s_waitcnt lgkmcnt(0)
	v_mfma_f32_16x16x32_bf16 v[124:127], v[128:131], v[184:187], v[124:127]
	v_mfma_f32_16x16x32_bf16 v[120:123], v[136:139], v[184:187], v[120:123]
	v_mfma_f32_16x16x32_bf16 v[108:111], v[128:131], v[192:195], v[108:111]
	v_mfma_f32_16x16x32_bf16 v[104:107], v[136:139], v[192:195], v[104:107]
	v_mfma_f32_16x16x32_bf16 v[96:99], v[128:131], v[200:203], v[96:99]
	v_mfma_f32_16x16x32_bf16 v[88:91], v[136:139], v[200:203], v[88:91]
	v_mfma_f32_16x16x32_bf16 v[80:83], v[128:131], v[212:215], v[80:83]
	v_mfma_f32_16x16x32_bf16 v[72:75], v[136:139], v[212:215], v[72:75]
	v_mfma_f32_16x16x32_bf16 v[124:127], v[132:135], v[188:191], v[124:127]
	v_mfma_f32_16x16x32_bf16 v[120:123], v[140:143], v[188:191], v[120:123]
	v_mfma_f32_16x16x32_bf16 v[108:111], v[132:135], v[196:199], v[108:111]
	v_mfma_f32_16x16x32_bf16 v[104:107], v[140:143], v[196:199], v[104:107]
	v_mfma_f32_16x16x32_bf16 v[96:99], v[132:135], v[204:207], v[96:99]
	v_mfma_f32_16x16x32_bf16 v[88:91], v[140:143], v[204:207], v[88:91]
	v_mfma_f32_16x16x32_bf16 v[80:83], v[132:135], v[216:219], v[80:83]
	v_mfma_f32_16x16x32_bf16 v[72:75], v[140:143], v[216:219], v[72:75]
	s_setprio 0
	s_setprio 1
	v_mfma_f32_16x16x32_bf16 v[116:119], v[144:147], v[184:187], v[116:119]
	v_mfma_f32_16x16x32_bf16 v[112:115], v[168:171], v[184:187], v[112:115]
	v_mfma_f32_16x16x32_bf16 v[100:103], v[144:147], v[192:195], v[100:103]
	v_mfma_f32_16x16x32_bf16 v[92:95], v[168:171], v[192:195], v[92:95]
	v_mfma_f32_16x16x32_bf16 v[84:87], v[144:147], v[200:203], v[84:87]
	v_mfma_f32_16x16x32_bf16 v[76:79], v[168:171], v[200:203], v[76:79]
	v_mfma_f32_16x16x32_bf16 v[68:71], v[144:147], v[212:215], v[68:71]
	v_mfma_f32_16x16x32_bf16 v[64:67], v[168:171], v[212:215], v[64:67]
	v_mfma_f32_16x16x32_bf16 v[116:119], v[148:151], v[188:191], v[116:119]
	v_mfma_f32_16x16x32_bf16 v[112:115], v[172:175], v[188:191], v[112:115]
	v_mfma_f32_16x16x32_bf16 v[100:103], v[148:151], v[196:199], v[100:103]
	v_mfma_f32_16x16x32_bf16 v[92:95], v[172:175], v[196:199], v[92:95]
	v_mfma_f32_16x16x32_bf16 v[84:87], v[148:151], v[204:207], v[84:87]
	v_mfma_f32_16x16x32_bf16 v[76:79], v[172:175], v[204:207], v[76:79]
	v_mfma_f32_16x16x32_bf16 v[68:71], v[148:151], v[216:219], v[68:71]
	v_mfma_f32_16x16x32_bf16 v[64:67], v[172:175], v[216:219], v[64:67]
	s_setprio 0
	s_barrier
	s_add_i32 s60, s83, s64
	v_lshl_add_u64 v[176:177], v[176:177], 0, s[4:5]
	s_mov_b32 m0, s60
	ds_read_b128 v[184:187], v183 offset:49152
	ds_read_b128 v[188:191], v183 offset:50176
	ds_read_b128 v[192:195], v183 offset:51200
	ds_read_b128 v[196:199], v183 offset:52224
	ds_read_b128 v[200:203], v183 offset:53248
	ds_read_b128 v[204:207], v183 offset:54272
	ds_read_b128 v[212:215], v183 offset:55296
	ds_read_b128 v[216:219], v183 offset:56320
	global_load_lds_dwordx4 v[176:177], off
	s_add_i32 m0, s60, 0x2000
	s_add_u32 s46, s46, 0x20080
	v_lshl_add_u64 v[176:177], v[208:209], 0, s[4:5]
	s_addc_u32 s47, s47, 0
	s_add_i32 s60, s84, s64
	global_load_lds_dwordx4 v[176:177], off
	v_lshl_add_u64 v[176:177], s[46:47], 0, v[154:155]
	s_mov_b32 m0, s60
	s_nop 0
	global_load_lds_dwordx4 v[176:177], off
	v_lshl_add_u64 v[176:177], s[46:47], 0, v[158:159]
	s_add_i32 m0, s60, 0x2000
	s_nop 0
	global_load_lds_dwordx4 v[176:177], off
	v_lshl_add_u64 v[176:177], v[210:211], 0, s[4:5]
	s_mov_b32 m0, s72
	s_nop 0
	global_load_lds_dwordx4 v[176:177], off
	v_lshl_add_u64 v[176:177], v[220:221], 0, s[4:5]
	s_mov_b32 m0, s73
	s_nop 0
	global_load_lds_dwordx4 v[176:177], off
	s_waitcnt vmcnt(8)
	s_waitcnt lgkmcnt(0)
	s_barrier
	s_setprio 1
	s_waitcnt lgkmcnt(0)
	v_mfma_f32_16x16x32_bf16 v[60:63], v[128:131], v[184:187], v[60:63]
	v_mfma_f32_16x16x32_bf16 v[56:59], v[136:139], v[184:187], v[56:59]
	v_mfma_f32_16x16x32_bf16 v[48:51], v[128:131], v[192:195], v[48:51]
	v_mfma_f32_16x16x32_bf16 v[40:43], v[136:139], v[192:195], v[40:43]
	v_mfma_f32_16x16x32_bf16 v[32:35], v[128:131], v[200:203], v[32:35]
	v_mfma_f32_16x16x32_bf16 v[24:27], v[136:139], v[200:203], v[24:27]
	v_mfma_f32_16x16x32_bf16 v[16:19], v[128:131], v[212:215], v[16:19]
	v_mfma_f32_16x16x32_bf16 v[8:11], v[136:139], v[212:215], v[8:11]
	v_mfma_f32_16x16x32_bf16 v[60:63], v[132:135], v[188:191], v[60:63]
	v_mfma_f32_16x16x32_bf16 v[56:59], v[140:143], v[188:191], v[56:59]
	v_mfma_f32_16x16x32_bf16 v[48:51], v[132:135], v[196:199], v[48:51]
	v_mfma_f32_16x16x32_bf16 v[40:43], v[140:143], v[196:199], v[40:43]
	v_mfma_f32_16x16x32_bf16 v[32:35], v[132:135], v[204:207], v[32:35]
	v_mfma_f32_16x16x32_bf16 v[24:27], v[140:143], v[204:207], v[24:27]
	v_mfma_f32_16x16x32_bf16 v[16:19], v[132:135], v[216:219], v[16:19]
	v_mfma_f32_16x16x32_bf16 v[8:11], v[140:143], v[216:219], v[8:11]
	s_setprio 0
	s_setprio 1
	v_mfma_f32_16x16x32_bf16 v[52:55], v[144:147], v[184:187], v[52:55]
	v_mfma_f32_16x16x32_bf16 v[44:47], v[168:171], v[184:187], v[44:47]
	v_mfma_f32_16x16x32_bf16 v[36:39], v[144:147], v[192:195], v[36:39]
	v_mfma_f32_16x16x32_bf16 v[28:31], v[168:171], v[192:195], v[28:31]
	v_mfma_f32_16x16x32_bf16 v[20:23], v[144:147], v[200:203], v[20:23]
	v_mfma_f32_16x16x32_bf16 v[12:15], v[168:171], v[200:203], v[12:15]
	v_mfma_f32_16x16x32_bf16 v[4:7], v[144:147], v[212:215], v[4:7]
	v_mfma_f32_16x16x32_bf16 v[0:3], v[168:171], v[212:215], v[0:3]
	v_mfma_f32_16x16x32_bf16 v[52:55], v[148:151], v[188:191], v[52:55]
	v_mfma_f32_16x16x32_bf16 v[44:47], v[172:175], v[188:191], v[44:47]
	v_mfma_f32_16x16x32_bf16 v[36:39], v[148:151], v[196:199], v[36:39]
	v_mfma_f32_16x16x32_bf16 v[28:31], v[172:175], v[196:199], v[28:31]
	v_mfma_f32_16x16x32_bf16 v[20:23], v[148:151], v[204:207], v[20:23]
	v_mfma_f32_16x16x32_bf16 v[12:15], v[172:175], v[204:207], v[12:15]
	v_mfma_f32_16x16x32_bf16 v[4:7], v[148:151], v[216:219], v[4:7]
	v_mfma_f32_16x16x32_bf16 v[0:3], v[172:175], v[216:219], v[0:3]
	s_setprio 0
	s_barrier
	s_add_i32 s82, s82, 2
	s_add_u32 s40, s40, 0x100
	s_addc_u32 s41, s41, 0
	s_add_u32 s80, s80, 0x100
	s_addc_u32 s81, s81, 0
	s_cmp_gt_u32 s82, 5
	s_cbranch_scc0 .LBB0_1413
	s_and_b64 vcc, exec, s[6:7]
	s_cbranch_vccz .LBB0_1416
	s_barrier
.LBB0_1416:
	s_lshl_b32 s11, s36, 8
	v_mov_b32_e32 v128, v179
	v_mov_b32_e32 v129, v178
	s_add_i32 s11, s11, s70
	s_andn2_b64 vcc, exec, s[8:9]
	v_add_u32_e32 v170, s11, v129
	s_lshl_b32 s11, s37, 8
	s_or_b32 s11, s11, s71
	v_lshl_add_u32 v128, v128, 3, s11
	v_ashrrev_i32_e32 v129, 31, v128
	v_lshlrev_b64 v[168:169], 1, v[128:129]
	v_ashrrev_i32_e32 v171, 31, v170
	v_lshl_add_u64 v[172:173], s[56:57], 0, v[168:169]
	v_lshlrev_b64 v[128:129], 12, v[170:171]
	v_lshl_add_u64 v[128:129], v[172:173], 0, v[128:129]
	global_load_dwordx4 v[184:187], v[128:129], off
	global_load_dwordx4 v[188:191], v[128:129], off offset:256
	v_add_u32_e32 v192, 16, v170
	v_ashrrev_i32_e32 v193, 31, v192
	v_lshlrev_b64 v[128:129], 12, v[192:193]
	v_lshl_add_u64 v[128:129], v[172:173], 0, v[128:129]
	global_load_dwordx4 v[148:151], v[128:129], off
	global_load_dwordx4 v[144:147], v[128:129], off offset:256
	v_add_u32_e32 v176, 32, v170
	v_ashrrev_i32_e32 v177, 31, v176
	v_lshlrev_b64 v[128:129], 12, v[176:177]
	v_lshl_add_u64 v[128:129], v[172:173], 0, v[128:129]
	global_load_dwordx4 v[140:143], v[128:129], off
	global_load_dwordx4 v[132:135], v[128:129], off offset:256
	v_add_u32_e32 v174, 48, v170
	v_ashrrev_i32_e32 v175, 31, v174
	v_lshlrev_b64 v[128:129], 12, v[174:175]
	v_lshl_add_u64 v[128:129], v[172:173], 0, v[128:129]
	global_load_dwordx4 v[136:139], v[128:129], off
	s_nop 0
	global_load_dwordx4 v[128:131], v[128:129], off offset:256
	v_lshlrev_b64 v[194:195], 11, v[170:171]
	v_lshl_add_u64 v[194:195], s[42:43], 0, v[194:195]
	v_lshl_add_u64 v[194:195], v[194:195], 0, v[168:169]
	s_mov_b64 s[36:37], -1
	v_add_u32_e32 v200, 0x80, v170
	v_ashrrev_i32_e32 v201, 31, v200
	v_lshlrev_b64 v[252:253], 12, v[200:201]
	v_lshl_add_u64 v[200:201], v[172:173], 0, v[252:253]
	global_load_dwordx4 v[196:199], v[200:201], off
	global_load_dwordx4 v[204:207], v[200:201], off offset:256
	v_add_u32_e32 v200, 0x90, v170
	v_ashrrev_i32_e32 v201, 31, v200
	v_lshlrev_b64 v[252:253], 12, v[200:201]
	v_lshl_add_u64 v[200:201], v[172:173], 0, v[252:253]
	global_load_dwordx4 v[208:211], v[200:201], off
	global_load_dwordx4 v[212:215], v[200:201], off offset:256
	v_add_u32_e32 v200, 0xa0, v170
	v_ashrrev_i32_e32 v201, 31, v200
	v_lshlrev_b64 v[252:253], 12, v[200:201]
	v_lshl_add_u64 v[200:201], v[172:173], 0, v[252:253]
	global_load_dwordx4 v[216:219], v[200:201], off
	global_load_dwordx4 v[220:223], v[200:201], off offset:256
	v_add_u32_e32 v200, 0xb0, v170
	v_ashrrev_i32_e32 v201, 31, v200
	v_lshlrev_b64 v[252:253], 12, v[200:201]
	v_lshl_add_u64 v[200:201], v[172:173], 0, v[252:253]
	global_load_dwordx4 v[224:227], v[200:201], off
	global_load_dwordx4 v[228:231], v[200:201], off offset:256
	s_waitcnt vmcnt(8)
	v_lshlrev_b32_e32 v171, 16, v184
	v_mul_f32_e32 v124, v124, v171
	v_and_b32_e32 v171, 0xffff0000, v184
	v_mul_f32_e32 v125, v125, v171
	v_lshlrev_b32_e32 v171, 16, v185
	v_mul_f32_e32 v126, v126, v171
	v_and_b32_e32 v171, 0xffff0000, v185
	v_mul_f32_e32 v127, v127, v171
	v_lshlrev_b32_e32 v171, 16, v186
	v_mul_f32_e32 v171, v120, v171
	v_and_b32_e32 v120, 0xffff0000, v186
	v_mul_f32_e32 v184, v121, v120
	v_lshlrev_b32_e32 v120, 16, v187
	v_mul_f32_e32 v185, v122, v120
	v_and_b32_e32 v120, 0xffff0000, v187
	v_mul_f32_e32 v123, v123, v120
	v_cvt_pk_bf16_f32 v120, v124, v125
	v_cvt_pk_bf16_f32 v121, v126, v127
	v_cvt_pk_bf16_f32 v122, v171, v184
	v_cvt_pk_bf16_f32 v123, v185, v123
	global_store_dwordx4 v[194:195], v[120:123], off
	s_nop 1
	v_lshlrev_b32_e32 v120, 16, v188
	v_mul_f32_e32 v116, v116, v120
	v_and_b32_e32 v120, 0xffff0000, v188
	v_mul_f32_e32 v117, v117, v120
	v_lshlrev_b32_e32 v120, 16, v189
	v_mul_f32_e32 v118, v118, v120
	v_and_b32_e32 v120, 0xffff0000, v189
	v_mul_f32_e32 v119, v119, v120
	v_lshlrev_b32_e32 v120, 16, v190
	v_mul_f32_e32 v120, v112, v120
	v_and_b32_e32 v112, 0xffff0000, v190
	v_mul_f32_e32 v121, v113, v112
	v_lshlrev_b32_e32 v112, 16, v191
	v_mul_f32_e32 v122, v114, v112
	v_and_b32_e32 v112, 0xffff0000, v191
	v_mul_f32_e32 v115, v115, v112
	v_cvt_pk_bf16_f32 v112, v116, v117
	v_cvt_pk_bf16_f32 v113, v118, v119
	v_cvt_pk_bf16_f32 v114, v120, v121
	v_cvt_pk_bf16_f32 v115, v122, v115
	global_store_dwordx4 v[194:195], v[112:115], off offset:256
	s_nop 1
	v_lshlrev_b32_e32 v114, 16, v148
	v_mul_f32_e32 v108, v108, v114
	v_and_b32_e32 v114, 0xffff0000, v148
	v_mul_f32_e32 v109, v109, v114
	v_lshlrev_b32_e32 v114, 16, v149
	v_mul_f32_e32 v110, v110, v114
	v_and_b32_e32 v114, 0xffff0000, v149
	v_mul_f32_e32 v111, v111, v114
	v_lshlrev_b32_e32 v114, 16, v150
	v_mul_f32_e32 v114, v104, v114
	v_and_b32_e32 v104, 0xffff0000, v150
	v_lshlrev_b64 v[112:113], 11, v[192:193]
	v_mul_f32_e32 v115, v105, v104
	v_lshlrev_b32_e32 v104, 16, v151
	v_lshl_add_u64 v[112:113], s[42:43], 0, v[112:113]
	v_mul_f32_e32 v116, v106, v104
	v_and_b32_e32 v104, 0xffff0000, v151
	v_lshl_add_u64 v[112:113], v[112:113], 0, v[168:169]
	v_mul_f32_e32 v107, v107, v104
	v_cvt_pk_bf16_f32 v104, v108, v109
	v_cvt_pk_bf16_f32 v105, v110, v111
	v_cvt_pk_bf16_f32 v106, v114, v115
	v_cvt_pk_bf16_f32 v107, v116, v107
	global_store_dwordx4 v[112:113], v[104:107], off
	s_nop 1
	v_lshlrev_b32_e32 v104, 16, v144
	v_mul_f32_e32 v100, v100, v104
	v_and_b32_e32 v104, 0xffff0000, v144
	v_mul_f32_e32 v101, v101, v104
	v_lshlrev_b32_e32 v104, 16, v145
	v_mul_f32_e32 v102, v102, v104
	v_and_b32_e32 v104, 0xffff0000, v145
	v_mul_f32_e32 v103, v103, v104
	v_lshlrev_b32_e32 v104, 16, v146
	v_mul_f32_e32 v104, v92, v104
	v_and_b32_e32 v92, 0xffff0000, v146
	v_mul_f32_e32 v105, v93, v92
	v_lshlrev_b32_e32 v92, 16, v147
	v_mul_f32_e32 v106, v94, v92
	v_and_b32_e32 v92, 0xffff0000, v147
	v_mul_f32_e32 v95, v95, v92
	v_cvt_pk_bf16_f32 v92, v100, v101
	v_cvt_pk_bf16_f32 v93, v102, v103
	v_cvt_pk_bf16_f32 v94, v104, v105
	v_cvt_pk_bf16_f32 v95, v106, v95
	global_store_dwordx4 v[112:113], v[92:95], off offset:256
	v_add_u32_e32 v102, 0xb0, v170
	v_ashrrev_i32_e32 v103, 31, v102
	v_lshlrev_b32_e32 v94, 16, v140
	v_mul_f32_e32 v94, v96, v94
	v_lshlrev_b32_e32 v96, 16, v141
	v_and_b32_e32 v95, 0xffff0000, v140
	v_mul_f32_e32 v96, v98, v96
	v_lshlrev_b32_e32 v98, 16, v142
	v_mul_f32_e32 v95, v97, v95
	v_and_b32_e32 v97, 0xffff0000, v141
	v_mul_f32_e32 v98, v88, v98
	v_and_b32_e32 v88, 0xffff0000, v142
	v_lshlrev_b64 v[92:93], 11, v[176:177]
	v_mul_f32_e32 v97, v99, v97
	v_mul_f32_e32 v99, v89, v88
	v_lshlrev_b32_e32 v88, 16, v143
	v_lshl_add_u64 v[92:93], s[42:43], 0, v[92:93]
	v_mul_f32_e32 v100, v90, v88
	v_and_b32_e32 v88, 0xffff0000, v143
	v_lshl_add_u64 v[92:93], v[92:93], 0, v[168:169]
	v_mul_f32_e32 v91, v91, v88
	v_cvt_pk_bf16_f32 v88, v94, v95
	v_cvt_pk_bf16_f32 v89, v96, v97
	v_cvt_pk_bf16_f32 v90, v98, v99
	v_cvt_pk_bf16_f32 v91, v100, v91
	global_store_dwordx4 v[92:93], v[88:91], off
	v_add_u32_e32 v96, 0x80, v170
	v_ashrrev_i32_e32 v97, 31, v96
	v_lshlrev_b32_e32 v88, 16, v132
	v_mul_f32_e32 v84, v84, v88
	v_and_b32_e32 v88, 0xffff0000, v132
	v_mul_f32_e32 v85, v85, v88
	v_lshlrev_b32_e32 v88, 16, v133
	v_mul_f32_e32 v86, v86, v88
	v_and_b32_e32 v88, 0xffff0000, v133
	v_mul_f32_e32 v87, v87, v88
	v_lshlrev_b32_e32 v88, 16, v134
	v_mul_f32_e32 v88, v76, v88
	v_and_b32_e32 v76, 0xffff0000, v134
	v_mul_f32_e32 v89, v77, v76
	v_lshlrev_b32_e32 v76, 16, v135
	v_mul_f32_e32 v90, v78, v76
	v_and_b32_e32 v76, 0xffff0000, v135
	v_mul_f32_e32 v79, v79, v76
	v_cvt_pk_bf16_f32 v76, v84, v85
	v_cvt_pk_bf16_f32 v77, v86, v87
	v_cvt_pk_bf16_f32 v78, v88, v89
	v_cvt_pk_bf16_f32 v79, v90, v79
	global_store_dwordx4 v[92:93], v[76:79], off offset:256
	v_add_u32_e32 v98, 0x90, v170
	v_ashrrev_i32_e32 v99, 31, v98
	v_lshlrev_b32_e32 v78, 16, v136
	v_mul_f32_e32 v78, v80, v78
	v_lshlrev_b32_e32 v80, 16, v137
	v_and_b32_e32 v79, 0xffff0000, v136
	v_mul_f32_e32 v80, v82, v80
	v_lshlrev_b32_e32 v82, 16, v138
	v_mul_f32_e32 v79, v81, v79
	v_and_b32_e32 v81, 0xffff0000, v137
	v_mul_f32_e32 v82, v72, v82
	v_and_b32_e32 v72, 0xffff0000, v138
	v_lshlrev_b64 v[76:77], 11, v[174:175]
	v_mul_f32_e32 v81, v83, v81
	v_mul_f32_e32 v83, v73, v72
	v_lshlrev_b32_e32 v72, 16, v139
	v_lshl_add_u64 v[76:77], s[42:43], 0, v[76:77]
	v_mul_f32_e32 v84, v74, v72
	v_and_b32_e32 v72, 0xffff0000, v139
	v_lshl_add_u64 v[76:77], v[76:77], 0, v[168:169]
	v_mul_f32_e32 v75, v75, v72
	v_cvt_pk_bf16_f32 v72, v78, v79
	v_cvt_pk_bf16_f32 v73, v80, v81
	v_cvt_pk_bf16_f32 v74, v82, v83
	v_cvt_pk_bf16_f32 v75, v84, v75
	global_store_dwordx4 v[76:77], v[72:75], off
	v_add_u32_e32 v100, 0xa0, v170
	v_ashrrev_i32_e32 v101, 31, v100
	v_lshlrev_b32_e32 v72, 16, v128
	v_mul_f32_e32 v68, v68, v72
	v_and_b32_e32 v72, 0xffff0000, v128
	v_mul_f32_e32 v69, v69, v72
	v_lshlrev_b32_e32 v72, 16, v129
	v_mul_f32_e32 v70, v70, v72
	v_and_b32_e32 v72, 0xffff0000, v129
	v_mul_f32_e32 v71, v71, v72
	v_lshlrev_b32_e32 v72, 16, v130
	v_mul_f32_e32 v72, v64, v72
	v_and_b32_e32 v64, 0xffff0000, v130
	v_mul_f32_e32 v73, v65, v64
	v_lshlrev_b32_e32 v64, 16, v131
	v_mul_f32_e32 v74, v66, v64
	v_and_b32_e32 v64, 0xffff0000, v131
	v_mul_f32_e32 v67, v67, v64
	v_cvt_pk_bf16_f32 v64, v68, v69
	v_cvt_pk_bf16_f32 v65, v70, v71
	v_cvt_pk_bf16_f32 v66, v72, v73
	v_cvt_pk_bf16_f32 v67, v74, v67
	global_store_dwordx4 v[76:77], v[64:67], off offset:256
	v_lshlrev_b64 v[72:73], 12, v[98:99]
	v_lshl_add_u64 v[76:77], v[172:173], 0, v[72:73]
	v_lshlrev_b64 v[64:65], 12, v[96:97]
	v_lshl_add_u64 v[68:69], v[172:173], 0, v[64:65]
	s_waitcnt vmcnt(8)
	v_mov_b32_e32 v64, v196
	v_mov_b32_e32 v65, v197
	v_mov_b32_e32 v66, v198
	v_mov_b32_e32 v67, v199
	s_nop 0
	v_mov_b32_e32 v68, v204
	v_mov_b32_e32 v69, v205
	v_mov_b32_e32 v70, v206
	v_mov_b32_e32 v71, v207
	s_nop 0
	v_mov_b32_e32 v72, v208
	v_mov_b32_e32 v73, v209
	v_mov_b32_e32 v74, v210
	v_mov_b32_e32 v75, v211
	s_nop 0
	v_mov_b32_e32 v76, v212
	v_mov_b32_e32 v77, v213
	v_mov_b32_e32 v78, v214
	v_mov_b32_e32 v79, v215
	v_lshlrev_b64 v[80:81], 12, v[100:101]
	v_lshl_add_u64 v[84:85], v[172:173], 0, v[80:81]
	v_mov_b32_e32 v80, v216
	v_mov_b32_e32 v81, v217
	v_mov_b32_e32 v82, v218
	v_mov_b32_e32 v83, v219
	s_nop 0
	v_mov_b32_e32 v84, v220
	v_mov_b32_e32 v85, v221
	v_mov_b32_e32 v86, v222
	v_mov_b32_e32 v87, v223
	v_lshlrev_b64 v[88:89], 12, v[102:103]
	v_lshl_add_u64 v[92:93], v[172:173], 0, v[88:89]
	v_mov_b32_e32 v88, v224
	v_mov_b32_e32 v89, v225
	v_mov_b32_e32 v90, v226
	v_mov_b32_e32 v91, v227
	s_nop 0
	v_mov_b32_e32 v92, v228
	v_mov_b32_e32 v93, v229
	v_mov_b32_e32 v94, v230
	v_mov_b32_e32 v95, v231
	v_lshlrev_b64 v[96:97], 11, v[96:97]
	v_lshl_add_u64 v[96:97], s[42:43], 0, v[96:97]
	v_lshl_add_u64 v[96:97], v[96:97], 0, v[168:169]
	v_lshlrev_b32_e32 v104, 16, v64
	v_and_b32_e32 v64, 0xffff0000, v64
	v_mul_f32_e32 v61, v61, v64
	v_lshlrev_b32_e32 v64, 16, v65
	v_mul_f32_e32 v62, v62, v64
	v_and_b32_e32 v64, 0xffff0000, v65
	v_mul_f32_e32 v63, v63, v64
	v_lshlrev_b32_e32 v64, 16, v66
	v_mul_f32_e32 v64, v56, v64
	v_and_b32_e32 v56, 0xffff0000, v66
	v_mul_f32_e32 v65, v57, v56
	v_lshlrev_b32_e32 v56, 16, v67
	v_mul_f32_e32 v66, v58, v56
	v_and_b32_e32 v56, 0xffff0000, v67
	v_mul_f32_e32 v60, v60, v104
	v_mul_f32_e32 v59, v59, v56
	v_cvt_pk_bf16_f32 v56, v60, v61
	v_cvt_pk_bf16_f32 v57, v62, v63
	v_cvt_pk_bf16_f32 v58, v64, v65
	v_cvt_pk_bf16_f32 v59, v66, v59
	global_store_dwordx4 v[96:97], v[56:59], off
	s_nop 0
	v_lshlrev_b32_e32 v56, 16, v68
	v_mul_f32_e32 v52, v52, v56
	v_and_b32_e32 v56, 0xffff0000, v68
	v_mul_f32_e32 v53, v53, v56
	v_lshlrev_b32_e32 v56, 16, v69
	v_mul_f32_e32 v54, v54, v56
	v_and_b32_e32 v56, 0xffff0000, v69
	v_mul_f32_e32 v55, v55, v56
	v_lshlrev_b32_e32 v56, 16, v70
	v_mul_f32_e32 v56, v44, v56
	v_and_b32_e32 v44, 0xffff0000, v70
	v_mul_f32_e32 v57, v45, v44
	v_lshlrev_b32_e32 v44, 16, v71
	v_mul_f32_e32 v58, v46, v44
	v_and_b32_e32 v44, 0xffff0000, v71
	v_mul_f32_e32 v47, v47, v44
	v_cvt_pk_bf16_f32 v44, v52, v53
	v_cvt_pk_bf16_f32 v45, v54, v55
	v_cvt_pk_bf16_f32 v46, v56, v57
	v_cvt_pk_bf16_f32 v47, v58, v47
	global_store_dwordx4 v[96:97], v[44:47], off offset:256
	s_nop 0
	v_lshlrev_b32_e32 v46, 16, v72
	v_mul_f32_e32 v46, v48, v46
	v_lshlrev_b32_e32 v48, 16, v73
	v_and_b32_e32 v47, 0xffff0000, v72
	v_mul_f32_e32 v48, v50, v48
	v_lshlrev_b32_e32 v50, 16, v74
	v_mul_f32_e32 v47, v49, v47
	v_and_b32_e32 v49, 0xffff0000, v73
	v_mul_f32_e32 v50, v40, v50
	v_and_b32_e32 v40, 0xffff0000, v74
	v_lshlrev_b64 v[44:45], 11, v[98:99]
	v_mul_f32_e32 v49, v51, v49
	v_mul_f32_e32 v51, v41, v40
	v_lshlrev_b32_e32 v40, 16, v75
	v_lshl_add_u64 v[44:45], s[42:43], 0, v[44:45]
	v_mul_f32_e32 v52, v42, v40
	v_and_b32_e32 v40, 0xffff0000, v75
	v_lshl_add_u64 v[44:45], v[44:45], 0, v[168:169]
	v_mul_f32_e32 v43, v43, v40
	v_cvt_pk_bf16_f32 v40, v46, v47
	v_cvt_pk_bf16_f32 v41, v48, v49
	v_cvt_pk_bf16_f32 v42, v50, v51
	v_cvt_pk_bf16_f32 v43, v52, v43
	global_store_dwordx4 v[44:45], v[40:43], off
	s_nop 0
	v_lshlrev_b32_e32 v40, 16, v76
	v_mul_f32_e32 v36, v36, v40
	v_and_b32_e32 v40, 0xffff0000, v76
	v_mul_f32_e32 v37, v37, v40
	v_lshlrev_b32_e32 v40, 16, v77
	v_mul_f32_e32 v38, v38, v40
	v_and_b32_e32 v40, 0xffff0000, v77
	v_mul_f32_e32 v39, v39, v40
	v_lshlrev_b32_e32 v40, 16, v78
	v_mul_f32_e32 v40, v28, v40
	v_and_b32_e32 v28, 0xffff0000, v78
	v_mul_f32_e32 v41, v29, v28
	v_lshlrev_b32_e32 v28, 16, v79
	v_mul_f32_e32 v42, v30, v28
	v_and_b32_e32 v28, 0xffff0000, v79
	v_mul_f32_e32 v31, v31, v28
	v_cvt_pk_bf16_f32 v28, v36, v37
	v_cvt_pk_bf16_f32 v29, v38, v39
	v_cvt_pk_bf16_f32 v30, v40, v41
	v_cvt_pk_bf16_f32 v31, v42, v31
	global_store_dwordx4 v[44:45], v[28:31], off offset:256
	s_nop 0
	v_lshlrev_b32_e32 v30, 16, v80
	v_mul_f32_e32 v30, v32, v30
	v_lshlrev_b32_e32 v32, 16, v81
	v_and_b32_e32 v31, 0xffff0000, v80
	v_mul_f32_e32 v32, v34, v32
	v_lshlrev_b32_e32 v34, 16, v82
	v_mul_f32_e32 v31, v33, v31
	v_and_b32_e32 v33, 0xffff0000, v81
	v_mul_f32_e32 v34, v24, v34
	v_and_b32_e32 v24, 0xffff0000, v82
	v_lshlrev_b64 v[28:29], 11, v[100:101]
	v_mul_f32_e32 v33, v35, v33
	v_mul_f32_e32 v35, v25, v24
	v_lshlrev_b32_e32 v24, 16, v83
	v_lshl_add_u64 v[28:29], s[42:43], 0, v[28:29]
	v_mul_f32_e32 v36, v26, v24
	v_and_b32_e32 v24, 0xffff0000, v83
	v_lshl_add_u64 v[28:29], v[28:29], 0, v[168:169]
	v_mul_f32_e32 v27, v27, v24
	v_cvt_pk_bf16_f32 v24, v30, v31
	v_cvt_pk_bf16_f32 v25, v32, v33
	v_cvt_pk_bf16_f32 v26, v34, v35
	v_cvt_pk_bf16_f32 v27, v36, v27
	global_store_dwordx4 v[28:29], v[24:27], off
	s_nop 0
	v_lshlrev_b32_e32 v24, 16, v84
	v_mul_f32_e32 v20, v20, v24
	v_and_b32_e32 v24, 0xffff0000, v84
	v_mul_f32_e32 v21, v21, v24
	v_lshlrev_b32_e32 v24, 16, v85
	v_mul_f32_e32 v22, v22, v24
	v_and_b32_e32 v24, 0xffff0000, v85
	v_mul_f32_e32 v23, v23, v24
	v_lshlrev_b32_e32 v24, 16, v86
	v_mul_f32_e32 v24, v12, v24
	v_and_b32_e32 v12, 0xffff0000, v86
	v_mul_f32_e32 v25, v13, v12
	v_lshlrev_b32_e32 v12, 16, v87
	v_mul_f32_e32 v26, v14, v12
	v_and_b32_e32 v12, 0xffff0000, v87
	v_mul_f32_e32 v15, v15, v12
	v_cvt_pk_bf16_f32 v12, v20, v21
	v_cvt_pk_bf16_f32 v13, v22, v23
	v_cvt_pk_bf16_f32 v14, v24, v25
	v_cvt_pk_bf16_f32 v15, v26, v15
	global_store_dwordx4 v[28:29], v[12:15], off offset:256
	s_nop 0
	v_lshlrev_b32_e32 v14, 16, v88
	v_mul_f32_e32 v14, v16, v14
	v_lshlrev_b32_e32 v16, 16, v89
	v_and_b32_e32 v15, 0xffff0000, v88
	v_mul_f32_e32 v16, v18, v16
	v_lshlrev_b32_e32 v18, 16, v90
	v_mul_f32_e32 v15, v17, v15
	v_and_b32_e32 v17, 0xffff0000, v89
	v_mul_f32_e32 v18, v8, v18
	v_and_b32_e32 v8, 0xffff0000, v90
	v_lshlrev_b64 v[12:13], 11, v[102:103]
	v_mul_f32_e32 v17, v19, v17
	v_mul_f32_e32 v19, v9, v8
	v_lshlrev_b32_e32 v8, 16, v91
	v_lshl_add_u64 v[12:13], s[42:43], 0, v[12:13]
	v_mul_f32_e32 v20, v10, v8
	v_and_b32_e32 v8, 0xffff0000, v91
	v_lshl_add_u64 v[12:13], v[12:13], 0, v[168:169]
	v_mul_f32_e32 v11, v11, v8
	v_cvt_pk_bf16_f32 v8, v14, v15
	v_cvt_pk_bf16_f32 v9, v16, v17
	v_cvt_pk_bf16_f32 v10, v18, v19
	v_cvt_pk_bf16_f32 v11, v20, v11
	global_store_dwordx4 v[12:13], v[8:11], off
	s_nop 0
	v_lshlrev_b32_e32 v8, 16, v92
	v_mul_f32_e32 v4, v4, v8
	v_and_b32_e32 v8, 0xffff0000, v92
	v_mul_f32_e32 v5, v5, v8
	v_lshlrev_b32_e32 v8, 16, v93
	v_mul_f32_e32 v6, v6, v8
	v_and_b32_e32 v8, 0xffff0000, v93
	v_mul_f32_e32 v7, v7, v8
	v_lshlrev_b32_e32 v8, 16, v94
	v_mul_f32_e32 v8, v0, v8
	v_and_b32_e32 v0, 0xffff0000, v94
	v_mul_f32_e32 v9, v1, v0
	v_lshlrev_b32_e32 v0, 16, v95
	v_mul_f32_e32 v10, v2, v0
	v_and_b32_e32 v0, 0xffff0000, v95
	v_mul_f32_e32 v3, v3, v0
	v_cvt_pk_bf16_f32 v0, v4, v5
	v_cvt_pk_bf16_f32 v1, v6, v7
	v_cvt_pk_bf16_f32 v2, v8, v9
	v_cvt_pk_bf16_f32 v3, v10, v3
	global_store_dwordx4 v[12:13], v[0:3], off offset:256
	s_mov_b32 s99, 1
	s_cbranch_vccnz .LBB0_1405
	s_andn2_b64 vcc, exec, s[0:1]
	s_cbranch_vccnz .LBB0_1404
	s_barrier
	s_branch .LBB0_1404

.LBB0_1427:
	v_bfe_u32 v213, v8, 4, 2
	v_and_b32_e32 v212, 15, v8
	v_lshlrev_b32_e32 v9, 4, v213
	v_lshlrev_b32_e32 v8, 2, v8
	s_sext_i32_i8 s47, s4
	v_lshl_or_b32 v9, v212, 6, v9
	s_lshl_b32 s4, s5, 13
	v_and_b32_e32 v8, 32, v8
	v_bitop3_b32 v10, v9, s4, v8 bitop3:0xde
	s_lshl_b32 s4, s7, 5
	s_and_b32 s70, s4, 0x60
	s_lshl_b32 s4, s70, 7
	s_lshl_b32 s69, s5, 6
	v_bitop3_b32 v214, v9, s4, v8 bitop3:0xde
	s_mov_b64 s[4:5], 0x80
	s_add_i32 m0, s65, 0x18000
	v_lshl_add_u64 v[6:7], v[6:7], 0, s[4:5]
	s_waitcnt vmcnt(2)
	s_barrier
	global_load_lds_dwordx4 v[6:7], off
	v_lshl_add_u64 v[4:5], v[4:5], 0, s[4:5]
	s_add_i32 m0, s65, 0x1a000
	s_add_i32 s71, s65, 0x8000
	s_add_i32 s72, s65, 0xa000
	global_load_lds_dwordx4 v[4:5], off
	v_lshl_add_u64 v[0:1], v[0:1], 0, s[4:5]
	s_mov_b32 m0, s71
	s_add_u32 s8, s82, 0x10080
	global_load_lds_dwordx4 v[0:1], off
	v_lshl_add_u64 v[0:1], v[2:3], 0, s[4:5]
	s_mov_b32 m0, s72
	s_addc_u32 s9, s83, 0
	global_load_lds_dwordx4 v[0:1], off
	s_add_i32 m0, s65, 0x1c000
	v_lshl_add_u64 v[0:1], s[8:9], 0, v[186:187]
	global_load_lds_dwordx4 v[0:1], off
	v_lshl_add_u64 v[0:1], s[8:9], 0, v[190:191]
	s_add_i32 m0, s65, 0x1e000
	s_cmpk_lt_u32 s6, 0x100
	global_load_lds_dwordx4 v[0:1], off
	s_cselect_b64 s[6:7], -1, 0
	s_add_u32 s10, s38, s2
	s_waitcnt vmcnt(6)
	s_addc_u32 s11, s33, s3
	s_add_i32 s79, 0, 0x10000
	s_add_i32 s81, 0, 0x14000
	v_add_u32_e32 v215, s79, v214
	v_add_u32_e32 v216, s81, v214
	s_add_i32 s79, s79, s64
	s_add_i32 s81, s81, s64
	v_mov_b64_e32 v[192:193], 0x200
	v_mov_b64_e32 v[194:195], 0x1ff
	v_add_u32_e32 v217, 0, v10
	s_add_i32 s73, s65, 0xc000
	s_add_i32 s78, s65, 0xe000
	s_mov_b64 s[12:13], 0x100
	s_mov_b64 s[14:15], 0x180
	s_add_i32 s80, s79, 0x2000
	s_add_i32 s84, s81, 0x2000
	s_barrier
	s_mov_b32 s99, 0
	s_branch .LBB0_1430

.Lrlx13p1b:
	s_waitcnt vmcnt(24)
	s_branch .Lrlx13p1b_done
.LBB0_1428:
	s_add_u32 s10, s10, s38
	s_addc_u32 s11, s11, s33
	s_mov_b64 s[46:47], 0

.LBB0_1436:
	ds_read_b128 v[0:3], v215
	ds_read_b128 v[4:7], v215 offset:1024
	ds_read_b128 v[8:11], v215 offset:2048
	ds_read_b128 v[12:15], v215 offset:3072
	ds_read_b128 v[16:19], v216
	ds_read_b128 v[20:23], v216 offset:1024
	ds_read_b128 v[24:27], v216 offset:2048
	ds_read_b128 v[28:31], v216 offset:3072
	s_ashr_i32 s37, s36, 31
	s_lshl_b64 s[40:41], s[36:37], 17
	v_readlane_b32 s60, v255, 24
	v_readlane_b32 s61, v255, 25
	s_add_u32 s40, s60, s40
	s_addc_u32 s41, s61, s41
	s_and_b64 s[60:61], s[8:9], exec
	s_cselect_b32 s93, s41, s75
	s_cselect_b32 s92, s40, s74
	s_ashr_i32 s35, s34, 31
	s_lshl_b64 s[60:61], s[34:35], 17
	v_readlane_b32 s86, v255, 30
	v_readlane_b32 s87, v255, 31
	s_add_u32 s60, s86, s60
	s_addc_u32 s61, s87, s61
	s_and_b64 s[86:87], s[8:9], exec
	s_cselect_b32 s89, s61, s83
	s_cselect_b32 s88, s60, s82
	s_add_u32 s86, s74, 0x10080
	s_addc_u32 s87, s75, 0
	s_mov_b32 m0, s73
	v_lshl_add_u64 v[64:65], s[86:87], 0, v[184:185]
	ds_read_b128 v[32:35], v217
	ds_read_b128 v[36:39], v217 offset:1024
	ds_read_b128 v[40:43], v217 offset:2048
	ds_read_b128 v[44:47], v217 offset:3072
	ds_read_b128 v[48:51], v217 offset:4096
	ds_read_b128 v[52:55], v217 offset:5120
	ds_read_b128 v[56:59], v217 offset:6144
	ds_read_b128 v[60:63], v217 offset:7168
	global_load_lds_dwordx4 v[64:65], off
	v_lshl_add_u64 v[64:65], s[86:87], 0, v[188:189]
	s_mov_b32 m0, s78
	s_nop 0
	global_load_lds_dwordx4 v[64:65], off
	s_cmp_lg_u32 s99, 0
	s_cbranch_scc1 .Lrlx13p1a
	s_waitcnt vmcnt(8)
.Lrlx13p1a_done:
	s_waitcnt lgkmcnt(0)
	s_barrier
	s_setprio 1
	s_waitcnt lgkmcnt(0)
	v_mfma_f32_16x16x32_bf16 v[64:67], v[0:3], v[32:35], 0
	v_mfma_f32_16x16x32_bf16 v[68:71], v[8:11], v[32:35], 0
	v_mfma_f32_16x16x32_bf16 v[72:75], v[0:3], v[40:43], 0
	v_mfma_f32_16x16x32_bf16 v[76:79], v[8:11], v[40:43], 0
	v_mfma_f32_16x16x32_bf16 v[80:83], v[0:3], v[48:51], 0
	v_mfma_f32_16x16x32_bf16 v[84:87], v[8:11], v[48:51], 0
	v_mfma_f32_16x16x32_bf16 v[88:91], v[0:3], v[56:59], 0
	v_mfma_f32_16x16x32_bf16 v[92:95], v[8:11], v[56:59], 0
	v_mfma_f32_16x16x32_bf16 v[64:67], v[4:7], v[36:39], v[64:67]
	v_mfma_f32_16x16x32_bf16 v[68:71], v[12:15], v[36:39], v[68:71]
	v_mfma_f32_16x16x32_bf16 v[72:75], v[4:7], v[44:47], v[72:75]
	v_mfma_f32_16x16x32_bf16 v[76:79], v[12:15], v[44:47], v[76:79]
	v_mfma_f32_16x16x32_bf16 v[80:83], v[4:7], v[52:55], v[80:83]
	v_mfma_f32_16x16x32_bf16 v[84:87], v[12:15], v[52:55], v[84:87]
	v_mfma_f32_16x16x32_bf16 v[88:91], v[4:7], v[60:63], v[88:91]
	v_mfma_f32_16x16x32_bf16 v[92:95], v[12:15], v[60:63], v[92:95]
	s_setprio 0
	s_setprio 1
	v_mfma_f32_16x16x32_bf16 v[96:99], v[16:19], v[32:35], 0
	v_mfma_f32_16x16x32_bf16 v[32:35], v[24:27], v[32:35], 0
	v_mfma_f32_16x16x32_bf16 v[96:99], v[20:23], v[36:39], v[96:99]
	v_mfma_f32_16x16x32_bf16 v[32:35], v[28:31], v[36:39], v[32:35]
	v_mfma_f32_16x16x32_bf16 v[36:39], v[16:19], v[40:43], 0
	v_mfma_f32_16x16x32_bf16 v[40:43], v[24:27], v[40:43], 0
	v_mfma_f32_16x16x32_bf16 v[36:39], v[20:23], v[44:47], v[36:39]
	v_mfma_f32_16x16x32_bf16 v[40:43], v[28:31], v[44:47], v[40:43]
	v_mfma_f32_16x16x32_bf16 v[44:47], v[16:19], v[48:51], 0
	v_mfma_f32_16x16x32_bf16 v[48:51], v[24:27], v[48:51], 0
	v_mfma_f32_16x16x32_bf16 v[44:47], v[20:23], v[52:55], v[44:47]
	v_mfma_f32_16x16x32_bf16 v[48:51], v[28:31], v[52:55], v[48:51]
	v_mfma_f32_16x16x32_bf16 v[52:55], v[16:19], v[56:59], 0
	v_mfma_f32_16x16x32_bf16 v[56:59], v[24:27], v[56:59], 0
	v_mfma_f32_16x16x32_bf16 v[52:55], v[20:23], v[60:63], v[52:55]
	v_mfma_f32_16x16x32_bf16 v[56:59], v[28:31], v[60:63], v[56:59]
	s_setprio 0
	s_barrier
	v_lshl_add_u64 v[204:205], s[82:83], 0, v[186:187]
	s_mov_b32 m0, s79
	v_lshl_add_u64 v[128:129], v[204:205], 0, s[12:13]
	v_lshl_add_u64 v[206:207], s[82:83], 0, v[190:191]
	s_add_u32 s86, s82, 0x10100
	ds_read_b128 v[60:63], v217 offset:16384
	ds_read_b128 v[100:103], v217 offset:17408
	ds_read_b128 v[104:107], v217 offset:18432
	ds_read_b128 v[108:111], v217 offset:19456
	ds_read_b128 v[112:115], v217 offset:20480
	ds_read_b128 v[116:119], v217 offset:21504
	ds_read_b128 v[120:123], v217 offset:22528
	ds_read_b128 v[124:127], v217 offset:23552
	global_load_lds_dwordx4 v[128:129], off
	v_lshl_add_u64 v[128:129], v[206:207], 0, s[12:13]
	s_mov_b32 m0, s80
	s_addc_u32 s87, s83, 0
	global_load_lds_dwordx4 v[128:129], off
	v_lshl_add_u64 v[128:129], s[86:87], 0, v[186:187]
	s_mov_b32 m0, s81
	v_lshl_add_u64 v[208:209], s[74:75], 0, v[184:185]
	global_load_lds_dwordx4 v[128:129], off
	v_lshl_add_u64 v[128:129], s[86:87], 0, v[190:191]
	s_mov_b32 m0, s84
	v_lshl_add_u64 v[210:211], s[74:75], 0, v[188:189]
	global_load_lds_dwordx4 v[128:129], off
	v_lshl_add_u64 v[128:129], v[208:209], 0, s[12:13]
	s_mov_b32 m0, s65
	s_nop 0
	global_load_lds_dwordx4 v[128:129], off
	v_lshl_add_u64 v[128:129], v[210:211], 0, s[12:13]
	s_mov_b32 m0, s66
	s_nop 0
	global_load_lds_dwordx4 v[128:129], off
	s_cmp_lg_u32 s99, 0
	s_cbranch_scc1 .Lrlx13p1b
	s_waitcnt vmcnt(8)
.Lrlx13p1b_done:
	s_mov_b32 s99, 0
	s_waitcnt lgkmcnt(0)
	s_barrier
	s_setprio 1
	s_waitcnt lgkmcnt(0)
	v_mfma_f32_16x16x32_bf16 v[128:131], v[0:3], v[60:63], 0
	v_mfma_f32_16x16x32_bf16 v[136:139], v[0:3], v[104:107], 0
	v_mfma_f32_16x16x32_bf16 v[144:147], v[0:3], v[112:115], 0
	v_mfma_f32_16x16x32_bf16 v[0:3], v[0:3], v[120:123], 0
	v_mfma_f32_16x16x32_bf16 v[128:131], v[4:7], v[100:103], v[128:131]
	v_mfma_f32_16x16x32_bf16 v[136:139], v[4:7], v[108:111], v[136:139]
	v_mfma_f32_16x16x32_bf16 v[144:147], v[4:7], v[116:119], v[144:147]
	v_mfma_f32_16x16x32_bf16 v[0:3], v[4:7], v[124:127], v[0:3]
	v_mfma_f32_16x16x32_bf16 v[4:7], v[8:11], v[120:123], 0
	v_mfma_f32_16x16x32_bf16 v[132:135], v[8:11], v[60:63], 0
	v_mfma_f32_16x16x32_bf16 v[140:143], v[8:11], v[104:107], 0
	v_mfma_f32_16x16x32_bf16 v[148:151], v[8:11], v[112:115], 0
	v_mfma_f32_16x16x32_bf16 v[4:7], v[12:15], v[124:127], v[4:7]
	v_mfma_f32_16x16x32_bf16 v[132:135], v[12:15], v[100:103], v[132:135]
	v_mfma_f32_16x16x32_bf16 v[140:143], v[12:15], v[108:111], v[140:143]
	v_mfma_f32_16x16x32_bf16 v[148:151], v[12:15], v[116:119], v[148:151]
	s_setprio 0
	s_setprio 1
	v_mfma_f32_16x16x32_bf16 v[8:11], v[16:19], v[60:63], 0
	v_mfma_f32_16x16x32_bf16 v[12:15], v[24:27], v[60:63], 0
	v_mfma_f32_16x16x32_bf16 v[8:11], v[20:23], v[100:103], v[8:11]
	v_mfma_f32_16x16x32_bf16 v[12:15], v[28:31], v[100:103], v[12:15]
	v_mfma_f32_16x16x32_bf16 v[60:63], v[16:19], v[104:107], 0
	v_mfma_f32_16x16x32_bf16 v[100:103], v[24:27], v[104:107], 0
	v_mfma_f32_16x16x32_bf16 v[104:107], v[16:19], v[112:115], 0
	v_mfma_f32_16x16x32_bf16 v[16:19], v[16:19], v[120:123], 0
	v_mfma_f32_16x16x32_bf16 v[60:63], v[20:23], v[108:111], v[60:63]
	v_mfma_f32_16x16x32_bf16 v[100:103], v[28:31], v[108:111], v[100:103]
	v_mfma_f32_16x16x32_bf16 v[104:107], v[20:23], v[116:119], v[104:107]
	v_mfma_f32_16x16x32_bf16 v[108:111], v[24:27], v[112:115], 0
	v_mfma_f32_16x16x32_bf16 v[16:19], v[20:23], v[124:127], v[16:19]
	v_mfma_f32_16x16x32_bf16 v[20:23], v[24:27], v[120:123], 0
	v_mfma_f32_16x16x32_bf16 v[108:111], v[28:31], v[116:119], v[108:111]
	v_mfma_f32_16x16x32_bf16 v[20:23], v[28:31], v[124:127], v[20:23]
	s_setprio 0
	s_barrier
	s_add_i32 s85, 0, 0x18000
	s_add_i32 s37, 0, 0x1c000
	v_add_u32_e32 v226, s85, v214
	v_add_u32_e32 v227, s37, v214
	ds_read_b128 v[24:27], v226
	ds_read_b128 v[28:31], v226 offset:1024
	ds_read_b128 v[112:115], v226 offset:2048
	ds_read_b128 v[116:119], v226 offset:3072
	ds_read_b128 v[120:123], v227
	ds_read_b128 v[124:127], v227 offset:1024
	ds_read_b128 v[152:155], v227 offset:2048
	ds_read_b128 v[156:159], v227 offset:3072
	s_add_u32 s86, s74, 0x10100
	s_addc_u32 s87, s75, 0
	s_mov_b32 m0, s67
	v_lshl_add_u64 v[218:219], s[86:87], 0, v[184:185]
	ds_read_b128 v[160:163], v217 offset:32768
	ds_read_b128 v[164:167], v217 offset:33792
	ds_read_b128 v[168:171], v217 offset:34816
	ds_read_b128 v[172:175], v217 offset:35840
	ds_read_b128 v[176:179], v217 offset:36864
	ds_read_b128 v[180:183], v217 offset:37888
	ds_read_b128 v[196:199], v217 offset:38912
	ds_read_b128 v[200:203], v217 offset:39936
	global_load_lds_dwordx4 v[218:219], off
	v_lshl_add_u64 v[218:219], s[86:87], 0, v[188:189]
	s_mov_b32 m0, s68
	s_nop 0
	global_load_lds_dwordx4 v[218:219], off
	s_waitcnt vmcnt(8)
	s_waitcnt lgkmcnt(0)
	s_barrier
	s_setprio 1
	s_waitcnt lgkmcnt(0)
	v_mfma_f32_16x16x32_bf16 v[64:67], v[24:27], v[160:163], v[64:67]
	v_mfma_f32_16x16x32_bf16 v[68:71], v[112:115], v[160:163], v[68:71]
	v_mfma_f32_16x16x32_bf16 v[72:75], v[24:27], v[168:171], v[72:75]
	v_mfma_f32_16x16x32_bf16 v[76:79], v[112:115], v[168:171], v[76:79]
	v_mfma_f32_16x16x32_bf16 v[80:83], v[24:27], v[176:179], v[80:83]
	v_mfma_f32_16x16x32_bf16 v[84:87], v[112:115], v[176:179], v[84:87]
	v_mfma_f32_16x16x32_bf16 v[88:91], v[24:27], v[196:199], v[88:91]
	v_mfma_f32_16x16x32_bf16 v[92:95], v[112:115], v[196:199], v[92:95]
	v_mfma_f32_16x16x32_bf16 v[64:67], v[28:31], v[164:167], v[64:67]
	v_mfma_f32_16x16x32_bf16 v[68:71], v[116:119], v[164:167], v[68:71]
	v_mfma_f32_16x16x32_bf16 v[72:75], v[28:31], v[172:175], v[72:75]
	v_mfma_f32_16x16x32_bf16 v[76:79], v[116:119], v[172:175], v[76:79]
	v_mfma_f32_16x16x32_bf16 v[80:83], v[28:31], v[180:183], v[80:83]
	v_mfma_f32_16x16x32_bf16 v[84:87], v[116:119], v[180:183], v[84:87]
	v_mfma_f32_16x16x32_bf16 v[88:91], v[28:31], v[200:203], v[88:91]
	v_mfma_f32_16x16x32_bf16 v[92:95], v[116:119], v[200:203], v[92:95]
	s_setprio 0
	s_setprio 1
	v_mfma_f32_16x16x32_bf16 v[96:99], v[120:123], v[160:163], v[96:99]
	v_mfma_f32_16x16x32_bf16 v[32:35], v[152:155], v[160:163], v[32:35]
	v_mfma_f32_16x16x32_bf16 v[36:39], v[120:123], v[168:171], v[36:39]
	v_mfma_f32_16x16x32_bf16 v[40:43], v[152:155], v[168:171], v[40:43]
	v_mfma_f32_16x16x32_bf16 v[44:47], v[120:123], v[176:179], v[44:47]
	v_mfma_f32_16x16x32_bf16 v[48:51], v[152:155], v[176:179], v[48:51]
	v_mfma_f32_16x16x32_bf16 v[52:55], v[120:123], v[196:199], v[52:55]
	v_mfma_f32_16x16x32_bf16 v[56:59], v[152:155], v[196:199], v[56:59]
	v_mfma_f32_16x16x32_bf16 v[96:99], v[124:127], v[164:167], v[96:99]
	v_mfma_f32_16x16x32_bf16 v[32:35], v[156:159], v[164:167], v[32:35]
	v_mfma_f32_16x16x32_bf16 v[36:39], v[124:127], v[172:175], v[36:39]
	v_mfma_f32_16x16x32_bf16 v[40:43], v[156:159], v[172:175], v[40:43]
	v_mfma_f32_16x16x32_bf16 v[44:47], v[124:127], v[180:183], v[44:47]
	v_mfma_f32_16x16x32_bf16 v[48:51], v[156:159], v[180:183], v[48:51]
	v_mfma_f32_16x16x32_bf16 v[52:55], v[124:127], v[200:203], v[52:55]
	v_mfma_f32_16x16x32_bf16 v[56:59], v[156:159], v[200:203], v[56:59]
	s_setprio 0
	s_barrier
	s_add_i32 s85, s85, s64
	s_add_i32 s35, s85, 0x2000
	v_lshl_add_u64 v[204:205], v[204:205], 0, s[14:15]
	s_mov_b32 m0, s85
	s_add_u32 s82, s82, 0x10180
	ds_read_b128 v[160:163], v217 offset:49152
	ds_read_b128 v[164:167], v217 offset:50176
	ds_read_b128 v[168:171], v217 offset:51200
	ds_read_b128 v[172:175], v217 offset:52224
	ds_read_b128 v[176:179], v217 offset:53248
	ds_read_b128 v[180:183], v217 offset:54272
	ds_read_b128 v[196:199], v217 offset:55296
	ds_read_b128 v[200:203], v217 offset:56320
	global_load_lds_dwordx4 v[204:205], off
	v_lshl_add_u64 v[204:205], v[206:207], 0, s[14:15]
	s_mov_b32 m0, s35
	s_addc_u32 s83, s83, 0
	s_add_i32 s37, s37, s64
	global_load_lds_dwordx4 v[204:205], off
	v_lshl_add_u64 v[204:205], s[82:83], 0, v[186:187]
	s_mov_b32 m0, s37
	s_nop 0
	global_load_lds_dwordx4 v[204:205], off
	v_lshl_add_u64 v[204:205], s[82:83], 0, v[190:191]
	s_add_i32 s82, s37, 0x2000
	s_mov_b32 m0, s82
	s_nop 0
	global_load_lds_dwordx4 v[204:205], off
	v_lshl_add_u64 v[204:205], v[208:209], 0, s[14:15]
	s_mov_b32 m0, s71
	s_nop 0
	global_load_lds_dwordx4 v[204:205], off
	v_lshl_add_u64 v[204:205], v[210:211], 0, s[14:15]
	s_mov_b32 m0, s72
	s_nop 0
	global_load_lds_dwordx4 v[204:205], off
	s_waitcnt vmcnt(8)
	s_waitcnt lgkmcnt(0)
	s_barrier
	s_setprio 1
	s_waitcnt lgkmcnt(0)
	v_mfma_f32_16x16x32_bf16 v[0:3], v[24:27], v[196:199], v[0:3]
	v_mfma_f32_16x16x32_bf16 v[4:7], v[112:115], v[196:199], v[4:7]
	v_mfma_f32_16x16x32_bf16 v[128:131], v[24:27], v[160:163], v[128:131]
	v_mfma_f32_16x16x32_bf16 v[132:135], v[112:115], v[160:163], v[132:135]
	v_mfma_f32_16x16x32_bf16 v[136:139], v[24:27], v[168:171], v[136:139]
	v_mfma_f32_16x16x32_bf16 v[140:143], v[112:115], v[168:171], v[140:143]
	v_mfma_f32_16x16x32_bf16 v[144:147], v[24:27], v[176:179], v[144:147]
	v_mfma_f32_16x16x32_bf16 v[148:151], v[112:115], v[176:179], v[148:151]
	v_mfma_f32_16x16x32_bf16 v[0:3], v[28:31], v[200:203], v[0:3]
	v_mfma_f32_16x16x32_bf16 v[4:7], v[116:119], v[200:203], v[4:7]
	v_mfma_f32_16x16x32_bf16 v[128:131], v[28:31], v[164:167], v[128:131]
	v_mfma_f32_16x16x32_bf16 v[132:135], v[116:119], v[164:167], v[132:135]
	v_mfma_f32_16x16x32_bf16 v[136:139], v[28:31], v[172:175], v[136:139]
	v_mfma_f32_16x16x32_bf16 v[140:143], v[116:119], v[172:175], v[140:143]
	v_mfma_f32_16x16x32_bf16 v[144:147], v[28:31], v[180:183], v[144:147]
	v_mfma_f32_16x16x32_bf16 v[148:151], v[116:119], v[180:183], v[148:151]
	s_setprio 0
	s_setprio 1
	v_mfma_f32_16x16x32_bf16 v[8:11], v[120:123], v[160:163], v[8:11]
	v_mfma_f32_16x16x32_bf16 v[12:15], v[152:155], v[160:163], v[12:15]
	v_mfma_f32_16x16x32_bf16 v[24:27], v[120:123], v[168:171], v[60:63]
	v_mfma_f32_16x16x32_bf16 v[28:31], v[152:155], v[168:171], v[100:103]
	v_mfma_f32_16x16x32_bf16 v[60:63], v[120:123], v[176:179], v[104:107]
	v_mfma_f32_16x16x32_bf16 v[100:103], v[152:155], v[176:179], v[108:111]
	v_mfma_f32_16x16x32_bf16 v[16:19], v[120:123], v[196:199], v[16:19]
	v_mfma_f32_16x16x32_bf16 v[20:23], v[152:155], v[196:199], v[20:23]
	v_mfma_f32_16x16x32_bf16 v[8:11], v[124:127], v[164:167], v[8:11]
	v_mfma_f32_16x16x32_bf16 v[12:15], v[156:159], v[164:167], v[12:15]
	v_mfma_f32_16x16x32_bf16 v[24:27], v[124:127], v[172:175], v[24:27]
	v_mfma_f32_16x16x32_bf16 v[28:31], v[156:159], v[172:175], v[28:31]
	v_mfma_f32_16x16x32_bf16 v[60:63], v[124:127], v[180:183], v[60:63]
	v_mfma_f32_16x16x32_bf16 v[100:103], v[156:159], v[180:183], v[100:103]
	v_mfma_f32_16x16x32_bf16 v[16:19], v[124:127], v[200:203], v[16:19]
	v_mfma_f32_16x16x32_bf16 v[20:23], v[156:159], v[200:203], v[20:23]
	s_setprio 0
	s_barrier
	ds_read_b128 v[104:107], v215
	ds_read_b128 v[108:111], v215 offset:1024
	ds_read_b128 v[112:115], v215 offset:2048
	ds_read_b128 v[116:119], v215 offset:3072
	ds_read_b128 v[120:123], v216
	ds_read_b128 v[124:127], v216 offset:1024
	ds_read_b128 v[152:155], v216 offset:2048
	ds_read_b128 v[156:159], v216 offset:3072
	s_add_u32 s74, s74, 0x10180
	s_addc_u32 s75, s75, 0
	s_mov_b32 m0, s73
	v_lshl_add_u64 v[204:205], s[74:75], 0, v[184:185]
	ds_read_b128 v[160:163], v217
	ds_read_b128 v[164:167], v217 offset:1024
	ds_read_b128 v[168:171], v217 offset:2048
	ds_read_b128 v[172:175], v217 offset:3072
	ds_read_b128 v[176:179], v217 offset:4096
	ds_read_b128 v[180:183], v217 offset:5120
	ds_read_b128 v[196:199], v217 offset:6144
	ds_read_b128 v[200:203], v217 offset:7168
	global_load_lds_dwordx4 v[204:205], off
	v_lshl_add_u64 v[204:205], s[74:75], 0, v[188:189]
	s_mov_b32 m0, s78
	s_nop 0
	global_load_lds_dwordx4 v[204:205], off
	s_waitcnt vmcnt(8)
	s_waitcnt lgkmcnt(0)
	s_barrier
	s_setprio 1
	s_waitcnt lgkmcnt(0)
	v_mfma_f32_16x16x32_bf16 v[64:67], v[104:107], v[160:163], v[64:67]
	v_mfma_f32_16x16x32_bf16 v[68:71], v[112:115], v[160:163], v[68:71]
	v_mfma_f32_16x16x32_bf16 v[72:75], v[104:107], v[168:171], v[72:75]
	v_mfma_f32_16x16x32_bf16 v[76:79], v[112:115], v[168:171], v[76:79]
	v_mfma_f32_16x16x32_bf16 v[80:83], v[104:107], v[176:179], v[80:83]
	v_mfma_f32_16x16x32_bf16 v[84:87], v[112:115], v[176:179], v[84:87]
	v_mfma_f32_16x16x32_bf16 v[88:91], v[104:107], v[196:199], v[88:91]
	v_mfma_f32_16x16x32_bf16 v[64:67], v[108:111], v[164:167], v[64:67]
	v_mfma_f32_16x16x32_bf16 v[68:71], v[116:119], v[164:167], v[68:71]
	v_mfma_f32_16x16x32_bf16 v[72:75], v[108:111], v[172:175], v[72:75]
	v_mfma_f32_16x16x32_bf16 v[76:79], v[116:119], v[172:175], v[76:79]
	v_mfma_f32_16x16x32_bf16 v[80:83], v[108:111], v[180:183], v[80:83]
	v_mfma_f32_16x16x32_bf16 v[84:87], v[116:119], v[180:183], v[84:87]
	v_mfma_f32_16x16x32_bf16 v[204:207], v[108:111], v[200:203], v[88:91]
	v_mfma_f32_16x16x32_bf16 v[88:91], v[112:115], v[196:199], v[92:95]
	v_mfma_f32_16x16x32_bf16 v[218:221], v[116:119], v[200:203], v[88:91]
	s_setprio 0
	s_setprio 1
	v_mfma_f32_16x16x32_bf16 v[88:91], v[120:123], v[160:163], v[96:99]
	v_mfma_f32_16x16x32_bf16 v[32:35], v[152:155], v[160:163], v[32:35]
	v_mfma_f32_16x16x32_bf16 v[36:39], v[120:123], v[168:171], v[36:39]
	v_mfma_f32_16x16x32_bf16 v[40:43], v[152:155], v[168:171], v[40:43]
	v_mfma_f32_16x16x32_bf16 v[44:47], v[120:123], v[176:179], v[44:47]
	v_mfma_f32_16x16x32_bf16 v[48:51], v[152:155], v[176:179], v[48:51]
	v_mfma_f32_16x16x32_bf16 v[52:55], v[120:123], v[196:199], v[52:55]
	v_mfma_f32_16x16x32_bf16 v[56:59], v[152:155], v[196:199], v[56:59]
	v_mfma_f32_16x16x32_bf16 v[96:99], v[124:127], v[164:167], v[88:91]
	v_mfma_f32_16x16x32_bf16 v[32:35], v[156:159], v[164:167], v[32:35]
	v_mfma_f32_16x16x32_bf16 v[36:39], v[124:127], v[172:175], v[36:39]
	v_mfma_f32_16x16x32_bf16 v[40:43], v[156:159], v[172:175], v[40:43]
	v_mfma_f32_16x16x32_bf16 v[44:47], v[124:127], v[180:183], v[44:47]
	v_mfma_f32_16x16x32_bf16 v[48:51], v[156:159], v[180:183], v[48:51]
	v_mfma_f32_16x16x32_bf16 v[52:55], v[124:127], v[200:203], v[52:55]
	v_mfma_f32_16x16x32_bf16 v[56:59], v[156:159], v[200:203], v[56:59]
	s_setprio 0
	s_barrier
	s_mov_b32 m0, s79
	v_lshl_add_u64 v[208:209], s[88:89], 0, v[186:187]
	s_add_u32 s74, s88, 0x10000
	ds_read_b128 v[88:91], v217 offset:16384
	ds_read_b128 v[92:95], v217 offset:17408
	ds_read_b128 v[160:163], v217 offset:18432
	ds_read_b128 v[164:167], v217 offset:19456
	ds_read_b128 v[168:171], v217 offset:20480
	ds_read_b128 v[172:175], v217 offset:21504
	ds_read_b128 v[176:179], v217 offset:22528
	ds_read_b128 v[180:183], v217 offset:23552
	global_load_lds_dwordx4 v[208:209], off
	v_lshl_add_u64 v[210:211], s[88:89], 0, v[190:191]
	s_mov_b32 m0, s80
	s_addc_u32 s75, s89, 0
	global_load_lds_dwordx4 v[210:211], off
	v_lshl_add_u64 v[196:197], s[74:75], 0, v[186:187]
	s_mov_b32 m0, s81
	v_lshl_add_u64 v[250:251], s[92:93], 0, v[184:185]
	global_load_lds_dwordx4 v[196:197], off
	v_lshl_add_u64 v[196:197], s[74:75], 0, v[190:191]
	s_mov_b32 m0, s84
	v_lshl_add_u64 v[252:253], s[92:93], 0, v[188:189]
	global_load_lds_dwordx4 v[196:197], off
	s_mov_b32 m0, s65
	s_nop 0
	global_load_lds_dwordx4 v[250:251], off
	s_mov_b32 m0, s66
	s_nop 0
	global_load_lds_dwordx4 v[252:253], off
	s_waitcnt vmcnt(8)
	s_waitcnt lgkmcnt(0)
	s_barrier
	s_setprio 1
	s_waitcnt lgkmcnt(0)
	v_mfma_f32_16x16x32_bf16 v[0:3], v[104:107], v[176:179], v[0:3]
	v_mfma_f32_16x16x32_bf16 v[4:7], v[112:115], v[176:179], v[4:7]
	v_mfma_f32_16x16x32_bf16 v[128:131], v[104:107], v[88:91], v[128:131]
	v_mfma_f32_16x16x32_bf16 v[132:135], v[112:115], v[88:91], v[132:135]
	v_mfma_f32_16x16x32_bf16 v[136:139], v[104:107], v[160:163], v[136:139]
	v_mfma_f32_16x16x32_bf16 v[140:143], v[112:115], v[160:163], v[140:143]
	v_mfma_f32_16x16x32_bf16 v[144:147], v[104:107], v[168:171], v[144:147]
	v_mfma_f32_16x16x32_bf16 v[148:151], v[112:115], v[168:171], v[148:151]
	v_mfma_f32_16x16x32_bf16 v[0:3], v[108:111], v[180:183], v[0:3]
	v_mfma_f32_16x16x32_bf16 v[4:7], v[116:119], v[180:183], v[4:7]
	v_mfma_f32_16x16x32_bf16 v[128:131], v[108:111], v[92:95], v[128:131]
	v_mfma_f32_16x16x32_bf16 v[132:135], v[116:119], v[92:95], v[132:135]
	v_mfma_f32_16x16x32_bf16 v[136:139], v[108:111], v[164:167], v[136:139]
	v_mfma_f32_16x16x32_bf16 v[140:143], v[116:119], v[164:167], v[140:143]
	v_mfma_f32_16x16x32_bf16 v[144:147], v[108:111], v[172:175], v[144:147]
	v_mfma_f32_16x16x32_bf16 v[148:151], v[116:119], v[172:175], v[148:151]
	s_setprio 0
	s_setprio 1
	v_mfma_f32_16x16x32_bf16 v[8:11], v[120:123], v[88:91], v[8:11]
	v_mfma_f32_16x16x32_bf16 v[116:119], v[124:127], v[92:95], v[8:11]
	v_mfma_f32_16x16x32_bf16 v[8:11], v[152:155], v[88:91], v[12:15]
	v_mfma_f32_16x16x32_bf16 v[196:199], v[156:159], v[92:95], v[8:11]
	v_mfma_f32_16x16x32_bf16 v[8:11], v[120:123], v[160:163], v[24:27]
	v_mfma_f32_16x16x32_bf16 v[200:203], v[124:127], v[164:167], v[8:11]
	v_mfma_f32_16x16x32_bf16 v[8:11], v[152:155], v[160:163], v[28:31]
	v_mfma_f32_16x16x32_bf16 v[160:163], v[156:159], v[164:167], v[8:11]
	v_mfma_f32_16x16x32_bf16 v[8:11], v[120:123], v[168:171], v[60:63]
	v_mfma_f32_16x16x32_bf16 v[222:225], v[124:127], v[172:175], v[8:11]
	v_mfma_f32_16x16x32_bf16 v[8:11], v[152:155], v[168:171], v[100:103]
	v_mfma_f32_16x16x32_bf16 v[168:171], v[156:159], v[172:175], v[8:11]
	v_mfma_f32_16x16x32_bf16 v[8:11], v[120:123], v[176:179], v[16:19]
	v_mfma_f32_16x16x32_bf16 v[124:127], v[124:127], v[180:183], v[8:11]
	v_mfma_f32_16x16x32_bf16 v[8:11], v[152:155], v[176:179], v[20:23]
	v_mfma_f32_16x16x32_bf16 v[156:159], v[156:159], v[180:183], v[8:11]
	s_setprio 0
	s_barrier
	s_nop 4
	ds_read_b128 v[8:11], v226
	ds_read_b128 v[12:15], v226 offset:1024
	ds_read_b128 v[16:19], v226 offset:2048
	ds_read_b128 v[20:23], v226 offset:3072
	ds_read_b128 v[172:175], v227
	ds_read_b128 v[176:179], v227 offset:1024
	ds_read_b128 v[180:183], v227 offset:2048
	ds_read_b128 v[226:229], v227 offset:3072
	s_add_u32 s74, s92, 0x10000
	s_addc_u32 s75, s93, 0
	s_mov_b32 m0, s67
	v_lshl_add_u64 v[88:89], s[74:75], 0, v[184:185]
	ds_read_b128 v[24:27], v217 offset:32768
	ds_read_b128 v[28:31], v217 offset:33792
	ds_read_b128 v[60:63], v217 offset:34816
	ds_read_b128 v[230:233], v217 offset:35840
	ds_read_b128 v[234:237], v217 offset:36864
	ds_read_b128 v[238:241], v217 offset:37888
	ds_read_b128 v[242:245], v217 offset:38912
	ds_read_b128 v[246:249], v217 offset:39936
	global_load_lds_dwordx4 v[88:89], off
	v_lshl_add_u64 v[88:89], s[74:75], 0, v[188:189]
	s_mov_b32 m0, s68
	s_nop 0
	global_load_lds_dwordx4 v[88:89], off
	s_waitcnt vmcnt(8)
	s_waitcnt lgkmcnt(0)
	s_barrier
	s_setprio 1
	s_waitcnt lgkmcnt(0)
	v_mfma_f32_16x16x32_bf16 v[64:67], v[8:11], v[24:27], v[64:67]
	v_mfma_f32_16x16x32_bf16 v[164:167], v[12:15], v[28:31], v[64:67]
	v_mfma_f32_16x16x32_bf16 v[64:67], v[16:19], v[24:27], v[68:71]
	v_mfma_f32_16x16x32_bf16 v[152:155], v[20:23], v[28:31], v[64:67]
	v_mfma_f32_16x16x32_bf16 v[64:67], v[8:11], v[60:63], v[72:75]
	v_mfma_f32_16x16x32_bf16 v[108:111], v[12:15], v[230:233], v[64:67]
	v_mfma_f32_16x16x32_bf16 v[64:67], v[16:19], v[60:63], v[76:79]
	v_mfma_f32_16x16x32_bf16 v[104:107], v[20:23], v[230:233], v[64:67]
	v_mfma_f32_16x16x32_bf16 v[64:67], v[8:11], v[234:237], v[80:83]
	v_mfma_f32_16x16x32_bf16 v[92:95], v[12:15], v[238:241], v[64:67]
	v_mfma_f32_16x16x32_bf16 v[64:67], v[16:19], v[234:237], v[84:87]
	v_mfma_f32_16x16x32_bf16 v[88:91], v[20:23], v[238:241], v[64:67]
	v_mfma_f32_16x16x32_bf16 v[64:67], v[8:11], v[242:245], v[204:207]
	v_mfma_f32_16x16x32_bf16 v[76:79], v[12:15], v[246:249], v[64:67]
	v_mfma_f32_16x16x32_bf16 v[64:67], v[16:19], v[242:245], v[218:221]
	v_mfma_f32_16x16x32_bf16 v[72:75], v[20:23], v[246:249], v[64:67]
	s_setprio 0
	s_setprio 1
	v_mfma_f32_16x16x32_bf16 v[64:67], v[172:175], v[24:27], v[96:99]
	v_mfma_f32_16x16x32_bf16 v[24:27], v[180:183], v[24:27], v[32:35]
	v_mfma_f32_16x16x32_bf16 v[112:115], v[226:229], v[28:31], v[24:27]
	v_mfma_f32_16x16x32_bf16 v[24:27], v[172:175], v[60:63], v[36:39]
	v_mfma_f32_16x16x32_bf16 v[100:103], v[176:179], v[230:233], v[24:27]
	v_mfma_f32_16x16x32_bf16 v[24:27], v[180:183], v[60:63], v[40:43]
	v_mfma_f32_16x16x32_bf16 v[96:99], v[226:229], v[230:233], v[24:27]
	v_mfma_f32_16x16x32_bf16 v[24:27], v[172:175], v[234:237], v[44:47]
	v_mfma_f32_16x16x32_bf16 v[84:87], v[176:179], v[238:241], v[24:27]
	v_mfma_f32_16x16x32_bf16 v[24:27], v[180:183], v[234:237], v[48:51]
	v_mfma_f32_16x16x32_bf16 v[80:83], v[226:229], v[238:241], v[24:27]
	v_mfma_f32_16x16x32_bf16 v[24:27], v[172:175], v[242:245], v[52:55]
	v_mfma_f32_16x16x32_bf16 v[68:71], v[176:179], v[246:249], v[24:27]
	v_mfma_f32_16x16x32_bf16 v[24:27], v[180:183], v[242:245], v[56:59]
	v_mfma_f32_16x16x32_bf16 v[120:123], v[176:179], v[28:31], v[64:67]
	v_mfma_f32_16x16x32_bf16 v[64:67], v[226:229], v[246:249], v[24:27]
	s_setprio 0
	s_barrier
	s_mov_b32 m0, s85
	s_nop 2
	v_lshl_add_u64 v[24:25], v[208:209], 0, s[4:5]
	s_add_u32 s74, s88, 0x10080
	ds_read_b128 v[32:35], v217 offset:49152
	ds_read_b128 v[36:39], v217 offset:50176
	ds_read_b128 v[204:207], v217 offset:51200
	ds_read_b128 v[218:221], v217 offset:52224
	ds_read_b128 v[230:233], v217 offset:53248
	ds_read_b128 v[234:237], v217 offset:54272
	ds_read_b128 v[238:241], v217 offset:55296
	ds_read_b128 v[242:245], v217 offset:56320
	global_load_lds_dwordx4 v[24:25], off
	v_lshl_add_u64 v[24:25], v[210:211], 0, s[4:5]
	s_mov_b32 m0, s35
	s_addc_u32 s75, s89, 0
	global_load_lds_dwordx4 v[24:25], off
	v_lshl_add_u64 v[24:25], s[74:75], 0, v[186:187]
	s_mov_b32 m0, s37
	s_nop 0
	global_load_lds_dwordx4 v[24:25], off
	v_lshl_add_u64 v[24:25], s[74:75], 0, v[190:191]
	s_mov_b32 m0, s82
	s_nop 0
	global_load_lds_dwordx4 v[24:25], off
	v_lshl_add_u64 v[24:25], v[250:251], 0, s[4:5]
	s_mov_b32 m0, s71
	s_nop 0
	global_load_lds_dwordx4 v[24:25], off
	v_lshl_add_u64 v[24:25], v[252:253], 0, s[4:5]
	s_mov_b32 m0, s72
	s_nop 0
	global_load_lds_dwordx4 v[24:25], off
	s_waitcnt vmcnt(8)
	s_waitcnt lgkmcnt(0)
	s_barrier
	s_setprio 1
	s_waitcnt lgkmcnt(0)
	v_mfma_f32_16x16x32_bf16 v[24:27], v[8:11], v[32:35], v[128:131]
	v_mfma_f32_16x16x32_bf16 v[60:63], v[12:15], v[36:39], v[24:27]
	v_mfma_f32_16x16x32_bf16 v[24:27], v[16:19], v[32:35], v[132:135]
	v_mfma_f32_16x16x32_bf16 v[56:59], v[20:23], v[36:39], v[24:27]
	v_mfma_f32_16x16x32_bf16 v[24:27], v[8:11], v[204:207], v[136:139]
	v_mfma_f32_16x16x32_bf16 v[44:47], v[12:15], v[218:221], v[24:27]
	v_mfma_f32_16x16x32_bf16 v[24:27], v[16:19], v[204:207], v[140:143]
	v_mfma_f32_16x16x32_bf16 v[40:43], v[20:23], v[218:221], v[24:27]
	v_mfma_f32_16x16x32_bf16 v[24:27], v[8:11], v[230:233], v[144:147]
	v_mfma_f32_16x16x32_bf16 v[0:3], v[8:11], v[238:241], v[0:3]
	v_mfma_f32_16x16x32_bf16 v[28:31], v[12:15], v[234:237], v[24:27]
	v_mfma_f32_16x16x32_bf16 v[24:27], v[16:19], v[230:233], v[148:151]
	v_mfma_f32_16x16x32_bf16 v[12:15], v[12:15], v[242:245], v[0:3]
	v_mfma_f32_16x16x32_bf16 v[0:3], v[16:19], v[238:241], v[4:7]
	v_mfma_f32_16x16x32_bf16 v[24:27], v[20:23], v[234:237], v[24:27]
	v_mfma_f32_16x16x32_bf16 v[8:11], v[20:23], v[242:245], v[0:3]
	s_setprio 0
	s_setprio 1
	v_mfma_f32_16x16x32_bf16 v[0:3], v[172:175], v[32:35], v[116:119]
	v_mfma_f32_16x16x32_bf16 v[52:55], v[176:179], v[36:39], v[0:3]
	v_mfma_f32_16x16x32_bf16 v[0:3], v[180:183], v[32:35], v[196:199]
	v_mfma_f32_16x16x32_bf16 v[48:51], v[226:229], v[36:39], v[0:3]
	v_mfma_f32_16x16x32_bf16 v[0:3], v[172:175], v[204:207], v[200:203]
	v_mfma_f32_16x16x32_bf16 v[36:39], v[176:179], v[218:221], v[0:3]
	v_mfma_f32_16x16x32_bf16 v[0:3], v[180:183], v[204:207], v[160:163]
	v_mfma_f32_16x16x32_bf16 v[32:35], v[226:229], v[218:221], v[0:3]
	v_mfma_f32_16x16x32_bf16 v[0:3], v[172:175], v[230:233], v[222:225]
	v_mfma_f32_16x16x32_bf16 v[20:23], v[176:179], v[234:237], v[0:3]
	v_mfma_f32_16x16x32_bf16 v[0:3], v[180:183], v[230:233], v[168:171]
	v_mfma_f32_16x16x32_bf16 v[16:19], v[226:229], v[234:237], v[0:3]
	v_mfma_f32_16x16x32_bf16 v[0:3], v[172:175], v[238:241], v[124:127]
	v_mfma_f32_16x16x32_bf16 v[4:7], v[176:179], v[242:245], v[0:3]
	v_mfma_f32_16x16x32_bf16 v[0:3], v[180:183], v[238:241], v[156:159]
	v_mfma_f32_16x16x32_bf16 v[0:3], v[226:229], v[242:245], v[0:3]
	s_setprio 0
	s_barrier
	s_andn2_b64 vcc, exec, s[6:7]
	s_cbranch_vccnz .LBB0_1438
	s_barrier
.LBB0_1438:
	s_lshl_b32 s35, s46, 8
	v_mov_b32_e32 v116, v212
	v_mov_b32_e32 v117, v213
	s_add_i32 s35, s35, s69
	s_andn2_b64 vcc, exec, s[8:9]
	v_add_u32_e32 v198, s35, v116
	s_lshl_b32 s35, s47, 8
	s_or_b32 s35, s35, s70
	v_lshl_add_u32 v116, v117, 3, s35
	v_ashrrev_i32_e32 v117, 31, v116
	v_lshlrev_b64 v[196:197], 1, v[116:117]
	v_ashrrev_i32_e32 v199, 31, v198
	v_lshl_add_u64 v[202:203], s[56:57], 0, v[196:197]
	v_lshlrev_b64 v[116:117], 12, v[198:199]
	v_lshl_add_u64 v[200:201], s[42:43], 0, v[196:197]
	v_lshl_add_u64 v[116:117], v[202:203], 0, v[116:117]
	v_lshlrev_b64 v[210:211], 11, v[198:199]
	v_lshl_add_u64 v[118:119], v[200:201], 0, v[210:211]
	global_load_dwordx4 v[218:221], v[116:117], off offset:2048
	global_load_dwordx4 v[222:225], v[118:119], off
	global_load_dwordx4 v[180:183], v[116:117], off offset:2304
	global_load_dwordx4 v[176:179], v[118:119], off offset:256
	v_add_u32_e32 v116, 16, v198
	v_ashrrev_i32_e32 v117, 31, v116
	v_lshlrev_b64 v[118:119], 12, v[116:117]
	v_lshl_add_u64 v[118:119], v[202:203], 0, v[118:119]
	v_lshlrev_b64 v[208:209], 11, v[116:117]
	v_lshl_add_u64 v[116:117], v[200:201], 0, v[208:209]
	global_load_dwordx4 v[172:175], v[118:119], off offset:2048
	global_load_dwordx4 v[168:171], v[116:117], off
	global_load_dwordx4 v[160:163], v[118:119], off offset:2304
	global_load_dwordx4 v[148:151], v[116:117], off offset:256
	v_add_u32_e32 v116, 32, v198
	v_ashrrev_i32_e32 v117, 31, v116
	v_lshlrev_b64 v[118:119], 12, v[116:117]
	v_lshl_add_u64 v[118:119], v[202:203], 0, v[118:119]
	v_lshlrev_b64 v[206:207], 11, v[116:117]
	v_lshl_add_u64 v[116:117], v[200:201], 0, v[206:207]
	global_load_dwordx4 v[156:159], v[118:119], off offset:2048
	global_load_dwordx4 v[140:143], v[116:117], off
	global_load_dwordx4 v[132:135], v[118:119], off offset:2304
	global_load_dwordx4 v[124:127], v[116:117], off offset:256
	v_add_u32_e32 v116, 48, v198
	v_ashrrev_i32_e32 v117, 31, v116
	v_lshlrev_b64 v[118:119], 12, v[116:117]
	v_lshlrev_b64 v[204:205], 11, v[116:117]
	v_lshl_add_u64 v[118:119], v[202:203], 0, v[118:119]
	v_lshl_add_u64 v[116:117], v[200:201], 0, v[204:205]
	global_load_dwordx4 v[144:147], v[118:119], off offset:2048
	global_load_dwordx4 v[136:139], v[116:117], off
	global_load_dwordx4 v[128:131], v[118:119], off offset:2304
	s_nop 0
	global_load_dwordx4 v[116:119], v[116:117], off offset:256
	v_lshl_add_u64 v[210:211], s[42:43], 0, v[210:211]
	v_lshl_add_u64 v[210:211], v[210:211], 0, v[196:197]
	s_mov_b64 s[46:47], -1
	s_waitcnt vmcnt(0)
	v_lshlrev_b32_e32 v199, 16, v218
	v_lshlrev_b32_e32 v229, 16, v222
	v_and_b32_e32 v218, 0xffff0000, v218
	v_fmac_f32_e32 v229, v164, v199
	v_and_b32_e32 v164, 0xffff0000, v222
	v_lshlrev_b32_e32 v226, 16, v219
	v_fmac_f32_e32 v164, v165, v218
	v_lshlrev_b32_e32 v165, 16, v223
	v_and_b32_e32 v219, 0xffff0000, v219
	v_fmac_f32_e32 v165, v166, v226
	v_and_b32_e32 v166, 0xffff0000, v223
	v_lshlrev_b32_e32 v227, 16, v220
	v_and_b32_e32 v220, 0xffff0000, v220
	v_fmac_f32_e32 v166, v167, v219
	v_lshlrev_b32_e32 v167, 16, v224
	v_and_b32_e32 v199, 0xffff0000, v224
	v_lshlrev_b32_e32 v228, 16, v221
	v_and_b32_e32 v221, 0xffff0000, v221
	v_fmac_f32_e32 v167, v152, v227
	v_fmac_f32_e32 v199, v153, v220
	v_lshlrev_b32_e32 v218, 16, v225
	v_and_b32_e32 v219, 0xffff0000, v225
	v_cvt_pk_bf16_f32 v152, v229, v164
	v_cvt_pk_bf16_f32 v153, v165, v166
	v_fmac_f32_e32 v218, v154, v228
	v_fmac_f32_e32 v219, v155, v221
	v_cvt_pk_bf16_f32 v154, v167, v199
	v_cvt_pk_bf16_f32 v155, v218, v219
	global_store_dwordx4 v[210:211], v[152:155], off
	v_lshlrev_b32_e32 v164, 16, v182
	v_and_b32_e32 v165, 0xffff0000, v182
	v_lshlrev_b32_e32 v152, 16, v180
	v_and_b32_e32 v153, 0xffff0000, v180
	v_lshlrev_b32_e32 v180, 16, v176
	v_fmac_f32_e32 v180, v120, v152
	v_and_b32_e32 v120, 0xffff0000, v176
	v_lshlrev_b32_e32 v154, 16, v181
	v_fmac_f32_e32 v120, v121, v153
	v_lshlrev_b32_e32 v121, 16, v177
	v_and_b32_e32 v155, 0xffff0000, v181
	v_fmac_f32_e32 v121, v122, v154
	v_and_b32_e32 v122, 0xffff0000, v177
	v_lshlrev_b32_e32 v166, 16, v183
	v_and_b32_e32 v167, 0xffff0000, v183
	v_fmac_f32_e32 v122, v123, v155
	v_lshlrev_b32_e32 v123, 16, v178
	v_and_b32_e32 v152, 0xffff0000, v178
	v_lshlrev_b32_e32 v153, 16, v179
	v_and_b32_e32 v154, 0xffff0000, v179
	v_fmac_f32_e32 v123, v112, v164
	v_fmac_f32_e32 v152, v113, v165
	v_fmac_f32_e32 v153, v114, v166
	v_fmac_f32_e32 v154, v115, v167
	v_cvt_pk_bf16_f32 v112, v180, v120
	v_cvt_pk_bf16_f32 v113, v121, v122
	v_cvt_pk_bf16_f32 v114, v123, v152
	v_cvt_pk_bf16_f32 v115, v153, v154
	global_store_dwordx4 v[210:211], v[112:115], off offset:256
	v_lshlrev_b32_e32 v154, 16, v168
	v_lshlrev_b32_e32 v120, 16, v173
	v_lshlrev_b32_e32 v114, 16, v172
	v_and_b32_e32 v115, 0xffff0000, v172
	v_fmac_f32_e32 v154, v108, v114
	v_and_b32_e32 v108, 0xffff0000, v168
	v_fmac_f32_e32 v108, v109, v115
	v_lshlrev_b32_e32 v109, 16, v169
	v_and_b32_e32 v121, 0xffff0000, v173
	v_fmac_f32_e32 v109, v110, v120
	v_and_b32_e32 v110, 0xffff0000, v169
	v_lshl_add_u64 v[112:113], s[42:43], 0, v[208:209]
	v_lshlrev_b32_e32 v122, 16, v174
	v_and_b32_e32 v123, 0xffff0000, v174
	v_fmac_f32_e32 v110, v111, v121
	v_lshlrev_b32_e32 v111, 16, v170
	v_and_b32_e32 v114, 0xffff0000, v170
	v_lshl_add_u64 v[112:113], v[112:113], 0, v[196:197]
	v_lshlrev_b32_e32 v152, 16, v175
	v_and_b32_e32 v153, 0xffff0000, v175
	v_fmac_f32_e32 v111, v104, v122
	v_fmac_f32_e32 v114, v105, v123
	v_lshlrev_b32_e32 v115, 16, v171
	v_and_b32_e32 v120, 0xffff0000, v171
	v_cvt_pk_bf16_f32 v104, v154, v108
	v_fmac_f32_e32 v115, v106, v152
	v_fmac_f32_e32 v120, v107, v153
	v_cvt_pk_bf16_f32 v105, v109, v110
	v_cvt_pk_bf16_f32 v106, v111, v114
	v_cvt_pk_bf16_f32 v107, v115, v120
	global_store_dwordx4 v[112:113], v[104:107], off
	v_lshlrev_b32_e32 v114, 16, v148
	v_lshlrev_b32_e32 v108, 16, v162
	v_lshlrev_b32_e32 v104, 16, v160
	v_and_b32_e32 v105, 0xffff0000, v160
	v_fmac_f32_e32 v114, v100, v104
	v_and_b32_e32 v100, 0xffff0000, v148
	v_lshlrev_b32_e32 v106, 16, v161
	v_fmac_f32_e32 v100, v101, v105
	v_lshlrev_b32_e32 v101, 16, v149
	v_and_b32_e32 v107, 0xffff0000, v161
	v_fmac_f32_e32 v101, v102, v106
	v_and_b32_e32 v102, 0xffff0000, v149
	v_and_b32_e32 v109, 0xffff0000, v162
	v_lshlrev_b32_e32 v110, 16, v163
	v_and_b32_e32 v111, 0xffff0000, v163
	v_fmac_f32_e32 v102, v103, v107
	v_lshlrev_b32_e32 v103, 16, v150
	v_and_b32_e32 v104, 0xffff0000, v150
	v_lshlrev_b32_e32 v105, 16, v151
	v_and_b32_e32 v106, 0xffff0000, v151
	v_fmac_f32_e32 v103, v96, v108
	v_fmac_f32_e32 v104, v97, v109
	v_fmac_f32_e32 v105, v98, v110
	v_fmac_f32_e32 v106, v99, v111
	v_cvt_pk_bf16_f32 v96, v114, v100
	v_cvt_pk_bf16_f32 v97, v101, v102
	v_cvt_pk_bf16_f32 v98, v103, v104
	v_cvt_pk_bf16_f32 v99, v105, v106
	global_store_dwordx4 v[112:113], v[96:99], off offset:256
	v_lshlrev_b32_e32 v106, 16, v140
	v_lshlrev_b32_e32 v100, 16, v157
	v_lshlrev_b32_e32 v98, 16, v156
	v_and_b32_e32 v99, 0xffff0000, v156
	v_fmac_f32_e32 v106, v92, v98
	v_and_b32_e32 v92, 0xffff0000, v140
	v_fmac_f32_e32 v92, v93, v99
	v_lshlrev_b32_e32 v93, 16, v141
	v_and_b32_e32 v101, 0xffff0000, v157
	v_fmac_f32_e32 v93, v94, v100
	v_and_b32_e32 v94, 0xffff0000, v141
	v_lshl_add_u64 v[96:97], s[42:43], 0, v[206:207]
	v_lshlrev_b32_e32 v102, 16, v158
	v_and_b32_e32 v103, 0xffff0000, v158
	v_fmac_f32_e32 v94, v95, v101
	v_lshlrev_b32_e32 v95, 16, v142
	v_and_b32_e32 v98, 0xffff0000, v142
	v_lshl_add_u64 v[96:97], v[96:97], 0, v[196:197]
	v_lshlrev_b32_e32 v104, 16, v159
	v_and_b32_e32 v105, 0xffff0000, v159
	v_fmac_f32_e32 v95, v88, v102
	v_fmac_f32_e32 v98, v89, v103
	v_lshlrev_b32_e32 v99, 16, v143
	v_and_b32_e32 v100, 0xffff0000, v143
	v_cvt_pk_bf16_f32 v88, v106, v92
	v_fmac_f32_e32 v99, v90, v104
	v_fmac_f32_e32 v100, v91, v105
	v_cvt_pk_bf16_f32 v89, v93, v94
	v_cvt_pk_bf16_f32 v90, v95, v98
	v_cvt_pk_bf16_f32 v91, v99, v100
	global_store_dwordx4 v[96:97], v[88:91], off
	v_lshlrev_b32_e32 v98, 16, v124
	v_lshlrev_b32_e32 v92, 16, v134
	v_lshlrev_b32_e32 v88, 16, v132
	v_and_b32_e32 v89, 0xffff0000, v132
	v_fmac_f32_e32 v98, v84, v88
	v_and_b32_e32 v84, 0xffff0000, v124
	v_lshlrev_b32_e32 v90, 16, v133
	v_fmac_f32_e32 v84, v85, v89
	v_lshlrev_b32_e32 v85, 16, v125
	v_and_b32_e32 v91, 0xffff0000, v133
	v_fmac_f32_e32 v85, v86, v90
	v_and_b32_e32 v86, 0xffff0000, v125
	v_and_b32_e32 v93, 0xffff0000, v134
	v_lshlrev_b32_e32 v94, 16, v135
	v_and_b32_e32 v95, 0xffff0000, v135
	v_fmac_f32_e32 v86, v87, v91
	v_lshlrev_b32_e32 v87, 16, v126
	v_and_b32_e32 v88, 0xffff0000, v126
	v_lshlrev_b32_e32 v89, 16, v127
	v_and_b32_e32 v90, 0xffff0000, v127
	v_fmac_f32_e32 v87, v80, v92
	v_fmac_f32_e32 v88, v81, v93
	v_fmac_f32_e32 v89, v82, v94
	v_fmac_f32_e32 v90, v83, v95
	v_cvt_pk_bf16_f32 v80, v98, v84
	v_cvt_pk_bf16_f32 v81, v85, v86
	v_cvt_pk_bf16_f32 v82, v87, v88
	v_cvt_pk_bf16_f32 v83, v89, v90
	global_store_dwordx4 v[96:97], v[80:83], off offset:256
	v_lshlrev_b32_e32 v90, 16, v136
	v_lshlrev_b32_e32 v84, 16, v145
	v_lshlrev_b32_e32 v82, 16, v144
	v_and_b32_e32 v83, 0xffff0000, v144
	v_fmac_f32_e32 v90, v76, v82
	v_and_b32_e32 v76, 0xffff0000, v136
	v_fmac_f32_e32 v76, v77, v83
	v_lshlrev_b32_e32 v77, 16, v137
	v_and_b32_e32 v85, 0xffff0000, v145
	v_fmac_f32_e32 v77, v78, v84
	v_and_b32_e32 v78, 0xffff0000, v137
	v_lshl_add_u64 v[80:81], s[42:43], 0, v[204:205]
	v_lshlrev_b32_e32 v86, 16, v146
	v_and_b32_e32 v87, 0xffff0000, v146
	v_fmac_f32_e32 v78, v79, v85
	v_lshlrev_b32_e32 v79, 16, v138
	v_and_b32_e32 v82, 0xffff0000, v138
	v_lshl_add_u64 v[80:81], v[80:81], 0, v[196:197]
	v_lshlrev_b32_e32 v88, 16, v147
	v_and_b32_e32 v89, 0xffff0000, v147
	v_fmac_f32_e32 v79, v72, v86
	v_fmac_f32_e32 v82, v73, v87
	v_lshlrev_b32_e32 v83, 16, v139
	v_and_b32_e32 v84, 0xffff0000, v139
	v_cvt_pk_bf16_f32 v72, v90, v76
	v_fmac_f32_e32 v83, v74, v88
	v_fmac_f32_e32 v84, v75, v89
	v_cvt_pk_bf16_f32 v73, v77, v78
	v_cvt_pk_bf16_f32 v74, v79, v82
	v_cvt_pk_bf16_f32 v75, v83, v84
	global_store_dwordx4 v[80:81], v[72:75], off
	v_lshlrev_b32_e32 v82, 16, v116
	v_lshlrev_b32_e32 v76, 16, v130
	v_lshlrev_b32_e32 v72, 16, v128
	v_and_b32_e32 v73, 0xffff0000, v128
	v_fmac_f32_e32 v82, v68, v72
	v_and_b32_e32 v68, 0xffff0000, v116
	v_lshlrev_b32_e32 v74, 16, v129
	v_fmac_f32_e32 v68, v69, v73
	v_lshlrev_b32_e32 v69, 16, v117
	v_and_b32_e32 v75, 0xffff0000, v129
	v_fmac_f32_e32 v69, v70, v74
	v_and_b32_e32 v70, 0xffff0000, v117
	v_fmac_f32_e32 v70, v71, v75
	v_lshlrev_b32_e32 v71, 16, v118
	v_and_b32_e32 v77, 0xffff0000, v130
	v_lshlrev_b32_e32 v78, 16, v131
	v_and_b32_e32 v79, 0xffff0000, v131
	v_fmac_f32_e32 v71, v64, v76
	v_and_b32_e32 v72, 0xffff0000, v118
	v_lshlrev_b32_e32 v73, 16, v119
	v_and_b32_e32 v74, 0xffff0000, v119
	v_cvt_pk_bf16_f32 v64, v82, v68
	v_fmac_f32_e32 v72, v65, v77
	v_fmac_f32_e32 v73, v66, v78
	v_fmac_f32_e32 v74, v67, v79
	v_cvt_pk_bf16_f32 v65, v69, v70
	v_cvt_pk_bf16_f32 v66, v71, v72
	v_cvt_pk_bf16_f32 v67, v73, v74
	global_store_dwordx4 v[80:81], v[64:67], off offset:256
	s_nop 1
	v_add_u32_e32 v64, 0x80, v198
	v_ashrrev_i32_e32 v65, 31, v64
	v_lshlrev_b64 v[66:67], 12, v[64:65]
	v_lshl_add_u64 v[66:67], v[202:203], 0, v[66:67]
	v_lshlrev_b64 v[130:131], 11, v[64:65]
	v_lshl_add_u64 v[64:65], v[200:201], 0, v[130:131]
	global_load_dwordx4 v[86:89], v[66:67], off offset:2048
	global_load_dwordx4 v[90:93], v[64:65], off
	global_load_dwordx4 v[94:97], v[66:67], off offset:2304
	global_load_dwordx4 v[98:101], v[64:65], off offset:256
	v_add_u32_e32 v64, 0x90, v198
	v_ashrrev_i32_e32 v65, 31, v64
	v_lshlrev_b64 v[66:67], 12, v[64:65]
	v_lshl_add_u64 v[66:67], v[202:203], 0, v[66:67]
	v_lshlrev_b64 v[132:133], 11, v[64:65]
	v_lshl_add_u64 v[64:65], v[200:201], 0, v[132:133]
	global_load_dwordx4 v[102:105], v[66:67], off offset:2048
	global_load_dwordx4 v[106:109], v[64:65], off
	global_load_dwordx4 v[110:113], v[66:67], off offset:2304
	global_load_dwordx4 v[114:117], v[64:65], off offset:256
	v_add_u32_e32 v64, 0xa0, v198
	v_ashrrev_i32_e32 v65, 31, v64
	v_lshlrev_b64 v[66:67], 12, v[64:65]
	v_lshl_add_u64 v[66:67], v[202:203], 0, v[66:67]
	v_lshlrev_b64 v[134:135], 11, v[64:65]
	v_lshl_add_u64 v[64:65], v[200:201], 0, v[134:135]
	global_load_dwordx4 v[118:121], v[66:67], off offset:2048
	global_load_dwordx4 v[122:125], v[64:65], off
	global_load_dwordx4 v[126:129], v[66:67], off offset:2304
	global_load_dwordx4 v[80:83], v[64:65], off offset:256
	v_add_u32_e32 v64, 0xb0, v198
	v_ashrrev_i32_e32 v65, 31, v64
	v_lshlrev_b64 v[66:67], 12, v[64:65]
	v_lshlrev_b64 v[84:85], 11, v[64:65]
	v_lshl_add_u64 v[66:67], v[202:203], 0, v[66:67]
	v_lshl_add_u64 v[64:65], v[200:201], 0, v[84:85]
	global_load_dwordx4 v[76:79], v[66:67], off offset:2048
	global_load_dwordx4 v[72:75], v[64:65], off
	global_load_dwordx4 v[68:71], v[66:67], off offset:2304
	s_nop 0
	global_load_dwordx4 v[64:67], v[64:65], off offset:256
	v_lshl_add_u64 v[130:131], s[42:43], 0, v[130:131]
	v_lshl_add_u64 v[130:131], v[130:131], 0, v[196:197]
	s_waitcnt vmcnt(15)
	v_lshlrev_b32_e32 v136, 16, v86
	s_waitcnt vmcnt(14)
	v_lshlrev_b32_e32 v140, 16, v90
	v_and_b32_e32 v86, 0xffff0000, v86
	v_fmac_f32_e32 v140, v60, v136
	v_and_b32_e32 v60, 0xffff0000, v90
	v_lshlrev_b32_e32 v137, 16, v87
	v_fmac_f32_e32 v60, v61, v86
	v_lshlrev_b32_e32 v61, 16, v91
	v_and_b32_e32 v87, 0xffff0000, v87
	v_fmac_f32_e32 v61, v62, v137
	v_and_b32_e32 v62, 0xffff0000, v91
	v_lshlrev_b32_e32 v138, 16, v88
	v_and_b32_e32 v88, 0xffff0000, v88
	v_fmac_f32_e32 v62, v63, v87
	v_lshlrev_b32_e32 v63, 16, v92
	v_and_b32_e32 v86, 0xffff0000, v92
	v_lshlrev_b32_e32 v139, 16, v89
	v_and_b32_e32 v89, 0xffff0000, v89
	v_fmac_f32_e32 v63, v56, v138
	v_fmac_f32_e32 v86, v57, v88
	v_lshlrev_b32_e32 v87, 16, v93
	v_and_b32_e32 v88, 0xffff0000, v93
	v_cvt_pk_bf16_f32 v56, v140, v60
	v_fmac_f32_e32 v87, v58, v139
	v_fmac_f32_e32 v88, v59, v89
	v_cvt_pk_bf16_f32 v57, v61, v62
	v_cvt_pk_bf16_f32 v58, v63, v86
	v_cvt_pk_bf16_f32 v59, v87, v88
	global_store_dwordx4 v[130:131], v[56:59], off
	s_waitcnt vmcnt(13)
	v_lshlrev_b32_e32 v86, 16, v98
	v_lshlrev_b32_e32 v60, 16, v96
	v_lshlrev_b32_e32 v56, 16, v94
	v_and_b32_e32 v57, 0xffff0000, v94
	v_fmac_f32_e32 v86, v52, v56
	v_and_b32_e32 v52, 0xffff0000, v98
	v_lshlrev_b32_e32 v58, 16, v95
	v_fmac_f32_e32 v52, v53, v57
	v_lshlrev_b32_e32 v53, 16, v99
	v_and_b32_e32 v59, 0xffff0000, v95
	v_fmac_f32_e32 v53, v54, v58
	v_and_b32_e32 v54, 0xffff0000, v99
	v_and_b32_e32 v61, 0xffff0000, v96
	v_lshlrev_b32_e32 v62, 16, v97
	v_and_b32_e32 v63, 0xffff0000, v97
	v_fmac_f32_e32 v54, v55, v59
	v_lshlrev_b32_e32 v55, 16, v100
	v_and_b32_e32 v56, 0xffff0000, v100
	v_lshlrev_b32_e32 v57, 16, v101
	v_and_b32_e32 v58, 0xffff0000, v101
	v_fmac_f32_e32 v55, v48, v60
	v_fmac_f32_e32 v56, v49, v61
	v_fmac_f32_e32 v57, v50, v62
	v_fmac_f32_e32 v58, v51, v63
	v_cvt_pk_bf16_f32 v48, v86, v52
	v_cvt_pk_bf16_f32 v49, v53, v54
	v_cvt_pk_bf16_f32 v50, v55, v56
	v_cvt_pk_bf16_f32 v51, v57, v58
	global_store_dwordx4 v[130:131], v[48:51], off offset:256
	s_waitcnt vmcnt(12)
	v_lshlrev_b32_e32 v58, 16, v106
	v_lshlrev_b32_e32 v52, 16, v103
	v_lshlrev_b32_e32 v50, 16, v102
	v_and_b32_e32 v51, 0xffff0000, v102
	v_fmac_f32_e32 v58, v44, v50
	v_and_b32_e32 v44, 0xffff0000, v106
	v_fmac_f32_e32 v44, v45, v51
	v_lshlrev_b32_e32 v45, 16, v107
	v_and_b32_e32 v53, 0xffff0000, v103
	v_fmac_f32_e32 v45, v46, v52
	v_and_b32_e32 v46, 0xffff0000, v107
	v_lshl_add_u64 v[48:49], s[42:43], 0, v[132:133]
	v_lshlrev_b32_e32 v54, 16, v104
	v_and_b32_e32 v55, 0xffff0000, v104
	v_fmac_f32_e32 v46, v47, v53
	v_lshlrev_b32_e32 v47, 16, v108
	v_and_b32_e32 v50, 0xffff0000, v108
	v_lshl_add_u64 v[48:49], v[48:49], 0, v[196:197]
	v_lshlrev_b32_e32 v56, 16, v105
	v_and_b32_e32 v57, 0xffff0000, v105
	v_fmac_f32_e32 v47, v40, v54
	v_fmac_f32_e32 v50, v41, v55
	v_lshlrev_b32_e32 v51, 16, v109
	v_and_b32_e32 v52, 0xffff0000, v109
	v_cvt_pk_bf16_f32 v40, v58, v44
	v_fmac_f32_e32 v51, v42, v56
	v_fmac_f32_e32 v52, v43, v57
	v_cvt_pk_bf16_f32 v41, v45, v46
	v_cvt_pk_bf16_f32 v42, v47, v50
	v_cvt_pk_bf16_f32 v43, v51, v52
	global_store_dwordx4 v[48:49], v[40:43], off
	s_waitcnt vmcnt(11)
	v_lshlrev_b32_e32 v50, 16, v114
	v_lshlrev_b32_e32 v44, 16, v112
	v_lshlrev_b32_e32 v40, 16, v110
	v_and_b32_e32 v41, 0xffff0000, v110
	v_fmac_f32_e32 v50, v36, v40
	v_and_b32_e32 v36, 0xffff0000, v114
	v_lshlrev_b32_e32 v42, 16, v111
	v_fmac_f32_e32 v36, v37, v41
	v_lshlrev_b32_e32 v37, 16, v115
	v_and_b32_e32 v43, 0xffff0000, v111
	v_fmac_f32_e32 v37, v38, v42
	v_and_b32_e32 v38, 0xffff0000, v115
	v_and_b32_e32 v45, 0xffff0000, v112
	v_lshlrev_b32_e32 v46, 16, v113
	v_and_b32_e32 v47, 0xffff0000, v113
	v_fmac_f32_e32 v38, v39, v43
	v_lshlrev_b32_e32 v39, 16, v116
	v_and_b32_e32 v40, 0xffff0000, v116
	v_lshlrev_b32_e32 v41, 16, v117
	v_and_b32_e32 v42, 0xffff0000, v117
	v_fmac_f32_e32 v39, v32, v44
	v_fmac_f32_e32 v40, v33, v45
	v_fmac_f32_e32 v41, v34, v46
	v_fmac_f32_e32 v42, v35, v47
	v_cvt_pk_bf16_f32 v32, v50, v36
	v_cvt_pk_bf16_f32 v33, v37, v38
	v_cvt_pk_bf16_f32 v34, v39, v40
	v_cvt_pk_bf16_f32 v35, v41, v42
	global_store_dwordx4 v[48:49], v[32:35], off offset:256
	s_waitcnt vmcnt(10)
	v_lshlrev_b32_e32 v42, 16, v122
	v_lshlrev_b32_e32 v36, 16, v119
	v_lshlrev_b32_e32 v34, 16, v118
	v_and_b32_e32 v35, 0xffff0000, v118
	v_fmac_f32_e32 v42, v28, v34
	v_and_b32_e32 v28, 0xffff0000, v122
	v_fmac_f32_e32 v28, v29, v35
	v_lshlrev_b32_e32 v29, 16, v123
	v_and_b32_e32 v37, 0xffff0000, v119
	v_fmac_f32_e32 v29, v30, v36
	v_and_b32_e32 v30, 0xffff0000, v123
	v_lshl_add_u64 v[32:33], s[42:43], 0, v[134:135]
	v_lshlrev_b32_e32 v38, 16, v120
	v_and_b32_e32 v39, 0xffff0000, v120
	v_fmac_f32_e32 v30, v31, v37
	v_lshlrev_b32_e32 v31, 16, v124
	v_and_b32_e32 v34, 0xffff0000, v124
	v_lshl_add_u64 v[32:33], v[32:33], 0, v[196:197]
	v_lshlrev_b32_e32 v40, 16, v121
	v_and_b32_e32 v41, 0xffff0000, v121
	v_fmac_f32_e32 v31, v24, v38
	v_fmac_f32_e32 v34, v25, v39
	v_lshlrev_b32_e32 v35, 16, v125
	v_and_b32_e32 v36, 0xffff0000, v125
	v_cvt_pk_bf16_f32 v24, v42, v28
	v_fmac_f32_e32 v35, v26, v40
	v_fmac_f32_e32 v36, v27, v41
	v_cvt_pk_bf16_f32 v25, v29, v30
	v_cvt_pk_bf16_f32 v26, v31, v34
	v_cvt_pk_bf16_f32 v27, v35, v36
	global_store_dwordx4 v[32:33], v[24:27], off
	s_waitcnt vmcnt(9)
	v_lshlrev_b32_e32 v34, 16, v80
	v_lshlrev_b32_e32 v28, 16, v128
	v_lshlrev_b32_e32 v24, 16, v126
	v_and_b32_e32 v25, 0xffff0000, v126
	v_fmac_f32_e32 v34, v20, v24
	v_and_b32_e32 v20, 0xffff0000, v80
	v_lshlrev_b32_e32 v26, 16, v127
	v_fmac_f32_e32 v20, v21, v25
	v_lshlrev_b32_e32 v21, 16, v81
	v_and_b32_e32 v27, 0xffff0000, v127
	v_fmac_f32_e32 v21, v22, v26
	v_and_b32_e32 v22, 0xffff0000, v81
	v_and_b32_e32 v29, 0xffff0000, v128
	v_lshlrev_b32_e32 v30, 16, v129
	v_and_b32_e32 v31, 0xffff0000, v129
	v_fmac_f32_e32 v22, v23, v27
	v_lshlrev_b32_e32 v23, 16, v82
	v_and_b32_e32 v24, 0xffff0000, v82
	v_lshlrev_b32_e32 v25, 16, v83
	v_and_b32_e32 v26, 0xffff0000, v83
	v_fmac_f32_e32 v23, v16, v28
	v_fmac_f32_e32 v24, v17, v29
	v_fmac_f32_e32 v25, v18, v30
	v_fmac_f32_e32 v26, v19, v31
	v_cvt_pk_bf16_f32 v16, v34, v20
	v_cvt_pk_bf16_f32 v17, v21, v22
	v_cvt_pk_bf16_f32 v18, v23, v24
	v_cvt_pk_bf16_f32 v19, v25, v26
	global_store_dwordx4 v[32:33], v[16:19], off offset:256
	s_waitcnt vmcnt(8)
	v_lshlrev_b32_e32 v26, 16, v72
	v_lshlrev_b32_e32 v20, 16, v77
	v_lshlrev_b32_e32 v18, 16, v76
	v_and_b32_e32 v19, 0xffff0000, v76
	v_fmac_f32_e32 v26, v12, v18
	v_and_b32_e32 v12, 0xffff0000, v72
	v_fmac_f32_e32 v12, v13, v19
	v_lshlrev_b32_e32 v13, 16, v73
	v_and_b32_e32 v21, 0xffff0000, v77
	v_fmac_f32_e32 v13, v14, v20
	v_and_b32_e32 v14, 0xffff0000, v73
	v_lshl_add_u64 v[16:17], s[42:43], 0, v[84:85]
	v_lshlrev_b32_e32 v22, 16, v78
	v_and_b32_e32 v23, 0xffff0000, v78
	v_fmac_f32_e32 v14, v15, v21
	v_lshlrev_b32_e32 v15, 16, v74
	v_and_b32_e32 v18, 0xffff0000, v74
	v_lshl_add_u64 v[16:17], v[16:17], 0, v[196:197]
	v_lshlrev_b32_e32 v24, 16, v79
	v_and_b32_e32 v25, 0xffff0000, v79
	v_fmac_f32_e32 v15, v8, v22
	v_fmac_f32_e32 v18, v9, v23
	v_lshlrev_b32_e32 v19, 16, v75
	v_and_b32_e32 v20, 0xffff0000, v75
	v_cvt_pk_bf16_f32 v8, v26, v12
	v_fmac_f32_e32 v19, v10, v24
	v_fmac_f32_e32 v20, v11, v25
	v_cvt_pk_bf16_f32 v9, v13, v14
	v_cvt_pk_bf16_f32 v10, v15, v18
	v_cvt_pk_bf16_f32 v11, v19, v20
	global_store_dwordx4 v[16:17], v[8:11], off
	s_waitcnt vmcnt(7)
	v_lshlrev_b32_e32 v18, 16, v64
	v_lshlrev_b32_e32 v12, 16, v70
	v_lshlrev_b32_e32 v8, 16, v68
	v_and_b32_e32 v9, 0xffff0000, v68
	v_fmac_f32_e32 v18, v4, v8
	v_and_b32_e32 v4, 0xffff0000, v64
	v_lshlrev_b32_e32 v10, 16, v69
	v_fmac_f32_e32 v4, v5, v9
	v_lshlrev_b32_e32 v5, 16, v65
	v_and_b32_e32 v11, 0xffff0000, v69
	v_fmac_f32_e32 v5, v6, v10
	v_and_b32_e32 v6, 0xffff0000, v65
	v_and_b32_e32 v13, 0xffff0000, v70
	v_lshlrev_b32_e32 v14, 16, v71
	v_and_b32_e32 v15, 0xffff0000, v71
	v_fmac_f32_e32 v6, v7, v11
	v_lshlrev_b32_e32 v7, 16, v66
	v_and_b32_e32 v8, 0xffff0000, v66
	v_lshlrev_b32_e32 v9, 16, v67
	v_and_b32_e32 v10, 0xffff0000, v67
	v_fmac_f32_e32 v7, v0, v12
	v_fmac_f32_e32 v8, v1, v13
	v_fmac_f32_e32 v9, v2, v14
	v_fmac_f32_e32 v10, v3, v15
	v_cvt_pk_bf16_f32 v0, v18, v4
	v_cvt_pk_bf16_f32 v1, v5, v6
	v_cvt_pk_bf16_f32 v2, v7, v8
	v_cvt_pk_bf16_f32 v3, v9, v10
	global_store_dwordx4 v[16:17], v[0:3], off offset:256
	s_mov_b32 s99, 1
	s_cbranch_vccnz .LBB0_1429
	s_andn2_b64 vcc, exec, s[0:1]
	s_cbranch_vccnz .LBB0_1428
	s_barrier
	s_branch .LBB0_1428

.LBB0_1516:
	s_cmp_eq_u64 s[8:9], 0
	s_cbranch_scc1 .Lrs3skip14
	s_lshl_b32 s98, s36, 8
	s_add_i32 s98, s98, s11
	v_add_u32_e32 v150, s98, v153
	v_lshlrev_b32_e32 v200, 3, v151
	v_ashrrev_i32_e32 v201, 31, v200
	v_lshl_add_u64 v[200:201], v[200:201], 2, s[76:77]
	v_mov_b32_e32 v252, v150
	v_ashrrev_i32_e32 v253, 31, v252
	v_lshlrev_b64 v[252:253], 7, v[252:253]
	v_lshl_add_u64 v[252:253], v[200:201], 0, v[252:253]
	global_load_dwordx4 v[184:187], v[252:253], off offset:16
	global_load_dwordx4 v[188:191], v[252:253], off
	v_add_u32_e32 v252, 0x10, v150
	v_ashrrev_i32_e32 v253, 31, v252
	v_lshlrev_b64 v[252:253], 7, v[252:253]
	v_lshl_add_u64 v[252:253], v[200:201], 0, v[252:253]
	global_load_dwordx4 v[192:195], v[252:253], off offset:16
	global_load_dwordx4 v[196:199], v[252:253], off
	v_add_u32_e32 v252, 0x20, v150
	v_ashrrev_i32_e32 v253, 31, v252
	v_lshlrev_b64 v[252:253], 7, v[252:253]
	v_lshl_add_u64 v[252:253], v[200:201], 0, v[252:253]
	global_load_dwordx4 v[204:207], v[252:253], off offset:16
	global_load_dwordx4 v[208:211], v[252:253], off
	v_add_u32_e32 v252, 0x30, v150
	v_ashrrev_i32_e32 v253, 31, v252
	v_lshlrev_b64 v[252:253], 7, v[252:253]
	v_lshl_add_u64 v[252:253], v[200:201], 0, v[252:253]
	global_load_dwordx4 v[212:215], v[252:253], off offset:16
	global_load_dwordx4 v[216:219], v[252:253], off
	v_add_u32_e32 v252, 0x80, v150
	v_ashrrev_i32_e32 v253, 31, v252
	v_lshlrev_b64 v[252:253], 7, v[252:253]
	v_lshl_add_u64 v[252:253], v[200:201], 0, v[252:253]
	global_load_dwordx4 v[220:223], v[252:253], off offset:16
	global_load_dwordx4 v[224:227], v[252:253], off
	v_add_u32_e32 v252, 0x90, v150
	v_ashrrev_i32_e32 v253, 31, v252
	v_lshlrev_b64 v[252:253], 7, v[252:253]
	v_lshl_add_u64 v[252:253], v[200:201], 0, v[252:253]
	global_load_dwordx4 v[228:231], v[252:253], off offset:16
	global_load_dwordx4 v[232:235], v[252:253], off
	v_add_u32_e32 v252, 0xa0, v150
	v_ashrrev_i32_e32 v253, 31, v252
	v_lshlrev_b64 v[252:253], 7, v[252:253]
	v_lshl_add_u64 v[252:253], v[200:201], 0, v[252:253]
	global_load_dwordx4 v[236:239], v[252:253], off offset:16
	global_load_dwordx4 v[240:243], v[252:253], off
	v_add_u32_e32 v252, 0xb0, v150
	v_ashrrev_i32_e32 v253, 31, v252
	v_lshlrev_b64 v[252:253], 7, v[252:253]
	v_lshl_add_u64 v[252:253], v[200:201], 0, v[252:253]
	global_load_dwordx4 v[244:247], v[252:253], off offset:16
	global_load_dwordx4 v[248:251], v[252:253], off

.LBB0_1532:
	s_or_b64 exec, exec, s[46:47]
	s_andn2_b64 vcc, exec, s[8:9]
	s_mov_b64 s[8:9], -1
	s_cbranch_vccnz .LBB0_1505
	v_mov_b32_e32 v1, v151
	v_mov_b32_e32 v0, v153
	s_lshl_b32 s8, s36, 8
	s_add_i32 s8, s8, s11
	v_add_u32_e32 v0, s8, v0
	s_waitcnt lgkmcnt(0)
	v_lshlrev_b32_e32 v2, 3, v1
	v_ashrrev_i32_e32 v3, 31, v2
	v_ashrrev_i32_e32 v1, 31, v0
	v_lshl_add_u64 v[6:7], v[2:3], 2, s[76:77]
	v_lshlrev_b64 v[4:5], 7, v[0:1]
	v_lshl_add_u64 v[4:5], v[6:7], 0, v[4:5]
	s_waitcnt vmcnt(16)
	v_mov_b32_e32 v8, v184
	v_mov_b32_e32 v9, v185
	v_mov_b32_e32 v10, v186
	v_mov_b32_e32 v11, v187
	v_mov_b32_e32 v12, v188
	v_mov_b32_e32 v13, v189
	v_mov_b32_e32 v14, v190
	v_mov_b32_e32 v15, v191
	v_add_u32_e32 v56, 0x90, v0
	v_ashrrev_i32_e32 v57, 31, v56
	v_add_u32_e32 v58, 0xa0, v0
	v_ashrrev_i32_e32 v59, 31, v58
	v_add_u32_e32 v60, 0xb0, v0
	v_ashrrev_i32_e32 v61, 31, v60
	s_lshl_b32 s8, s34, 8
	s_or_b32 s8, s8, s66
	v_add_u32_e32 v2, s8, v2
	v_ashrrev_i32_e32 v3, 31, v2
	s_andn2_b64 vcc, exec, s[4:5]
	v_mov_b32_e32 v5, v8
	v_mov_b32_e32 v4, v12
	v_mov_b32_e32 v16, v14
	v_mov_b32_e32 v17, v10
	v_pk_add_f32 v[4:5], v[4:5], v[16:17]
	v_add_f32_e32 v8, v13, v15
	v_add_f32_e32 v10, v9, v11
	v_mov_b32_e32 v9, v4
	v_mov_b32_e32 v11, v5
	v_pk_add_f32 v[4:5], v[8:9], v[10:11]
	ds_bpermute_b32 v9, v155, v5
	ds_bpermute_b32 v8, v155, v4
	s_waitcnt lgkmcnt(0)
	v_pk_add_f32 v[48:49], v[4:5], v[8:9]
	v_add_u32_e32 v4, 16, v0
	v_ashrrev_i32_e32 v5, 31, v4
	v_lshlrev_b64 v[8:9], 7, v[4:5]
	v_lshl_add_u64 v[12:13], v[6:7], 0, v[8:9]
	v_mov_b32_e32 v8, v192
	v_mov_b32_e32 v9, v193
	v_mov_b32_e32 v10, v194
	v_mov_b32_e32 v11, v195
	s_nop 0
	v_mov_b32_e32 v12, v196
	v_mov_b32_e32 v13, v197
	v_mov_b32_e32 v14, v198
	v_mov_b32_e32 v15, v199
	ds_bpermute_b32 v51, v157, v49
	ds_bpermute_b32 v50, v157, v48
	v_mov_b32_e32 v17, v8
	v_mov_b32_e32 v16, v12
	v_mov_b32_e32 v18, v14
	v_mov_b32_e32 v19, v10
	v_pk_add_f32 v[16:17], v[16:17], v[18:19]
	v_add_f32_e32 v8, v13, v15
	v_add_f32_e32 v10, v9, v11
	v_mov_b32_e32 v9, v16
	v_mov_b32_e32 v11, v17
	v_pk_add_f32 v[8:9], v[8:9], v[10:11]
	ds_bpermute_b32 v11, v155, v9
	ds_bpermute_b32 v10, v155, v8
	s_waitcnt lgkmcnt(0)
	v_pk_add_f32 v[52:53], v[8:9], v[10:11]
	v_add_u32_e32 v8, 32, v0
	v_ashrrev_i32_e32 v9, 31, v8
	v_lshlrev_b64 v[10:11], 7, v[8:9]
	v_lshl_add_u64 v[14:15], v[6:7], 0, v[10:11]
	v_mov_b32_e32 v10, v204
	v_mov_b32_e32 v11, v205
	v_mov_b32_e32 v12, v206
	v_mov_b32_e32 v13, v207
	s_nop 0
	v_mov_b32_e32 v14, v208
	v_mov_b32_e32 v15, v209
	v_mov_b32_e32 v16, v210
	v_mov_b32_e32 v17, v211
	ds_bpermute_b32 v55, v157, v53
	ds_bpermute_b32 v54, v157, v52
	v_mov_b32_e32 v19, v10
	v_mov_b32_e32 v18, v14
	v_mov_b32_e32 v20, v16
	v_mov_b32_e32 v21, v12
	v_pk_add_f32 v[18:19], v[18:19], v[20:21]
	v_add_f32_e32 v10, v15, v17
	v_add_f32_e32 v12, v11, v13
	v_mov_b32_e32 v11, v18
	v_mov_b32_e32 v13, v19
	v_pk_add_f32 v[10:11], v[10:11], v[12:13]
	ds_bpermute_b32 v13, v155, v11
	ds_bpermute_b32 v12, v155, v10
	s_waitcnt lgkmcnt(0)
	v_pk_add_f32 v[64:65], v[10:11], v[12:13]
	v_add_u32_e32 v10, 48, v0
	v_ashrrev_i32_e32 v11, 31, v10
	v_lshlrev_b64 v[12:13], 7, v[10:11]
	v_lshl_add_u64 v[16:17], v[6:7], 0, v[12:13]
	v_mov_b32_e32 v12, v212
	v_mov_b32_e32 v13, v213
	v_mov_b32_e32 v14, v214
	v_mov_b32_e32 v15, v215
	s_nop 0
	v_mov_b32_e32 v16, v216
	v_mov_b32_e32 v17, v217
	v_mov_b32_e32 v18, v218
	v_mov_b32_e32 v19, v219
	ds_bpermute_b32 v67, v157, v65
	ds_bpermute_b32 v66, v157, v64
	v_mov_b32_e32 v21, v12
	v_mov_b32_e32 v20, v16
	v_mov_b32_e32 v22, v18
	v_mov_b32_e32 v23, v14
	v_pk_add_f32 v[20:21], v[20:21], v[22:23]
	v_add_f32_e32 v12, v17, v19
	v_add_f32_e32 v14, v13, v15
	v_mov_b32_e32 v13, v20
	v_mov_b32_e32 v15, v21
	v_pk_add_f32 v[12:13], v[12:13], v[14:15]
	ds_bpermute_b32 v15, v155, v13
	ds_bpermute_b32 v14, v155, v12
	s_waitcnt lgkmcnt(0)
	v_pk_add_f32 v[68:69], v[12:13], v[14:15]
	v_add_u32_e32 v12, 0x80, v0
	v_ashrrev_i32_e32 v13, 31, v12
	v_lshlrev_b64 v[14:15], 7, v[12:13]
	v_lshl_add_u64 v[18:19], v[6:7], 0, v[14:15]
	v_mov_b32_e32 v14, v220
	v_mov_b32_e32 v15, v221
	v_mov_b32_e32 v16, v222
	v_mov_b32_e32 v17, v223
	s_nop 0
	v_mov_b32_e32 v18, v224
	v_mov_b32_e32 v19, v225
	v_mov_b32_e32 v20, v226
	v_mov_b32_e32 v21, v227
	v_lshlrev_b64 v[0:1], 11, v[0:1]
	v_lshl_add_u64 v[0:1], s[44:45], 0, v[0:1]
	ds_bpermute_b32 v71, v157, v69
	ds_bpermute_b32 v70, v157, v68
	v_mov_b32_e32 v23, v14
	v_mov_b32_e32 v22, v18
	v_mov_b32_e32 v24, v20
	v_mov_b32_e32 v25, v16
	v_pk_add_f32 v[22:23], v[22:23], v[24:25]
	v_add_f32_e32 v14, v19, v21
	v_add_f32_e32 v16, v15, v17
	v_mov_b32_e32 v15, v22
	v_mov_b32_e32 v17, v23
	v_pk_add_f32 v[14:15], v[14:15], v[16:17]
	ds_bpermute_b32 v17, v155, v15
	ds_bpermute_b32 v16, v155, v14
	s_waitcnt lgkmcnt(0)
	v_pk_add_f32 v[112:113], v[14:15], v[16:17]
	v_lshlrev_b64 v[14:15], 7, v[56:57]
	v_lshl_add_u64 v[18:19], v[6:7], 0, v[14:15]
	v_mov_b32_e32 v14, v228
	v_mov_b32_e32 v15, v229
	v_mov_b32_e32 v16, v230
	v_mov_b32_e32 v17, v231
	s_nop 0
	v_mov_b32_e32 v18, v232
	v_mov_b32_e32 v19, v233
	v_mov_b32_e32 v20, v234
	v_mov_b32_e32 v21, v235
	ds_bpermute_b32 v115, v157, v113
	ds_bpermute_b32 v114, v157, v112
	v_mov_b32_e32 v23, v14
	v_mov_b32_e32 v22, v18
	v_mov_b32_e32 v24, v20
	v_mov_b32_e32 v25, v16
	v_pk_add_f32 v[22:23], v[22:23], v[24:25]
	v_add_f32_e32 v14, v19, v21
	v_add_f32_e32 v16, v15, v17
	v_mov_b32_e32 v15, v22
	v_mov_b32_e32 v17, v23
	v_pk_add_f32 v[14:15], v[14:15], v[16:17]
	ds_bpermute_b32 v17, v155, v15
	ds_bpermute_b32 v16, v155, v14
	s_waitcnt lgkmcnt(0)
	v_pk_add_f32 v[116:117], v[14:15], v[16:17]
	v_lshlrev_b64 v[14:15], 7, v[58:59]
	v_lshl_add_u64 v[18:19], v[6:7], 0, v[14:15]
	v_mov_b32_e32 v14, v236
	v_mov_b32_e32 v15, v237
	v_mov_b32_e32 v16, v238
	v_mov_b32_e32 v17, v239
	s_nop 0
	v_mov_b32_e32 v18, v240
	v_mov_b32_e32 v19, v241
	v_mov_b32_e32 v20, v242
	v_mov_b32_e32 v21, v243
	ds_bpermute_b32 v119, v157, v117
	ds_bpermute_b32 v118, v157, v116
	v_mov_b32_e32 v23, v14
	v_mov_b32_e32 v22, v18
	v_mov_b32_e32 v24, v20
	v_mov_b32_e32 v25, v16
	v_pk_add_f32 v[22:23], v[22:23], v[24:25]
	v_add_f32_e32 v14, v19, v21
	v_add_f32_e32 v16, v15, v17
	v_mov_b32_e32 v15, v22
	v_mov_b32_e32 v17, v23
	v_pk_add_f32 v[14:15], v[14:15], v[16:17]
	ds_bpermute_b32 v17, v155, v15
	ds_bpermute_b32 v16, v155, v14
	s_waitcnt lgkmcnt(0)
	v_pk_add_f32 v[120:121], v[14:15], v[16:17]
	v_lshlrev_b64 v[14:15], 7, v[60:61]
	v_lshl_add_u64 v[6:7], v[6:7], 0, v[14:15]
	v_mov_b32_e32 v14, v244
	v_mov_b32_e32 v15, v245
	v_mov_b32_e32 v16, v246
	v_mov_b32_e32 v17, v247
	v_mov_b32_e32 v18, v248
	v_mov_b32_e32 v19, v249
	v_mov_b32_e32 v20, v250
	v_mov_b32_e32 v21, v251
	ds_bpermute_b32 v123, v157, v121
	ds_bpermute_b32 v122, v157, v120
	v_mov_b32_e32 v7, v14
	v_mov_b32_e32 v6, v18
	v_mov_b32_e32 v22, v20
	v_mov_b32_e32 v23, v16
	v_pk_add_f32 v[6:7], v[6:7], v[22:23]
	v_add_f32_e32 v14, v19, v21
	v_add_f32_e32 v16, v15, v17
	v_mov_b32_e32 v15, v6
	v_mov_b32_e32 v17, v7
	v_pk_add_f32 v[6:7], v[14:15], v[16:17]
	ds_bpermute_b32 v15, v155, v7
	ds_bpermute_b32 v14, v155, v6
	s_waitcnt lgkmcnt(0)
	v_pk_add_f32 v[124:125], v[6:7], v[14:15]
	v_lshlrev_b64 v[6:7], 2, v[2:3]
	v_lshlrev_b64 v[2:3], 1, v[2:3]
	v_lshl_add_u64 v[74:75], v[0:1], 0, v[2:3]
	v_lshlrev_b64 v[0:1], 11, v[4:5]
	v_lshl_add_u64 v[0:1], s[44:45], 0, v[0:1]
	v_lshl_add_u64 v[76:77], v[0:1], 0, v[2:3]
	v_lshlrev_b64 v[0:1], 11, v[8:9]
	v_lshl_add_u64 v[0:1], s[44:45], 0, v[0:1]
	v_lshl_add_u64 v[78:79], v[0:1], 0, v[2:3]
	v_lshlrev_b64 v[0:1], 11, v[10:11]
	v_lshl_add_u64 v[0:1], s[44:45], 0, v[0:1]
	v_lshl_add_u64 v[80:81], v[0:1], 0, v[2:3]
	v_lshlrev_b64 v[0:1], 11, v[12:13]
	v_lshl_add_u64 v[0:1], s[44:45], 0, v[0:1]
	v_lshl_add_u64 v[146:147], v[0:1], 0, v[2:3]
	v_lshlrev_b64 v[0:1], 11, v[56:57]
	v_lshl_add_u64 v[0:1], s[44:45], 0, v[0:1]
	v_lshl_add_u64 v[56:57], v[0:1], 0, v[2:3]
	v_lshlrev_b64 v[0:1], 11, v[58:59]
	v_lshl_add_u64 v[0:1], s[44:45], 0, v[0:1]
	v_lshl_add_u64 v[58:59], v[0:1], 0, v[2:3]
	v_lshlrev_b64 v[0:1], 11, v[60:61]
	v_lshl_add_u64 v[0:1], s[44:45], 0, v[0:1]
	v_lshl_add_u64 v[62:63], s[28:29], 0, v[6:7]
	v_lshl_add_u64 v[72:73], s[30:31], 0, v[6:7]
	v_lshl_add_u64 v[148:149], v[0:1], 0, v[2:3]
	global_load_dwordx4 v[36:39], v[62:63], off offset:16
	global_load_dwordx4 v[44:47], v[62:63], off
	global_load_dwordx4 v[32:35], v[72:73], off offset:16
	global_load_dwordx4 v[40:43], v[72:73], off
	global_load_dwordx4 v[28:31], v[74:75], off
	global_load_dwordx4 v[24:27], v[76:77], off
	global_load_dwordx4 v[20:23], v[78:79], off
	global_load_dwordx4 v[16:19], v[80:81], off
	global_load_dwordx4 v[12:15], v[146:147], off
	global_load_dwordx4 v[8:11], v[56:57], off
	global_load_dwordx4 v[4:7], v[58:59], off
	global_load_dwordx4 v[0:3], v[148:149], off
	global_load_dwordx4 v[104:107], v[62:63], off offset:528
	global_load_dwordx4 v[108:111], v[62:63], off offset:512
	global_load_dwordx4 v[96:99], v[72:73], off offset:528
	global_load_dwordx4 v[100:103], v[72:73], off offset:512
	global_load_dwordx4 v[92:95], v[74:75], off offset:256
	global_load_dwordx4 v[88:91], v[76:77], off offset:256
	global_load_dwordx4 v[84:87], v[78:79], off offset:256
	s_nop 0
	global_load_dwordx4 v[80:83], v[80:81], off offset:256
	s_nop 0
	global_load_dwordx4 v[76:79], v[146:147], off offset:256
	global_load_dwordx4 v[72:75], v[56:57], off offset:256
	global_load_dwordx4 v[60:63], v[58:59], off offset:256
	s_nop 0
	global_load_dwordx4 v[56:59], v[148:149], off offset:256
	ds_bpermute_b32 v127, v157, v125
	ds_bpermute_b32 v126, v157, v124
	s_cbranch_vccnz .LBB0_1504
	s_barrier
	s_branch .LBB0_1504

.LBB0_1693:
	s_cmp_lg_u64 s[10:11], 0
	s_cbranch_scc1 .Lrs3skip16
	s_lshl_b32 s98, s78, 8
	s_add_i32 s98, s98, s15
	v_add_u32_e32 v150, s98, v153
	v_lshlrev_b32_e32 v200, 3, v151
	v_ashrrev_i32_e32 v201, 31, v200
	v_lshl_add_u64 v[200:201], v[200:201], 2, s[62:63]
	v_mov_b32_e32 v252, v150
	v_ashrrev_i32_e32 v253, 31, v252
	v_lshlrev_b64 v[252:253], 7, v[252:253]
	v_lshl_add_u64 v[252:253], v[200:201], 0, v[252:253]
	global_load_dwordx4 v[184:187], v[252:253], off offset:16
	global_load_dwordx4 v[188:191], v[252:253], off
	v_add_u32_e32 v252, 0x10, v150
	v_ashrrev_i32_e32 v253, 31, v252
	v_lshlrev_b64 v[252:253], 7, v[252:253]
	v_lshl_add_u64 v[252:253], v[200:201], 0, v[252:253]
	global_load_dwordx4 v[192:195], v[252:253], off offset:16
	global_load_dwordx4 v[196:199], v[252:253], off
	v_add_u32_e32 v252, 0x20, v150
	v_ashrrev_i32_e32 v253, 31, v252
	v_lshlrev_b64 v[252:253], 7, v[252:253]
	v_lshl_add_u64 v[252:253], v[200:201], 0, v[252:253]
	global_load_dwordx4 v[204:207], v[252:253], off offset:16
	global_load_dwordx4 v[208:211], v[252:253], off
	v_add_u32_e32 v252, 0x30, v150
	v_ashrrev_i32_e32 v253, 31, v252
	v_lshlrev_b64 v[252:253], 7, v[252:253]
	v_lshl_add_u64 v[252:253], v[200:201], 0, v[252:253]
	global_load_dwordx4 v[212:215], v[252:253], off offset:16
	global_load_dwordx4 v[216:219], v[252:253], off
	v_add_u32_e32 v252, 0x80, v150
	v_ashrrev_i32_e32 v253, 31, v252
	v_lshlrev_b64 v[252:253], 7, v[252:253]
	v_lshl_add_u64 v[252:253], v[200:201], 0, v[252:253]
	global_load_dwordx4 v[220:223], v[252:253], off offset:16
	global_load_dwordx4 v[224:227], v[252:253], off
	v_add_u32_e32 v252, 0x90, v150
	v_ashrrev_i32_e32 v253, 31, v252
	v_lshlrev_b64 v[252:253], 7, v[252:253]
	v_lshl_add_u64 v[252:253], v[200:201], 0, v[252:253]
	global_load_dwordx4 v[228:231], v[252:253], off offset:16
	global_load_dwordx4 v[232:235], v[252:253], off
	v_add_u32_e32 v252, 0xa0, v150
	v_ashrrev_i32_e32 v253, 31, v252
	v_lshlrev_b64 v[252:253], 7, v[252:253]
	v_lshl_add_u64 v[252:253], v[200:201], 0, v[252:253]
	global_load_dwordx4 v[236:239], v[252:253], off offset:16
	global_load_dwordx4 v[240:243], v[252:253], off
	v_add_u32_e32 v252, 0xb0, v150
	v_ashrrev_i32_e32 v253, 31, v252
	v_lshlrev_b64 v[252:253], 7, v[252:253]
	v_lshl_add_u64 v[252:253], v[200:201], 0, v[252:253]
	global_load_dwordx4 v[244:247], v[252:253], off offset:16
	global_load_dwordx4 v[248:251], v[252:253], off

.LBB0_1709:
	s_or_b64 exec, exec, s[46:47]
	s_and_b64 vcc, exec, s[10:11]
	s_mov_b64 s[10:11], -1
	s_cbranch_vccnz .LBB0_1678
	v_mov_b32_e32 v0, v153
	v_mov_b32_e32 v1, v151
	s_lshl_b32 s10, s78, 8
	s_add_i32 s10, s10, s15
	v_add_u32_e32 v0, s10, v0
	s_waitcnt lgkmcnt(0)
	v_lshlrev_b32_e32 v2, 3, v1
	v_ashrrev_i32_e32 v3, 31, v2
	v_ashrrev_i32_e32 v1, 31, v0
	v_lshl_add_u64 v[6:7], v[2:3], 2, s[62:63]
	v_lshlrev_b64 v[4:5], 7, v[0:1]
	v_lshl_add_u64 v[4:5], v[6:7], 0, v[4:5]
	s_waitcnt vmcnt(16)
	v_mov_b32_e32 v8, v184
	v_mov_b32_e32 v9, v185
	v_mov_b32_e32 v10, v186
	v_mov_b32_e32 v11, v187
	v_mov_b32_e32 v12, v188
	v_mov_b32_e32 v13, v189
	v_mov_b32_e32 v14, v190
	v_mov_b32_e32 v15, v191
	v_add_u32_e32 v56, 0x90, v0
	v_ashrrev_i32_e32 v57, 31, v56
	v_add_u32_e32 v58, 0xa0, v0
	v_ashrrev_i32_e32 v59, 31, v58
	v_add_u32_e32 v60, 0xb0, v0
	v_ashrrev_i32_e32 v61, 31, v60
	s_lshl_b32 s10, s73, 8
	s_or_b32 s10, s10, s66
	v_add_u32_e32 v2, s10, v2
	v_ashrrev_i32_e32 v3, 31, v2
	v_readlane_b32 s10, v255, 48
	v_readlane_b32 s11, v255, 49
	s_andn2_b64 vcc, exec, s[6:7]
	v_mov_b32_e32 v5, v8
	v_mov_b32_e32 v4, v12
	v_mov_b32_e32 v16, v14
	v_mov_b32_e32 v17, v10
	v_pk_add_f32 v[4:5], v[4:5], v[16:17]
	v_add_f32_e32 v8, v13, v15
	v_add_f32_e32 v10, v9, v11
	v_mov_b32_e32 v9, v4
	v_mov_b32_e32 v11, v5
	v_pk_add_f32 v[4:5], v[8:9], v[10:11]
	ds_bpermute_b32 v9, v155, v5
	ds_bpermute_b32 v8, v155, v4
	s_waitcnt lgkmcnt(0)
	v_pk_add_f32 v[48:49], v[4:5], v[8:9]
	v_add_u32_e32 v4, 16, v0
	v_ashrrev_i32_e32 v5, 31, v4
	v_lshlrev_b64 v[8:9], 7, v[4:5]
	v_lshl_add_u64 v[12:13], v[6:7], 0, v[8:9]
	v_mov_b32_e32 v8, v192
	v_mov_b32_e32 v9, v193
	v_mov_b32_e32 v10, v194
	v_mov_b32_e32 v11, v195
	s_nop 0
	v_mov_b32_e32 v12, v196
	v_mov_b32_e32 v13, v197
	v_mov_b32_e32 v14, v198
	v_mov_b32_e32 v15, v199
	ds_bpermute_b32 v51, v157, v49
	ds_bpermute_b32 v50, v157, v48
	v_mov_b32_e32 v17, v8
	v_mov_b32_e32 v16, v12
	v_mov_b32_e32 v18, v14
	v_mov_b32_e32 v19, v10
	v_pk_add_f32 v[16:17], v[16:17], v[18:19]
	v_add_f32_e32 v8, v13, v15
	v_add_f32_e32 v10, v9, v11
	v_mov_b32_e32 v9, v16
	v_mov_b32_e32 v11, v17
	v_pk_add_f32 v[8:9], v[8:9], v[10:11]
	ds_bpermute_b32 v11, v155, v9
	ds_bpermute_b32 v10, v155, v8
	s_waitcnt lgkmcnt(0)
	v_pk_add_f32 v[52:53], v[8:9], v[10:11]
	v_add_u32_e32 v8, 32, v0
	v_ashrrev_i32_e32 v9, 31, v8
	v_lshlrev_b64 v[10:11], 7, v[8:9]
	v_lshl_add_u64 v[14:15], v[6:7], 0, v[10:11]
	v_mov_b32_e32 v10, v204
	v_mov_b32_e32 v11, v205
	v_mov_b32_e32 v12, v206
	v_mov_b32_e32 v13, v207
	s_nop 0
	v_mov_b32_e32 v14, v208
	v_mov_b32_e32 v15, v209
	v_mov_b32_e32 v16, v210
	v_mov_b32_e32 v17, v211
	ds_bpermute_b32 v55, v157, v53
	ds_bpermute_b32 v54, v157, v52
	v_mov_b32_e32 v19, v10
	v_mov_b32_e32 v18, v14
	v_mov_b32_e32 v20, v16
	v_mov_b32_e32 v21, v12
	v_pk_add_f32 v[18:19], v[18:19], v[20:21]
	v_add_f32_e32 v10, v15, v17
	v_add_f32_e32 v12, v11, v13
	v_mov_b32_e32 v11, v18
	v_mov_b32_e32 v13, v19
	v_pk_add_f32 v[10:11], v[10:11], v[12:13]
	ds_bpermute_b32 v13, v155, v11
	ds_bpermute_b32 v12, v155, v10
	s_waitcnt lgkmcnt(0)
	v_pk_add_f32 v[64:65], v[10:11], v[12:13]
	v_add_u32_e32 v10, 48, v0
	v_ashrrev_i32_e32 v11, 31, v10
	v_lshlrev_b64 v[12:13], 7, v[10:11]
	v_lshl_add_u64 v[16:17], v[6:7], 0, v[12:13]
	v_mov_b32_e32 v12, v212
	v_mov_b32_e32 v13, v213
	v_mov_b32_e32 v14, v214
	v_mov_b32_e32 v15, v215
	s_nop 0
	v_mov_b32_e32 v16, v216
	v_mov_b32_e32 v17, v217
	v_mov_b32_e32 v18, v218
	v_mov_b32_e32 v19, v219
	ds_bpermute_b32 v67, v157, v65
	ds_bpermute_b32 v66, v157, v64
	v_mov_b32_e32 v21, v12
	v_mov_b32_e32 v20, v16
	v_mov_b32_e32 v22, v18
	v_mov_b32_e32 v23, v14
	v_pk_add_f32 v[20:21], v[20:21], v[22:23]
	v_add_f32_e32 v12, v17, v19
	v_add_f32_e32 v14, v13, v15
	v_mov_b32_e32 v13, v20
	v_mov_b32_e32 v15, v21
	v_pk_add_f32 v[12:13], v[12:13], v[14:15]
	ds_bpermute_b32 v15, v155, v13
	ds_bpermute_b32 v14, v155, v12
	s_waitcnt lgkmcnt(0)
	v_pk_add_f32 v[68:69], v[12:13], v[14:15]
	v_add_u32_e32 v12, 0x80, v0
	v_ashrrev_i32_e32 v13, 31, v12
	v_lshlrev_b64 v[14:15], 7, v[12:13]
	v_lshl_add_u64 v[18:19], v[6:7], 0, v[14:15]
	v_mov_b32_e32 v14, v220
	v_mov_b32_e32 v15, v221
	v_mov_b32_e32 v16, v222
	v_mov_b32_e32 v17, v223
	s_nop 0
	v_mov_b32_e32 v18, v224
	v_mov_b32_e32 v19, v225
	v_mov_b32_e32 v20, v226
	v_mov_b32_e32 v21, v227
	v_lshlrev_b64 v[0:1], 11, v[0:1]
	v_lshl_add_u64 v[0:1], s[44:45], 0, v[0:1]
	ds_bpermute_b32 v71, v157, v69
	ds_bpermute_b32 v70, v157, v68
	v_mov_b32_e32 v23, v14
	v_mov_b32_e32 v22, v18
	v_mov_b32_e32 v24, v20
	v_mov_b32_e32 v25, v16
	v_pk_add_f32 v[22:23], v[22:23], v[24:25]
	v_add_f32_e32 v14, v19, v21
	v_add_f32_e32 v16, v15, v17
	v_mov_b32_e32 v15, v22
	v_mov_b32_e32 v17, v23
	v_pk_add_f32 v[14:15], v[14:15], v[16:17]
	ds_bpermute_b32 v17, v155, v15
	ds_bpermute_b32 v16, v155, v14
	s_waitcnt lgkmcnt(0)
	v_pk_add_f32 v[112:113], v[14:15], v[16:17]
	v_lshlrev_b64 v[14:15], 7, v[56:57]
	v_lshl_add_u64 v[18:19], v[6:7], 0, v[14:15]
	v_mov_b32_e32 v14, v228
	v_mov_b32_e32 v15, v229
	v_mov_b32_e32 v16, v230
	v_mov_b32_e32 v17, v231
	s_nop 0
	v_mov_b32_e32 v18, v232
	v_mov_b32_e32 v19, v233
	v_mov_b32_e32 v20, v234
	v_mov_b32_e32 v21, v235
	ds_bpermute_b32 v115, v157, v113
	ds_bpermute_b32 v114, v157, v112
	v_mov_b32_e32 v23, v14
	v_mov_b32_e32 v22, v18
	v_mov_b32_e32 v24, v20
	v_mov_b32_e32 v25, v16
	v_pk_add_f32 v[22:23], v[22:23], v[24:25]
	v_add_f32_e32 v14, v19, v21
	v_add_f32_e32 v16, v15, v17
	v_mov_b32_e32 v15, v22
	v_mov_b32_e32 v17, v23
	v_pk_add_f32 v[14:15], v[14:15], v[16:17]
	ds_bpermute_b32 v17, v155, v15
	ds_bpermute_b32 v16, v155, v14
	s_waitcnt lgkmcnt(0)
	v_pk_add_f32 v[116:117], v[14:15], v[16:17]
	v_lshlrev_b64 v[14:15], 7, v[58:59]
	v_lshl_add_u64 v[18:19], v[6:7], 0, v[14:15]
	v_mov_b32_e32 v14, v236
	v_mov_b32_e32 v15, v237
	v_mov_b32_e32 v16, v238
	v_mov_b32_e32 v17, v239
	s_nop 0
	v_mov_b32_e32 v18, v240
	v_mov_b32_e32 v19, v241
	v_mov_b32_e32 v20, v242
	v_mov_b32_e32 v21, v243
	ds_bpermute_b32 v119, v157, v117
	ds_bpermute_b32 v118, v157, v116
	v_mov_b32_e32 v23, v14
	v_mov_b32_e32 v22, v18
	v_mov_b32_e32 v24, v20
	v_mov_b32_e32 v25, v16
	v_pk_add_f32 v[22:23], v[22:23], v[24:25]
	v_add_f32_e32 v14, v19, v21
	v_add_f32_e32 v16, v15, v17
	v_mov_b32_e32 v15, v22
	v_mov_b32_e32 v17, v23
	v_pk_add_f32 v[14:15], v[14:15], v[16:17]
	ds_bpermute_b32 v17, v155, v15
	ds_bpermute_b32 v16, v155, v14
	s_waitcnt lgkmcnt(0)
	v_pk_add_f32 v[120:121], v[14:15], v[16:17]
	v_lshlrev_b64 v[14:15], 7, v[60:61]
	v_lshl_add_u64 v[6:7], v[6:7], 0, v[14:15]
	v_mov_b32_e32 v14, v244
	v_mov_b32_e32 v15, v245
	v_mov_b32_e32 v16, v246
	v_mov_b32_e32 v17, v247
	v_mov_b32_e32 v18, v248
	v_mov_b32_e32 v19, v249
	v_mov_b32_e32 v20, v250
	v_mov_b32_e32 v21, v251
	ds_bpermute_b32 v123, v157, v121
	ds_bpermute_b32 v122, v157, v120
	v_mov_b32_e32 v7, v14
	v_mov_b32_e32 v6, v18
	v_mov_b32_e32 v22, v20
	v_mov_b32_e32 v23, v16
	v_pk_add_f32 v[6:7], v[6:7], v[22:23]
	v_add_f32_e32 v14, v19, v21
	v_add_f32_e32 v16, v15, v17
	v_mov_b32_e32 v15, v6
	v_mov_b32_e32 v17, v7
	v_pk_add_f32 v[6:7], v[14:15], v[16:17]
	ds_bpermute_b32 v15, v155, v7
	ds_bpermute_b32 v14, v155, v6
	s_waitcnt lgkmcnt(0)
	v_pk_add_f32 v[124:125], v[6:7], v[14:15]
	v_lshlrev_b64 v[6:7], 2, v[2:3]
	v_lshlrev_b64 v[2:3], 1, v[2:3]
	v_lshl_add_u64 v[74:75], v[0:1], 0, v[2:3]
	v_lshlrev_b64 v[0:1], 11, v[4:5]
	v_lshl_add_u64 v[0:1], s[44:45], 0, v[0:1]
	v_lshl_add_u64 v[76:77], v[0:1], 0, v[2:3]
	v_lshlrev_b64 v[0:1], 11, v[8:9]
	v_lshl_add_u64 v[0:1], s[44:45], 0, v[0:1]
	v_lshl_add_u64 v[78:79], v[0:1], 0, v[2:3]
	v_lshlrev_b64 v[0:1], 11, v[10:11]
	v_lshl_add_u64 v[0:1], s[44:45], 0, v[0:1]
	v_lshl_add_u64 v[80:81], v[0:1], 0, v[2:3]
	v_lshlrev_b64 v[0:1], 11, v[12:13]
	v_lshl_add_u64 v[0:1], s[44:45], 0, v[0:1]
	v_lshl_add_u64 v[146:147], v[0:1], 0, v[2:3]
	v_lshlrev_b64 v[0:1], 11, v[56:57]
	v_lshl_add_u64 v[0:1], s[44:45], 0, v[0:1]
	v_lshl_add_u64 v[56:57], v[0:1], 0, v[2:3]
	v_lshlrev_b64 v[0:1], 11, v[58:59]
	v_lshl_add_u64 v[0:1], s[44:45], 0, v[0:1]
	v_lshl_add_u64 v[58:59], v[0:1], 0, v[2:3]
	v_lshlrev_b64 v[0:1], 11, v[60:61]
	v_lshl_add_u64 v[0:1], s[44:45], 0, v[0:1]
	v_lshl_add_u64 v[62:63], s[10:11], 0, v[6:7]
	v_lshl_add_u64 v[72:73], s[0:1], 0, v[6:7]
	v_lshl_add_u64 v[148:149], v[0:1], 0, v[2:3]
	global_load_dwordx4 v[36:39], v[62:63], off offset:16
	global_load_dwordx4 v[44:47], v[62:63], off
	global_load_dwordx4 v[32:35], v[72:73], off offset:16
	global_load_dwordx4 v[40:43], v[72:73], off
	global_load_dwordx4 v[28:31], v[74:75], off
	global_load_dwordx4 v[24:27], v[76:77], off
	global_load_dwordx4 v[20:23], v[78:79], off
	global_load_dwordx4 v[16:19], v[80:81], off
	global_load_dwordx4 v[12:15], v[146:147], off
	global_load_dwordx4 v[8:11], v[56:57], off
	global_load_dwordx4 v[4:7], v[58:59], off
	global_load_dwordx4 v[0:3], v[148:149], off
	global_load_dwordx4 v[104:107], v[62:63], off offset:528
	global_load_dwordx4 v[108:111], v[62:63], off offset:512
	global_load_dwordx4 v[96:99], v[72:73], off offset:528
	global_load_dwordx4 v[100:103], v[72:73], off offset:512
	global_load_dwordx4 v[92:95], v[74:75], off offset:256
	global_load_dwordx4 v[88:91], v[76:77], off offset:256
	global_load_dwordx4 v[84:87], v[78:79], off offset:256
	s_nop 0
	global_load_dwordx4 v[80:83], v[80:81], off offset:256
	s_nop 0
	global_load_dwordx4 v[76:79], v[146:147], off offset:256
	global_load_dwordx4 v[72:75], v[56:57], off offset:256
	global_load_dwordx4 v[60:63], v[58:59], off offset:256
	s_nop 0
	global_load_dwordx4 v[56:59], v[148:149], off offset:256
	ds_bpermute_b32 v127, v157, v125
	ds_bpermute_b32 v126, v157, v124
	s_cbranch_vccnz .LBB0_1677
	s_barrier
	s_branch .LBB0_1677

.Lrlx21p0b:
	s_waitcnt vmcnt(24)
	s_branch .Lrlx21p0b_done
.LBB0_2265:
	s_mov_b64 s[36:37], 0

.LBB0_2274:
	ds_read_b128 v[128:131], v181
	ds_read_b128 v[132:135], v181 offset:1024
	ds_read_b128 v[136:139], v181 offset:2048
	ds_read_b128 v[140:143], v181 offset:3072
	ds_read_b128 v[144:147], v182
	ds_read_b128 v[148:151], v182 offset:1024
	ds_read_b128 v[168:171], v182 offset:2048
	ds_read_b128 v[172:175], v182 offset:3072
	s_add_u32 s46, s40, 0xfffe0080
	s_addc_u32 s47, s41, -1
	s_cmp_eq_u32 s82, 4
	s_cselect_b32 s61, s13, s47
	s_cselect_b32 s60, s78, s46
	s_cselect_b32 s47, s9, s81
	s_cselect_b32 s46, s79, s80
	v_lshl_add_u64 v[176:177], s[40:41], 0, v[160:161]
	s_add_i32 m0, s65, 0xc000
	ds_read_b128 v[184:187], v183
	ds_read_b128 v[188:191], v183 offset:1024
	ds_read_b128 v[192:195], v183 offset:2048
	ds_read_b128 v[196:199], v183 offset:3072
	ds_read_b128 v[200:203], v183 offset:4096
	ds_read_b128 v[204:207], v183 offset:5120
	ds_read_b128 v[212:215], v183 offset:6144
	ds_read_b128 v[216:219], v183 offset:7168
	global_load_lds_dwordx4 v[176:177], off
	v_lshl_add_u64 v[176:177], s[40:41], 0, v[162:163]
	s_add_i32 m0, s65, 0xe000
	s_nop 0
	global_load_lds_dwordx4 v[176:177], off
	s_cmp_lg_u32 s99, 0
	s_cbranch_scc1 .Lrlx21p0a
	s_waitcnt vmcnt(8)

.LBB0_2277:
	s_lshl_b32 s9, s36, 8
	v_mov_b32_e32 v128, v178
	v_mov_b32_e32 v129, v179
	s_add_i32 s9, s9, s70
	s_andn2_b64 vcc, exec, s[10:11]
	v_add_u32_e32 v170, s9, v128
	s_lshl_b32 s9, s37, 8
	s_or_b32 s9, s9, s71
	v_lshl_add_u32 v128, v129, 3, s9
	v_ashrrev_i32_e32 v129, 31, v128
	v_lshlrev_b64 v[168:169], 1, v[128:129]
	v_ashrrev_i32_e32 v171, 31, v170
	v_lshl_add_u64 v[172:173], s[56:57], 0, v[168:169]
	v_lshlrev_b64 v[128:129], 12, v[170:171]
	v_lshl_add_u64 v[128:129], v[172:173], 0, v[128:129]
	global_load_dwordx4 v[184:187], v[128:129], off
	global_load_dwordx4 v[188:191], v[128:129], off offset:256
	v_add_u32_e32 v192, 16, v170
	v_ashrrev_i32_e32 v193, 31, v192
	v_lshlrev_b64 v[128:129], 12, v[192:193]
	v_lshl_add_u64 v[128:129], v[172:173], 0, v[128:129]
	global_load_dwordx4 v[148:151], v[128:129], off
	global_load_dwordx4 v[144:147], v[128:129], off offset:256
	v_add_u32_e32 v176, 32, v170
	v_ashrrev_i32_e32 v177, 31, v176
	v_lshlrev_b64 v[128:129], 12, v[176:177]
	v_lshl_add_u64 v[128:129], v[172:173], 0, v[128:129]
	global_load_dwordx4 v[140:143], v[128:129], off
	global_load_dwordx4 v[132:135], v[128:129], off offset:256
	v_add_u32_e32 v174, 48, v170
	v_ashrrev_i32_e32 v175, 31, v174
	v_lshlrev_b64 v[128:129], 12, v[174:175]
	v_lshl_add_u64 v[128:129], v[172:173], 0, v[128:129]
	global_load_dwordx4 v[136:139], v[128:129], off
	s_nop 0
	global_load_dwordx4 v[128:131], v[128:129], off offset:256
	v_lshlrev_b64 v[194:195], 11, v[170:171]
	v_lshl_add_u64 v[194:195], s[42:43], 0, v[194:195]
	v_lshl_add_u64 v[194:195], v[194:195], 0, v[168:169]
	s_mov_b64 s[36:37], -1
	v_add_u32_e32 v200, 0x80, v170
	v_ashrrev_i32_e32 v201, 31, v200
	v_lshlrev_b64 v[252:253], 12, v[200:201]
	v_lshl_add_u64 v[200:201], v[172:173], 0, v[252:253]
	global_load_dwordx4 v[196:199], v[200:201], off
	global_load_dwordx4 v[204:207], v[200:201], off offset:256
	v_add_u32_e32 v200, 0x90, v170
	v_ashrrev_i32_e32 v201, 31, v200
	v_lshlrev_b64 v[252:253], 12, v[200:201]
	v_lshl_add_u64 v[200:201], v[172:173], 0, v[252:253]
	global_load_dwordx4 v[208:211], v[200:201], off
	global_load_dwordx4 v[212:215], v[200:201], off offset:256
	v_add_u32_e32 v200, 0xa0, v170
	v_ashrrev_i32_e32 v201, 31, v200
	v_lshlrev_b64 v[252:253], 12, v[200:201]
	v_lshl_add_u64 v[200:201], v[172:173], 0, v[252:253]
	global_load_dwordx4 v[216:219], v[200:201], off
	global_load_dwordx4 v[220:223], v[200:201], off offset:256
	v_add_u32_e32 v200, 0xb0, v170
	v_ashrrev_i32_e32 v201, 31, v200
	v_lshlrev_b64 v[252:253], 12, v[200:201]
	v_lshl_add_u64 v[200:201], v[172:173], 0, v[252:253]
	global_load_dwordx4 v[224:227], v[200:201], off
	global_load_dwordx4 v[228:231], v[200:201], off offset:256
	s_waitcnt vmcnt(8)
	v_lshlrev_b32_e32 v171, 16, v184
	v_mul_f32_e32 v124, v124, v171
	v_and_b32_e32 v171, 0xffff0000, v184
	v_mul_f32_e32 v125, v125, v171
	v_lshlrev_b32_e32 v171, 16, v185
	v_mul_f32_e32 v126, v126, v171
	v_and_b32_e32 v171, 0xffff0000, v185
	v_mul_f32_e32 v127, v127, v171
	v_lshlrev_b32_e32 v171, 16, v186
	v_mul_f32_e32 v171, v120, v171
	v_and_b32_e32 v120, 0xffff0000, v186
	v_mul_f32_e32 v184, v121, v120
	v_lshlrev_b32_e32 v120, 16, v187
	v_mul_f32_e32 v185, v122, v120
	v_and_b32_e32 v120, 0xffff0000, v187
	v_mul_f32_e32 v123, v123, v120
	v_cvt_pk_bf16_f32 v120, v124, v125
	v_cvt_pk_bf16_f32 v121, v126, v127
	v_cvt_pk_bf16_f32 v122, v171, v184
	v_cvt_pk_bf16_f32 v123, v185, v123
	global_store_dwordx4 v[194:195], v[120:123], off
	s_nop 1
	v_lshlrev_b32_e32 v120, 16, v188
	v_mul_f32_e32 v116, v116, v120
	v_and_b32_e32 v120, 0xffff0000, v188
	v_mul_f32_e32 v117, v117, v120
	v_lshlrev_b32_e32 v120, 16, v189
	v_mul_f32_e32 v118, v118, v120
	v_and_b32_e32 v120, 0xffff0000, v189
	v_mul_f32_e32 v119, v119, v120
	v_lshlrev_b32_e32 v120, 16, v190
	v_mul_f32_e32 v120, v112, v120
	v_and_b32_e32 v112, 0xffff0000, v190
	v_mul_f32_e32 v121, v113, v112
	v_lshlrev_b32_e32 v112, 16, v191
	v_mul_f32_e32 v122, v114, v112
	v_and_b32_e32 v112, 0xffff0000, v191
	v_mul_f32_e32 v115, v115, v112
	v_cvt_pk_bf16_f32 v112, v116, v117
	v_cvt_pk_bf16_f32 v113, v118, v119
	v_cvt_pk_bf16_f32 v114, v120, v121
	v_cvt_pk_bf16_f32 v115, v122, v115
	global_store_dwordx4 v[194:195], v[112:115], off offset:256
	s_nop 1
	v_lshlrev_b32_e32 v114, 16, v148
	v_mul_f32_e32 v108, v108, v114
	v_and_b32_e32 v114, 0xffff0000, v148
	v_mul_f32_e32 v109, v109, v114
	v_lshlrev_b32_e32 v114, 16, v149
	v_mul_f32_e32 v110, v110, v114
	v_and_b32_e32 v114, 0xffff0000, v149
	v_mul_f32_e32 v111, v111, v114
	v_lshlrev_b32_e32 v114, 16, v150
	v_mul_f32_e32 v114, v104, v114
	v_and_b32_e32 v104, 0xffff0000, v150
	v_lshlrev_b64 v[112:113], 11, v[192:193]
	v_mul_f32_e32 v115, v105, v104
	v_lshlrev_b32_e32 v104, 16, v151
	v_lshl_add_u64 v[112:113], s[42:43], 0, v[112:113]
	v_mul_f32_e32 v116, v106, v104
	v_and_b32_e32 v104, 0xffff0000, v151
	v_lshl_add_u64 v[112:113], v[112:113], 0, v[168:169]
	v_mul_f32_e32 v107, v107, v104
	v_cvt_pk_bf16_f32 v104, v108, v109
	v_cvt_pk_bf16_f32 v105, v110, v111
	v_cvt_pk_bf16_f32 v106, v114, v115
	v_cvt_pk_bf16_f32 v107, v116, v107
	global_store_dwordx4 v[112:113], v[104:107], off
	s_nop 1
	v_lshlrev_b32_e32 v104, 16, v144
	v_mul_f32_e32 v100, v100, v104
	v_and_b32_e32 v104, 0xffff0000, v144
	v_mul_f32_e32 v101, v101, v104
	v_lshlrev_b32_e32 v104, 16, v145
	v_mul_f32_e32 v102, v102, v104
	v_and_b32_e32 v104, 0xffff0000, v145
	v_mul_f32_e32 v103, v103, v104
	v_lshlrev_b32_e32 v104, 16, v146
	v_mul_f32_e32 v104, v92, v104
	v_and_b32_e32 v92, 0xffff0000, v146
	v_mul_f32_e32 v105, v93, v92
	v_lshlrev_b32_e32 v92, 16, v147
	v_mul_f32_e32 v106, v94, v92
	v_and_b32_e32 v92, 0xffff0000, v147
	v_mul_f32_e32 v95, v95, v92
	v_cvt_pk_bf16_f32 v92, v100, v101
	v_cvt_pk_bf16_f32 v93, v102, v103
	v_cvt_pk_bf16_f32 v94, v104, v105
	v_cvt_pk_bf16_f32 v95, v106, v95
	global_store_dwordx4 v[112:113], v[92:95], off offset:256
	v_add_u32_e32 v102, 0xb0, v170
	v_ashrrev_i32_e32 v103, 31, v102
	v_lshlrev_b32_e32 v94, 16, v140
	v_mul_f32_e32 v94, v96, v94
	v_lshlrev_b32_e32 v96, 16, v141
	v_and_b32_e32 v95, 0xffff0000, v140
	v_mul_f32_e32 v96, v98, v96
	v_lshlrev_b32_e32 v98, 16, v142
	v_mul_f32_e32 v95, v97, v95
	v_and_b32_e32 v97, 0xffff0000, v141
	v_mul_f32_e32 v98, v88, v98
	v_and_b32_e32 v88, 0xffff0000, v142
	v_lshlrev_b64 v[92:93], 11, v[176:177]
	v_mul_f32_e32 v97, v99, v97
	v_mul_f32_e32 v99, v89, v88
	v_lshlrev_b32_e32 v88, 16, v143
	v_lshl_add_u64 v[92:93], s[42:43], 0, v[92:93]
	v_mul_f32_e32 v100, v90, v88
	v_and_b32_e32 v88, 0xffff0000, v143
	v_lshl_add_u64 v[92:93], v[92:93], 0, v[168:169]
	v_mul_f32_e32 v91, v91, v88
	v_cvt_pk_bf16_f32 v88, v94, v95
	v_cvt_pk_bf16_f32 v89, v96, v97
	v_cvt_pk_bf16_f32 v90, v98, v99
	v_cvt_pk_bf16_f32 v91, v100, v91
	global_store_dwordx4 v[92:93], v[88:91], off
	v_add_u32_e32 v96, 0x80, v170
	v_ashrrev_i32_e32 v97, 31, v96
	v_lshlrev_b32_e32 v88, 16, v132
	v_mul_f32_e32 v84, v84, v88
	v_and_b32_e32 v88, 0xffff0000, v132
	v_mul_f32_e32 v85, v85, v88
	v_lshlrev_b32_e32 v88, 16, v133
	v_mul_f32_e32 v86, v86, v88
	v_and_b32_e32 v88, 0xffff0000, v133
	v_mul_f32_e32 v87, v87, v88
	v_lshlrev_b32_e32 v88, 16, v134
	v_mul_f32_e32 v88, v76, v88
	v_and_b32_e32 v76, 0xffff0000, v134
	v_mul_f32_e32 v89, v77, v76
	v_lshlrev_b32_e32 v76, 16, v135
	v_mul_f32_e32 v90, v78, v76
	v_and_b32_e32 v76, 0xffff0000, v135
	v_mul_f32_e32 v79, v79, v76
	v_cvt_pk_bf16_f32 v76, v84, v85
	v_cvt_pk_bf16_f32 v77, v86, v87
	v_cvt_pk_bf16_f32 v78, v88, v89
	v_cvt_pk_bf16_f32 v79, v90, v79
	global_store_dwordx4 v[92:93], v[76:79], off offset:256
	v_add_u32_e32 v98, 0x90, v170
	v_ashrrev_i32_e32 v99, 31, v98
	v_lshlrev_b32_e32 v78, 16, v136
	v_mul_f32_e32 v78, v80, v78
	v_lshlrev_b32_e32 v80, 16, v137
	v_and_b32_e32 v79, 0xffff0000, v136
	v_mul_f32_e32 v80, v82, v80
	v_lshlrev_b32_e32 v82, 16, v138
	v_mul_f32_e32 v79, v81, v79
	v_and_b32_e32 v81, 0xffff0000, v137
	v_mul_f32_e32 v82, v72, v82
	v_and_b32_e32 v72, 0xffff0000, v138
	v_lshlrev_b64 v[76:77], 11, v[174:175]
	v_mul_f32_e32 v81, v83, v81
	v_mul_f32_e32 v83, v73, v72
	v_lshlrev_b32_e32 v72, 16, v139
	v_lshl_add_u64 v[76:77], s[42:43], 0, v[76:77]
	v_mul_f32_e32 v84, v74, v72
	v_and_b32_e32 v72, 0xffff0000, v139
	v_lshl_add_u64 v[76:77], v[76:77], 0, v[168:169]
	v_mul_f32_e32 v75, v75, v72
	v_cvt_pk_bf16_f32 v72, v78, v79
	v_cvt_pk_bf16_f32 v73, v80, v81
	v_cvt_pk_bf16_f32 v74, v82, v83
	v_cvt_pk_bf16_f32 v75, v84, v75
	global_store_dwordx4 v[76:77], v[72:75], off
	v_add_u32_e32 v100, 0xa0, v170
	v_ashrrev_i32_e32 v101, 31, v100
	v_lshlrev_b32_e32 v72, 16, v128
	v_mul_f32_e32 v68, v68, v72
	v_and_b32_e32 v72, 0xffff0000, v128
	v_mul_f32_e32 v69, v69, v72
	v_lshlrev_b32_e32 v72, 16, v129
	v_mul_f32_e32 v70, v70, v72
	v_and_b32_e32 v72, 0xffff0000, v129
	v_mul_f32_e32 v71, v71, v72
	v_lshlrev_b32_e32 v72, 16, v130
	v_mul_f32_e32 v72, v64, v72
	v_and_b32_e32 v64, 0xffff0000, v130
	v_mul_f32_e32 v73, v65, v64
	v_lshlrev_b32_e32 v64, 16, v131
	v_mul_f32_e32 v74, v66, v64
	v_and_b32_e32 v64, 0xffff0000, v131
	v_mul_f32_e32 v67, v67, v64
	v_cvt_pk_bf16_f32 v64, v68, v69
	v_cvt_pk_bf16_f32 v65, v70, v71
	v_cvt_pk_bf16_f32 v66, v72, v73
	v_cvt_pk_bf16_f32 v67, v74, v67
	global_store_dwordx4 v[76:77], v[64:67], off offset:256
	v_lshlrev_b64 v[72:73], 12, v[98:99]
	v_lshl_add_u64 v[76:77], v[172:173], 0, v[72:73]
	v_lshlrev_b64 v[64:65], 12, v[96:97]
	v_lshl_add_u64 v[68:69], v[172:173], 0, v[64:65]
	s_waitcnt vmcnt(8)
	v_mov_b32_e32 v64, v196
	v_mov_b32_e32 v65, v197
	v_mov_b32_e32 v66, v198
	v_mov_b32_e32 v67, v199
	s_nop 0
	v_mov_b32_e32 v68, v204
	v_mov_b32_e32 v69, v205
	v_mov_b32_e32 v70, v206
	v_mov_b32_e32 v71, v207
	s_nop 0
	v_mov_b32_e32 v72, v208
	v_mov_b32_e32 v73, v209
	v_mov_b32_e32 v74, v210
	v_mov_b32_e32 v75, v211
	s_nop 0
	v_mov_b32_e32 v76, v212
	v_mov_b32_e32 v77, v213
	v_mov_b32_e32 v78, v214
	v_mov_b32_e32 v79, v215
	v_lshlrev_b64 v[80:81], 12, v[100:101]
	v_lshl_add_u64 v[84:85], v[172:173], 0, v[80:81]
	v_mov_b32_e32 v80, v216
	v_mov_b32_e32 v81, v217
	v_mov_b32_e32 v82, v218
	v_mov_b32_e32 v83, v219
	s_nop 0
	v_mov_b32_e32 v84, v220
	v_mov_b32_e32 v85, v221
	v_mov_b32_e32 v86, v222
	v_mov_b32_e32 v87, v223
	v_lshlrev_b64 v[88:89], 12, v[102:103]
	v_lshl_add_u64 v[92:93], v[172:173], 0, v[88:89]
	v_mov_b32_e32 v88, v224
	v_mov_b32_e32 v89, v225
	v_mov_b32_e32 v90, v226
	v_mov_b32_e32 v91, v227
	s_nop 0
	v_mov_b32_e32 v92, v228
	v_mov_b32_e32 v93, v229
	v_mov_b32_e32 v94, v230
	v_mov_b32_e32 v95, v231
	v_lshlrev_b64 v[96:97], 11, v[96:97]
	v_lshl_add_u64 v[96:97], s[42:43], 0, v[96:97]
	v_lshl_add_u64 v[96:97], v[96:97], 0, v[168:169]
	v_lshlrev_b32_e32 v104, 16, v64
	v_and_b32_e32 v64, 0xffff0000, v64
	v_mul_f32_e32 v61, v61, v64
	v_lshlrev_b32_e32 v64, 16, v65
	v_mul_f32_e32 v62, v62, v64
	v_and_b32_e32 v64, 0xffff0000, v65
	v_mul_f32_e32 v63, v63, v64
	v_lshlrev_b32_e32 v64, 16, v66
	v_mul_f32_e32 v64, v56, v64
	v_and_b32_e32 v56, 0xffff0000, v66
	v_mul_f32_e32 v65, v57, v56
	v_lshlrev_b32_e32 v56, 16, v67
	v_mul_f32_e32 v66, v58, v56
	v_and_b32_e32 v56, 0xffff0000, v67
	v_mul_f32_e32 v60, v60, v104
	v_mul_f32_e32 v59, v59, v56
	v_cvt_pk_bf16_f32 v56, v60, v61
	v_cvt_pk_bf16_f32 v57, v62, v63
	v_cvt_pk_bf16_f32 v58, v64, v65
	v_cvt_pk_bf16_f32 v59, v66, v59
	global_store_dwordx4 v[96:97], v[56:59], off
	s_nop 0
	v_lshlrev_b32_e32 v56, 16, v68
	v_mul_f32_e32 v52, v52, v56
	v_and_b32_e32 v56, 0xffff0000, v68
	v_mul_f32_e32 v53, v53, v56
	v_lshlrev_b32_e32 v56, 16, v69
	v_mul_f32_e32 v54, v54, v56
	v_and_b32_e32 v56, 0xffff0000, v69
	v_mul_f32_e32 v55, v55, v56
	v_lshlrev_b32_e32 v56, 16, v70
	v_mul_f32_e32 v56, v44, v56
	v_and_b32_e32 v44, 0xffff0000, v70
	v_mul_f32_e32 v57, v45, v44
	v_lshlrev_b32_e32 v44, 16, v71
	v_mul_f32_e32 v58, v46, v44
	v_and_b32_e32 v44, 0xffff0000, v71
	v_mul_f32_e32 v47, v47, v44
	v_cvt_pk_bf16_f32 v44, v52, v53
	v_cvt_pk_bf16_f32 v45, v54, v55
	v_cvt_pk_bf16_f32 v46, v56, v57
	v_cvt_pk_bf16_f32 v47, v58, v47
	global_store_dwordx4 v[96:97], v[44:47], off offset:256
	s_nop 0
	v_lshlrev_b32_e32 v46, 16, v72
	v_mul_f32_e32 v46, v48, v46
	v_lshlrev_b32_e32 v48, 16, v73
	v_and_b32_e32 v47, 0xffff0000, v72
	v_mul_f32_e32 v48, v50, v48
	v_lshlrev_b32_e32 v50, 16, v74
	v_mul_f32_e32 v47, v49, v47
	v_and_b32_e32 v49, 0xffff0000, v73
	v_mul_f32_e32 v50, v40, v50
	v_and_b32_e32 v40, 0xffff0000, v74
	v_lshlrev_b64 v[44:45], 11, v[98:99]
	v_mul_f32_e32 v49, v51, v49
	v_mul_f32_e32 v51, v41, v40
	v_lshlrev_b32_e32 v40, 16, v75
	v_lshl_add_u64 v[44:45], s[42:43], 0, v[44:45]
	v_mul_f32_e32 v52, v42, v40
	v_and_b32_e32 v40, 0xffff0000, v75
	v_lshl_add_u64 v[44:45], v[44:45], 0, v[168:169]
	v_mul_f32_e32 v43, v43, v40
	v_cvt_pk_bf16_f32 v40, v46, v47
	v_cvt_pk_bf16_f32 v41, v48, v49
	v_cvt_pk_bf16_f32 v42, v50, v51
	v_cvt_pk_bf16_f32 v43, v52, v43
	global_store_dwordx4 v[44:45], v[40:43], off
	s_nop 0
	v_lshlrev_b32_e32 v40, 16, v76
	v_mul_f32_e32 v36, v36, v40
	v_and_b32_e32 v40, 0xffff0000, v76
	v_mul_f32_e32 v37, v37, v40
	v_lshlrev_b32_e32 v40, 16, v77
	v_mul_f32_e32 v38, v38, v40
	v_and_b32_e32 v40, 0xffff0000, v77
	v_mul_f32_e32 v39, v39, v40
	v_lshlrev_b32_e32 v40, 16, v78
	v_mul_f32_e32 v40, v28, v40
	v_and_b32_e32 v28, 0xffff0000, v78
	v_mul_f32_e32 v41, v29, v28
	v_lshlrev_b32_e32 v28, 16, v79
	v_mul_f32_e32 v42, v30, v28
	v_and_b32_e32 v28, 0xffff0000, v79
	v_mul_f32_e32 v31, v31, v28
	v_cvt_pk_bf16_f32 v28, v36, v37
	v_cvt_pk_bf16_f32 v29, v38, v39
	v_cvt_pk_bf16_f32 v30, v40, v41
	v_cvt_pk_bf16_f32 v31, v42, v31
	global_store_dwordx4 v[44:45], v[28:31], off offset:256
	s_nop 0
	v_lshlrev_b32_e32 v30, 16, v80
	v_mul_f32_e32 v30, v32, v30
	v_lshlrev_b32_e32 v32, 16, v81
	v_and_b32_e32 v31, 0xffff0000, v80
	v_mul_f32_e32 v32, v34, v32
	v_lshlrev_b32_e32 v34, 16, v82
	v_mul_f32_e32 v31, v33, v31
	v_and_b32_e32 v33, 0xffff0000, v81
	v_mul_f32_e32 v34, v24, v34
	v_and_b32_e32 v24, 0xffff0000, v82
	v_lshlrev_b64 v[28:29], 11, v[100:101]
	v_mul_f32_e32 v33, v35, v33
	v_mul_f32_e32 v35, v25, v24
	v_lshlrev_b32_e32 v24, 16, v83
	v_lshl_add_u64 v[28:29], s[42:43], 0, v[28:29]
	v_mul_f32_e32 v36, v26, v24
	v_and_b32_e32 v24, 0xffff0000, v83
	v_lshl_add_u64 v[28:29], v[28:29], 0, v[168:169]
	v_mul_f32_e32 v27, v27, v24
	v_cvt_pk_bf16_f32 v24, v30, v31
	v_cvt_pk_bf16_f32 v25, v32, v33
	v_cvt_pk_bf16_f32 v26, v34, v35
	v_cvt_pk_bf16_f32 v27, v36, v27
	global_store_dwordx4 v[28:29], v[24:27], off
	s_nop 0
	v_lshlrev_b32_e32 v24, 16, v84
	v_mul_f32_e32 v20, v20, v24
	v_and_b32_e32 v24, 0xffff0000, v84
	v_mul_f32_e32 v21, v21, v24
	v_lshlrev_b32_e32 v24, 16, v85
	v_mul_f32_e32 v22, v22, v24
	v_and_b32_e32 v24, 0xffff0000, v85
	v_mul_f32_e32 v23, v23, v24
	v_lshlrev_b32_e32 v24, 16, v86
	v_mul_f32_e32 v24, v12, v24
	v_and_b32_e32 v12, 0xffff0000, v86
	v_mul_f32_e32 v25, v13, v12
	v_lshlrev_b32_e32 v12, 16, v87
	v_mul_f32_e32 v26, v14, v12
	v_and_b32_e32 v12, 0xffff0000, v87
	v_mul_f32_e32 v15, v15, v12
	v_cvt_pk_bf16_f32 v12, v20, v21
	v_cvt_pk_bf16_f32 v13, v22, v23
	v_cvt_pk_bf16_f32 v14, v24, v25
	v_cvt_pk_bf16_f32 v15, v26, v15
	global_store_dwordx4 v[28:29], v[12:15], off offset:256
	s_nop 0
	v_lshlrev_b32_e32 v14, 16, v88
	v_mul_f32_e32 v14, v16, v14
	v_lshlrev_b32_e32 v16, 16, v89
	v_and_b32_e32 v15, 0xffff0000, v88
	v_mul_f32_e32 v16, v18, v16
	v_lshlrev_b32_e32 v18, 16, v90
	v_mul_f32_e32 v15, v17, v15
	v_and_b32_e32 v17, 0xffff0000, v89
	v_mul_f32_e32 v18, v8, v18
	v_and_b32_e32 v8, 0xffff0000, v90
	v_lshlrev_b64 v[12:13], 11, v[102:103]
	v_mul_f32_e32 v17, v19, v17
	v_mul_f32_e32 v19, v9, v8
	v_lshlrev_b32_e32 v8, 16, v91
	v_lshl_add_u64 v[12:13], s[42:43], 0, v[12:13]
	v_mul_f32_e32 v20, v10, v8
	v_and_b32_e32 v8, 0xffff0000, v91
	v_lshl_add_u64 v[12:13], v[12:13], 0, v[168:169]
	v_mul_f32_e32 v11, v11, v8
	v_cvt_pk_bf16_f32 v8, v14, v15
	v_cvt_pk_bf16_f32 v9, v16, v17
	v_cvt_pk_bf16_f32 v10, v18, v19
	v_cvt_pk_bf16_f32 v11, v20, v11
	global_store_dwordx4 v[12:13], v[8:11], off
	s_nop 0
	v_lshlrev_b32_e32 v8, 16, v92
	v_mul_f32_e32 v4, v4, v8
	v_and_b32_e32 v8, 0xffff0000, v92
	v_mul_f32_e32 v5, v5, v8
	v_lshlrev_b32_e32 v8, 16, v93
	v_mul_f32_e32 v6, v6, v8
	v_and_b32_e32 v8, 0xffff0000, v93
	v_mul_f32_e32 v7, v7, v8
	v_lshlrev_b32_e32 v8, 16, v94
	v_mul_f32_e32 v8, v0, v8
	v_and_b32_e32 v0, 0xffff0000, v94
	v_mul_f32_e32 v9, v1, v0
	v_lshlrev_b32_e32 v0, 16, v95
	v_mul_f32_e32 v10, v2, v0
	v_and_b32_e32 v0, 0xffff0000, v95
	v_mul_f32_e32 v3, v3, v0
	v_cvt_pk_bf16_f32 v0, v4, v5
	v_cvt_pk_bf16_f32 v1, v6, v7
	v_cvt_pk_bf16_f32 v2, v8, v9
	v_cvt_pk_bf16_f32 v3, v10, v3
	global_store_dwordx4 v[12:13], v[0:3], off offset:256
	s_mov_b32 s99, 1
	s_cbranch_vccnz .LBB0_2266
	s_andn2_b64 vcc, exec, s[0:1]
	s_cbranch_vccnz .LBB0_2265
	s_barrier
	s_branch .LBB0_2265

.LBB0_2288:
	v_bfe_u32 v213, v8, 4, 2
	v_and_b32_e32 v212, 15, v8
	v_lshlrev_b32_e32 v9, 4, v213
	v_lshlrev_b32_e32 v8, 2, v8
	s_sext_i32_i8 s47, s4
	v_lshl_or_b32 v9, v212, 6, v9
	s_lshl_b32 s4, s5, 13
	v_and_b32_e32 v8, 32, v8
	v_bitop3_b32 v10, v9, s4, v8 bitop3:0xde
	s_lshl_b32 s4, s7, 5
	s_and_b32 s70, s4, 0x60
	s_lshl_b32 s4, s70, 7
	s_lshl_b32 s69, s5, 6
	v_bitop3_b32 v214, v9, s4, v8 bitop3:0xde
	s_mov_b64 s[4:5], 0x80
	s_add_i32 m0, s65, 0x18000
	v_lshl_add_u64 v[6:7], v[6:7], 0, s[4:5]
	s_waitcnt vmcnt(2)
	s_barrier
	global_load_lds_dwordx4 v[6:7], off
	v_lshl_add_u64 v[4:5], v[4:5], 0, s[4:5]
	s_add_i32 m0, s65, 0x1a000
	s_add_i32 s71, s65, 0x8000
	s_add_i32 s72, s65, 0xa000
	global_load_lds_dwordx4 v[4:5], off
	v_lshl_add_u64 v[0:1], v[0:1], 0, s[4:5]
	s_mov_b32 m0, s71
	s_add_u32 s8, s82, 0x10080
	global_load_lds_dwordx4 v[0:1], off
	v_lshl_add_u64 v[0:1], v[2:3], 0, s[4:5]
	s_mov_b32 m0, s72
	s_addc_u32 s9, s83, 0
	global_load_lds_dwordx4 v[0:1], off
	s_add_i32 m0, s65, 0x1c000
	v_lshl_add_u64 v[0:1], s[8:9], 0, v[186:187]
	global_load_lds_dwordx4 v[0:1], off
	v_lshl_add_u64 v[0:1], s[8:9], 0, v[190:191]
	s_add_i32 m0, s65, 0x1e000
	s_cmpk_lt_u32 s6, 0x100
	global_load_lds_dwordx4 v[0:1], off
	s_cselect_b64 s[6:7], -1, 0
	s_add_u32 s8, s38, s2
	s_waitcnt vmcnt(6)
	s_addc_u32 s9, s33, s3
	s_add_i32 s79, 0, 0x10000
	s_add_i32 s81, 0, 0x14000
	v_add_u32_e32 v215, s79, v214
	v_add_u32_e32 v216, s81, v214
	s_add_i32 s79, s79, s64
	s_add_i32 s81, s81, s64
	v_mov_b64_e32 v[192:193], 0x200
	v_mov_b64_e32 v[194:195], 0x1ff
	v_add_u32_e32 v217, 0, v10
	s_add_i32 s73, s65, 0xc000
	s_add_i32 s78, s65, 0xe000
	s_mov_b64 s[12:13], 0x100
	s_mov_b64 s[14:15], 0x180
	s_add_i32 s80, s79, 0x2000
	s_add_i32 s84, s81, 0x2000
	s_barrier
	s_mov_b32 s99, 0
	s_branch .LBB0_2291

.Lrlx21p1b:
	s_waitcnt vmcnt(24)
	s_branch .Lrlx21p1b_done
.LBB0_2289:
	s_add_u32 s8, s8, s38
	s_addc_u32 s9, s9, s33
	s_mov_b64 s[46:47], 0

.LBB0_2297:
	ds_read_b128 v[0:3], v215
	ds_read_b128 v[4:7], v215 offset:1024
	ds_read_b128 v[8:11], v215 offset:2048
	ds_read_b128 v[12:15], v215 offset:3072
	ds_read_b128 v[16:19], v216
	ds_read_b128 v[20:23], v216 offset:1024
	ds_read_b128 v[24:27], v216 offset:2048
	ds_read_b128 v[28:31], v216 offset:3072
	s_ashr_i32 s37, s36, 31
	s_lshl_b64 s[40:41], s[36:37], 17
	v_readlane_b32 s60, v255, 24
	v_readlane_b32 s61, v255, 25
	s_add_u32 s40, s60, s40
	s_addc_u32 s41, s61, s41
	s_and_b64 s[60:61], s[10:11], exec
	s_cselect_b32 s95, s41, s75
	s_cselect_b32 s94, s40, s74
	s_ashr_i32 s35, s34, 31
	s_lshl_b64 s[60:61], s[34:35], 17
	v_readlane_b32 s86, v255, 30
	v_readlane_b32 s87, v255, 31
	s_add_u32 s60, s86, s60
	s_addc_u32 s61, s87, s61
	s_and_b64 s[86:87], s[10:11], exec
	s_cselect_b32 s89, s61, s83
	s_cselect_b32 s88, s60, s82
	s_add_u32 s86, s74, 0x10080
	s_addc_u32 s87, s75, 0
	s_mov_b32 m0, s73
	v_lshl_add_u64 v[64:65], s[86:87], 0, v[184:185]
	ds_read_b128 v[32:35], v217
	ds_read_b128 v[36:39], v217 offset:1024
	ds_read_b128 v[40:43], v217 offset:2048
	ds_read_b128 v[44:47], v217 offset:3072
	ds_read_b128 v[48:51], v217 offset:4096
	ds_read_b128 v[52:55], v217 offset:5120
	ds_read_b128 v[56:59], v217 offset:6144
	ds_read_b128 v[60:63], v217 offset:7168
	global_load_lds_dwordx4 v[64:65], off
	v_lshl_add_u64 v[64:65], s[86:87], 0, v[188:189]
	s_mov_b32 m0, s78
	s_nop 0
	global_load_lds_dwordx4 v[64:65], off
	s_cmp_lg_u32 s99, 0
	s_cbranch_scc1 .Lrlx21p1a
	s_waitcnt vmcnt(8)

.Lrlx21p1b_done:
	s_mov_b32 s99, 0
	s_waitcnt lgkmcnt(0)
	s_barrier
	s_setprio 1
	s_waitcnt lgkmcnt(0)
	v_mfma_f32_16x16x32_bf16 v[128:131], v[0:3], v[60:63], 0
	v_mfma_f32_16x16x32_bf16 v[136:139], v[0:3], v[104:107], 0
	v_mfma_f32_16x16x32_bf16 v[144:147], v[0:3], v[112:115], 0
	v_mfma_f32_16x16x32_bf16 v[0:3], v[0:3], v[120:123], 0
	v_mfma_f32_16x16x32_bf16 v[128:131], v[4:7], v[100:103], v[128:131]
	v_mfma_f32_16x16x32_bf16 v[136:139], v[4:7], v[108:111], v[136:139]
	v_mfma_f32_16x16x32_bf16 v[144:147], v[4:7], v[116:119], v[144:147]
	v_mfma_f32_16x16x32_bf16 v[0:3], v[4:7], v[124:127], v[0:3]
	v_mfma_f32_16x16x32_bf16 v[4:7], v[8:11], v[120:123], 0
	v_mfma_f32_16x16x32_bf16 v[132:135], v[8:11], v[60:63], 0
	v_mfma_f32_16x16x32_bf16 v[140:143], v[8:11], v[104:107], 0
	v_mfma_f32_16x16x32_bf16 v[148:151], v[8:11], v[112:115], 0
	v_mfma_f32_16x16x32_bf16 v[4:7], v[12:15], v[124:127], v[4:7]
	v_mfma_f32_16x16x32_bf16 v[132:135], v[12:15], v[100:103], v[132:135]
	v_mfma_f32_16x16x32_bf16 v[140:143], v[12:15], v[108:111], v[140:143]
	v_mfma_f32_16x16x32_bf16 v[148:151], v[12:15], v[116:119], v[148:151]
	s_setprio 0
	s_setprio 1
	v_mfma_f32_16x16x32_bf16 v[8:11], v[16:19], v[60:63], 0
	v_mfma_f32_16x16x32_bf16 v[12:15], v[24:27], v[60:63], 0
	v_mfma_f32_16x16x32_bf16 v[8:11], v[20:23], v[100:103], v[8:11]
	v_mfma_f32_16x16x32_bf16 v[12:15], v[28:31], v[100:103], v[12:15]
	v_mfma_f32_16x16x32_bf16 v[60:63], v[16:19], v[104:107], 0
	v_mfma_f32_16x16x32_bf16 v[100:103], v[24:27], v[104:107], 0
	v_mfma_f32_16x16x32_bf16 v[104:107], v[16:19], v[112:115], 0
	v_mfma_f32_16x16x32_bf16 v[16:19], v[16:19], v[120:123], 0
	v_mfma_f32_16x16x32_bf16 v[60:63], v[20:23], v[108:111], v[60:63]
	v_mfma_f32_16x16x32_bf16 v[100:103], v[28:31], v[108:111], v[100:103]
	v_mfma_f32_16x16x32_bf16 v[104:107], v[20:23], v[116:119], v[104:107]
	v_mfma_f32_16x16x32_bf16 v[108:111], v[24:27], v[112:115], 0
	v_mfma_f32_16x16x32_bf16 v[16:19], v[20:23], v[124:127], v[16:19]
	v_mfma_f32_16x16x32_bf16 v[20:23], v[24:27], v[120:123], 0
	v_mfma_f32_16x16x32_bf16 v[108:111], v[28:31], v[116:119], v[108:111]
	v_mfma_f32_16x16x32_bf16 v[20:23], v[28:31], v[124:127], v[20:23]
	s_setprio 0
	s_barrier
	s_add_i32 s85, 0, 0x18000
	s_add_i32 s37, 0, 0x1c000
	v_add_u32_e32 v226, s85, v214
	v_add_u32_e32 v227, s37, v214
	ds_read_b128 v[24:27], v226
	ds_read_b128 v[28:31], v226 offset:1024
	ds_read_b128 v[112:115], v226 offset:2048
	ds_read_b128 v[116:119], v226 offset:3072
	ds_read_b128 v[120:123], v227
	ds_read_b128 v[124:127], v227 offset:1024
	ds_read_b128 v[152:155], v227 offset:2048
	ds_read_b128 v[156:159], v227 offset:3072
	s_add_u32 s86, s74, 0x10100
	s_addc_u32 s87, s75, 0
	s_mov_b32 m0, s67
	v_lshl_add_u64 v[218:219], s[86:87], 0, v[184:185]
	ds_read_b128 v[160:163], v217 offset:32768
	ds_read_b128 v[164:167], v217 offset:33792
	ds_read_b128 v[168:171], v217 offset:34816
	ds_read_b128 v[172:175], v217 offset:35840
	ds_read_b128 v[176:179], v217 offset:36864
	ds_read_b128 v[180:183], v217 offset:37888
	ds_read_b128 v[196:199], v217 offset:38912
	ds_read_b128 v[200:203], v217 offset:39936
	global_load_lds_dwordx4 v[218:219], off
	v_lshl_add_u64 v[218:219], s[86:87], 0, v[188:189]
	s_mov_b32 m0, s68
	s_nop 0
	global_load_lds_dwordx4 v[218:219], off
	s_waitcnt vmcnt(8)
	s_waitcnt lgkmcnt(0)
	s_barrier
	s_setprio 1
	s_waitcnt lgkmcnt(0)
	v_mfma_f32_16x16x32_bf16 v[64:67], v[24:27], v[160:163], v[64:67]
	v_mfma_f32_16x16x32_bf16 v[68:71], v[112:115], v[160:163], v[68:71]
	v_mfma_f32_16x16x32_bf16 v[72:75], v[24:27], v[168:171], v[72:75]
	v_mfma_f32_16x16x32_bf16 v[76:79], v[112:115], v[168:171], v[76:79]
	v_mfma_f32_16x16x32_bf16 v[80:83], v[24:27], v[176:179], v[80:83]
	v_mfma_f32_16x16x32_bf16 v[84:87], v[112:115], v[176:179], v[84:87]
	v_mfma_f32_16x16x32_bf16 v[88:91], v[24:27], v[196:199], v[88:91]
	v_mfma_f32_16x16x32_bf16 v[92:95], v[112:115], v[196:199], v[92:95]
	v_mfma_f32_16x16x32_bf16 v[64:67], v[28:31], v[164:167], v[64:67]
	v_mfma_f32_16x16x32_bf16 v[68:71], v[116:119], v[164:167], v[68:71]
	v_mfma_f32_16x16x32_bf16 v[72:75], v[28:31], v[172:175], v[72:75]
	v_mfma_f32_16x16x32_bf16 v[76:79], v[116:119], v[172:175], v[76:79]
	v_mfma_f32_16x16x32_bf16 v[80:83], v[28:31], v[180:183], v[80:83]
	v_mfma_f32_16x16x32_bf16 v[84:87], v[116:119], v[180:183], v[84:87]
	v_mfma_f32_16x16x32_bf16 v[88:91], v[28:31], v[200:203], v[88:91]
	v_mfma_f32_16x16x32_bf16 v[92:95], v[116:119], v[200:203], v[92:95]
	s_setprio 0
	s_setprio 1
	v_mfma_f32_16x16x32_bf16 v[96:99], v[120:123], v[160:163], v[96:99]
	v_mfma_f32_16x16x32_bf16 v[32:35], v[152:155], v[160:163], v[32:35]
	v_mfma_f32_16x16x32_bf16 v[36:39], v[120:123], v[168:171], v[36:39]
	v_mfma_f32_16x16x32_bf16 v[40:43], v[152:155], v[168:171], v[40:43]
	v_mfma_f32_16x16x32_bf16 v[44:47], v[120:123], v[176:179], v[44:47]
	v_mfma_f32_16x16x32_bf16 v[48:51], v[152:155], v[176:179], v[48:51]
	v_mfma_f32_16x16x32_bf16 v[52:55], v[120:123], v[196:199], v[52:55]
	v_mfma_f32_16x16x32_bf16 v[56:59], v[152:155], v[196:199], v[56:59]
	v_mfma_f32_16x16x32_bf16 v[96:99], v[124:127], v[164:167], v[96:99]
	v_mfma_f32_16x16x32_bf16 v[32:35], v[156:159], v[164:167], v[32:35]
	v_mfma_f32_16x16x32_bf16 v[36:39], v[124:127], v[172:175], v[36:39]
	v_mfma_f32_16x16x32_bf16 v[40:43], v[156:159], v[172:175], v[40:43]
	v_mfma_f32_16x16x32_bf16 v[44:47], v[124:127], v[180:183], v[44:47]
	v_mfma_f32_16x16x32_bf16 v[48:51], v[156:159], v[180:183], v[48:51]
	v_mfma_f32_16x16x32_bf16 v[52:55], v[124:127], v[200:203], v[52:55]
	v_mfma_f32_16x16x32_bf16 v[56:59], v[156:159], v[200:203], v[56:59]
	s_setprio 0
	s_barrier
	s_add_i32 s85, s85, s64
	s_add_i32 s35, s85, 0x2000
	v_lshl_add_u64 v[204:205], v[204:205], 0, s[14:15]
	s_mov_b32 m0, s85
	s_add_u32 s82, s82, 0x10180
	ds_read_b128 v[160:163], v217 offset:49152
	ds_read_b128 v[164:167], v217 offset:50176
	ds_read_b128 v[168:171], v217 offset:51200
	ds_read_b128 v[172:175], v217 offset:52224
	ds_read_b128 v[176:179], v217 offset:53248
	ds_read_b128 v[180:183], v217 offset:54272
	ds_read_b128 v[196:199], v217 offset:55296
	ds_read_b128 v[200:203], v217 offset:56320
	global_load_lds_dwordx4 v[204:205], off
	v_lshl_add_u64 v[204:205], v[206:207], 0, s[14:15]
	s_mov_b32 m0, s35
	s_addc_u32 s83, s83, 0
	s_add_i32 s37, s37, s64
	global_load_lds_dwordx4 v[204:205], off
	v_lshl_add_u64 v[204:205], s[82:83], 0, v[186:187]
	s_mov_b32 m0, s37
	s_nop 0
	global_load_lds_dwordx4 v[204:205], off
	v_lshl_add_u64 v[204:205], s[82:83], 0, v[190:191]
	s_add_i32 s82, s37, 0x2000
	s_mov_b32 m0, s82
	s_nop 0
	global_load_lds_dwordx4 v[204:205], off
	v_lshl_add_u64 v[204:205], v[208:209], 0, s[14:15]
	s_mov_b32 m0, s71
	s_nop 0
	global_load_lds_dwordx4 v[204:205], off
	v_lshl_add_u64 v[204:205], v[210:211], 0, s[14:15]
	s_mov_b32 m0, s72
	s_nop 0
	global_load_lds_dwordx4 v[204:205], off
	s_waitcnt vmcnt(8)
	s_waitcnt lgkmcnt(0)
	s_barrier
	s_setprio 1
	s_waitcnt lgkmcnt(0)
	v_mfma_f32_16x16x32_bf16 v[0:3], v[24:27], v[196:199], v[0:3]
	v_mfma_f32_16x16x32_bf16 v[4:7], v[112:115], v[196:199], v[4:7]
	v_mfma_f32_16x16x32_bf16 v[128:131], v[24:27], v[160:163], v[128:131]
	v_mfma_f32_16x16x32_bf16 v[132:135], v[112:115], v[160:163], v[132:135]
	v_mfma_f32_16x16x32_bf16 v[136:139], v[24:27], v[168:171], v[136:139]
	v_mfma_f32_16x16x32_bf16 v[140:143], v[112:115], v[168:171], v[140:143]
	v_mfma_f32_16x16x32_bf16 v[144:147], v[24:27], v[176:179], v[144:147]
	v_mfma_f32_16x16x32_bf16 v[148:151], v[112:115], v[176:179], v[148:151]
	v_mfma_f32_16x16x32_bf16 v[0:3], v[28:31], v[200:203], v[0:3]
	v_mfma_f32_16x16x32_bf16 v[4:7], v[116:119], v[200:203], v[4:7]
	v_mfma_f32_16x16x32_bf16 v[128:131], v[28:31], v[164:167], v[128:131]
	v_mfma_f32_16x16x32_bf16 v[132:135], v[116:119], v[164:167], v[132:135]
	v_mfma_f32_16x16x32_bf16 v[136:139], v[28:31], v[172:175], v[136:139]
	v_mfma_f32_16x16x32_bf16 v[140:143], v[116:119], v[172:175], v[140:143]
	v_mfma_f32_16x16x32_bf16 v[144:147], v[28:31], v[180:183], v[144:147]
	v_mfma_f32_16x16x32_bf16 v[148:151], v[116:119], v[180:183], v[148:151]
	s_setprio 0
	s_setprio 1
	v_mfma_f32_16x16x32_bf16 v[8:11], v[120:123], v[160:163], v[8:11]
	v_mfma_f32_16x16x32_bf16 v[12:15], v[152:155], v[160:163], v[12:15]
	v_mfma_f32_16x16x32_bf16 v[24:27], v[120:123], v[168:171], v[60:63]
	v_mfma_f32_16x16x32_bf16 v[28:31], v[152:155], v[168:171], v[100:103]
	v_mfma_f32_16x16x32_bf16 v[60:63], v[120:123], v[176:179], v[104:107]
	v_mfma_f32_16x16x32_bf16 v[100:103], v[152:155], v[176:179], v[108:111]
	v_mfma_f32_16x16x32_bf16 v[16:19], v[120:123], v[196:199], v[16:19]
	v_mfma_f32_16x16x32_bf16 v[20:23], v[152:155], v[196:199], v[20:23]
	v_mfma_f32_16x16x32_bf16 v[8:11], v[124:127], v[164:167], v[8:11]
	v_mfma_f32_16x16x32_bf16 v[12:15], v[156:159], v[164:167], v[12:15]
	v_mfma_f32_16x16x32_bf16 v[24:27], v[124:127], v[172:175], v[24:27]
	v_mfma_f32_16x16x32_bf16 v[28:31], v[156:159], v[172:175], v[28:31]
	v_mfma_f32_16x16x32_bf16 v[60:63], v[124:127], v[180:183], v[60:63]
	v_mfma_f32_16x16x32_bf16 v[100:103], v[156:159], v[180:183], v[100:103]
	v_mfma_f32_16x16x32_bf16 v[16:19], v[124:127], v[200:203], v[16:19]
	v_mfma_f32_16x16x32_bf16 v[20:23], v[156:159], v[200:203], v[20:23]
	s_setprio 0
	s_barrier
	ds_read_b128 v[104:107], v215
	ds_read_b128 v[108:111], v215 offset:1024
	ds_read_b128 v[112:115], v215 offset:2048
	ds_read_b128 v[116:119], v215 offset:3072
	ds_read_b128 v[120:123], v216
	ds_read_b128 v[124:127], v216 offset:1024
	ds_read_b128 v[152:155], v216 offset:2048
	ds_read_b128 v[156:159], v216 offset:3072
	s_add_u32 s74, s74, 0x10180
	s_addc_u32 s75, s75, 0
	s_mov_b32 m0, s73
	v_lshl_add_u64 v[204:205], s[74:75], 0, v[184:185]
	ds_read_b128 v[160:163], v217
	ds_read_b128 v[164:167], v217 offset:1024
	ds_read_b128 v[168:171], v217 offset:2048
	ds_read_b128 v[172:175], v217 offset:3072
	ds_read_b128 v[176:179], v217 offset:4096
	ds_read_b128 v[180:183], v217 offset:5120
	ds_read_b128 v[196:199], v217 offset:6144
	ds_read_b128 v[200:203], v217 offset:7168
	global_load_lds_dwordx4 v[204:205], off
	v_lshl_add_u64 v[204:205], s[74:75], 0, v[188:189]
	s_mov_b32 m0, s78
	s_nop 0
	global_load_lds_dwordx4 v[204:205], off
	s_waitcnt vmcnt(8)
	s_waitcnt lgkmcnt(0)
	s_barrier
	s_setprio 1
	s_waitcnt lgkmcnt(0)
	v_mfma_f32_16x16x32_bf16 v[64:67], v[104:107], v[160:163], v[64:67]
	v_mfma_f32_16x16x32_bf16 v[68:71], v[112:115], v[160:163], v[68:71]
	v_mfma_f32_16x16x32_bf16 v[72:75], v[104:107], v[168:171], v[72:75]
	v_mfma_f32_16x16x32_bf16 v[76:79], v[112:115], v[168:171], v[76:79]
	v_mfma_f32_16x16x32_bf16 v[80:83], v[104:107], v[176:179], v[80:83]
	v_mfma_f32_16x16x32_bf16 v[84:87], v[112:115], v[176:179], v[84:87]
	v_mfma_f32_16x16x32_bf16 v[88:91], v[104:107], v[196:199], v[88:91]
	v_mfma_f32_16x16x32_bf16 v[64:67], v[108:111], v[164:167], v[64:67]
	v_mfma_f32_16x16x32_bf16 v[68:71], v[116:119], v[164:167], v[68:71]
	v_mfma_f32_16x16x32_bf16 v[72:75], v[108:111], v[172:175], v[72:75]
	v_mfma_f32_16x16x32_bf16 v[76:79], v[116:119], v[172:175], v[76:79]
	v_mfma_f32_16x16x32_bf16 v[80:83], v[108:111], v[180:183], v[80:83]
	v_mfma_f32_16x16x32_bf16 v[84:87], v[116:119], v[180:183], v[84:87]
	v_mfma_f32_16x16x32_bf16 v[204:207], v[108:111], v[200:203], v[88:91]
	v_mfma_f32_16x16x32_bf16 v[88:91], v[112:115], v[196:199], v[92:95]
	v_mfma_f32_16x16x32_bf16 v[218:221], v[116:119], v[200:203], v[88:91]
	s_setprio 0
	s_setprio 1
	v_mfma_f32_16x16x32_bf16 v[88:91], v[120:123], v[160:163], v[96:99]
	v_mfma_f32_16x16x32_bf16 v[32:35], v[152:155], v[160:163], v[32:35]
	v_mfma_f32_16x16x32_bf16 v[36:39], v[120:123], v[168:171], v[36:39]
	v_mfma_f32_16x16x32_bf16 v[40:43], v[152:155], v[168:171], v[40:43]
	v_mfma_f32_16x16x32_bf16 v[44:47], v[120:123], v[176:179], v[44:47]
	v_mfma_f32_16x16x32_bf16 v[48:51], v[152:155], v[176:179], v[48:51]
	v_mfma_f32_16x16x32_bf16 v[52:55], v[120:123], v[196:199], v[52:55]
	v_mfma_f32_16x16x32_bf16 v[56:59], v[152:155], v[196:199], v[56:59]
	v_mfma_f32_16x16x32_bf16 v[96:99], v[124:127], v[164:167], v[88:91]
	v_mfma_f32_16x16x32_bf16 v[32:35], v[156:159], v[164:167], v[32:35]
	v_mfma_f32_16x16x32_bf16 v[36:39], v[124:127], v[172:175], v[36:39]
	v_mfma_f32_16x16x32_bf16 v[40:43], v[156:159], v[172:175], v[40:43]
	v_mfma_f32_16x16x32_bf16 v[44:47], v[124:127], v[180:183], v[44:47]
	v_mfma_f32_16x16x32_bf16 v[48:51], v[156:159], v[180:183], v[48:51]
	v_mfma_f32_16x16x32_bf16 v[52:55], v[124:127], v[200:203], v[52:55]
	v_mfma_f32_16x16x32_bf16 v[56:59], v[156:159], v[200:203], v[56:59]
	s_setprio 0
	s_barrier
	s_mov_b32 m0, s79
	v_lshl_add_u64 v[208:209], s[88:89], 0, v[186:187]
	s_add_u32 s74, s88, 0x10000
	ds_read_b128 v[88:91], v217 offset:16384
	ds_read_b128 v[92:95], v217 offset:17408
	ds_read_b128 v[160:163], v217 offset:18432
	ds_read_b128 v[164:167], v217 offset:19456
	ds_read_b128 v[168:171], v217 offset:20480
	ds_read_b128 v[172:175], v217 offset:21504
	ds_read_b128 v[176:179], v217 offset:22528
	ds_read_b128 v[180:183], v217 offset:23552
	global_load_lds_dwordx4 v[208:209], off
	v_lshl_add_u64 v[210:211], s[88:89], 0, v[190:191]
	s_mov_b32 m0, s80
	s_addc_u32 s75, s89, 0
	global_load_lds_dwordx4 v[210:211], off
	v_lshl_add_u64 v[196:197], s[74:75], 0, v[186:187]
	s_mov_b32 m0, s81
	v_lshl_add_u64 v[250:251], s[94:95], 0, v[184:185]
	global_load_lds_dwordx4 v[196:197], off
	v_lshl_add_u64 v[196:197], s[74:75], 0, v[190:191]
	s_mov_b32 m0, s84
	v_lshl_add_u64 v[252:253], s[94:95], 0, v[188:189]
	global_load_lds_dwordx4 v[196:197], off
	s_mov_b32 m0, s65
	s_nop 0
	global_load_lds_dwordx4 v[250:251], off
	s_mov_b32 m0, s66
	s_nop 0
	global_load_lds_dwordx4 v[252:253], off
	s_waitcnt vmcnt(8)
	s_waitcnt lgkmcnt(0)
	s_barrier
	s_setprio 1
	s_waitcnt lgkmcnt(0)
	v_mfma_f32_16x16x32_bf16 v[0:3], v[104:107], v[176:179], v[0:3]
	v_mfma_f32_16x16x32_bf16 v[4:7], v[112:115], v[176:179], v[4:7]
	v_mfma_f32_16x16x32_bf16 v[128:131], v[104:107], v[88:91], v[128:131]
	v_mfma_f32_16x16x32_bf16 v[132:135], v[112:115], v[88:91], v[132:135]
	v_mfma_f32_16x16x32_bf16 v[136:139], v[104:107], v[160:163], v[136:139]
	v_mfma_f32_16x16x32_bf16 v[140:143], v[112:115], v[160:163], v[140:143]
	v_mfma_f32_16x16x32_bf16 v[144:147], v[104:107], v[168:171], v[144:147]
	v_mfma_f32_16x16x32_bf16 v[148:151], v[112:115], v[168:171], v[148:151]
	v_mfma_f32_16x16x32_bf16 v[0:3], v[108:111], v[180:183], v[0:3]
	v_mfma_f32_16x16x32_bf16 v[4:7], v[116:119], v[180:183], v[4:7]
	v_mfma_f32_16x16x32_bf16 v[128:131], v[108:111], v[92:95], v[128:131]
	v_mfma_f32_16x16x32_bf16 v[132:135], v[116:119], v[92:95], v[132:135]
	v_mfma_f32_16x16x32_bf16 v[136:139], v[108:111], v[164:167], v[136:139]
	v_mfma_f32_16x16x32_bf16 v[140:143], v[116:119], v[164:167], v[140:143]
	v_mfma_f32_16x16x32_bf16 v[144:147], v[108:111], v[172:175], v[144:147]
	v_mfma_f32_16x16x32_bf16 v[148:151], v[116:119], v[172:175], v[148:151]
	s_setprio 0
	s_setprio 1
	v_mfma_f32_16x16x32_bf16 v[8:11], v[120:123], v[88:91], v[8:11]
	v_mfma_f32_16x16x32_bf16 v[116:119], v[124:127], v[92:95], v[8:11]
	v_mfma_f32_16x16x32_bf16 v[8:11], v[152:155], v[88:91], v[12:15]
	v_mfma_f32_16x16x32_bf16 v[196:199], v[156:159], v[92:95], v[8:11]
	v_mfma_f32_16x16x32_bf16 v[8:11], v[120:123], v[160:163], v[24:27]
	v_mfma_f32_16x16x32_bf16 v[200:203], v[124:127], v[164:167], v[8:11]
	v_mfma_f32_16x16x32_bf16 v[8:11], v[152:155], v[160:163], v[28:31]
	v_mfma_f32_16x16x32_bf16 v[160:163], v[156:159], v[164:167], v[8:11]
	v_mfma_f32_16x16x32_bf16 v[8:11], v[120:123], v[168:171], v[60:63]
	v_mfma_f32_16x16x32_bf16 v[222:225], v[124:127], v[172:175], v[8:11]
	v_mfma_f32_16x16x32_bf16 v[8:11], v[152:155], v[168:171], v[100:103]
	v_mfma_f32_16x16x32_bf16 v[168:171], v[156:159], v[172:175], v[8:11]
	v_mfma_f32_16x16x32_bf16 v[8:11], v[120:123], v[176:179], v[16:19]
	v_mfma_f32_16x16x32_bf16 v[124:127], v[124:127], v[180:183], v[8:11]
	v_mfma_f32_16x16x32_bf16 v[8:11], v[152:155], v[176:179], v[20:23]
	v_mfma_f32_16x16x32_bf16 v[156:159], v[156:159], v[180:183], v[8:11]
	s_setprio 0
	s_barrier
	s_nop 4
	ds_read_b128 v[8:11], v226
	ds_read_b128 v[12:15], v226 offset:1024
	ds_read_b128 v[16:19], v226 offset:2048
	ds_read_b128 v[20:23], v226 offset:3072
	ds_read_b128 v[172:175], v227
	ds_read_b128 v[176:179], v227 offset:1024
	ds_read_b128 v[180:183], v227 offset:2048
	ds_read_b128 v[226:229], v227 offset:3072
	s_add_u32 s74, s94, 0x10000
	s_addc_u32 s75, s95, 0
	s_mov_b32 m0, s67
	v_lshl_add_u64 v[88:89], s[74:75], 0, v[184:185]
	ds_read_b128 v[24:27], v217 offset:32768
	ds_read_b128 v[28:31], v217 offset:33792
	ds_read_b128 v[60:63], v217 offset:34816
	ds_read_b128 v[230:233], v217 offset:35840
	ds_read_b128 v[234:237], v217 offset:36864
	ds_read_b128 v[238:241], v217 offset:37888
	ds_read_b128 v[242:245], v217 offset:38912
	ds_read_b128 v[246:249], v217 offset:39936
	global_load_lds_dwordx4 v[88:89], off
	v_lshl_add_u64 v[88:89], s[74:75], 0, v[188:189]
	s_mov_b32 m0, s68
	s_nop 0
	global_load_lds_dwordx4 v[88:89], off
	s_waitcnt vmcnt(8)
	s_waitcnt lgkmcnt(0)
	s_barrier
	s_setprio 1
	s_waitcnt lgkmcnt(0)
	v_mfma_f32_16x16x32_bf16 v[64:67], v[8:11], v[24:27], v[64:67]
	v_mfma_f32_16x16x32_bf16 v[164:167], v[12:15], v[28:31], v[64:67]
	v_mfma_f32_16x16x32_bf16 v[64:67], v[16:19], v[24:27], v[68:71]
	v_mfma_f32_16x16x32_bf16 v[152:155], v[20:23], v[28:31], v[64:67]
	v_mfma_f32_16x16x32_bf16 v[64:67], v[8:11], v[60:63], v[72:75]
	v_mfma_f32_16x16x32_bf16 v[108:111], v[12:15], v[230:233], v[64:67]
	v_mfma_f32_16x16x32_bf16 v[64:67], v[16:19], v[60:63], v[76:79]
	v_mfma_f32_16x16x32_bf16 v[104:107], v[20:23], v[230:233], v[64:67]
	v_mfma_f32_16x16x32_bf16 v[64:67], v[8:11], v[234:237], v[80:83]
	v_mfma_f32_16x16x32_bf16 v[92:95], v[12:15], v[238:241], v[64:67]
	v_mfma_f32_16x16x32_bf16 v[64:67], v[16:19], v[234:237], v[84:87]
	v_mfma_f32_16x16x32_bf16 v[88:91], v[20:23], v[238:241], v[64:67]
	v_mfma_f32_16x16x32_bf16 v[64:67], v[8:11], v[242:245], v[204:207]
	v_mfma_f32_16x16x32_bf16 v[76:79], v[12:15], v[246:249], v[64:67]
	v_mfma_f32_16x16x32_bf16 v[64:67], v[16:19], v[242:245], v[218:221]
	v_mfma_f32_16x16x32_bf16 v[72:75], v[20:23], v[246:249], v[64:67]
	s_setprio 0
	s_setprio 1
	v_mfma_f32_16x16x32_bf16 v[64:67], v[172:175], v[24:27], v[96:99]
	v_mfma_f32_16x16x32_bf16 v[24:27], v[180:183], v[24:27], v[32:35]
	v_mfma_f32_16x16x32_bf16 v[112:115], v[226:229], v[28:31], v[24:27]
	v_mfma_f32_16x16x32_bf16 v[24:27], v[172:175], v[60:63], v[36:39]
	v_mfma_f32_16x16x32_bf16 v[100:103], v[176:179], v[230:233], v[24:27]
	v_mfma_f32_16x16x32_bf16 v[24:27], v[180:183], v[60:63], v[40:43]
	v_mfma_f32_16x16x32_bf16 v[96:99], v[226:229], v[230:233], v[24:27]
	v_mfma_f32_16x16x32_bf16 v[24:27], v[172:175], v[234:237], v[44:47]
	v_mfma_f32_16x16x32_bf16 v[84:87], v[176:179], v[238:241], v[24:27]
	v_mfma_f32_16x16x32_bf16 v[24:27], v[180:183], v[234:237], v[48:51]
	v_mfma_f32_16x16x32_bf16 v[80:83], v[226:229], v[238:241], v[24:27]
	v_mfma_f32_16x16x32_bf16 v[24:27], v[172:175], v[242:245], v[52:55]
	v_mfma_f32_16x16x32_bf16 v[68:71], v[176:179], v[246:249], v[24:27]
	v_mfma_f32_16x16x32_bf16 v[24:27], v[180:183], v[242:245], v[56:59]
	v_mfma_f32_16x16x32_bf16 v[120:123], v[176:179], v[28:31], v[64:67]
	v_mfma_f32_16x16x32_bf16 v[64:67], v[226:229], v[246:249], v[24:27]
	s_setprio 0
	s_barrier
	s_mov_b32 m0, s85
	s_nop 2
	v_lshl_add_u64 v[24:25], v[208:209], 0, s[4:5]
	s_add_u32 s74, s88, 0x10080
	ds_read_b128 v[32:35], v217 offset:49152
	ds_read_b128 v[36:39], v217 offset:50176
	ds_read_b128 v[204:207], v217 offset:51200
	ds_read_b128 v[218:221], v217 offset:52224
	ds_read_b128 v[230:233], v217 offset:53248
	ds_read_b128 v[234:237], v217 offset:54272
	ds_read_b128 v[238:241], v217 offset:55296
	ds_read_b128 v[242:245], v217 offset:56320
	global_load_lds_dwordx4 v[24:25], off
	v_lshl_add_u64 v[24:25], v[210:211], 0, s[4:5]
	s_mov_b32 m0, s35
	s_addc_u32 s75, s89, 0
	global_load_lds_dwordx4 v[24:25], off
	v_lshl_add_u64 v[24:25], s[74:75], 0, v[186:187]
	s_mov_b32 m0, s37
	s_nop 0
	global_load_lds_dwordx4 v[24:25], off
	v_lshl_add_u64 v[24:25], s[74:75], 0, v[190:191]
	s_mov_b32 m0, s82
	s_nop 0
	global_load_lds_dwordx4 v[24:25], off
	v_lshl_add_u64 v[24:25], v[250:251], 0, s[4:5]
	s_mov_b32 m0, s71
	s_nop 0
	global_load_lds_dwordx4 v[24:25], off
	v_lshl_add_u64 v[24:25], v[252:253], 0, s[4:5]
	s_mov_b32 m0, s72
	s_nop 0
	global_load_lds_dwordx4 v[24:25], off
	s_waitcnt vmcnt(8)
	s_waitcnt lgkmcnt(0)
	s_barrier
	s_setprio 1
	s_waitcnt lgkmcnt(0)
	v_mfma_f32_16x16x32_bf16 v[24:27], v[8:11], v[32:35], v[128:131]
	v_mfma_f32_16x16x32_bf16 v[60:63], v[12:15], v[36:39], v[24:27]
	v_mfma_f32_16x16x32_bf16 v[24:27], v[16:19], v[32:35], v[132:135]
	v_mfma_f32_16x16x32_bf16 v[56:59], v[20:23], v[36:39], v[24:27]
	v_mfma_f32_16x16x32_bf16 v[24:27], v[8:11], v[204:207], v[136:139]
	v_mfma_f32_16x16x32_bf16 v[44:47], v[12:15], v[218:221], v[24:27]
	v_mfma_f32_16x16x32_bf16 v[24:27], v[16:19], v[204:207], v[140:143]
	v_mfma_f32_16x16x32_bf16 v[40:43], v[20:23], v[218:221], v[24:27]
	v_mfma_f32_16x16x32_bf16 v[24:27], v[8:11], v[230:233], v[144:147]
	v_mfma_f32_16x16x32_bf16 v[0:3], v[8:11], v[238:241], v[0:3]
	v_mfma_f32_16x16x32_bf16 v[28:31], v[12:15], v[234:237], v[24:27]
	v_mfma_f32_16x16x32_bf16 v[24:27], v[16:19], v[230:233], v[148:151]
	v_mfma_f32_16x16x32_bf16 v[12:15], v[12:15], v[242:245], v[0:3]
	v_mfma_f32_16x16x32_bf16 v[0:3], v[16:19], v[238:241], v[4:7]
	v_mfma_f32_16x16x32_bf16 v[24:27], v[20:23], v[234:237], v[24:27]
	v_mfma_f32_16x16x32_bf16 v[8:11], v[20:23], v[242:245], v[0:3]
	s_setprio 0
	s_setprio 1
	v_mfma_f32_16x16x32_bf16 v[0:3], v[172:175], v[32:35], v[116:119]
	v_mfma_f32_16x16x32_bf16 v[52:55], v[176:179], v[36:39], v[0:3]
	v_mfma_f32_16x16x32_bf16 v[0:3], v[180:183], v[32:35], v[196:199]
	v_mfma_f32_16x16x32_bf16 v[48:51], v[226:229], v[36:39], v[0:3]
	v_mfma_f32_16x16x32_bf16 v[0:3], v[172:175], v[204:207], v[200:203]
	v_mfma_f32_16x16x32_bf16 v[36:39], v[176:179], v[218:221], v[0:3]
	v_mfma_f32_16x16x32_bf16 v[0:3], v[180:183], v[204:207], v[160:163]
	v_mfma_f32_16x16x32_bf16 v[32:35], v[226:229], v[218:221], v[0:3]
	v_mfma_f32_16x16x32_bf16 v[0:3], v[172:175], v[230:233], v[222:225]
	v_mfma_f32_16x16x32_bf16 v[20:23], v[176:179], v[234:237], v[0:3]
	v_mfma_f32_16x16x32_bf16 v[0:3], v[180:183], v[230:233], v[168:171]
	v_mfma_f32_16x16x32_bf16 v[16:19], v[226:229], v[234:237], v[0:3]
	v_mfma_f32_16x16x32_bf16 v[0:3], v[172:175], v[238:241], v[124:127]
	v_mfma_f32_16x16x32_bf16 v[4:7], v[176:179], v[242:245], v[0:3]
	v_mfma_f32_16x16x32_bf16 v[0:3], v[180:183], v[238:241], v[156:159]
	v_mfma_f32_16x16x32_bf16 v[0:3], v[226:229], v[242:245], v[0:3]
	s_setprio 0
	s_barrier
	s_andn2_b64 vcc, exec, s[6:7]
	s_cbranch_vccnz .LBB0_2299
	s_barrier
.LBB0_2299:
	s_lshl_b32 s35, s46, 8
	v_mov_b32_e32 v116, v213
	v_mov_b32_e32 v117, v212
	s_add_i32 s35, s35, s69
	s_andn2_b64 vcc, exec, s[10:11]
	v_add_u32_e32 v198, s35, v117
	s_lshl_b32 s35, s47, 8
	s_or_b32 s35, s35, s70
	v_lshl_add_u32 v116, v116, 3, s35
	v_ashrrev_i32_e32 v117, 31, v116
	v_lshlrev_b64 v[196:197], 1, v[116:117]
	v_ashrrev_i32_e32 v199, 31, v198
	v_lshl_add_u64 v[202:203], s[56:57], 0, v[196:197]
	v_lshlrev_b64 v[116:117], 12, v[198:199]
	v_lshl_add_u64 v[200:201], s[42:43], 0, v[196:197]
	v_lshl_add_u64 v[116:117], v[202:203], 0, v[116:117]
	v_lshlrev_b64 v[210:211], 11, v[198:199]
	v_lshl_add_u64 v[118:119], v[200:201], 0, v[210:211]
	global_load_dwordx4 v[218:221], v[116:117], off offset:2048
	global_load_dwordx4 v[222:225], v[118:119], off
	global_load_dwordx4 v[180:183], v[116:117], off offset:2304
	global_load_dwordx4 v[176:179], v[118:119], off offset:256
	v_add_u32_e32 v116, 16, v198
	v_ashrrev_i32_e32 v117, 31, v116
	v_lshlrev_b64 v[118:119], 12, v[116:117]
	v_lshl_add_u64 v[118:119], v[202:203], 0, v[118:119]
	v_lshlrev_b64 v[208:209], 11, v[116:117]
	v_lshl_add_u64 v[116:117], v[200:201], 0, v[208:209]
	global_load_dwordx4 v[172:175], v[118:119], off offset:2048
	global_load_dwordx4 v[168:171], v[116:117], off
	global_load_dwordx4 v[160:163], v[118:119], off offset:2304
	global_load_dwordx4 v[148:151], v[116:117], off offset:256
	v_add_u32_e32 v116, 32, v198
	v_ashrrev_i32_e32 v117, 31, v116
	v_lshlrev_b64 v[118:119], 12, v[116:117]
	v_lshl_add_u64 v[118:119], v[202:203], 0, v[118:119]
	v_lshlrev_b64 v[206:207], 11, v[116:117]
	v_lshl_add_u64 v[116:117], v[200:201], 0, v[206:207]
	global_load_dwordx4 v[156:159], v[118:119], off offset:2048
	global_load_dwordx4 v[140:143], v[116:117], off
	global_load_dwordx4 v[132:135], v[118:119], off offset:2304
	global_load_dwordx4 v[124:127], v[116:117], off offset:256
	v_add_u32_e32 v116, 48, v198
	v_ashrrev_i32_e32 v117, 31, v116
	v_lshlrev_b64 v[118:119], 12, v[116:117]
	v_lshlrev_b64 v[204:205], 11, v[116:117]
	v_lshl_add_u64 v[118:119], v[202:203], 0, v[118:119]
	v_lshl_add_u64 v[116:117], v[200:201], 0, v[204:205]
	global_load_dwordx4 v[144:147], v[118:119], off offset:2048
	global_load_dwordx4 v[136:139], v[116:117], off
	global_load_dwordx4 v[128:131], v[118:119], off offset:2304
	s_nop 0
	global_load_dwordx4 v[116:119], v[116:117], off offset:256
	v_lshl_add_u64 v[210:211], s[42:43], 0, v[210:211]
	v_lshl_add_u64 v[210:211], v[210:211], 0, v[196:197]
	s_mov_b64 s[46:47], -1
	s_waitcnt vmcnt(0)
	v_lshlrev_b32_e32 v199, 16, v218
	v_lshlrev_b32_e32 v229, 16, v222
	v_and_b32_e32 v218, 0xffff0000, v218
	v_fmac_f32_e32 v229, v164, v199
	v_and_b32_e32 v164, 0xffff0000, v222
	v_lshlrev_b32_e32 v226, 16, v219
	v_fmac_f32_e32 v164, v165, v218
	v_lshlrev_b32_e32 v165, 16, v223
	v_and_b32_e32 v219, 0xffff0000, v219
	v_fmac_f32_e32 v165, v166, v226
	v_and_b32_e32 v166, 0xffff0000, v223
	v_lshlrev_b32_e32 v227, 16, v220
	v_and_b32_e32 v220, 0xffff0000, v220
	v_fmac_f32_e32 v166, v167, v219
	v_lshlrev_b32_e32 v167, 16, v224
	v_and_b32_e32 v199, 0xffff0000, v224
	v_lshlrev_b32_e32 v228, 16, v221
	v_and_b32_e32 v221, 0xffff0000, v221
	v_fmac_f32_e32 v167, v152, v227
	v_fmac_f32_e32 v199, v153, v220
	v_lshlrev_b32_e32 v218, 16, v225
	v_and_b32_e32 v219, 0xffff0000, v225
	v_cvt_pk_bf16_f32 v152, v229, v164
	v_cvt_pk_bf16_f32 v153, v165, v166
	v_fmac_f32_e32 v218, v154, v228
	v_fmac_f32_e32 v219, v155, v221
	v_cvt_pk_bf16_f32 v154, v167, v199
	v_cvt_pk_bf16_f32 v155, v218, v219
	global_store_dwordx4 v[210:211], v[152:155], off
	v_lshlrev_b32_e32 v164, 16, v182
	v_and_b32_e32 v165, 0xffff0000, v182
	v_lshlrev_b32_e32 v152, 16, v180
	v_and_b32_e32 v153, 0xffff0000, v180
	v_lshlrev_b32_e32 v180, 16, v176
	v_fmac_f32_e32 v180, v120, v152
	v_and_b32_e32 v120, 0xffff0000, v176
	v_lshlrev_b32_e32 v154, 16, v181
	v_fmac_f32_e32 v120, v121, v153
	v_lshlrev_b32_e32 v121, 16, v177
	v_and_b32_e32 v155, 0xffff0000, v181
	v_fmac_f32_e32 v121, v122, v154
	v_and_b32_e32 v122, 0xffff0000, v177
	v_lshlrev_b32_e32 v166, 16, v183
	v_and_b32_e32 v167, 0xffff0000, v183
	v_fmac_f32_e32 v122, v123, v155
	v_lshlrev_b32_e32 v123, 16, v178
	v_and_b32_e32 v152, 0xffff0000, v178
	v_lshlrev_b32_e32 v153, 16, v179
	v_and_b32_e32 v154, 0xffff0000, v179
	v_fmac_f32_e32 v123, v112, v164
	v_fmac_f32_e32 v152, v113, v165
	v_fmac_f32_e32 v153, v114, v166
	v_fmac_f32_e32 v154, v115, v167
	v_cvt_pk_bf16_f32 v112, v180, v120
	v_cvt_pk_bf16_f32 v113, v121, v122
	v_cvt_pk_bf16_f32 v114, v123, v152
	v_cvt_pk_bf16_f32 v115, v153, v154
	global_store_dwordx4 v[210:211], v[112:115], off offset:256
	v_lshlrev_b32_e32 v154, 16, v168
	v_lshlrev_b32_e32 v120, 16, v173
	v_lshlrev_b32_e32 v114, 16, v172
	v_and_b32_e32 v115, 0xffff0000, v172
	v_fmac_f32_e32 v154, v108, v114
	v_and_b32_e32 v108, 0xffff0000, v168
	v_fmac_f32_e32 v108, v109, v115
	v_lshlrev_b32_e32 v109, 16, v169
	v_and_b32_e32 v121, 0xffff0000, v173
	v_fmac_f32_e32 v109, v110, v120
	v_and_b32_e32 v110, 0xffff0000, v169
	v_lshl_add_u64 v[112:113], s[42:43], 0, v[208:209]
	v_lshlrev_b32_e32 v122, 16, v174
	v_and_b32_e32 v123, 0xffff0000, v174
	v_fmac_f32_e32 v110, v111, v121
	v_lshlrev_b32_e32 v111, 16, v170
	v_and_b32_e32 v114, 0xffff0000, v170
	v_lshl_add_u64 v[112:113], v[112:113], 0, v[196:197]
	v_lshlrev_b32_e32 v152, 16, v175
	v_and_b32_e32 v153, 0xffff0000, v175
	v_fmac_f32_e32 v111, v104, v122
	v_fmac_f32_e32 v114, v105, v123
	v_lshlrev_b32_e32 v115, 16, v171
	v_and_b32_e32 v120, 0xffff0000, v171
	v_cvt_pk_bf16_f32 v104, v154, v108
	v_fmac_f32_e32 v115, v106, v152
	v_fmac_f32_e32 v120, v107, v153
	v_cvt_pk_bf16_f32 v105, v109, v110
	v_cvt_pk_bf16_f32 v106, v111, v114
	v_cvt_pk_bf16_f32 v107, v115, v120
	global_store_dwordx4 v[112:113], v[104:107], off
	v_lshlrev_b32_e32 v114, 16, v148
	v_lshlrev_b32_e32 v108, 16, v162
	v_lshlrev_b32_e32 v104, 16, v160
	v_and_b32_e32 v105, 0xffff0000, v160
	v_fmac_f32_e32 v114, v100, v104
	v_and_b32_e32 v100, 0xffff0000, v148
	v_lshlrev_b32_e32 v106, 16, v161
	v_fmac_f32_e32 v100, v101, v105
	v_lshlrev_b32_e32 v101, 16, v149
	v_and_b32_e32 v107, 0xffff0000, v161
	v_fmac_f32_e32 v101, v102, v106
	v_and_b32_e32 v102, 0xffff0000, v149
	v_and_b32_e32 v109, 0xffff0000, v162
	v_lshlrev_b32_e32 v110, 16, v163
	v_and_b32_e32 v111, 0xffff0000, v163
	v_fmac_f32_e32 v102, v103, v107
	v_lshlrev_b32_e32 v103, 16, v150
	v_and_b32_e32 v104, 0xffff0000, v150
	v_lshlrev_b32_e32 v105, 16, v151
	v_and_b32_e32 v106, 0xffff0000, v151
	v_fmac_f32_e32 v103, v96, v108
	v_fmac_f32_e32 v104, v97, v109
	v_fmac_f32_e32 v105, v98, v110
	v_fmac_f32_e32 v106, v99, v111
	v_cvt_pk_bf16_f32 v96, v114, v100
	v_cvt_pk_bf16_f32 v97, v101, v102
	v_cvt_pk_bf16_f32 v98, v103, v104
	v_cvt_pk_bf16_f32 v99, v105, v106
	global_store_dwordx4 v[112:113], v[96:99], off offset:256
	v_lshlrev_b32_e32 v106, 16, v140
	v_lshlrev_b32_e32 v100, 16, v157
	v_lshlrev_b32_e32 v98, 16, v156
	v_and_b32_e32 v99, 0xffff0000, v156
	v_fmac_f32_e32 v106, v92, v98
	v_and_b32_e32 v92, 0xffff0000, v140
	v_fmac_f32_e32 v92, v93, v99
	v_lshlrev_b32_e32 v93, 16, v141
	v_and_b32_e32 v101, 0xffff0000, v157
	v_fmac_f32_e32 v93, v94, v100
	v_and_b32_e32 v94, 0xffff0000, v141
	v_lshl_add_u64 v[96:97], s[42:43], 0, v[206:207]
	v_lshlrev_b32_e32 v102, 16, v158
	v_and_b32_e32 v103, 0xffff0000, v158
	v_fmac_f32_e32 v94, v95, v101
	v_lshlrev_b32_e32 v95, 16, v142
	v_and_b32_e32 v98, 0xffff0000, v142
	v_lshl_add_u64 v[96:97], v[96:97], 0, v[196:197]
	v_lshlrev_b32_e32 v104, 16, v159
	v_and_b32_e32 v105, 0xffff0000, v159
	v_fmac_f32_e32 v95, v88, v102
	v_fmac_f32_e32 v98, v89, v103
	v_lshlrev_b32_e32 v99, 16, v143
	v_and_b32_e32 v100, 0xffff0000, v143
	v_cvt_pk_bf16_f32 v88, v106, v92
	v_fmac_f32_e32 v99, v90, v104
	v_fmac_f32_e32 v100, v91, v105
	v_cvt_pk_bf16_f32 v89, v93, v94
	v_cvt_pk_bf16_f32 v90, v95, v98
	v_cvt_pk_bf16_f32 v91, v99, v100
	global_store_dwordx4 v[96:97], v[88:91], off
	v_lshlrev_b32_e32 v98, 16, v124
	v_lshlrev_b32_e32 v92, 16, v134
	v_lshlrev_b32_e32 v88, 16, v132
	v_and_b32_e32 v89, 0xffff0000, v132
	v_fmac_f32_e32 v98, v84, v88
	v_and_b32_e32 v84, 0xffff0000, v124
	v_lshlrev_b32_e32 v90, 16, v133
	v_fmac_f32_e32 v84, v85, v89
	v_lshlrev_b32_e32 v85, 16, v125
	v_and_b32_e32 v91, 0xffff0000, v133
	v_fmac_f32_e32 v85, v86, v90
	v_and_b32_e32 v86, 0xffff0000, v125
	v_and_b32_e32 v93, 0xffff0000, v134
	v_lshlrev_b32_e32 v94, 16, v135
	v_and_b32_e32 v95, 0xffff0000, v135
	v_fmac_f32_e32 v86, v87, v91
	v_lshlrev_b32_e32 v87, 16, v126
	v_and_b32_e32 v88, 0xffff0000, v126
	v_lshlrev_b32_e32 v89, 16, v127
	v_and_b32_e32 v90, 0xffff0000, v127
	v_fmac_f32_e32 v87, v80, v92
	v_fmac_f32_e32 v88, v81, v93
	v_fmac_f32_e32 v89, v82, v94
	v_fmac_f32_e32 v90, v83, v95
	v_cvt_pk_bf16_f32 v80, v98, v84
	v_cvt_pk_bf16_f32 v81, v85, v86
	v_cvt_pk_bf16_f32 v82, v87, v88
	v_cvt_pk_bf16_f32 v83, v89, v90
	global_store_dwordx4 v[96:97], v[80:83], off offset:256
	v_lshlrev_b32_e32 v90, 16, v136
	v_lshlrev_b32_e32 v84, 16, v145
	v_lshlrev_b32_e32 v82, 16, v144
	v_and_b32_e32 v83, 0xffff0000, v144
	v_fmac_f32_e32 v90, v76, v82
	v_and_b32_e32 v76, 0xffff0000, v136
	v_fmac_f32_e32 v76, v77, v83
	v_lshlrev_b32_e32 v77, 16, v137
	v_and_b32_e32 v85, 0xffff0000, v145
	v_fmac_f32_e32 v77, v78, v84
	v_and_b32_e32 v78, 0xffff0000, v137
	v_lshl_add_u64 v[80:81], s[42:43], 0, v[204:205]
	v_lshlrev_b32_e32 v86, 16, v146
	v_and_b32_e32 v87, 0xffff0000, v146
	v_fmac_f32_e32 v78, v79, v85
	v_lshlrev_b32_e32 v79, 16, v138
	v_and_b32_e32 v82, 0xffff0000, v138
	v_lshl_add_u64 v[80:81], v[80:81], 0, v[196:197]
	v_lshlrev_b32_e32 v88, 16, v147
	v_and_b32_e32 v89, 0xffff0000, v147
	v_fmac_f32_e32 v79, v72, v86
	v_fmac_f32_e32 v82, v73, v87
	v_lshlrev_b32_e32 v83, 16, v139
	v_and_b32_e32 v84, 0xffff0000, v139
	v_cvt_pk_bf16_f32 v72, v90, v76
	v_fmac_f32_e32 v83, v74, v88
	v_fmac_f32_e32 v84, v75, v89
	v_cvt_pk_bf16_f32 v73, v77, v78
	v_cvt_pk_bf16_f32 v74, v79, v82
	v_cvt_pk_bf16_f32 v75, v83, v84
	global_store_dwordx4 v[80:81], v[72:75], off
	v_lshlrev_b32_e32 v82, 16, v116
	v_lshlrev_b32_e32 v76, 16, v130
	v_lshlrev_b32_e32 v72, 16, v128
	v_and_b32_e32 v73, 0xffff0000, v128
	v_fmac_f32_e32 v82, v68, v72
	v_and_b32_e32 v68, 0xffff0000, v116
	v_lshlrev_b32_e32 v74, 16, v129
	v_fmac_f32_e32 v68, v69, v73
	v_lshlrev_b32_e32 v69, 16, v117
	v_and_b32_e32 v75, 0xffff0000, v129
	v_fmac_f32_e32 v69, v70, v74
	v_and_b32_e32 v70, 0xffff0000, v117
	v_fmac_f32_e32 v70, v71, v75
	v_lshlrev_b32_e32 v71, 16, v118
	v_and_b32_e32 v77, 0xffff0000, v130
	v_lshlrev_b32_e32 v78, 16, v131
	v_and_b32_e32 v79, 0xffff0000, v131
	v_fmac_f32_e32 v71, v64, v76
	v_and_b32_e32 v72, 0xffff0000, v118
	v_lshlrev_b32_e32 v73, 16, v119
	v_and_b32_e32 v74, 0xffff0000, v119
	v_cvt_pk_bf16_f32 v64, v82, v68
	v_fmac_f32_e32 v72, v65, v77
	v_fmac_f32_e32 v73, v66, v78
	v_fmac_f32_e32 v74, v67, v79
	v_cvt_pk_bf16_f32 v65, v69, v70
	v_cvt_pk_bf16_f32 v66, v71, v72
	v_cvt_pk_bf16_f32 v67, v73, v74
	global_store_dwordx4 v[80:81], v[64:67], off offset:256
	s_nop 1
	v_add_u32_e32 v64, 0x80, v198
	v_ashrrev_i32_e32 v65, 31, v64
	v_lshlrev_b64 v[66:67], 12, v[64:65]
	v_lshl_add_u64 v[66:67], v[202:203], 0, v[66:67]
	v_lshlrev_b64 v[130:131], 11, v[64:65]
	v_lshl_add_u64 v[64:65], v[200:201], 0, v[130:131]
	global_load_dwordx4 v[86:89], v[66:67], off offset:2048
	global_load_dwordx4 v[90:93], v[64:65], off
	global_load_dwordx4 v[94:97], v[66:67], off offset:2304
	global_load_dwordx4 v[98:101], v[64:65], off offset:256
	v_add_u32_e32 v64, 0x90, v198
	v_ashrrev_i32_e32 v65, 31, v64
	v_lshlrev_b64 v[66:67], 12, v[64:65]
	v_lshl_add_u64 v[66:67], v[202:203], 0, v[66:67]
	v_lshlrev_b64 v[132:133], 11, v[64:65]
	v_lshl_add_u64 v[64:65], v[200:201], 0, v[132:133]
	global_load_dwordx4 v[102:105], v[66:67], off offset:2048
	global_load_dwordx4 v[106:109], v[64:65], off
	global_load_dwordx4 v[110:113], v[66:67], off offset:2304
	global_load_dwordx4 v[114:117], v[64:65], off offset:256
	v_add_u32_e32 v64, 0xa0, v198
	v_ashrrev_i32_e32 v65, 31, v64
	v_lshlrev_b64 v[66:67], 12, v[64:65]
	v_lshl_add_u64 v[66:67], v[202:203], 0, v[66:67]
	v_lshlrev_b64 v[134:135], 11, v[64:65]
	v_lshl_add_u64 v[64:65], v[200:201], 0, v[134:135]
	global_load_dwordx4 v[118:121], v[66:67], off offset:2048
	global_load_dwordx4 v[122:125], v[64:65], off
	global_load_dwordx4 v[126:129], v[66:67], off offset:2304
	global_load_dwordx4 v[80:83], v[64:65], off offset:256
	v_add_u32_e32 v64, 0xb0, v198
	v_ashrrev_i32_e32 v65, 31, v64
	v_lshlrev_b64 v[66:67], 12, v[64:65]
	v_lshlrev_b64 v[84:85], 11, v[64:65]
	v_lshl_add_u64 v[66:67], v[202:203], 0, v[66:67]
	v_lshl_add_u64 v[64:65], v[200:201], 0, v[84:85]
	global_load_dwordx4 v[76:79], v[66:67], off offset:2048
	global_load_dwordx4 v[72:75], v[64:65], off
	global_load_dwordx4 v[68:71], v[66:67], off offset:2304
	s_nop 0
	global_load_dwordx4 v[64:67], v[64:65], off offset:256
	v_lshl_add_u64 v[130:131], s[42:43], 0, v[130:131]
	v_lshl_add_u64 v[130:131], v[130:131], 0, v[196:197]
	s_waitcnt vmcnt(15)
	v_lshlrev_b32_e32 v136, 16, v86
	s_waitcnt vmcnt(14)
	v_lshlrev_b32_e32 v140, 16, v90
	v_and_b32_e32 v86, 0xffff0000, v86
	v_fmac_f32_e32 v140, v60, v136
	v_and_b32_e32 v60, 0xffff0000, v90
	v_lshlrev_b32_e32 v137, 16, v87
	v_fmac_f32_e32 v60, v61, v86
	v_lshlrev_b32_e32 v61, 16, v91
	v_and_b32_e32 v87, 0xffff0000, v87
	v_fmac_f32_e32 v61, v62, v137
	v_and_b32_e32 v62, 0xffff0000, v91
	v_lshlrev_b32_e32 v138, 16, v88
	v_and_b32_e32 v88, 0xffff0000, v88
	v_fmac_f32_e32 v62, v63, v87
	v_lshlrev_b32_e32 v63, 16, v92
	v_and_b32_e32 v86, 0xffff0000, v92
	v_lshlrev_b32_e32 v139, 16, v89
	v_and_b32_e32 v89, 0xffff0000, v89
	v_fmac_f32_e32 v63, v56, v138
	v_fmac_f32_e32 v86, v57, v88
	v_lshlrev_b32_e32 v87, 16, v93
	v_and_b32_e32 v88, 0xffff0000, v93
	v_cvt_pk_bf16_f32 v56, v140, v60
	v_fmac_f32_e32 v87, v58, v139
	v_fmac_f32_e32 v88, v59, v89
	v_cvt_pk_bf16_f32 v57, v61, v62
	v_cvt_pk_bf16_f32 v58, v63, v86
	v_cvt_pk_bf16_f32 v59, v87, v88
	global_store_dwordx4 v[130:131], v[56:59], off
	s_waitcnt vmcnt(13)
	v_lshlrev_b32_e32 v86, 16, v98
	v_lshlrev_b32_e32 v60, 16, v96
	v_lshlrev_b32_e32 v56, 16, v94
	v_and_b32_e32 v57, 0xffff0000, v94
	v_fmac_f32_e32 v86, v52, v56
	v_and_b32_e32 v52, 0xffff0000, v98
	v_lshlrev_b32_e32 v58, 16, v95
	v_fmac_f32_e32 v52, v53, v57
	v_lshlrev_b32_e32 v53, 16, v99
	v_and_b32_e32 v59, 0xffff0000, v95
	v_fmac_f32_e32 v53, v54, v58
	v_and_b32_e32 v54, 0xffff0000, v99
	v_and_b32_e32 v61, 0xffff0000, v96
	v_lshlrev_b32_e32 v62, 16, v97
	v_and_b32_e32 v63, 0xffff0000, v97
	v_fmac_f32_e32 v54, v55, v59
	v_lshlrev_b32_e32 v55, 16, v100
	v_and_b32_e32 v56, 0xffff0000, v100
	v_lshlrev_b32_e32 v57, 16, v101
	v_and_b32_e32 v58, 0xffff0000, v101
	v_fmac_f32_e32 v55, v48, v60
	v_fmac_f32_e32 v56, v49, v61
	v_fmac_f32_e32 v57, v50, v62
	v_fmac_f32_e32 v58, v51, v63
	v_cvt_pk_bf16_f32 v48, v86, v52
	v_cvt_pk_bf16_f32 v49, v53, v54
	v_cvt_pk_bf16_f32 v50, v55, v56
	v_cvt_pk_bf16_f32 v51, v57, v58
	global_store_dwordx4 v[130:131], v[48:51], off offset:256
	s_waitcnt vmcnt(12)
	v_lshlrev_b32_e32 v58, 16, v106
	v_lshlrev_b32_e32 v52, 16, v103
	v_lshlrev_b32_e32 v50, 16, v102
	v_and_b32_e32 v51, 0xffff0000, v102
	v_fmac_f32_e32 v58, v44, v50
	v_and_b32_e32 v44, 0xffff0000, v106
	v_fmac_f32_e32 v44, v45, v51
	v_lshlrev_b32_e32 v45, 16, v107
	v_and_b32_e32 v53, 0xffff0000, v103
	v_fmac_f32_e32 v45, v46, v52
	v_and_b32_e32 v46, 0xffff0000, v107
	v_lshl_add_u64 v[48:49], s[42:43], 0, v[132:133]
	v_lshlrev_b32_e32 v54, 16, v104
	v_and_b32_e32 v55, 0xffff0000, v104
	v_fmac_f32_e32 v46, v47, v53
	v_lshlrev_b32_e32 v47, 16, v108
	v_and_b32_e32 v50, 0xffff0000, v108
	v_lshl_add_u64 v[48:49], v[48:49], 0, v[196:197]
	v_lshlrev_b32_e32 v56, 16, v105
	v_and_b32_e32 v57, 0xffff0000, v105
	v_fmac_f32_e32 v47, v40, v54
	v_fmac_f32_e32 v50, v41, v55
	v_lshlrev_b32_e32 v51, 16, v109
	v_and_b32_e32 v52, 0xffff0000, v109
	v_cvt_pk_bf16_f32 v40, v58, v44
	v_fmac_f32_e32 v51, v42, v56
	v_fmac_f32_e32 v52, v43, v57
	v_cvt_pk_bf16_f32 v41, v45, v46
	v_cvt_pk_bf16_f32 v42, v47, v50
	v_cvt_pk_bf16_f32 v43, v51, v52
	global_store_dwordx4 v[48:49], v[40:43], off
	s_waitcnt vmcnt(11)
	v_lshlrev_b32_e32 v50, 16, v114
	v_lshlrev_b32_e32 v44, 16, v112
	v_lshlrev_b32_e32 v40, 16, v110
	v_and_b32_e32 v41, 0xffff0000, v110
	v_fmac_f32_e32 v50, v36, v40
	v_and_b32_e32 v36, 0xffff0000, v114
	v_lshlrev_b32_e32 v42, 16, v111
	v_fmac_f32_e32 v36, v37, v41
	v_lshlrev_b32_e32 v37, 16, v115
	v_and_b32_e32 v43, 0xffff0000, v111
	v_fmac_f32_e32 v37, v38, v42
	v_and_b32_e32 v38, 0xffff0000, v115
	v_and_b32_e32 v45, 0xffff0000, v112
	v_lshlrev_b32_e32 v46, 16, v113
	v_and_b32_e32 v47, 0xffff0000, v113
	v_fmac_f32_e32 v38, v39, v43
	v_lshlrev_b32_e32 v39, 16, v116
	v_and_b32_e32 v40, 0xffff0000, v116
	v_lshlrev_b32_e32 v41, 16, v117
	v_and_b32_e32 v42, 0xffff0000, v117
	v_fmac_f32_e32 v39, v32, v44
	v_fmac_f32_e32 v40, v33, v45
	v_fmac_f32_e32 v41, v34, v46
	v_fmac_f32_e32 v42, v35, v47
	v_cvt_pk_bf16_f32 v32, v50, v36
	v_cvt_pk_bf16_f32 v33, v37, v38
	v_cvt_pk_bf16_f32 v34, v39, v40
	v_cvt_pk_bf16_f32 v35, v41, v42
	global_store_dwordx4 v[48:49], v[32:35], off offset:256
	s_waitcnt vmcnt(10)
	v_lshlrev_b32_e32 v42, 16, v122
	v_lshlrev_b32_e32 v36, 16, v119
	v_lshlrev_b32_e32 v34, 16, v118
	v_and_b32_e32 v35, 0xffff0000, v118
	v_fmac_f32_e32 v42, v28, v34
	v_and_b32_e32 v28, 0xffff0000, v122
	v_fmac_f32_e32 v28, v29, v35
	v_lshlrev_b32_e32 v29, 16, v123
	v_and_b32_e32 v37, 0xffff0000, v119
	v_fmac_f32_e32 v29, v30, v36
	v_and_b32_e32 v30, 0xffff0000, v123
	v_lshl_add_u64 v[32:33], s[42:43], 0, v[134:135]
	v_lshlrev_b32_e32 v38, 16, v120
	v_and_b32_e32 v39, 0xffff0000, v120
	v_fmac_f32_e32 v30, v31, v37
	v_lshlrev_b32_e32 v31, 16, v124
	v_and_b32_e32 v34, 0xffff0000, v124
	v_lshl_add_u64 v[32:33], v[32:33], 0, v[196:197]
	v_lshlrev_b32_e32 v40, 16, v121
	v_and_b32_e32 v41, 0xffff0000, v121
	v_fmac_f32_e32 v31, v24, v38
	v_fmac_f32_e32 v34, v25, v39
	v_lshlrev_b32_e32 v35, 16, v125
	v_and_b32_e32 v36, 0xffff0000, v125
	v_cvt_pk_bf16_f32 v24, v42, v28
	v_fmac_f32_e32 v35, v26, v40
	v_fmac_f32_e32 v36, v27, v41
	v_cvt_pk_bf16_f32 v25, v29, v30
	v_cvt_pk_bf16_f32 v26, v31, v34
	v_cvt_pk_bf16_f32 v27, v35, v36
	global_store_dwordx4 v[32:33], v[24:27], off
	s_waitcnt vmcnt(9)
	v_lshlrev_b32_e32 v34, 16, v80
	v_lshlrev_b32_e32 v28, 16, v128
	v_lshlrev_b32_e32 v24, 16, v126
	v_and_b32_e32 v25, 0xffff0000, v126
	v_fmac_f32_e32 v34, v20, v24
	v_and_b32_e32 v20, 0xffff0000, v80
	v_lshlrev_b32_e32 v26, 16, v127
	v_fmac_f32_e32 v20, v21, v25
	v_lshlrev_b32_e32 v21, 16, v81
	v_and_b32_e32 v27, 0xffff0000, v127
	v_fmac_f32_e32 v21, v22, v26
	v_and_b32_e32 v22, 0xffff0000, v81
	v_and_b32_e32 v29, 0xffff0000, v128
	v_lshlrev_b32_e32 v30, 16, v129
	v_and_b32_e32 v31, 0xffff0000, v129
	v_fmac_f32_e32 v22, v23, v27
	v_lshlrev_b32_e32 v23, 16, v82
	v_and_b32_e32 v24, 0xffff0000, v82
	v_lshlrev_b32_e32 v25, 16, v83
	v_and_b32_e32 v26, 0xffff0000, v83
	v_fmac_f32_e32 v23, v16, v28
	v_fmac_f32_e32 v24, v17, v29
	v_fmac_f32_e32 v25, v18, v30
	v_fmac_f32_e32 v26, v19, v31
	v_cvt_pk_bf16_f32 v16, v34, v20
	v_cvt_pk_bf16_f32 v17, v21, v22
	v_cvt_pk_bf16_f32 v18, v23, v24
	v_cvt_pk_bf16_f32 v19, v25, v26
	global_store_dwordx4 v[32:33], v[16:19], off offset:256
	s_waitcnt vmcnt(8)
	v_lshlrev_b32_e32 v26, 16, v72
	v_lshlrev_b32_e32 v20, 16, v77
	v_lshlrev_b32_e32 v18, 16, v76
	v_and_b32_e32 v19, 0xffff0000, v76
	v_fmac_f32_e32 v26, v12, v18
	v_and_b32_e32 v12, 0xffff0000, v72
	v_fmac_f32_e32 v12, v13, v19
	v_lshlrev_b32_e32 v13, 16, v73
	v_and_b32_e32 v21, 0xffff0000, v77
	v_fmac_f32_e32 v13, v14, v20
	v_and_b32_e32 v14, 0xffff0000, v73
	v_lshl_add_u64 v[16:17], s[42:43], 0, v[84:85]
	v_lshlrev_b32_e32 v22, 16, v78
	v_and_b32_e32 v23, 0xffff0000, v78
	v_fmac_f32_e32 v14, v15, v21
	v_lshlrev_b32_e32 v15, 16, v74
	v_and_b32_e32 v18, 0xffff0000, v74
	v_lshl_add_u64 v[16:17], v[16:17], 0, v[196:197]
	v_lshlrev_b32_e32 v24, 16, v79
	v_and_b32_e32 v25, 0xffff0000, v79
	v_fmac_f32_e32 v15, v8, v22
	v_fmac_f32_e32 v18, v9, v23
	v_lshlrev_b32_e32 v19, 16, v75
	v_and_b32_e32 v20, 0xffff0000, v75
	v_cvt_pk_bf16_f32 v8, v26, v12
	v_fmac_f32_e32 v19, v10, v24
	v_fmac_f32_e32 v20, v11, v25
	v_cvt_pk_bf16_f32 v9, v13, v14
	v_cvt_pk_bf16_f32 v10, v15, v18
	v_cvt_pk_bf16_f32 v11, v19, v20
	global_store_dwordx4 v[16:17], v[8:11], off
	s_waitcnt vmcnt(7)
	v_lshlrev_b32_e32 v18, 16, v64
	v_lshlrev_b32_e32 v12, 16, v70
	v_lshlrev_b32_e32 v8, 16, v68
	v_and_b32_e32 v9, 0xffff0000, v68
	v_fmac_f32_e32 v18, v4, v8
	v_and_b32_e32 v4, 0xffff0000, v64
	v_lshlrev_b32_e32 v10, 16, v69
	v_fmac_f32_e32 v4, v5, v9
	v_lshlrev_b32_e32 v5, 16, v65
	v_and_b32_e32 v11, 0xffff0000, v69
	v_fmac_f32_e32 v5, v6, v10
	v_and_b32_e32 v6, 0xffff0000, v65
	v_and_b32_e32 v13, 0xffff0000, v70
	v_lshlrev_b32_e32 v14, 16, v71
	v_and_b32_e32 v15, 0xffff0000, v71
	v_fmac_f32_e32 v6, v7, v11
	v_lshlrev_b32_e32 v7, 16, v66
	v_and_b32_e32 v8, 0xffff0000, v66
	v_lshlrev_b32_e32 v9, 16, v67
	v_and_b32_e32 v10, 0xffff0000, v67
	v_fmac_f32_e32 v7, v0, v12
	v_fmac_f32_e32 v8, v1, v13
	v_fmac_f32_e32 v9, v2, v14
	v_fmac_f32_e32 v10, v3, v15
	v_cvt_pk_bf16_f32 v0, v18, v4
	v_cvt_pk_bf16_f32 v1, v5, v6
	v_cvt_pk_bf16_f32 v2, v7, v8
	v_cvt_pk_bf16_f32 v3, v9, v10
	global_store_dwordx4 v[16:17], v[0:3], off offset:256
	s_mov_b32 s99, 1
	s_cbranch_vccnz .LBB0_2290
	s_andn2_b64 vcc, exec, s[0:1]
	s_cbranch_vccnz .LBB0_2289
	s_barrier
	s_branch .LBB0_2289

.LBB0_2377:
	s_cmp_eq_u64 s[10:11], 0
	s_cbranch_scc1 .Lrs3skip22
	s_lshl_b32 s98, s60, 8
	s_add_i32 s98, s98, s13
	v_add_u32_e32 v150, s98, v153
	v_lshlrev_b32_e32 v200, 3, v151
	v_ashrrev_i32_e32 v201, 31, v200
	v_lshl_add_u64 v[200:201], v[200:201], 2, s[76:77]
	v_mov_b32_e32 v252, v150
	v_ashrrev_i32_e32 v253, 31, v252
	v_lshlrev_b64 v[252:253], 7, v[252:253]
	v_lshl_add_u64 v[252:253], v[200:201], 0, v[252:253]
	global_load_dwordx4 v[184:187], v[252:253], off offset:16
	global_load_dwordx4 v[188:191], v[252:253], off
	v_add_u32_e32 v252, 0x10, v150
	v_ashrrev_i32_e32 v253, 31, v252
	v_lshlrev_b64 v[252:253], 7, v[252:253]
	v_lshl_add_u64 v[252:253], v[200:201], 0, v[252:253]
	global_load_dwordx4 v[192:195], v[252:253], off offset:16
	global_load_dwordx4 v[196:199], v[252:253], off
	v_add_u32_e32 v252, 0x20, v150
	v_ashrrev_i32_e32 v253, 31, v252
	v_lshlrev_b64 v[252:253], 7, v[252:253]
	v_lshl_add_u64 v[252:253], v[200:201], 0, v[252:253]
	global_load_dwordx4 v[204:207], v[252:253], off offset:16
	global_load_dwordx4 v[208:211], v[252:253], off
	v_add_u32_e32 v252, 0x30, v150
	v_ashrrev_i32_e32 v253, 31, v252
	v_lshlrev_b64 v[252:253], 7, v[252:253]
	v_lshl_add_u64 v[252:253], v[200:201], 0, v[252:253]
	global_load_dwordx4 v[212:215], v[252:253], off offset:16
	global_load_dwordx4 v[216:219], v[252:253], off
	v_add_u32_e32 v252, 0x80, v150
	v_ashrrev_i32_e32 v253, 31, v252
	v_lshlrev_b64 v[252:253], 7, v[252:253]
	v_lshl_add_u64 v[252:253], v[200:201], 0, v[252:253]
	global_load_dwordx4 v[220:223], v[252:253], off offset:16
	global_load_dwordx4 v[224:227], v[252:253], off
	v_add_u32_e32 v252, 0x90, v150
	v_ashrrev_i32_e32 v253, 31, v252
	v_lshlrev_b64 v[252:253], 7, v[252:253]
	v_lshl_add_u64 v[252:253], v[200:201], 0, v[252:253]
	global_load_dwordx4 v[228:231], v[252:253], off offset:16
	global_load_dwordx4 v[232:235], v[252:253], off
	v_add_u32_e32 v252, 0xa0, v150
	v_ashrrev_i32_e32 v253, 31, v252
	v_lshlrev_b64 v[252:253], 7, v[252:253]
	v_lshl_add_u64 v[252:253], v[200:201], 0, v[252:253]
	global_load_dwordx4 v[236:239], v[252:253], off offset:16
	global_load_dwordx4 v[240:243], v[252:253], off
	v_add_u32_e32 v252, 0xb0, v150
	v_ashrrev_i32_e32 v253, 31, v252
	v_lshlrev_b64 v[252:253], 7, v[252:253]
	v_lshl_add_u64 v[252:253], v[200:201], 0, v[252:253]
	global_load_dwordx4 v[244:247], v[252:253], off offset:16
	global_load_dwordx4 v[248:251], v[252:253], off

.LBB0_2393:
	s_or_b64 exec, exec, s[46:47]
	s_andn2_b64 vcc, exec, s[10:11]
	s_mov_b64 s[10:11], -1
	s_cbranch_vccnz .LBB0_2366
	v_mov_b32_e32 v0, v153
	v_mov_b32_e32 v1, v151
	s_lshl_b32 s10, s60, 8
	s_add_i32 s10, s10, s13
	v_add_u32_e32 v0, s10, v0
	s_waitcnt lgkmcnt(0)
	v_lshlrev_b32_e32 v2, 3, v1
	v_ashrrev_i32_e32 v3, 31, v2
	v_ashrrev_i32_e32 v1, 31, v0
	v_lshl_add_u64 v[6:7], v[2:3], 2, s[76:77]
	v_lshlrev_b64 v[4:5], 7, v[0:1]
	v_lshl_add_u64 v[4:5], v[6:7], 0, v[4:5]
	s_waitcnt vmcnt(16)
	v_mov_b32_e32 v8, v184
	v_mov_b32_e32 v9, v185
	v_mov_b32_e32 v10, v186
	v_mov_b32_e32 v11, v187
	v_mov_b32_e32 v12, v188
	v_mov_b32_e32 v13, v189
	v_mov_b32_e32 v14, v190
	v_mov_b32_e32 v15, v191
	v_add_u32_e32 v56, 0x90, v0
	v_ashrrev_i32_e32 v57, 31, v56
	v_add_u32_e32 v58, 0xa0, v0
	v_ashrrev_i32_e32 v59, 31, v58
	v_add_u32_e32 v60, 0xb0, v0
	v_ashrrev_i32_e32 v61, 31, v60
	s_lshl_b32 s10, s36, 8
	s_or_b32 s10, s10, s66
	v_add_u32_e32 v2, s10, v2
	v_ashrrev_i32_e32 v3, 31, v2
	v_readlane_b32 s10, v255, 48
	v_readlane_b32 s11, v255, 49
	s_andn2_b64 vcc, exec, s[6:7]
	v_mov_b32_e32 v5, v8
	v_mov_b32_e32 v4, v12
	v_mov_b32_e32 v16, v14
	v_mov_b32_e32 v17, v10
	v_pk_add_f32 v[4:5], v[4:5], v[16:17]
	v_add_f32_e32 v8, v13, v15
	v_add_f32_e32 v10, v9, v11
	v_mov_b32_e32 v9, v4
	v_mov_b32_e32 v11, v5
	v_pk_add_f32 v[4:5], v[8:9], v[10:11]
	ds_bpermute_b32 v9, v155, v5
	ds_bpermute_b32 v8, v155, v4
	s_waitcnt lgkmcnt(0)
	v_pk_add_f32 v[48:49], v[4:5], v[8:9]
	v_add_u32_e32 v4, 16, v0
	v_ashrrev_i32_e32 v5, 31, v4
	v_lshlrev_b64 v[8:9], 7, v[4:5]
	v_lshl_add_u64 v[12:13], v[6:7], 0, v[8:9]
	v_mov_b32_e32 v8, v192
	v_mov_b32_e32 v9, v193
	v_mov_b32_e32 v10, v194
	v_mov_b32_e32 v11, v195
	s_nop 0
	v_mov_b32_e32 v12, v196
	v_mov_b32_e32 v13, v197
	v_mov_b32_e32 v14, v198
	v_mov_b32_e32 v15, v199
	ds_bpermute_b32 v51, v157, v49
	ds_bpermute_b32 v50, v157, v48
	v_mov_b32_e32 v17, v8
	v_mov_b32_e32 v16, v12
	v_mov_b32_e32 v18, v14
	v_mov_b32_e32 v19, v10
	v_pk_add_f32 v[16:17], v[16:17], v[18:19]
	v_add_f32_e32 v8, v13, v15
	v_add_f32_e32 v10, v9, v11
	v_mov_b32_e32 v9, v16
	v_mov_b32_e32 v11, v17
	v_pk_add_f32 v[8:9], v[8:9], v[10:11]
	ds_bpermute_b32 v11, v155, v9
	ds_bpermute_b32 v10, v155, v8
	s_waitcnt lgkmcnt(0)
	v_pk_add_f32 v[52:53], v[8:9], v[10:11]
	v_add_u32_e32 v8, 32, v0
	v_ashrrev_i32_e32 v9, 31, v8
	v_lshlrev_b64 v[10:11], 7, v[8:9]
	v_lshl_add_u64 v[14:15], v[6:7], 0, v[10:11]
	v_mov_b32_e32 v10, v204
	v_mov_b32_e32 v11, v205
	v_mov_b32_e32 v12, v206
	v_mov_b32_e32 v13, v207
	s_nop 0
	v_mov_b32_e32 v14, v208
	v_mov_b32_e32 v15, v209
	v_mov_b32_e32 v16, v210
	v_mov_b32_e32 v17, v211
	ds_bpermute_b32 v55, v157, v53
	ds_bpermute_b32 v54, v157, v52
	v_mov_b32_e32 v19, v10
	v_mov_b32_e32 v18, v14
	v_mov_b32_e32 v20, v16
	v_mov_b32_e32 v21, v12
	v_pk_add_f32 v[18:19], v[18:19], v[20:21]
	v_add_f32_e32 v10, v15, v17
	v_add_f32_e32 v12, v11, v13
	v_mov_b32_e32 v11, v18
	v_mov_b32_e32 v13, v19
	v_pk_add_f32 v[10:11], v[10:11], v[12:13]
	ds_bpermute_b32 v13, v155, v11
	ds_bpermute_b32 v12, v155, v10
	s_waitcnt lgkmcnt(0)
	v_pk_add_f32 v[64:65], v[10:11], v[12:13]
	v_add_u32_e32 v10, 48, v0
	v_ashrrev_i32_e32 v11, 31, v10
	v_lshlrev_b64 v[12:13], 7, v[10:11]
	v_lshl_add_u64 v[16:17], v[6:7], 0, v[12:13]
	v_mov_b32_e32 v12, v212
	v_mov_b32_e32 v13, v213
	v_mov_b32_e32 v14, v214
	v_mov_b32_e32 v15, v215
	s_nop 0
	v_mov_b32_e32 v16, v216
	v_mov_b32_e32 v17, v217
	v_mov_b32_e32 v18, v218
	v_mov_b32_e32 v19, v219
	ds_bpermute_b32 v67, v157, v65
	ds_bpermute_b32 v66, v157, v64
	v_mov_b32_e32 v21, v12
	v_mov_b32_e32 v20, v16
	v_mov_b32_e32 v22, v18
	v_mov_b32_e32 v23, v14
	v_pk_add_f32 v[20:21], v[20:21], v[22:23]
	v_add_f32_e32 v12, v17, v19
	v_add_f32_e32 v14, v13, v15
	v_mov_b32_e32 v13, v20
	v_mov_b32_e32 v15, v21
	v_pk_add_f32 v[12:13], v[12:13], v[14:15]
	ds_bpermute_b32 v15, v155, v13
	ds_bpermute_b32 v14, v155, v12
	s_waitcnt lgkmcnt(0)
	v_pk_add_f32 v[68:69], v[12:13], v[14:15]
	v_add_u32_e32 v12, 0x80, v0
	v_ashrrev_i32_e32 v13, 31, v12
	v_lshlrev_b64 v[14:15], 7, v[12:13]
	v_lshl_add_u64 v[18:19], v[6:7], 0, v[14:15]
	v_mov_b32_e32 v14, v220
	v_mov_b32_e32 v15, v221
	v_mov_b32_e32 v16, v222
	v_mov_b32_e32 v17, v223
	s_nop 0
	v_mov_b32_e32 v18, v224
	v_mov_b32_e32 v19, v225
	v_mov_b32_e32 v20, v226
	v_mov_b32_e32 v21, v227
	v_lshlrev_b64 v[0:1], 11, v[0:1]
	v_lshl_add_u64 v[0:1], s[44:45], 0, v[0:1]
	ds_bpermute_b32 v71, v157, v69
	ds_bpermute_b32 v70, v157, v68
	v_mov_b32_e32 v23, v14
	v_mov_b32_e32 v22, v18
	v_mov_b32_e32 v24, v20
	v_mov_b32_e32 v25, v16
	v_pk_add_f32 v[22:23], v[22:23], v[24:25]
	v_add_f32_e32 v14, v19, v21
	v_add_f32_e32 v16, v15, v17
	v_mov_b32_e32 v15, v22
	v_mov_b32_e32 v17, v23
	v_pk_add_f32 v[14:15], v[14:15], v[16:17]
	ds_bpermute_b32 v17, v155, v15
	ds_bpermute_b32 v16, v155, v14
	s_waitcnt lgkmcnt(0)
	v_pk_add_f32 v[112:113], v[14:15], v[16:17]
	v_lshlrev_b64 v[14:15], 7, v[56:57]
	v_lshl_add_u64 v[18:19], v[6:7], 0, v[14:15]
	v_mov_b32_e32 v14, v228
	v_mov_b32_e32 v15, v229
	v_mov_b32_e32 v16, v230
	v_mov_b32_e32 v17, v231
	s_nop 0
	v_mov_b32_e32 v18, v232
	v_mov_b32_e32 v19, v233
	v_mov_b32_e32 v20, v234
	v_mov_b32_e32 v21, v235
	ds_bpermute_b32 v115, v157, v113
	ds_bpermute_b32 v114, v157, v112
	v_mov_b32_e32 v23, v14
	v_mov_b32_e32 v22, v18
	v_mov_b32_e32 v24, v20
	v_mov_b32_e32 v25, v16
	v_pk_add_f32 v[22:23], v[22:23], v[24:25]
	v_add_f32_e32 v14, v19, v21
	v_add_f32_e32 v16, v15, v17
	v_mov_b32_e32 v15, v22
	v_mov_b32_e32 v17, v23
	v_pk_add_f32 v[14:15], v[14:15], v[16:17]
	ds_bpermute_b32 v17, v155, v15
	ds_bpermute_b32 v16, v155, v14
	s_waitcnt lgkmcnt(0)
	v_pk_add_f32 v[116:117], v[14:15], v[16:17]
	v_lshlrev_b64 v[14:15], 7, v[58:59]
	v_lshl_add_u64 v[18:19], v[6:7], 0, v[14:15]
	v_mov_b32_e32 v14, v236
	v_mov_b32_e32 v15, v237
	v_mov_b32_e32 v16, v238
	v_mov_b32_e32 v17, v239
	s_nop 0
	v_mov_b32_e32 v18, v240
	v_mov_b32_e32 v19, v241
	v_mov_b32_e32 v20, v242
	v_mov_b32_e32 v21, v243
	ds_bpermute_b32 v119, v157, v117
	ds_bpermute_b32 v118, v157, v116
	v_mov_b32_e32 v23, v14
	v_mov_b32_e32 v22, v18
	v_mov_b32_e32 v24, v20
	v_mov_b32_e32 v25, v16
	v_pk_add_f32 v[22:23], v[22:23], v[24:25]
	v_add_f32_e32 v14, v19, v21
	v_add_f32_e32 v16, v15, v17
	v_mov_b32_e32 v15, v22
	v_mov_b32_e32 v17, v23
	v_pk_add_f32 v[14:15], v[14:15], v[16:17]
	ds_bpermute_b32 v17, v155, v15
	ds_bpermute_b32 v16, v155, v14
	s_waitcnt lgkmcnt(0)
	v_pk_add_f32 v[120:121], v[14:15], v[16:17]
	v_lshlrev_b64 v[14:15], 7, v[60:61]
	v_lshl_add_u64 v[6:7], v[6:7], 0, v[14:15]
	v_mov_b32_e32 v14, v244
	v_mov_b32_e32 v15, v245
	v_mov_b32_e32 v16, v246
	v_mov_b32_e32 v17, v247
	v_mov_b32_e32 v18, v248
	v_mov_b32_e32 v19, v249
	v_mov_b32_e32 v20, v250
	v_mov_b32_e32 v21, v251
	ds_bpermute_b32 v123, v157, v121
	ds_bpermute_b32 v122, v157, v120
	v_mov_b32_e32 v7, v14
	v_mov_b32_e32 v6, v18
	v_mov_b32_e32 v22, v20
	v_mov_b32_e32 v23, v16
	v_pk_add_f32 v[6:7], v[6:7], v[22:23]
	v_add_f32_e32 v14, v19, v21
	v_add_f32_e32 v16, v15, v17
	v_mov_b32_e32 v15, v6
	v_mov_b32_e32 v17, v7
	v_pk_add_f32 v[6:7], v[14:15], v[16:17]
	ds_bpermute_b32 v15, v155, v7
	ds_bpermute_b32 v14, v155, v6
	s_waitcnt lgkmcnt(0)
	v_pk_add_f32 v[124:125], v[6:7], v[14:15]
	v_lshlrev_b64 v[6:7], 2, v[2:3]
	v_lshlrev_b64 v[2:3], 1, v[2:3]
	v_lshl_add_u64 v[74:75], v[0:1], 0, v[2:3]
	v_lshlrev_b64 v[0:1], 11, v[4:5]
	v_lshl_add_u64 v[0:1], s[44:45], 0, v[0:1]
	v_lshl_add_u64 v[76:77], v[0:1], 0, v[2:3]
	v_lshlrev_b64 v[0:1], 11, v[8:9]
	v_lshl_add_u64 v[0:1], s[44:45], 0, v[0:1]
	v_lshl_add_u64 v[78:79], v[0:1], 0, v[2:3]
	v_lshlrev_b64 v[0:1], 11, v[10:11]
	v_lshl_add_u64 v[0:1], s[44:45], 0, v[0:1]
	v_lshl_add_u64 v[80:81], v[0:1], 0, v[2:3]
	v_lshlrev_b64 v[0:1], 11, v[12:13]
	v_lshl_add_u64 v[0:1], s[44:45], 0, v[0:1]
	v_lshl_add_u64 v[146:147], v[0:1], 0, v[2:3]
	v_lshlrev_b64 v[0:1], 11, v[56:57]
	v_lshl_add_u64 v[0:1], s[44:45], 0, v[0:1]
	v_lshl_add_u64 v[56:57], v[0:1], 0, v[2:3]
	v_lshlrev_b64 v[0:1], 11, v[58:59]
	v_lshl_add_u64 v[0:1], s[44:45], 0, v[0:1]
	v_lshl_add_u64 v[58:59], v[0:1], 0, v[2:3]
	v_lshlrev_b64 v[0:1], 11, v[60:61]
	v_lshl_add_u64 v[0:1], s[44:45], 0, v[0:1]
	v_lshl_add_u64 v[62:63], s[10:11], 0, v[6:7]
	v_lshl_add_u64 v[72:73], s[0:1], 0, v[6:7]
	v_lshl_add_u64 v[148:149], v[0:1], 0, v[2:3]
	global_load_dwordx4 v[36:39], v[62:63], off offset:16
	global_load_dwordx4 v[44:47], v[62:63], off
	global_load_dwordx4 v[32:35], v[72:73], off offset:16
	global_load_dwordx4 v[40:43], v[72:73], off
	global_load_dwordx4 v[28:31], v[74:75], off
	global_load_dwordx4 v[24:27], v[76:77], off
	global_load_dwordx4 v[20:23], v[78:79], off
	global_load_dwordx4 v[16:19], v[80:81], off
	global_load_dwordx4 v[12:15], v[146:147], off
	global_load_dwordx4 v[8:11], v[56:57], off
	global_load_dwordx4 v[4:7], v[58:59], off
	global_load_dwordx4 v[0:3], v[148:149], off
	global_load_dwordx4 v[104:107], v[62:63], off offset:528
	global_load_dwordx4 v[108:111], v[62:63], off offset:512
	global_load_dwordx4 v[96:99], v[72:73], off offset:528
	global_load_dwordx4 v[100:103], v[72:73], off offset:512
	global_load_dwordx4 v[92:95], v[74:75], off offset:256
	global_load_dwordx4 v[88:91], v[76:77], off offset:256
	global_load_dwordx4 v[84:87], v[78:79], off offset:256
	s_nop 0
	global_load_dwordx4 v[80:83], v[80:81], off offset:256
	s_nop 0
	global_load_dwordx4 v[76:79], v[146:147], off offset:256
	global_load_dwordx4 v[72:75], v[56:57], off offset:256
	global_load_dwordx4 v[60:63], v[58:59], off offset:256
	s_nop 0
	global_load_dwordx4 v[56:59], v[148:149], off offset:256
	ds_bpermute_b32 v127, v157, v125
	ds_bpermute_b32 v126, v157, v124
	s_cbranch_vccnz .LBB0_2365
	s_barrier
	s_branch .LBB0_2365

.LBB0_2572:
	s_or_b64 exec, exec, s[46:47]
	s_and_b64 vcc, exec, s[10:11]
	s_mov_b64 s[10:11], -1
	s_cbranch_vccnz .LBB0_2541
	v_mov_b32_e32 v0, v153
	v_mov_b32_e32 v1, v151
	s_lshl_b32 s10, s78, 8
	s_add_i32 s10, s10, s15
	v_add_u32_e32 v0, s10, v0
	s_waitcnt lgkmcnt(0)
	v_lshlrev_b32_e32 v2, 3, v1
	v_ashrrev_i32_e32 v3, 31, v2
	v_ashrrev_i32_e32 v1, 31, v0
	v_lshl_add_u64 v[6:7], v[2:3], 2, s[62:63]
	v_lshlrev_b64 v[4:5], 7, v[0:1]
	v_lshl_add_u64 v[4:5], v[6:7], 0, v[4:5]
	s_waitcnt vmcnt(16)
	v_mov_b32_e32 v8, v184
	v_mov_b32_e32 v9, v185
	v_mov_b32_e32 v10, v186
	v_mov_b32_e32 v11, v187
	v_mov_b32_e32 v12, v188
	v_mov_b32_e32 v13, v189
	v_mov_b32_e32 v14, v190
	v_mov_b32_e32 v15, v191
	v_add_u32_e32 v56, 0x90, v0
	v_ashrrev_i32_e32 v57, 31, v56
	v_add_u32_e32 v58, 0xa0, v0
	v_ashrrev_i32_e32 v59, 31, v58
	v_add_u32_e32 v60, 0xb0, v0
	v_ashrrev_i32_e32 v61, 31, v60
	s_lshl_b32 s10, s73, 8
	s_or_b32 s10, s10, s66
	v_add_u32_e32 v2, s10, v2
	v_ashrrev_i32_e32 v3, 31, v2
	v_readlane_b32 s10, v255, 50
	v_readlane_b32 s11, v255, 51
	s_andn2_b64 vcc, exec, s[6:7]
	v_mov_b32_e32 v5, v8
	v_mov_b32_e32 v4, v12
	v_mov_b32_e32 v16, v14
	v_mov_b32_e32 v17, v10
	v_pk_add_f32 v[4:5], v[4:5], v[16:17]
	v_add_f32_e32 v8, v13, v15
	v_add_f32_e32 v10, v9, v11
	v_mov_b32_e32 v9, v4
	v_mov_b32_e32 v11, v5
	v_pk_add_f32 v[4:5], v[8:9], v[10:11]
	ds_bpermute_b32 v9, v155, v5
	ds_bpermute_b32 v8, v155, v4
	s_waitcnt lgkmcnt(0)
	v_pk_add_f32 v[48:49], v[4:5], v[8:9]
	v_add_u32_e32 v4, 16, v0
	v_ashrrev_i32_e32 v5, 31, v4
	v_lshlrev_b64 v[8:9], 7, v[4:5]
	v_lshl_add_u64 v[12:13], v[6:7], 0, v[8:9]
	v_mov_b32_e32 v8, v192
	v_mov_b32_e32 v9, v193
	v_mov_b32_e32 v10, v194
	v_mov_b32_e32 v11, v195
	s_nop 0
	v_mov_b32_e32 v12, v196
	v_mov_b32_e32 v13, v197
	v_mov_b32_e32 v14, v198
	v_mov_b32_e32 v15, v199
	ds_bpermute_b32 v51, v157, v49
	ds_bpermute_b32 v50, v157, v48
	v_mov_b32_e32 v17, v8
	v_mov_b32_e32 v16, v12
	v_mov_b32_e32 v18, v14
	v_mov_b32_e32 v19, v10
	v_pk_add_f32 v[16:17], v[16:17], v[18:19]
	v_add_f32_e32 v8, v13, v15
	v_add_f32_e32 v10, v9, v11
	v_mov_b32_e32 v9, v16
	v_mov_b32_e32 v11, v17
	v_pk_add_f32 v[8:9], v[8:9], v[10:11]
	ds_bpermute_b32 v11, v155, v9
	ds_bpermute_b32 v10, v155, v8
	s_waitcnt lgkmcnt(0)
	v_pk_add_f32 v[52:53], v[8:9], v[10:11]
	v_add_u32_e32 v8, 32, v0
	v_ashrrev_i32_e32 v9, 31, v8
	v_lshlrev_b64 v[10:11], 7, v[8:9]
	v_lshl_add_u64 v[14:15], v[6:7], 0, v[10:11]
	v_mov_b32_e32 v10, v204
	v_mov_b32_e32 v11, v205
	v_mov_b32_e32 v12, v206
	v_mov_b32_e32 v13, v207
	s_nop 0
	v_mov_b32_e32 v14, v208
	v_mov_b32_e32 v15, v209
	v_mov_b32_e32 v16, v210
	v_mov_b32_e32 v17, v211
	ds_bpermute_b32 v55, v157, v53
	ds_bpermute_b32 v54, v157, v52
	v_mov_b32_e32 v19, v10
	v_mov_b32_e32 v18, v14
	v_mov_b32_e32 v20, v16
	v_mov_b32_e32 v21, v12
	v_pk_add_f32 v[18:19], v[18:19], v[20:21]
	v_add_f32_e32 v10, v15, v17
	v_add_f32_e32 v12, v11, v13
	v_mov_b32_e32 v11, v18
	v_mov_b32_e32 v13, v19
	v_pk_add_f32 v[10:11], v[10:11], v[12:13]
	ds_bpermute_b32 v13, v155, v11
	ds_bpermute_b32 v12, v155, v10
	s_waitcnt lgkmcnt(0)
	v_pk_add_f32 v[64:65], v[10:11], v[12:13]
	v_add_u32_e32 v10, 48, v0
	v_ashrrev_i32_e32 v11, 31, v10
	v_lshlrev_b64 v[12:13], 7, v[10:11]
	v_lshl_add_u64 v[16:17], v[6:7], 0, v[12:13]
	v_mov_b32_e32 v12, v212
	v_mov_b32_e32 v13, v213
	v_mov_b32_e32 v14, v214
	v_mov_b32_e32 v15, v215
	s_nop 0
	v_mov_b32_e32 v16, v216
	v_mov_b32_e32 v17, v217
	v_mov_b32_e32 v18, v218
	v_mov_b32_e32 v19, v219
	ds_bpermute_b32 v67, v157, v65
	ds_bpermute_b32 v66, v157, v64
	v_mov_b32_e32 v21, v12
	v_mov_b32_e32 v20, v16
	v_mov_b32_e32 v22, v18
	v_mov_b32_e32 v23, v14
	v_pk_add_f32 v[20:21], v[20:21], v[22:23]
	v_add_f32_e32 v12, v17, v19
	v_add_f32_e32 v14, v13, v15
	v_mov_b32_e32 v13, v20
	v_mov_b32_e32 v15, v21
	v_pk_add_f32 v[12:13], v[12:13], v[14:15]
	ds_bpermute_b32 v15, v155, v13
	ds_bpermute_b32 v14, v155, v12
	s_waitcnt lgkmcnt(0)
	v_pk_add_f32 v[68:69], v[12:13], v[14:15]
	v_add_u32_e32 v12, 0x80, v0
	v_ashrrev_i32_e32 v13, 31, v12
	v_lshlrev_b64 v[14:15], 7, v[12:13]
	v_lshl_add_u64 v[18:19], v[6:7], 0, v[14:15]
	v_mov_b32_e32 v14, v220
	v_mov_b32_e32 v15, v221
	v_mov_b32_e32 v16, v222
	v_mov_b32_e32 v17, v223
	s_nop 0
	v_mov_b32_e32 v18, v224
	v_mov_b32_e32 v19, v225
	v_mov_b32_e32 v20, v226
	v_mov_b32_e32 v21, v227
	v_lshlrev_b64 v[0:1], 11, v[0:1]
	v_lshl_add_u64 v[0:1], s[44:45], 0, v[0:1]
	ds_bpermute_b32 v71, v157, v69
	ds_bpermute_b32 v70, v157, v68
	v_mov_b32_e32 v23, v14
	v_mov_b32_e32 v22, v18
	v_mov_b32_e32 v24, v20
	v_mov_b32_e32 v25, v16
	v_pk_add_f32 v[22:23], v[22:23], v[24:25]
	v_add_f32_e32 v14, v19, v21
	v_add_f32_e32 v16, v15, v17
	v_mov_b32_e32 v15, v22
	v_mov_b32_e32 v17, v23
	v_pk_add_f32 v[14:15], v[14:15], v[16:17]
	ds_bpermute_b32 v17, v155, v15
	ds_bpermute_b32 v16, v155, v14
	s_waitcnt lgkmcnt(0)
	v_pk_add_f32 v[112:113], v[14:15], v[16:17]
	v_lshlrev_b64 v[14:15], 7, v[56:57]
	v_lshl_add_u64 v[18:19], v[6:7], 0, v[14:15]
	v_mov_b32_e32 v14, v228
	v_mov_b32_e32 v15, v229
	v_mov_b32_e32 v16, v230
	v_mov_b32_e32 v17, v231
	s_nop 0
	v_mov_b32_e32 v18, v232
	v_mov_b32_e32 v19, v233
	v_mov_b32_e32 v20, v234
	v_mov_b32_e32 v21, v235
	ds_bpermute_b32 v115, v157, v113
	ds_bpermute_b32 v114, v157, v112
	v_mov_b32_e32 v23, v14
	v_mov_b32_e32 v22, v18
	v_mov_b32_e32 v24, v20
	v_mov_b32_e32 v25, v16
	v_pk_add_f32 v[22:23], v[22:23], v[24:25]
	v_add_f32_e32 v14, v19, v21
	v_add_f32_e32 v16, v15, v17
	v_mov_b32_e32 v15, v22
	v_mov_b32_e32 v17, v23
	v_pk_add_f32 v[14:15], v[14:15], v[16:17]
	ds_bpermute_b32 v17, v155, v15
	ds_bpermute_b32 v16, v155, v14
	s_waitcnt lgkmcnt(0)
	v_pk_add_f32 v[116:117], v[14:15], v[16:17]
	v_lshlrev_b64 v[14:15], 7, v[58:59]
	v_lshl_add_u64 v[18:19], v[6:7], 0, v[14:15]
	v_mov_b32_e32 v14, v236
	v_mov_b32_e32 v15, v237
	v_mov_b32_e32 v16, v238
	v_mov_b32_e32 v17, v239
	s_nop 0
	v_mov_b32_e32 v18, v240
	v_mov_b32_e32 v19, v241
	v_mov_b32_e32 v20, v242
	v_mov_b32_e32 v21, v243
	ds_bpermute_b32 v119, v157, v117
	ds_bpermute_b32 v118, v157, v116
	v_mov_b32_e32 v23, v14
	v_mov_b32_e32 v22, v18
	v_mov_b32_e32 v24, v20
	v_mov_b32_e32 v25, v16
	v_pk_add_f32 v[22:23], v[22:23], v[24:25]
	v_add_f32_e32 v14, v19, v21
	v_add_f32_e32 v16, v15, v17
	v_mov_b32_e32 v15, v22
	v_mov_b32_e32 v17, v23
	v_pk_add_f32 v[14:15], v[14:15], v[16:17]
	ds_bpermute_b32 v17, v155, v15
	ds_bpermute_b32 v16, v155, v14
	s_waitcnt lgkmcnt(0)
	v_pk_add_f32 v[120:121], v[14:15], v[16:17]
	v_lshlrev_b64 v[14:15], 7, v[60:61]
	v_lshl_add_u64 v[6:7], v[6:7], 0, v[14:15]
	v_mov_b32_e32 v14, v244
	v_mov_b32_e32 v15, v245
	v_mov_b32_e32 v16, v246
	v_mov_b32_e32 v17, v247
	v_mov_b32_e32 v18, v248
	v_mov_b32_e32 v19, v249
	v_mov_b32_e32 v20, v250
	v_mov_b32_e32 v21, v251
	ds_bpermute_b32 v123, v157, v121
	ds_bpermute_b32 v122, v157, v120
	v_mov_b32_e32 v7, v14
	v_mov_b32_e32 v6, v18
	v_mov_b32_e32 v22, v20
	v_mov_b32_e32 v23, v16
	v_pk_add_f32 v[6:7], v[6:7], v[22:23]
	v_add_f32_e32 v14, v19, v21
	v_add_f32_e32 v16, v15, v17
	v_mov_b32_e32 v15, v6
	v_mov_b32_e32 v17, v7
	v_pk_add_f32 v[6:7], v[14:15], v[16:17]
	ds_bpermute_b32 v15, v155, v7
	ds_bpermute_b32 v14, v155, v6
	s_waitcnt lgkmcnt(0)
	v_pk_add_f32 v[124:125], v[6:7], v[14:15]
	v_lshlrev_b64 v[6:7], 2, v[2:3]
	v_lshlrev_b64 v[2:3], 1, v[2:3]
	v_lshl_add_u64 v[74:75], v[0:1], 0, v[2:3]
	v_lshlrev_b64 v[0:1], 11, v[4:5]
	v_lshl_add_u64 v[0:1], s[44:45], 0, v[0:1]
	v_lshl_add_u64 v[76:77], v[0:1], 0, v[2:3]
	v_lshlrev_b64 v[0:1], 11, v[8:9]
	v_lshl_add_u64 v[0:1], s[44:45], 0, v[0:1]
	v_lshl_add_u64 v[78:79], v[0:1], 0, v[2:3]
	v_lshlrev_b64 v[0:1], 11, v[10:11]
	v_lshl_add_u64 v[0:1], s[44:45], 0, v[0:1]
	v_lshl_add_u64 v[80:81], v[0:1], 0, v[2:3]
	v_lshlrev_b64 v[0:1], 11, v[12:13]
	v_lshl_add_u64 v[0:1], s[44:45], 0, v[0:1]
	v_lshl_add_u64 v[146:147], v[0:1], 0, v[2:3]
	v_lshlrev_b64 v[0:1], 11, v[56:57]
	v_lshl_add_u64 v[0:1], s[44:45], 0, v[0:1]
	v_lshl_add_u64 v[56:57], v[0:1], 0, v[2:3]
	v_lshlrev_b64 v[0:1], 11, v[58:59]
	v_lshl_add_u64 v[0:1], s[44:45], 0, v[0:1]
	v_lshl_add_u64 v[58:59], v[0:1], 0, v[2:3]
	v_lshlrev_b64 v[0:1], 11, v[60:61]
	v_lshl_add_u64 v[0:1], s[44:45], 0, v[0:1]
	v_lshl_add_u64 v[62:63], s[10:11], 0, v[6:7]
	v_lshl_add_u64 v[72:73], s[0:1], 0, v[6:7]
	v_lshl_add_u64 v[148:149], v[0:1], 0, v[2:3]
	global_load_dwordx4 v[36:39], v[62:63], off offset:16
	global_load_dwordx4 v[44:47], v[62:63], off
	global_load_dwordx4 v[32:35], v[72:73], off offset:16
	global_load_dwordx4 v[40:43], v[72:73], off
	global_load_dwordx4 v[28:31], v[74:75], off
	global_load_dwordx4 v[24:27], v[76:77], off
	global_load_dwordx4 v[20:23], v[78:79], off
	global_load_dwordx4 v[16:19], v[80:81], off
	global_load_dwordx4 v[12:15], v[146:147], off
	global_load_dwordx4 v[8:11], v[56:57], off
	global_load_dwordx4 v[4:7], v[58:59], off
	global_load_dwordx4 v[0:3], v[148:149], off
	global_load_dwordx4 v[104:107], v[62:63], off offset:528
	global_load_dwordx4 v[108:111], v[62:63], off offset:512
	global_load_dwordx4 v[96:99], v[72:73], off offset:528
	global_load_dwordx4 v[100:103], v[72:73], off offset:512
	global_load_dwordx4 v[92:95], v[74:75], off offset:256
	global_load_dwordx4 v[88:91], v[76:77], off offset:256
	global_load_dwordx4 v[84:87], v[78:79], off offset:256
	s_nop 0
	global_load_dwordx4 v[80:83], v[80:81], off offset:256
	s_nop 0
	global_load_dwordx4 v[76:79], v[146:147], off offset:256
	global_load_dwordx4 v[72:75], v[56:57], off offset:256
	global_load_dwordx4 v[60:63], v[58:59], off offset:256
	s_nop 0
	global_load_dwordx4 v[56:59], v[148:149], off offset:256
	ds_bpermute_b32 v127, v157, v125
	ds_bpermute_b32 v126, v157, v124
	s_cbranch_vccnz .LBB0_2540
	s_barrier
	s_branch .LBB0_2540

.LBB0_3128:
	s_lshl_b32 s47, s4, 6
	s_lshl_b32 s10, s4, 13
	s_lshl_b32 s4, s5, 5
	s_and_b32 s48, s4, 0x60
	s_mov_b64 s[4:5], 0x80
	s_add_i32 m0, s23, 0x18000
	v_lshl_add_u64 v[6:7], v[6:7], 0, s[4:5]
	s_lshl_b32 s11, s48, 7
	s_waitcnt vmcnt(2)
	s_barrier
	global_load_lds_dwordx4 v[6:7], off
	v_lshl_add_u64 v[4:5], v[4:5], 0, s[4:5]
	s_add_i32 m0, s23, 0x1a000
	s_add_i32 s49, s23, 0x8000
	s_add_i32 s50, s23, 0xa000
	global_load_lds_dwordx4 v[4:5], off
	v_lshl_add_u64 v[0:1], v[0:1], 0, s[4:5]
	s_mov_b32 m0, s49
	s_add_u32 s8, s26, 0x20080
	global_load_lds_dwordx4 v[0:1], off
	v_lshl_add_u64 v[0:1], v[2:3], 0, s[4:5]
	s_mov_b32 m0, s50
	s_addc_u32 s9, s27, 0
	global_load_lds_dwordx4 v[0:1], off
	s_add_i32 m0, s23, 0x1c000
	v_lshl_add_u64 v[0:1], s[8:9], 0, v[130:131]
	global_load_lds_dwordx4 v[0:1], off
	v_lshl_add_u64 v[0:1], s[8:9], 0, v[134:135]
	s_add_i32 m0, s23, 0x1e000
	v_bfe_u32 v151, v8, 4, 2
	global_load_lds_dwordx4 v[0:1], off
	v_and_b32_e32 v150, 15, v8
	v_lshlrev_b32_e32 v0, 4, v151
	v_lshlrev_b32_e32 v1, 2, v8
	v_lshl_or_b32 v0, v150, 6, v0
	v_and_b32_e32 v1, 32, v1
	v_bitop3_b32 v2, v0, s10, v1 bitop3:0xde
	v_bitop3_b32 v152, v0, s11, v1 bitop3:0xde
	v_lshlrev_b32_e32 v0, 13, v9
	v_and_b32_e32 v0, 0xffffc000, v0
	v_lshl_add_u32 v0, v10, 10, v0
	v_and_b32_e32 v1, 1, v9
	v_lshl_or_b32 v0, v1, 6, v0
	v_lshl_add_u32 v136, v11, 1, v0
	v_lshlrev_b32_e32 v0, 13, v12
	v_and_b32_e32 v0, 0xffffc000, v0
	s_waitcnt vmcnt(6)
	s_cmpk_lt_u32 s7, 0x100
	v_lshl_add_u32 v0, v13, 10, v0
	v_and_b32_e32 v1, 1, v12
	s_cselect_b64 s[8:9], -1, 0
	v_lshl_or_b32 v0, v1, 6, v0
	s_add_i32 s51, 0, 0x10000
	s_add_i32 s52, 0, 0x14000
	s_sext_i32_i8 s53, s6
	v_mov_b32_e32 v137, v131
	v_lshl_add_u32 v138, v14, 1, v0
	v_mov_b32_e32 v139, v131
	v_mov_b64_e32 v[140:141], 0x200
	v_mov_b64_e32 v[142:143], 0x1ff
	v_add_u32_e32 v153, s51, v152
	v_add_u32_e32 v154, s52, v152
	v_add_u32_e32 v155, 0, v2
	s_barrier
	s_mov_b32 s99, 0
	s_branch .LBB0_3131

.Lrlx29p0b:
	s_waitcnt vmcnt(24)
	s_branch .Lrlx29p0b_done
.LBB0_3129:
	s_mov_b64 s[6:7], 0

.LBB0_3138:
	ds_read_b128 v[144:147], v153
	ds_read_b128 v[156:159], v153 offset:1024
	ds_read_b128 v[160:163], v153 offset:2048
	ds_read_b128 v[164:167], v153 offset:3072
	ds_read_b128 v[168:171], v154
	ds_read_b128 v[172:175], v154 offset:1024
	ds_read_b128 v[176:179], v154 offset:2048
	ds_read_b128 v[180:183], v154 offset:3072
	s_add_u32 s26, s24, 0xfffe0080
	s_addc_u32 s27, s25, -1
	s_cmp_eq_u32 s64, 4
	s_cselect_b32 s35, s13, s27
	s_cselect_b32 s34, s54, s26
	s_cselect_b32 s27, s11, s61
	s_cselect_b32 s26, s55, s60
	v_lshl_add_u64 v[148:149], s[24:25], 0, v[136:137]
	s_add_i32 m0, s23, 0xc000
	ds_read_b128 v[184:187], v155
	ds_read_b128 v[188:191], v155 offset:1024
	ds_read_b128 v[192:195], v155 offset:2048
	ds_read_b128 v[196:199], v155 offset:3072
	ds_read_b128 v[200:203], v155 offset:4096
	ds_read_b128 v[204:207], v155 offset:5120
	ds_read_b128 v[212:215], v155 offset:6144
	ds_read_b128 v[216:219], v155 offset:7168
	global_load_lds_dwordx4 v[148:149], off
	v_lshl_add_u64 v[148:149], s[24:25], 0, v[138:139]
	s_add_i32 m0, s23, 0xe000
	s_nop 0
	global_load_lds_dwordx4 v[148:149], off
	s_cmp_lg_u32 s99, 0
	s_cbranch_scc1 .Lrlx29p0a
	s_waitcnt vmcnt(8)
.Lrlx29p0a_done:
	s_waitcnt lgkmcnt(0)
	s_barrier
	s_setprio 1
	s_waitcnt lgkmcnt(0)
	v_mfma_f32_16x16x32_bf16 v[124:127], v[144:147], v[184:187], v[124:127]
	v_mfma_f32_16x16x32_bf16 v[120:123], v[160:163], v[184:187], v[120:123]
	v_mfma_f32_16x16x32_bf16 v[116:119], v[144:147], v[192:195], v[116:119]
	v_mfma_f32_16x16x32_bf16 v[108:111], v[160:163], v[192:195], v[108:111]
	v_mfma_f32_16x16x32_bf16 v[96:99], v[144:147], v[200:203], v[96:99]
	v_mfma_f32_16x16x32_bf16 v[88:91], v[160:163], v[200:203], v[88:91]
	v_mfma_f32_16x16x32_bf16 v[80:83], v[144:147], v[212:215], v[80:83]
	v_mfma_f32_16x16x32_bf16 v[72:75], v[160:163], v[212:215], v[72:75]
	v_mfma_f32_16x16x32_bf16 v[124:127], v[156:159], v[188:191], v[124:127]
	v_mfma_f32_16x16x32_bf16 v[120:123], v[164:167], v[188:191], v[120:123]
	v_mfma_f32_16x16x32_bf16 v[116:119], v[156:159], v[196:199], v[116:119]
	v_mfma_f32_16x16x32_bf16 v[108:111], v[164:167], v[196:199], v[108:111]
	v_mfma_f32_16x16x32_bf16 v[96:99], v[156:159], v[204:207], v[96:99]
	v_mfma_f32_16x16x32_bf16 v[88:91], v[164:167], v[204:207], v[88:91]
	v_mfma_f32_16x16x32_bf16 v[80:83], v[156:159], v[216:219], v[80:83]
	v_mfma_f32_16x16x32_bf16 v[72:75], v[164:167], v[216:219], v[72:75]
	s_setprio 0
	s_setprio 1
	v_mfma_f32_16x16x32_bf16 v[112:115], v[168:171], v[184:187], v[112:115]
	v_mfma_f32_16x16x32_bf16 v[104:107], v[176:179], v[184:187], v[104:107]
	v_mfma_f32_16x16x32_bf16 v[100:103], v[168:171], v[192:195], v[100:103]
	v_mfma_f32_16x16x32_bf16 v[92:95], v[176:179], v[192:195], v[92:95]
	v_mfma_f32_16x16x32_bf16 v[84:87], v[168:171], v[200:203], v[84:87]
	v_mfma_f32_16x16x32_bf16 v[76:79], v[176:179], v[200:203], v[76:79]
	v_mfma_f32_16x16x32_bf16 v[68:71], v[168:171], v[212:215], v[68:71]
	v_mfma_f32_16x16x32_bf16 v[64:67], v[176:179], v[212:215], v[64:67]
	v_mfma_f32_16x16x32_bf16 v[112:115], v[172:175], v[188:191], v[112:115]
	v_mfma_f32_16x16x32_bf16 v[104:107], v[180:183], v[188:191], v[104:107]
	v_mfma_f32_16x16x32_bf16 v[100:103], v[172:175], v[196:199], v[100:103]
	v_mfma_f32_16x16x32_bf16 v[92:95], v[180:183], v[196:199], v[92:95]
	v_mfma_f32_16x16x32_bf16 v[84:87], v[172:175], v[204:207], v[84:87]
	v_mfma_f32_16x16x32_bf16 v[76:79], v[180:183], v[204:207], v[76:79]
	v_mfma_f32_16x16x32_bf16 v[68:71], v[172:175], v[216:219], v[68:71]
	v_mfma_f32_16x16x32_bf16 v[64:67], v[180:183], v[216:219], v[64:67]
	s_setprio 0
	s_barrier
	s_add_i32 s65, s51, s36
	v_lshl_add_u64 v[148:149], s[26:27], 0, v[130:131]
	s_mov_b32 m0, s65
	ds_read_b128 v[184:187], v155 offset:16384
	ds_read_b128 v[188:191], v155 offset:17408
	ds_read_b128 v[192:195], v155 offset:18432
	ds_read_b128 v[196:199], v155 offset:19456
	ds_read_b128 v[200:203], v155 offset:20480
	ds_read_b128 v[204:207], v155 offset:21504
	ds_read_b128 v[212:215], v155 offset:22528
	ds_read_b128 v[216:219], v155 offset:23552
	global_load_lds_dwordx4 v[148:149], off
	s_add_i32 m0, s65, 0x2000
	s_add_u32 s66, s26, 0x20000
	v_lshl_add_u64 v[208:209], s[26:27], 0, v[134:135]
	s_addc_u32 s67, s27, 0
	s_add_i32 s65, s52, s36
	global_load_lds_dwordx4 v[208:209], off
	v_lshl_add_u64 v[210:211], s[66:67], 0, v[130:131]
	s_mov_b32 m0, s65
	v_lshl_add_u64 v[220:221], s[34:35], 0, v[132:133]
	global_load_lds_dwordx4 v[210:211], off
	v_lshl_add_u64 v[210:211], s[66:67], 0, v[134:135]
	s_add_i32 m0, s65, 0x2000
	s_nop 0
	global_load_lds_dwordx4 v[210:211], off
	v_lshl_add_u64 v[210:211], s[34:35], 0, v[128:129]
	s_mov_b32 m0, s23
	s_nop 0
	global_load_lds_dwordx4 v[210:211], off
	s_mov_b32 m0, s37
	s_nop 0
	global_load_lds_dwordx4 v[220:221], off
	s_cmp_lg_u32 s99, 0
	s_cbranch_scc1 .Lrlx29p0b
	s_waitcnt vmcnt(8)
.Lrlx29p0b_done:
	s_mov_b32 s99, 0
	s_waitcnt lgkmcnt(0)
	s_barrier
	s_setprio 1
	s_waitcnt lgkmcnt(0)
	v_mfma_f32_16x16x32_bf16 v[60:63], v[144:147], v[184:187], v[60:63]
	v_mfma_f32_16x16x32_bf16 v[56:59], v[160:163], v[184:187], v[56:59]
	v_mfma_f32_16x16x32_bf16 v[48:51], v[144:147], v[192:195], v[48:51]
	v_mfma_f32_16x16x32_bf16 v[40:43], v[160:163], v[192:195], v[40:43]
	v_mfma_f32_16x16x32_bf16 v[32:35], v[144:147], v[200:203], v[32:35]
	v_mfma_f32_16x16x32_bf16 v[24:27], v[160:163], v[200:203], v[24:27]
	v_mfma_f32_16x16x32_bf16 v[16:19], v[144:147], v[212:215], v[16:19]
	v_mfma_f32_16x16x32_bf16 v[8:11], v[160:163], v[212:215], v[8:11]
	v_mfma_f32_16x16x32_bf16 v[60:63], v[156:159], v[188:191], v[60:63]
	v_mfma_f32_16x16x32_bf16 v[56:59], v[164:167], v[188:191], v[56:59]
	v_mfma_f32_16x16x32_bf16 v[48:51], v[156:159], v[196:199], v[48:51]
	v_mfma_f32_16x16x32_bf16 v[40:43], v[164:167], v[196:199], v[40:43]
	v_mfma_f32_16x16x32_bf16 v[32:35], v[156:159], v[204:207], v[32:35]
	v_mfma_f32_16x16x32_bf16 v[24:27], v[164:167], v[204:207], v[24:27]
	v_mfma_f32_16x16x32_bf16 v[16:19], v[156:159], v[216:219], v[16:19]
	v_mfma_f32_16x16x32_bf16 v[8:11], v[164:167], v[216:219], v[8:11]
	s_setprio 0
	s_setprio 1
	v_mfma_f32_16x16x32_bf16 v[52:55], v[168:171], v[184:187], v[52:55]
	v_mfma_f32_16x16x32_bf16 v[44:47], v[176:179], v[184:187], v[44:47]
	v_mfma_f32_16x16x32_bf16 v[36:39], v[168:171], v[192:195], v[36:39]
	v_mfma_f32_16x16x32_bf16 v[28:31], v[176:179], v[192:195], v[28:31]
	v_mfma_f32_16x16x32_bf16 v[20:23], v[168:171], v[200:203], v[20:23]
	v_mfma_f32_16x16x32_bf16 v[12:15], v[176:179], v[200:203], v[12:15]
	v_mfma_f32_16x16x32_bf16 v[4:7], v[168:171], v[212:215], v[4:7]
	v_mfma_f32_16x16x32_bf16 v[0:3], v[176:179], v[212:215], v[0:3]
	v_mfma_f32_16x16x32_bf16 v[52:55], v[172:175], v[188:191], v[52:55]
	v_mfma_f32_16x16x32_bf16 v[44:47], v[180:183], v[188:191], v[44:47]
	v_mfma_f32_16x16x32_bf16 v[36:39], v[172:175], v[196:199], v[36:39]
	v_mfma_f32_16x16x32_bf16 v[28:31], v[180:183], v[196:199], v[28:31]
	v_mfma_f32_16x16x32_bf16 v[20:23], v[172:175], v[204:207], v[20:23]
	v_mfma_f32_16x16x32_bf16 v[12:15], v[180:183], v[204:207], v[12:15]
	v_mfma_f32_16x16x32_bf16 v[4:7], v[172:175], v[216:219], v[4:7]
	v_mfma_f32_16x16x32_bf16 v[0:3], v[180:183], v[216:219], v[0:3]
	s_setprio 0
	s_barrier
	s_add_i32 s65, 0, 0x18000
	s_add_i32 s66, 0, 0x1c000
	v_add_u32_e32 v164, s65, v152
	v_add_u32_e32 v180, s66, v152
	ds_read_b128 v[144:147], v164
	ds_read_b128 v[156:159], v164 offset:1024
	ds_read_b128 v[160:163], v164 offset:2048
	ds_read_b128 v[164:167], v164 offset:3072
	ds_read_b128 v[168:171], v180
	ds_read_b128 v[172:175], v180 offset:1024
	ds_read_b128 v[176:179], v180 offset:2048
	ds_read_b128 v[180:183], v180 offset:3072
	s_add_u32 s34, s34, 0x20000
	s_addc_u32 s35, s35, 0
	s_mov_b32 m0, s40
	v_lshl_add_u64 v[222:223], s[34:35], 0, v[128:129]
	ds_read_b128 v[184:187], v155 offset:32768
	ds_read_b128 v[188:191], v155 offset:33792
	ds_read_b128 v[192:195], v155 offset:34816
	ds_read_b128 v[196:199], v155 offset:35840
	ds_read_b128 v[200:203], v155 offset:36864
	ds_read_b128 v[204:207], v155 offset:37888
	ds_read_b128 v[212:215], v155 offset:38912
	ds_read_b128 v[216:219], v155 offset:39936
	global_load_lds_dwordx4 v[222:223], off
	v_lshl_add_u64 v[222:223], s[34:35], 0, v[132:133]
	s_mov_b32 m0, s41
	s_nop 0
	global_load_lds_dwordx4 v[222:223], off
	s_waitcnt vmcnt(8)
	s_waitcnt lgkmcnt(0)
	s_barrier
	s_setprio 1
	s_waitcnt lgkmcnt(0)
	v_mfma_f32_16x16x32_bf16 v[124:127], v[144:147], v[184:187], v[124:127]
	v_mfma_f32_16x16x32_bf16 v[120:123], v[160:163], v[184:187], v[120:123]
	v_mfma_f32_16x16x32_bf16 v[116:119], v[144:147], v[192:195], v[116:119]
	v_mfma_f32_16x16x32_bf16 v[108:111], v[160:163], v[192:195], v[108:111]
	v_mfma_f32_16x16x32_bf16 v[96:99], v[144:147], v[200:203], v[96:99]
	v_mfma_f32_16x16x32_bf16 v[88:91], v[160:163], v[200:203], v[88:91]
	v_mfma_f32_16x16x32_bf16 v[80:83], v[144:147], v[212:215], v[80:83]
	v_mfma_f32_16x16x32_bf16 v[72:75], v[160:163], v[212:215], v[72:75]
	v_mfma_f32_16x16x32_bf16 v[124:127], v[156:159], v[188:191], v[124:127]
	v_mfma_f32_16x16x32_bf16 v[120:123], v[164:167], v[188:191], v[120:123]
	v_mfma_f32_16x16x32_bf16 v[116:119], v[156:159], v[196:199], v[116:119]
	v_mfma_f32_16x16x32_bf16 v[108:111], v[164:167], v[196:199], v[108:111]
	v_mfma_f32_16x16x32_bf16 v[96:99], v[156:159], v[204:207], v[96:99]
	v_mfma_f32_16x16x32_bf16 v[88:91], v[164:167], v[204:207], v[88:91]
	v_mfma_f32_16x16x32_bf16 v[80:83], v[156:159], v[216:219], v[80:83]
	v_mfma_f32_16x16x32_bf16 v[72:75], v[164:167], v[216:219], v[72:75]
	s_setprio 0
	s_setprio 1
	v_mfma_f32_16x16x32_bf16 v[112:115], v[168:171], v[184:187], v[112:115]
	v_mfma_f32_16x16x32_bf16 v[104:107], v[176:179], v[184:187], v[104:107]
	v_mfma_f32_16x16x32_bf16 v[100:103], v[168:171], v[192:195], v[100:103]
	v_mfma_f32_16x16x32_bf16 v[92:95], v[176:179], v[192:195], v[92:95]
	v_mfma_f32_16x16x32_bf16 v[84:87], v[168:171], v[200:203], v[84:87]
	v_mfma_f32_16x16x32_bf16 v[76:79], v[176:179], v[200:203], v[76:79]
	v_mfma_f32_16x16x32_bf16 v[68:71], v[168:171], v[212:215], v[68:71]
	v_mfma_f32_16x16x32_bf16 v[64:67], v[176:179], v[212:215], v[64:67]
	v_mfma_f32_16x16x32_bf16 v[112:115], v[172:175], v[188:191], v[112:115]
	v_mfma_f32_16x16x32_bf16 v[104:107], v[180:183], v[188:191], v[104:107]
	v_mfma_f32_16x16x32_bf16 v[100:103], v[172:175], v[196:199], v[100:103]
	v_mfma_f32_16x16x32_bf16 v[92:95], v[180:183], v[196:199], v[92:95]
	v_mfma_f32_16x16x32_bf16 v[84:87], v[172:175], v[204:207], v[84:87]
	v_mfma_f32_16x16x32_bf16 v[76:79], v[180:183], v[204:207], v[76:79]
	v_mfma_f32_16x16x32_bf16 v[68:71], v[172:175], v[216:219], v[68:71]
	v_mfma_f32_16x16x32_bf16 v[64:67], v[180:183], v[216:219], v[64:67]
	s_setprio 0
	s_barrier
	s_add_i32 s34, s65, s36
	v_lshl_add_u64 v[148:149], v[148:149], 0, s[4:5]
	s_mov_b32 m0, s34
	ds_read_b128 v[184:187], v155 offset:49152
	ds_read_b128 v[188:191], v155 offset:50176
	ds_read_b128 v[192:195], v155 offset:51200
	ds_read_b128 v[196:199], v155 offset:52224
	ds_read_b128 v[200:203], v155 offset:53248
	ds_read_b128 v[204:207], v155 offset:54272
	ds_read_b128 v[212:215], v155 offset:55296
	ds_read_b128 v[216:219], v155 offset:56320
	global_load_lds_dwordx4 v[148:149], off
	s_add_i32 m0, s34, 0x2000
	s_add_u32 s26, s26, 0x20080
	v_lshl_add_u64 v[148:149], v[208:209], 0, s[4:5]
	s_addc_u32 s27, s27, 0
	s_add_i32 s34, s66, s36
	global_load_lds_dwordx4 v[148:149], off
	v_lshl_add_u64 v[148:149], s[26:27], 0, v[130:131]
	s_mov_b32 m0, s34
	s_nop 0
	global_load_lds_dwordx4 v[148:149], off
	v_lshl_add_u64 v[148:149], s[26:27], 0, v[134:135]
	s_add_i32 m0, s34, 0x2000
	s_nop 0
	global_load_lds_dwordx4 v[148:149], off
	v_lshl_add_u64 v[148:149], v[210:211], 0, s[4:5]
	s_mov_b32 m0, s49
	s_nop 0
	global_load_lds_dwordx4 v[148:149], off
	v_lshl_add_u64 v[148:149], v[220:221], 0, s[4:5]
	s_mov_b32 m0, s50
	s_nop 0
	global_load_lds_dwordx4 v[148:149], off
	s_waitcnt vmcnt(8)
	s_waitcnt lgkmcnt(0)
	s_barrier
	s_setprio 1
	s_waitcnt lgkmcnt(0)
	v_mfma_f32_16x16x32_bf16 v[60:63], v[144:147], v[184:187], v[60:63]
	v_mfma_f32_16x16x32_bf16 v[56:59], v[160:163], v[184:187], v[56:59]
	v_mfma_f32_16x16x32_bf16 v[48:51], v[144:147], v[192:195], v[48:51]
	v_mfma_f32_16x16x32_bf16 v[40:43], v[160:163], v[192:195], v[40:43]
	v_mfma_f32_16x16x32_bf16 v[32:35], v[144:147], v[200:203], v[32:35]
	v_mfma_f32_16x16x32_bf16 v[24:27], v[160:163], v[200:203], v[24:27]
	v_mfma_f32_16x16x32_bf16 v[16:19], v[144:147], v[212:215], v[16:19]
	v_mfma_f32_16x16x32_bf16 v[8:11], v[160:163], v[212:215], v[8:11]
	v_mfma_f32_16x16x32_bf16 v[60:63], v[156:159], v[188:191], v[60:63]
	v_mfma_f32_16x16x32_bf16 v[56:59], v[164:167], v[188:191], v[56:59]
	v_mfma_f32_16x16x32_bf16 v[48:51], v[156:159], v[196:199], v[48:51]
	v_mfma_f32_16x16x32_bf16 v[40:43], v[164:167], v[196:199], v[40:43]
	v_mfma_f32_16x16x32_bf16 v[32:35], v[156:159], v[204:207], v[32:35]
	v_mfma_f32_16x16x32_bf16 v[24:27], v[164:167], v[204:207], v[24:27]
	v_mfma_f32_16x16x32_bf16 v[16:19], v[156:159], v[216:219], v[16:19]
	v_mfma_f32_16x16x32_bf16 v[8:11], v[164:167], v[216:219], v[8:11]
	s_setprio 0
	s_setprio 1
	v_mfma_f32_16x16x32_bf16 v[52:55], v[168:171], v[184:187], v[52:55]
	v_mfma_f32_16x16x32_bf16 v[44:47], v[176:179], v[184:187], v[44:47]
	v_mfma_f32_16x16x32_bf16 v[36:39], v[168:171], v[192:195], v[36:39]
	v_mfma_f32_16x16x32_bf16 v[28:31], v[176:179], v[192:195], v[28:31]
	v_mfma_f32_16x16x32_bf16 v[20:23], v[168:171], v[200:203], v[20:23]
	v_mfma_f32_16x16x32_bf16 v[12:15], v[176:179], v[200:203], v[12:15]
	v_mfma_f32_16x16x32_bf16 v[4:7], v[168:171], v[212:215], v[4:7]
	v_mfma_f32_16x16x32_bf16 v[0:3], v[176:179], v[212:215], v[0:3]
	v_mfma_f32_16x16x32_bf16 v[52:55], v[172:175], v[188:191], v[52:55]
	v_mfma_f32_16x16x32_bf16 v[44:47], v[180:183], v[188:191], v[44:47]
	v_mfma_f32_16x16x32_bf16 v[36:39], v[172:175], v[196:199], v[36:39]
	v_mfma_f32_16x16x32_bf16 v[28:31], v[180:183], v[196:199], v[28:31]
	v_mfma_f32_16x16x32_bf16 v[20:23], v[172:175], v[204:207], v[20:23]
	v_mfma_f32_16x16x32_bf16 v[12:15], v[180:183], v[204:207], v[12:15]
	v_mfma_f32_16x16x32_bf16 v[4:7], v[172:175], v[216:219], v[4:7]
	v_mfma_f32_16x16x32_bf16 v[0:3], v[180:183], v[216:219], v[0:3]
	s_setprio 0
	s_barrier
	s_add_i32 s64, s64, 2
	s_add_u32 s24, s24, 0x100
	s_addc_u32 s25, s25, 0
	s_add_u32 s60, s60, 0x100
	s_addc_u32 s61, s61, 0
	s_cmp_gt_u32 s64, 5
	s_cbranch_scc0 .LBB0_3138
	s_and_b64 vcc, exec, s[8:9]
	s_cbranch_vccz .LBB0_3141
	s_barrier
.LBB0_3141:
	s_lshl_b32 s11, s22, 8
	v_mov_b32_e32 v144, v150
	v_mov_b32_e32 v145, v151
	s_add_i32 s11, s11, s47
	s_andn2_b64 vcc, exec, s[6:7]
	v_add_u32_e32 v146, s11, v144
	s_lshl_b32 s11, s53, 8
	s_or_b32 s11, s11, s48
	v_lshl_add_u32 v144, v145, 3, s11
	v_ashrrev_i32_e32 v145, 31, v144
	v_lshlrev_b64 v[144:145], 1, v[144:145]
	v_ashrrev_i32_e32 v147, 31, v146
	v_lshl_add_u64 v[148:149], s[56:57], 0, v[144:145]
	v_lshlrev_b64 v[156:157], 12, v[146:147]
	v_lshl_add_u64 v[160:161], v[148:149], 0, v[156:157]
	v_add_u32_e32 v172, 16, v146
	global_load_dwordx4 v[156:159], v[160:161], off
	s_nop 0
	global_load_dwordx4 v[160:163], v[160:161], off offset:256
	v_ashrrev_i32_e32 v173, 31, v172
	v_lshlrev_b64 v[164:165], 12, v[172:173]
	v_lshl_add_u64 v[168:169], v[148:149], 0, v[164:165]
	global_load_dwordx4 v[164:167], v[168:169], off
	v_add_u32_e32 v188, 32, v146
	global_load_dwordx4 v[168:171], v[168:169], off offset:256
	v_add_u32_e32 v190, 48, v146
	v_ashrrev_i32_e32 v189, 31, v188
	v_ashrrev_i32_e32 v191, 31, v190
	v_lshlrev_b64 v[174:175], 11, v[146:147]
	v_lshlrev_b64 v[176:177], 12, v[188:189]
	v_lshlrev_b64 v[178:179], 12, v[190:191]
	v_lshl_add_u64 v[174:175], s[42:43], 0, v[174:175]
	v_lshlrev_b64 v[172:173], 11, v[172:173]
	v_lshl_add_u64 v[176:177], v[148:149], 0, v[176:177]
	v_lshl_add_u64 v[184:185], v[148:149], 0, v[178:179]
	v_lshl_add_u64 v[192:193], v[174:175], 0, v[144:145]
	v_lshl_add_u64 v[194:195], s[42:43], 0, v[172:173]
	global_load_dwordx4 v[172:175], v[176:177], off
	s_nop 0
	global_load_dwordx4 v[176:179], v[176:177], off offset:256
	s_nop 0
	global_load_dwordx4 v[180:183], v[184:185], off
	s_nop 0
	global_load_dwordx4 v[184:187], v[184:185], off offset:256
	v_lshl_add_u64 v[194:195], v[194:195], 0, v[144:145]
	s_mov_b64 s[6:7], -1
	v_add_u32_e32 v250, 0x80, v146
	v_ashrrev_i32_e32 v251, 31, v250
	v_lshlrev_b64 v[252:253], 12, v[250:251]
	v_lshl_add_u64 v[250:251], v[148:149], 0, v[252:253]
	global_load_dwordx4 v[206:209], v[250:251], off
	global_load_dwordx4 v[210:213], v[250:251], off offset:256
	v_add_u32_e32 v250, 0x90, v146
	v_ashrrev_i32_e32 v251, 31, v250
	v_lshlrev_b64 v[252:253], 12, v[250:251]
	v_lshl_add_u64 v[250:251], v[148:149], 0, v[252:253]
	global_load_dwordx4 v[214:217], v[250:251], off
	global_load_dwordx4 v[218:221], v[250:251], off offset:256
	v_add_u32_e32 v250, 0xa0, v146
	v_ashrrev_i32_e32 v251, 31, v250
	v_lshlrev_b64 v[252:253], 12, v[250:251]
	v_lshl_add_u64 v[250:251], v[148:149], 0, v[252:253]
	global_load_dwordx4 v[222:225], v[250:251], off
	global_load_dwordx4 v[226:229], v[250:251], off offset:256
	v_add_u32_e32 v250, 0xb0, v146
	v_ashrrev_i32_e32 v251, 31, v250
	v_lshlrev_b64 v[252:253], 12, v[250:251]
	v_lshl_add_u64 v[250:251], v[148:149], 0, v[252:253]
	global_load_dwordx4 v[230:233], v[250:251], off
	global_load_dwordx4 v[234:237], v[250:251], off offset:256
	s_waitcnt vmcnt(8)
	v_lshlrev_b32_e32 v147, 16, v156
	v_and_b32_e32 v156, 0xffff0000, v156
	v_lshlrev_b32_e32 v201, 16, v162
	v_lshlrev_b32_e32 v196, 16, v157
	v_and_b32_e32 v157, 0xffff0000, v157
	v_lshlrev_b32_e32 v197, 16, v158
	v_and_b32_e32 v158, 0xffff0000, v158
	v_lshlrev_b32_e32 v198, 16, v159
	v_and_b32_e32 v159, 0xffff0000, v159
	v_lshlrev_b32_e32 v199, 16, v160
	v_and_b32_e32 v160, 0xffff0000, v160
	v_and_b32_e32 v162, 0xffff0000, v162
	v_lshlrev_b32_e32 v202, 16, v163
	v_and_b32_e32 v163, 0xffff0000, v163
	v_mul_f32_e32 v124, v124, v147
	v_mul_f32_e32 v125, v125, v156
	v_mul_f32_e32 v147, v104, v201
	v_cvt_pk_bf16_f32 v104, v124, v125
	v_lshlrev_b32_e32 v200, 16, v161
	v_and_b32_e32 v161, 0xffff0000, v161
	v_mul_f32_e32 v126, v126, v196
	v_mul_f32_e32 v127, v127, v157
	v_mul_f32_e32 v120, v120, v197
	v_mul_f32_e32 v121, v121, v158
	v_mul_f32_e32 v122, v122, v198
	v_mul_f32_e32 v123, v123, v159
	v_mul_f32_e32 v112, v112, v199
	v_mul_f32_e32 v113, v113, v160
	v_mul_f32_e32 v156, v105, v162
	v_mul_f32_e32 v157, v106, v202
	v_mul_f32_e32 v158, v107, v163
	v_cvt_pk_bf16_f32 v105, v126, v127
	v_cvt_pk_bf16_f32 v106, v120, v121
	v_cvt_pk_bf16_f32 v107, v122, v123
	global_store_dwordx4 v[192:193], v[104:107], off
	v_mul_f32_e32 v114, v114, v200
	v_mul_f32_e32 v115, v115, v161
	v_cvt_pk_bf16_f32 v104, v112, v113
	v_cvt_pk_bf16_f32 v105, v114, v115
	v_cvt_pk_bf16_f32 v106, v147, v156
	v_cvt_pk_bf16_f32 v107, v157, v158
	global_store_dwordx4 v[192:193], v[104:107], off offset:256
	v_lshlrev_b32_e32 v205, 16, v166
	v_lshlrev_b32_e32 v203, 16, v164
	v_and_b32_e32 v104, 0xffff0000, v166
	v_mul_f32_e32 v107, v109, v104
	v_lshlrev_b32_e32 v104, 16, v167
	v_and_b32_e32 v164, 0xffff0000, v164
	v_mul_f32_e32 v106, v108, v205
	v_mul_f32_e32 v108, v110, v104
	v_and_b32_e32 v104, 0xffff0000, v167
	v_lshlrev_b32_e32 v204, 16, v165
	v_and_b32_e32 v165, 0xffff0000, v165
	v_mul_f32_e32 v116, v116, v203
	v_mul_f32_e32 v117, v117, v164
	v_mul_f32_e32 v109, v111, v104
	v_cvt_pk_bf16_f32 v104, v116, v117
	v_mul_f32_e32 v118, v118, v204
	v_mul_f32_e32 v119, v119, v165
	v_cvt_pk_bf16_f32 v105, v118, v119
	v_cvt_pk_bf16_f32 v106, v106, v107
	v_cvt_pk_bf16_f32 v107, v108, v109
	global_store_dwordx4 v[194:195], v[104:107], off
	s_nop 1
	v_lshlrev_b32_e32 v104, 16, v168
	v_mul_f32_e32 v100, v100, v104
	v_and_b32_e32 v104, 0xffff0000, v168
	v_mul_f32_e32 v101, v101, v104
	v_lshlrev_b32_e32 v104, 16, v169
	v_mul_f32_e32 v102, v102, v104
	v_and_b32_e32 v104, 0xffff0000, v169
	v_mul_f32_e32 v103, v103, v104
	v_lshlrev_b32_e32 v104, 16, v170
	v_mul_f32_e32 v104, v92, v104
	v_and_b32_e32 v92, 0xffff0000, v170
	v_mul_f32_e32 v105, v93, v92
	v_lshlrev_b32_e32 v92, 16, v171
	v_mul_f32_e32 v106, v94, v92
	v_and_b32_e32 v92, 0xffff0000, v171
	v_mul_f32_e32 v95, v95, v92
	v_cvt_pk_bf16_f32 v92, v100, v101
	v_cvt_pk_bf16_f32 v93, v102, v103
	v_cvt_pk_bf16_f32 v94, v104, v105
	v_cvt_pk_bf16_f32 v95, v106, v95
	global_store_dwordx4 v[194:195], v[92:95], off offset:256
	v_add_u32_e32 v102, 0xb0, v146
	v_ashrrev_i32_e32 v103, 31, v102
	v_lshlrev_b32_e32 v94, 16, v172
	v_mul_f32_e32 v94, v96, v94
	v_lshlrev_b32_e32 v96, 16, v173
	v_and_b32_e32 v95, 0xffff0000, v172
	v_mul_f32_e32 v96, v98, v96
	v_lshlrev_b32_e32 v98, 16, v174
	v_mul_f32_e32 v95, v97, v95
	v_and_b32_e32 v97, 0xffff0000, v173
	v_mul_f32_e32 v98, v88, v98
	v_and_b32_e32 v88, 0xffff0000, v174
	v_lshlrev_b64 v[92:93], 11, v[188:189]
	v_mul_f32_e32 v97, v99, v97
	v_mul_f32_e32 v99, v89, v88
	v_lshlrev_b32_e32 v88, 16, v175
	v_lshl_add_u64 v[92:93], s[42:43], 0, v[92:93]
	v_mul_f32_e32 v100, v90, v88
	v_and_b32_e32 v88, 0xffff0000, v175
	v_lshl_add_u64 v[92:93], v[92:93], 0, v[144:145]
	v_mul_f32_e32 v91, v91, v88
	v_cvt_pk_bf16_f32 v88, v94, v95
	v_cvt_pk_bf16_f32 v89, v96, v97
	v_cvt_pk_bf16_f32 v90, v98, v99
	v_cvt_pk_bf16_f32 v91, v100, v91
	global_store_dwordx4 v[92:93], v[88:91], off
	v_add_u32_e32 v96, 0x80, v146
	v_ashrrev_i32_e32 v97, 31, v96
	v_lshlrev_b32_e32 v88, 16, v176
	v_mul_f32_e32 v84, v84, v88
	v_and_b32_e32 v88, 0xffff0000, v176
	v_mul_f32_e32 v85, v85, v88
	v_lshlrev_b32_e32 v88, 16, v177
	v_mul_f32_e32 v86, v86, v88
	v_and_b32_e32 v88, 0xffff0000, v177
	v_mul_f32_e32 v87, v87, v88
	v_lshlrev_b32_e32 v88, 16, v178
	v_mul_f32_e32 v88, v76, v88
	v_and_b32_e32 v76, 0xffff0000, v178
	v_mul_f32_e32 v89, v77, v76
	v_lshlrev_b32_e32 v76, 16, v179
	v_mul_f32_e32 v90, v78, v76
	v_and_b32_e32 v76, 0xffff0000, v179
	v_mul_f32_e32 v79, v79, v76
	v_cvt_pk_bf16_f32 v76, v84, v85
	v_cvt_pk_bf16_f32 v77, v86, v87
	v_cvt_pk_bf16_f32 v78, v88, v89
	v_cvt_pk_bf16_f32 v79, v90, v79
	global_store_dwordx4 v[92:93], v[76:79], off offset:256
	v_add_u32_e32 v98, 0x90, v146
	v_ashrrev_i32_e32 v99, 31, v98
	v_lshlrev_b32_e32 v78, 16, v180
	v_mul_f32_e32 v78, v80, v78
	v_lshlrev_b32_e32 v80, 16, v181
	v_and_b32_e32 v79, 0xffff0000, v180
	v_mul_f32_e32 v80, v82, v80
	v_lshlrev_b32_e32 v82, 16, v182
	v_mul_f32_e32 v79, v81, v79
	v_and_b32_e32 v81, 0xffff0000, v181
	v_mul_f32_e32 v82, v72, v82
	v_and_b32_e32 v72, 0xffff0000, v182
	v_lshlrev_b64 v[76:77], 11, v[190:191]
	v_mul_f32_e32 v81, v83, v81
	v_mul_f32_e32 v83, v73, v72
	v_lshlrev_b32_e32 v72, 16, v183
	v_lshl_add_u64 v[76:77], s[42:43], 0, v[76:77]
	v_mul_f32_e32 v84, v74, v72
	v_and_b32_e32 v72, 0xffff0000, v183
	v_lshl_add_u64 v[76:77], v[76:77], 0, v[144:145]
	v_mul_f32_e32 v75, v75, v72
	v_cvt_pk_bf16_f32 v72, v78, v79
	v_cvt_pk_bf16_f32 v73, v80, v81
	v_cvt_pk_bf16_f32 v74, v82, v83
	v_cvt_pk_bf16_f32 v75, v84, v75
	global_store_dwordx4 v[76:77], v[72:75], off
	v_add_u32_e32 v100, 0xa0, v146
	v_ashrrev_i32_e32 v101, 31, v100
	v_lshlrev_b32_e32 v72, 16, v184
	v_mul_f32_e32 v68, v68, v72
	v_and_b32_e32 v72, 0xffff0000, v184
	v_mul_f32_e32 v69, v69, v72
	v_lshlrev_b32_e32 v72, 16, v185
	v_mul_f32_e32 v70, v70, v72
	v_and_b32_e32 v72, 0xffff0000, v185
	v_mul_f32_e32 v71, v71, v72
	v_lshlrev_b32_e32 v72, 16, v186
	v_mul_f32_e32 v72, v64, v72
	v_and_b32_e32 v64, 0xffff0000, v186
	v_mul_f32_e32 v73, v65, v64
	v_lshlrev_b32_e32 v64, 16, v187
	v_mul_f32_e32 v74, v66, v64
	v_and_b32_e32 v64, 0xffff0000, v187
	v_mul_f32_e32 v67, v67, v64
	v_cvt_pk_bf16_f32 v64, v68, v69
	v_cvt_pk_bf16_f32 v65, v70, v71
	v_cvt_pk_bf16_f32 v66, v72, v73
	v_cvt_pk_bf16_f32 v67, v74, v67
	global_store_dwordx4 v[76:77], v[64:67], off offset:256
	v_lshlrev_b64 v[72:73], 12, v[98:99]
	v_lshl_add_u64 v[76:77], v[148:149], 0, v[72:73]
	v_lshlrev_b64 v[64:65], 12, v[96:97]
	v_lshl_add_u64 v[68:69], v[148:149], 0, v[64:65]
	s_waitcnt vmcnt(8)
	v_mov_b32_e32 v64, v206
	v_mov_b32_e32 v65, v207
	v_mov_b32_e32 v66, v208
	v_mov_b32_e32 v67, v209
	s_nop 0
	v_mov_b32_e32 v68, v210
	v_mov_b32_e32 v69, v211
	v_mov_b32_e32 v70, v212
	v_mov_b32_e32 v71, v213
	s_nop 0
	v_mov_b32_e32 v72, v214
	v_mov_b32_e32 v73, v215
	v_mov_b32_e32 v74, v216
	v_mov_b32_e32 v75, v217
	s_nop 0
	v_mov_b32_e32 v76, v218
	v_mov_b32_e32 v77, v219
	v_mov_b32_e32 v78, v220
	v_mov_b32_e32 v79, v221
	v_lshlrev_b64 v[80:81], 12, v[100:101]
	v_lshl_add_u64 v[84:85], v[148:149], 0, v[80:81]
	v_mov_b32_e32 v80, v222
	v_mov_b32_e32 v81, v223
	v_mov_b32_e32 v82, v224
	v_mov_b32_e32 v83, v225
	s_nop 0
	v_mov_b32_e32 v84, v226
	v_mov_b32_e32 v85, v227
	v_mov_b32_e32 v86, v228
	v_mov_b32_e32 v87, v229
	v_lshlrev_b64 v[88:89], 12, v[102:103]
	v_lshl_add_u64 v[92:93], v[148:149], 0, v[88:89]
	v_mov_b32_e32 v88, v230
	v_mov_b32_e32 v89, v231
	v_mov_b32_e32 v90, v232
	v_mov_b32_e32 v91, v233
	s_nop 0
	v_mov_b32_e32 v92, v234
	v_mov_b32_e32 v93, v235
	v_mov_b32_e32 v94, v236
	v_mov_b32_e32 v95, v237
	v_lshlrev_b64 v[96:97], 11, v[96:97]
	v_lshl_add_u64 v[96:97], s[42:43], 0, v[96:97]
	v_lshl_add_u64 v[96:97], v[96:97], 0, v[144:145]
	v_lshlrev_b32_e32 v104, 16, v64
	v_and_b32_e32 v64, 0xffff0000, v64
	v_mul_f32_e32 v61, v61, v64
	v_lshlrev_b32_e32 v64, 16, v65
	v_mul_f32_e32 v62, v62, v64
	v_and_b32_e32 v64, 0xffff0000, v65
	v_mul_f32_e32 v63, v63, v64
	v_lshlrev_b32_e32 v64, 16, v66
	v_mul_f32_e32 v64, v56, v64
	v_and_b32_e32 v56, 0xffff0000, v66
	v_mul_f32_e32 v65, v57, v56
	v_lshlrev_b32_e32 v56, 16, v67
	v_mul_f32_e32 v66, v58, v56
	v_and_b32_e32 v56, 0xffff0000, v67
	v_mul_f32_e32 v60, v60, v104
	v_mul_f32_e32 v59, v59, v56
	v_cvt_pk_bf16_f32 v56, v60, v61
	v_cvt_pk_bf16_f32 v57, v62, v63
	v_cvt_pk_bf16_f32 v58, v64, v65
	v_cvt_pk_bf16_f32 v59, v66, v59
	global_store_dwordx4 v[96:97], v[56:59], off
	s_nop 0
	v_lshlrev_b32_e32 v56, 16, v68
	v_mul_f32_e32 v52, v52, v56
	v_and_b32_e32 v56, 0xffff0000, v68
	v_mul_f32_e32 v53, v53, v56
	v_lshlrev_b32_e32 v56, 16, v69
	v_mul_f32_e32 v54, v54, v56
	v_and_b32_e32 v56, 0xffff0000, v69
	v_mul_f32_e32 v55, v55, v56
	v_lshlrev_b32_e32 v56, 16, v70
	v_mul_f32_e32 v56, v44, v56
	v_and_b32_e32 v44, 0xffff0000, v70
	v_mul_f32_e32 v57, v45, v44
	v_lshlrev_b32_e32 v44, 16, v71
	v_mul_f32_e32 v58, v46, v44
	v_and_b32_e32 v44, 0xffff0000, v71
	v_mul_f32_e32 v47, v47, v44
	v_cvt_pk_bf16_f32 v44, v52, v53
	v_cvt_pk_bf16_f32 v45, v54, v55
	v_cvt_pk_bf16_f32 v46, v56, v57
	v_cvt_pk_bf16_f32 v47, v58, v47
	global_store_dwordx4 v[96:97], v[44:47], off offset:256
	s_nop 0
	v_lshlrev_b32_e32 v46, 16, v72
	v_mul_f32_e32 v46, v48, v46
	v_lshlrev_b32_e32 v48, 16, v73
	v_and_b32_e32 v47, 0xffff0000, v72
	v_mul_f32_e32 v48, v50, v48
	v_lshlrev_b32_e32 v50, 16, v74
	v_mul_f32_e32 v47, v49, v47
	v_and_b32_e32 v49, 0xffff0000, v73
	v_mul_f32_e32 v50, v40, v50
	v_and_b32_e32 v40, 0xffff0000, v74
	v_lshlrev_b64 v[44:45], 11, v[98:99]
	v_mul_f32_e32 v49, v51, v49
	v_mul_f32_e32 v51, v41, v40
	v_lshlrev_b32_e32 v40, 16, v75
	v_lshl_add_u64 v[44:45], s[42:43], 0, v[44:45]
	v_mul_f32_e32 v52, v42, v40
	v_and_b32_e32 v40, 0xffff0000, v75
	v_lshl_add_u64 v[44:45], v[44:45], 0, v[144:145]
	v_mul_f32_e32 v43, v43, v40
	v_cvt_pk_bf16_f32 v40, v46, v47
	v_cvt_pk_bf16_f32 v41, v48, v49
	v_cvt_pk_bf16_f32 v42, v50, v51
	v_cvt_pk_bf16_f32 v43, v52, v43
	global_store_dwordx4 v[44:45], v[40:43], off
	s_nop 0
	v_lshlrev_b32_e32 v40, 16, v76
	v_mul_f32_e32 v36, v36, v40
	v_and_b32_e32 v40, 0xffff0000, v76
	v_mul_f32_e32 v37, v37, v40
	v_lshlrev_b32_e32 v40, 16, v77
	v_mul_f32_e32 v38, v38, v40
	v_and_b32_e32 v40, 0xffff0000, v77
	v_mul_f32_e32 v39, v39, v40
	v_lshlrev_b32_e32 v40, 16, v78
	v_mul_f32_e32 v40, v28, v40
	v_and_b32_e32 v28, 0xffff0000, v78
	v_mul_f32_e32 v41, v29, v28
	v_lshlrev_b32_e32 v28, 16, v79
	v_mul_f32_e32 v42, v30, v28
	v_and_b32_e32 v28, 0xffff0000, v79
	v_mul_f32_e32 v31, v31, v28
	v_cvt_pk_bf16_f32 v28, v36, v37
	v_cvt_pk_bf16_f32 v29, v38, v39
	v_cvt_pk_bf16_f32 v30, v40, v41
	v_cvt_pk_bf16_f32 v31, v42, v31
	global_store_dwordx4 v[44:45], v[28:31], off offset:256
	s_nop 0
	v_lshlrev_b32_e32 v30, 16, v80
	v_mul_f32_e32 v30, v32, v30
	v_lshlrev_b32_e32 v32, 16, v81
	v_and_b32_e32 v31, 0xffff0000, v80
	v_mul_f32_e32 v32, v34, v32
	v_lshlrev_b32_e32 v34, 16, v82
	v_mul_f32_e32 v31, v33, v31
	v_and_b32_e32 v33, 0xffff0000, v81
	v_mul_f32_e32 v34, v24, v34
	v_and_b32_e32 v24, 0xffff0000, v82
	v_lshlrev_b64 v[28:29], 11, v[100:101]
	v_mul_f32_e32 v33, v35, v33
	v_mul_f32_e32 v35, v25, v24
	v_lshlrev_b32_e32 v24, 16, v83
	v_lshl_add_u64 v[28:29], s[42:43], 0, v[28:29]
	v_mul_f32_e32 v36, v26, v24
	v_and_b32_e32 v24, 0xffff0000, v83
	v_lshl_add_u64 v[28:29], v[28:29], 0, v[144:145]
	v_mul_f32_e32 v27, v27, v24
	v_cvt_pk_bf16_f32 v24, v30, v31
	v_cvt_pk_bf16_f32 v25, v32, v33
	v_cvt_pk_bf16_f32 v26, v34, v35
	v_cvt_pk_bf16_f32 v27, v36, v27
	global_store_dwordx4 v[28:29], v[24:27], off
	s_nop 0
	v_lshlrev_b32_e32 v24, 16, v84
	v_mul_f32_e32 v20, v20, v24
	v_and_b32_e32 v24, 0xffff0000, v84
	v_mul_f32_e32 v21, v21, v24
	v_lshlrev_b32_e32 v24, 16, v85
	v_mul_f32_e32 v22, v22, v24
	v_and_b32_e32 v24, 0xffff0000, v85
	v_mul_f32_e32 v23, v23, v24
	v_lshlrev_b32_e32 v24, 16, v86
	v_mul_f32_e32 v24, v12, v24
	v_and_b32_e32 v12, 0xffff0000, v86
	v_mul_f32_e32 v25, v13, v12
	v_lshlrev_b32_e32 v12, 16, v87
	v_mul_f32_e32 v26, v14, v12
	v_and_b32_e32 v12, 0xffff0000, v87
	v_mul_f32_e32 v15, v15, v12
	v_cvt_pk_bf16_f32 v12, v20, v21
	v_cvt_pk_bf16_f32 v13, v22, v23
	v_cvt_pk_bf16_f32 v14, v24, v25
	v_cvt_pk_bf16_f32 v15, v26, v15
	global_store_dwordx4 v[28:29], v[12:15], off offset:256
	s_nop 0
	v_lshlrev_b32_e32 v14, 16, v88
	v_mul_f32_e32 v14, v16, v14
	v_lshlrev_b32_e32 v16, 16, v89
	v_and_b32_e32 v15, 0xffff0000, v88
	v_mul_f32_e32 v16, v18, v16
	v_lshlrev_b32_e32 v18, 16, v90
	v_mul_f32_e32 v15, v17, v15
	v_and_b32_e32 v17, 0xffff0000, v89
	v_mul_f32_e32 v18, v8, v18
	v_and_b32_e32 v8, 0xffff0000, v90
	v_lshlrev_b64 v[12:13], 11, v[102:103]
	v_mul_f32_e32 v17, v19, v17
	v_mul_f32_e32 v19, v9, v8
	v_lshlrev_b32_e32 v8, 16, v91
	v_lshl_add_u64 v[12:13], s[42:43], 0, v[12:13]
	v_mul_f32_e32 v20, v10, v8
	v_and_b32_e32 v8, 0xffff0000, v91
	v_lshl_add_u64 v[12:13], v[12:13], 0, v[144:145]
	v_mul_f32_e32 v11, v11, v8
	v_cvt_pk_bf16_f32 v8, v14, v15
	v_cvt_pk_bf16_f32 v9, v16, v17
	v_cvt_pk_bf16_f32 v10, v18, v19
	v_cvt_pk_bf16_f32 v11, v20, v11
	global_store_dwordx4 v[12:13], v[8:11], off
	s_nop 0
	v_lshlrev_b32_e32 v8, 16, v92
	v_mul_f32_e32 v4, v4, v8
	v_and_b32_e32 v8, 0xffff0000, v92
	v_mul_f32_e32 v5, v5, v8
	v_lshlrev_b32_e32 v8, 16, v93
	v_mul_f32_e32 v6, v6, v8
	v_and_b32_e32 v8, 0xffff0000, v93
	v_mul_f32_e32 v7, v7, v8
	v_lshlrev_b32_e32 v8, 16, v94
	v_mul_f32_e32 v8, v0, v8
	v_and_b32_e32 v0, 0xffff0000, v94
	v_mul_f32_e32 v9, v1, v0
	v_lshlrev_b32_e32 v0, 16, v95
	v_mul_f32_e32 v10, v2, v0
	v_and_b32_e32 v0, 0xffff0000, v95
	v_mul_f32_e32 v3, v3, v0
	v_cvt_pk_bf16_f32 v0, v4, v5
	v_cvt_pk_bf16_f32 v1, v6, v7
	v_cvt_pk_bf16_f32 v2, v8, v9
	v_cvt_pk_bf16_f32 v3, v10, v3
	global_store_dwordx4 v[12:13], v[0:3], off offset:256
	s_mov_b32 s99, 1
	s_cbranch_vccnz .LBB0_3130
	s_andn2_b64 vcc, exec, s[0:1]
	s_cbranch_vccnz .LBB0_3129
	s_barrier
	s_branch .LBB0_3129

.LBB0_3152:
	s_lshl_b32 s54, s4, 6
	s_lshl_b32 s10, s4, 13
	s_lshl_b32 s4, s5, 5
	s_and_b32 s55, s4, 0x60
	s_mov_b64 s[4:5], 0x80
	s_add_i32 m0, s35, 0x18000
	v_lshl_add_u64 v[6:7], v[6:7], 0, s[4:5]
	s_lshl_b32 s11, s55, 7
	s_waitcnt vmcnt(2)
	s_barrier
	global_load_lds_dwordx4 v[6:7], off
	v_lshl_add_u64 v[4:5], v[4:5], 0, s[4:5]
	s_add_i32 m0, s35, 0x1a000
	s_add_i32 s60, s35, 0x8000
	s_add_i32 s61, s35, 0xa000
	global_load_lds_dwordx4 v[4:5], off
	v_lshl_add_u64 v[0:1], v[0:1], 0, s[4:5]
	s_mov_b32 m0, s60
	s_add_u32 s8, s40, 0x10080
	global_load_lds_dwordx4 v[0:1], off
	v_lshl_add_u64 v[0:1], v[2:3], 0, s[4:5]
	s_mov_b32 m0, s61
	s_addc_u32 s9, s41, 0
	global_load_lds_dwordx4 v[0:1], off
	s_add_i32 m0, s35, 0x1c000
	v_lshl_add_u64 v[0:1], s[8:9], 0, v[150:151]
	global_load_lds_dwordx4 v[0:1], off
	v_lshl_add_u64 v[0:1], s[8:9], 0, v[154:155]
	s_add_i32 m0, s35, 0x1e000
	v_bfe_u32 v171, v8, 4, 2
	global_load_lds_dwordx4 v[0:1], off
	v_and_b32_e32 v170, 15, v8
	v_lshlrev_b32_e32 v0, 4, v171
	v_lshlrev_b32_e32 v1, 2, v8
	v_lshl_or_b32 v0, v170, 6, v0
	v_and_b32_e32 v1, 32, v1
	s_cmpk_lt_u32 s7, 0x100
	v_bitop3_b32 v2, v0, s10, v1 bitop3:0xde
	s_cselect_b64 s[8:9], -1, 0
	s_add_u32 s10, s38, s2
	v_bitop3_b32 v172, v0, s11, v1 bitop3:0xde
	s_waitcnt vmcnt(6)
	s_addc_u32 s11, s33, s3
	s_add_i32 s66, 0, 0x10000
	s_add_i32 s68, 0, 0x14000
	v_add_u32_e32 v173, s66, v172
	v_add_u32_e32 v174, s68, v172
	s_add_i32 s66, s66, s50
	s_add_i32 s68, s68, s50
	s_sext_i32_i8 s70, s6
	v_mov_b64_e32 v[156:157], 0x200
	v_mov_b64_e32 v[158:159], 0x1ff
	v_add_u32_e32 v175, 0, v2
	s_add_i32 s64, s35, 0xc000
	s_add_i32 s65, s35, 0xe000
	s_mov_b64 s[12:13], 0x100
	s_mov_b64 s[16:17], 0x180
	s_add_i32 s67, s66, 0x2000
	s_add_i32 s69, s68, 0x2000
	s_barrier
	s_mov_b32 s99, 0
	s_branch .LBB0_3155

.Lrlx29p1b:
	s_waitcnt vmcnt(24)
	s_branch .Lrlx29p1b_done
.LBB0_3153:
	s_add_u32 s10, s10, s38
	s_addc_u32 s11, s11, s33
	s_mov_b64 s[6:7], 0

.LBB0_3161:
	ds_read_b128 v[0:3], v173
	ds_read_b128 v[4:7], v173 offset:1024
	ds_read_b128 v[8:11], v173 offset:2048
	ds_read_b128 v[12:15], v173 offset:3072
	ds_read_b128 v[16:19], v174
	ds_read_b128 v[20:23], v174 offset:1024
	ds_read_b128 v[24:27], v174 offset:2048
	ds_read_b128 v[28:31], v174 offset:3072
	s_ashr_i32 s23, s22, 31
	s_lshl_b64 s[24:25], s[22:23], 17
	v_readlane_b32 s26, v255, 24
	v_readlane_b32 s27, v255, 25
	s_add_u32 s24, s26, s24
	s_addc_u32 s25, s27, s25
	s_and_b64 s[26:27], s[6:7], exec
	s_cselect_b32 s49, s25, s37
	s_cselect_b32 s48, s24, s36
	s_ashr_i32 s19, s18, 31
	s_lshl_b64 s[26:27], s[18:19], 17
	v_readlane_b32 s46, v255, 30
	v_readlane_b32 s47, v255, 31
	s_add_u32 s26, s46, s26
	s_addc_u32 s27, s47, s27
	s_and_b64 s[46:47], s[6:7], exec
	s_cselect_b32 s47, s27, s41
	s_cselect_b32 s46, s26, s40
	s_add_u32 s72, s36, 0x10080
	s_addc_u32 s73, s37, 0
	s_mov_b32 m0, s64
	v_lshl_add_u64 v[64:65], s[72:73], 0, v[148:149]
	ds_read_b128 v[32:35], v175
	ds_read_b128 v[36:39], v175 offset:1024
	ds_read_b128 v[40:43], v175 offset:2048
	ds_read_b128 v[44:47], v175 offset:3072
	ds_read_b128 v[48:51], v175 offset:4096
	ds_read_b128 v[52:55], v175 offset:5120
	ds_read_b128 v[56:59], v175 offset:6144
	ds_read_b128 v[60:63], v175 offset:7168
	global_load_lds_dwordx4 v[64:65], off
	v_lshl_add_u64 v[64:65], s[72:73], 0, v[152:153]
	s_mov_b32 m0, s65
	s_nop 0
	global_load_lds_dwordx4 v[64:65], off
	s_cmp_lg_u32 s99, 0
	s_cbranch_scc1 .Lrlx29p1a
	s_waitcnt vmcnt(8)
.Lrlx29p1a_done:
	s_waitcnt lgkmcnt(0)
	s_barrier
	s_setprio 1
	s_waitcnt lgkmcnt(0)
	v_mfma_f32_16x16x32_bf16 v[64:67], v[0:3], v[32:35], 0
	v_mfma_f32_16x16x32_bf16 v[68:71], v[8:11], v[32:35], 0
	v_mfma_f32_16x16x32_bf16 v[72:75], v[0:3], v[40:43], 0
	v_mfma_f32_16x16x32_bf16 v[76:79], v[8:11], v[40:43], 0
	v_mfma_f32_16x16x32_bf16 v[80:83], v[0:3], v[48:51], 0
	v_mfma_f32_16x16x32_bf16 v[84:87], v[8:11], v[48:51], 0
	v_mfma_f32_16x16x32_bf16 v[88:91], v[0:3], v[56:59], 0
	v_mfma_f32_16x16x32_bf16 v[92:95], v[8:11], v[56:59], 0
	v_mfma_f32_16x16x32_bf16 v[64:67], v[4:7], v[36:39], v[64:67]
	v_mfma_f32_16x16x32_bf16 v[68:71], v[12:15], v[36:39], v[68:71]
	v_mfma_f32_16x16x32_bf16 v[72:75], v[4:7], v[44:47], v[72:75]
	v_mfma_f32_16x16x32_bf16 v[76:79], v[12:15], v[44:47], v[76:79]
	v_mfma_f32_16x16x32_bf16 v[80:83], v[4:7], v[52:55], v[80:83]
	v_mfma_f32_16x16x32_bf16 v[84:87], v[12:15], v[52:55], v[84:87]
	v_mfma_f32_16x16x32_bf16 v[88:91], v[4:7], v[60:63], v[88:91]
	v_mfma_f32_16x16x32_bf16 v[92:95], v[12:15], v[60:63], v[92:95]
	s_setprio 0
	s_setprio 1
	v_mfma_f32_16x16x32_bf16 v[96:99], v[16:19], v[32:35], 0
	v_mfma_f32_16x16x32_bf16 v[32:35], v[24:27], v[32:35], 0
	v_mfma_f32_16x16x32_bf16 v[96:99], v[20:23], v[36:39], v[96:99]
	v_mfma_f32_16x16x32_bf16 v[32:35], v[28:31], v[36:39], v[32:35]
	v_mfma_f32_16x16x32_bf16 v[36:39], v[16:19], v[40:43], 0
	v_mfma_f32_16x16x32_bf16 v[40:43], v[24:27], v[40:43], 0
	v_mfma_f32_16x16x32_bf16 v[36:39], v[20:23], v[44:47], v[36:39]
	v_mfma_f32_16x16x32_bf16 v[40:43], v[28:31], v[44:47], v[40:43]
	v_mfma_f32_16x16x32_bf16 v[44:47], v[16:19], v[48:51], 0
	v_mfma_f32_16x16x32_bf16 v[48:51], v[24:27], v[48:51], 0
	v_mfma_f32_16x16x32_bf16 v[44:47], v[20:23], v[52:55], v[44:47]
	v_mfma_f32_16x16x32_bf16 v[48:51], v[28:31], v[52:55], v[48:51]
	v_mfma_f32_16x16x32_bf16 v[52:55], v[16:19], v[56:59], 0
	v_mfma_f32_16x16x32_bf16 v[56:59], v[24:27], v[56:59], 0
	v_mfma_f32_16x16x32_bf16 v[52:55], v[20:23], v[60:63], v[52:55]
	v_mfma_f32_16x16x32_bf16 v[56:59], v[28:31], v[60:63], v[56:59]
	s_setprio 0
	s_barrier
	v_lshl_add_u64 v[168:169], s[40:41], 0, v[150:151]
	s_mov_b32 m0, s66
	v_lshl_add_u64 v[128:129], v[168:169], 0, s[12:13]
	v_lshl_add_u64 v[208:209], s[40:41], 0, v[154:155]
	s_add_u32 s72, s40, 0x10100
	ds_read_b128 v[60:63], v175 offset:16384
	ds_read_b128 v[100:103], v175 offset:17408
	ds_read_b128 v[104:107], v175 offset:18432
	ds_read_b128 v[108:111], v175 offset:19456
	ds_read_b128 v[112:115], v175 offset:20480
	ds_read_b128 v[116:119], v175 offset:21504
	ds_read_b128 v[120:123], v175 offset:22528
	ds_read_b128 v[124:127], v175 offset:23552
	global_load_lds_dwordx4 v[128:129], off
	v_lshl_add_u64 v[128:129], v[208:209], 0, s[12:13]
	s_mov_b32 m0, s67
	s_addc_u32 s73, s41, 0
	global_load_lds_dwordx4 v[128:129], off
	v_lshl_add_u64 v[128:129], s[72:73], 0, v[150:151]
	s_mov_b32 m0, s68
	v_lshl_add_u64 v[210:211], s[36:37], 0, v[148:149]
	global_load_lds_dwordx4 v[128:129], off
	v_lshl_add_u64 v[128:129], s[72:73], 0, v[154:155]
	s_mov_b32 m0, s69
	v_lshl_add_u64 v[216:217], s[36:37], 0, v[152:153]
	global_load_lds_dwordx4 v[128:129], off
	v_lshl_add_u64 v[128:129], v[210:211], 0, s[12:13]
	s_mov_b32 m0, s35
	s_nop 0
	global_load_lds_dwordx4 v[128:129], off
	v_lshl_add_u64 v[128:129], v[216:217], 0, s[12:13]
	s_mov_b32 m0, s51
	s_nop 0
	global_load_lds_dwordx4 v[128:129], off
	s_cmp_lg_u32 s99, 0
	s_cbranch_scc1 .Lrlx29p1b
	s_waitcnt vmcnt(8)
.Lrlx29p1b_done:
	s_mov_b32 s99, 0
	s_waitcnt lgkmcnt(0)
	s_barrier
	s_setprio 1
	s_waitcnt lgkmcnt(0)
	v_mfma_f32_16x16x32_bf16 v[128:131], v[0:3], v[60:63], 0
	v_mfma_f32_16x16x32_bf16 v[136:139], v[0:3], v[104:107], 0
	v_mfma_f32_16x16x32_bf16 v[144:147], v[0:3], v[112:115], 0
	v_mfma_f32_16x16x32_bf16 v[0:3], v[0:3], v[120:123], 0
	v_mfma_f32_16x16x32_bf16 v[128:131], v[4:7], v[100:103], v[128:131]
	v_mfma_f32_16x16x32_bf16 v[132:135], v[8:11], v[60:63], 0
	v_mfma_f32_16x16x32_bf16 v[136:139], v[4:7], v[108:111], v[136:139]
	v_mfma_f32_16x16x32_bf16 v[140:143], v[8:11], v[104:107], 0
	v_mfma_f32_16x16x32_bf16 v[144:147], v[4:7], v[116:119], v[144:147]
	v_mfma_f32_16x16x32_bf16 v[0:3], v[4:7], v[124:127], v[0:3]
	v_mfma_f32_16x16x32_bf16 v[4:7], v[8:11], v[120:123], 0
	v_mfma_f32_16x16x32_bf16 v[132:135], v[12:15], v[100:103], v[132:135]
	v_mfma_f32_16x16x32_bf16 v[140:143], v[12:15], v[108:111], v[140:143]
	v_mfma_f32_16x16x32_bf16 v[160:163], v[8:11], v[112:115], 0
	v_mfma_f32_16x16x32_bf16 v[4:7], v[12:15], v[124:127], v[4:7]
	v_mfma_f32_16x16x32_bf16 v[160:163], v[12:15], v[116:119], v[160:163]
	s_setprio 0
	s_setprio 1
	v_mfma_f32_16x16x32_bf16 v[8:11], v[16:19], v[60:63], 0
	v_mfma_f32_16x16x32_bf16 v[12:15], v[24:27], v[60:63], 0
	v_mfma_f32_16x16x32_bf16 v[8:11], v[20:23], v[100:103], v[8:11]
	v_mfma_f32_16x16x32_bf16 v[12:15], v[28:31], v[100:103], v[12:15]
	v_mfma_f32_16x16x32_bf16 v[60:63], v[16:19], v[104:107], 0
	v_mfma_f32_16x16x32_bf16 v[100:103], v[24:27], v[104:107], 0
	v_mfma_f32_16x16x32_bf16 v[104:107], v[16:19], v[112:115], 0
	v_mfma_f32_16x16x32_bf16 v[16:19], v[16:19], v[120:123], 0
	v_mfma_f32_16x16x32_bf16 v[60:63], v[20:23], v[108:111], v[60:63]
	v_mfma_f32_16x16x32_bf16 v[100:103], v[28:31], v[108:111], v[100:103]
	v_mfma_f32_16x16x32_bf16 v[104:107], v[20:23], v[116:119], v[104:107]
	v_mfma_f32_16x16x32_bf16 v[108:111], v[24:27], v[112:115], 0
	v_mfma_f32_16x16x32_bf16 v[16:19], v[20:23], v[124:127], v[16:19]
	v_mfma_f32_16x16x32_bf16 v[20:23], v[24:27], v[120:123], 0
	v_mfma_f32_16x16x32_bf16 v[108:111], v[28:31], v[116:119], v[108:111]
	v_mfma_f32_16x16x32_bf16 v[20:23], v[28:31], v[124:127], v[20:23]
	s_setprio 0
	s_barrier
	s_add_i32 s71, 0, 0x18000
	s_add_i32 s23, 0, 0x1c000
	v_add_u32_e32 v236, s71, v172
	v_add_u32_e32 v237, s23, v172
	ds_read_b128 v[24:27], v236
	ds_read_b128 v[28:31], v236 offset:1024
	ds_read_b128 v[112:115], v236 offset:2048
	ds_read_b128 v[116:119], v236 offset:3072
	ds_read_b128 v[120:123], v237
	ds_read_b128 v[124:127], v237 offset:1024
	ds_read_b128 v[164:167], v237 offset:2048
	ds_read_b128 v[176:179], v237 offset:3072
	s_add_u32 s72, s36, 0x10100
	s_addc_u32 s73, s37, 0
	s_mov_b32 m0, s52
	v_lshl_add_u64 v[218:219], s[72:73], 0, v[148:149]
	ds_read_b128 v[180:183], v175 offset:32768
	ds_read_b128 v[184:187], v175 offset:33792
	ds_read_b128 v[188:191], v175 offset:34816
	ds_read_b128 v[192:195], v175 offset:35840
	ds_read_b128 v[196:199], v175 offset:36864
	ds_read_b128 v[200:203], v175 offset:37888
	ds_read_b128 v[204:207], v175 offset:38912
	ds_read_b128 v[212:215], v175 offset:39936
	global_load_lds_dwordx4 v[218:219], off
	v_lshl_add_u64 v[218:219], s[72:73], 0, v[152:153]
	s_mov_b32 m0, s53
	s_nop 0
	global_load_lds_dwordx4 v[218:219], off
	s_waitcnt vmcnt(8)
	s_waitcnt lgkmcnt(0)
	s_barrier
	s_setprio 1
	s_waitcnt lgkmcnt(0)
	v_mfma_f32_16x16x32_bf16 v[64:67], v[24:27], v[180:183], v[64:67]
	v_mfma_f32_16x16x32_bf16 v[68:71], v[112:115], v[180:183], v[68:71]
	v_mfma_f32_16x16x32_bf16 v[72:75], v[24:27], v[188:191], v[72:75]
	v_mfma_f32_16x16x32_bf16 v[76:79], v[112:115], v[188:191], v[76:79]
	v_mfma_f32_16x16x32_bf16 v[80:83], v[24:27], v[196:199], v[80:83]
	v_mfma_f32_16x16x32_bf16 v[84:87], v[112:115], v[196:199], v[84:87]
	v_mfma_f32_16x16x32_bf16 v[88:91], v[24:27], v[204:207], v[88:91]
	v_mfma_f32_16x16x32_bf16 v[92:95], v[112:115], v[204:207], v[92:95]
	v_mfma_f32_16x16x32_bf16 v[64:67], v[28:31], v[184:187], v[64:67]
	v_mfma_f32_16x16x32_bf16 v[68:71], v[116:119], v[184:187], v[68:71]
	v_mfma_f32_16x16x32_bf16 v[72:75], v[28:31], v[192:195], v[72:75]
	v_mfma_f32_16x16x32_bf16 v[76:79], v[116:119], v[192:195], v[76:79]
	v_mfma_f32_16x16x32_bf16 v[80:83], v[28:31], v[200:203], v[80:83]
	v_mfma_f32_16x16x32_bf16 v[84:87], v[116:119], v[200:203], v[84:87]
	v_mfma_f32_16x16x32_bf16 v[88:91], v[28:31], v[212:215], v[88:91]
	v_mfma_f32_16x16x32_bf16 v[92:95], v[116:119], v[212:215], v[92:95]
	s_setprio 0
	s_setprio 1
	v_mfma_f32_16x16x32_bf16 v[96:99], v[120:123], v[180:183], v[96:99]
	v_mfma_f32_16x16x32_bf16 v[32:35], v[164:167], v[180:183], v[32:35]
	v_mfma_f32_16x16x32_bf16 v[36:39], v[120:123], v[188:191], v[36:39]
	v_mfma_f32_16x16x32_bf16 v[40:43], v[164:167], v[188:191], v[40:43]
	v_mfma_f32_16x16x32_bf16 v[44:47], v[120:123], v[196:199], v[44:47]
	v_mfma_f32_16x16x32_bf16 v[48:51], v[164:167], v[196:199], v[48:51]
	v_mfma_f32_16x16x32_bf16 v[52:55], v[120:123], v[204:207], v[52:55]
	v_mfma_f32_16x16x32_bf16 v[56:59], v[164:167], v[204:207], v[56:59]
	v_mfma_f32_16x16x32_bf16 v[96:99], v[124:127], v[184:187], v[96:99]
	v_mfma_f32_16x16x32_bf16 v[32:35], v[176:179], v[184:187], v[32:35]
	v_mfma_f32_16x16x32_bf16 v[36:39], v[124:127], v[192:195], v[36:39]
	v_mfma_f32_16x16x32_bf16 v[40:43], v[176:179], v[192:195], v[40:43]
	v_mfma_f32_16x16x32_bf16 v[44:47], v[124:127], v[200:203], v[44:47]
	v_mfma_f32_16x16x32_bf16 v[48:51], v[176:179], v[200:203], v[48:51]
	v_mfma_f32_16x16x32_bf16 v[52:55], v[124:127], v[212:215], v[52:55]
	v_mfma_f32_16x16x32_bf16 v[56:59], v[176:179], v[212:215], v[56:59]
	s_setprio 0
	s_barrier
	s_add_i32 s71, s71, s50
	s_add_i32 s19, s71, 0x2000
	v_lshl_add_u64 v[168:169], v[168:169], 0, s[16:17]
	s_mov_b32 m0, s71
	s_add_u32 s40, s40, 0x10180
	ds_read_b128 v[180:183], v175 offset:49152
	ds_read_b128 v[184:187], v175 offset:50176
	ds_read_b128 v[188:191], v175 offset:51200
	ds_read_b128 v[192:195], v175 offset:52224
	ds_read_b128 v[196:199], v175 offset:53248
	ds_read_b128 v[200:203], v175 offset:54272
	ds_read_b128 v[204:207], v175 offset:55296
	ds_read_b128 v[212:215], v175 offset:56320
	global_load_lds_dwordx4 v[168:169], off
	v_lshl_add_u64 v[168:169], v[208:209], 0, s[16:17]
	s_mov_b32 m0, s19
	s_addc_u32 s41, s41, 0
	s_add_i32 s23, s23, s50
	global_load_lds_dwordx4 v[168:169], off
	v_lshl_add_u64 v[168:169], s[40:41], 0, v[150:151]
	s_mov_b32 m0, s23
	s_nop 0
	global_load_lds_dwordx4 v[168:169], off
	v_lshl_add_u64 v[168:169], s[40:41], 0, v[154:155]
	s_add_i32 s40, s23, 0x2000
	s_mov_b32 m0, s40
	s_nop 0
	global_load_lds_dwordx4 v[168:169], off
	v_lshl_add_u64 v[168:169], v[210:211], 0, s[16:17]
	s_mov_b32 m0, s60
	s_nop 0
	global_load_lds_dwordx4 v[168:169], off
	v_lshl_add_u64 v[168:169], v[216:217], 0, s[16:17]
	s_mov_b32 m0, s61
	s_nop 0
	global_load_lds_dwordx4 v[168:169], off
	s_waitcnt vmcnt(8)
	s_waitcnt lgkmcnt(0)
	s_barrier
	s_setprio 1
	s_waitcnt lgkmcnt(0)
	v_mfma_f32_16x16x32_bf16 v[128:131], v[24:27], v[180:183], v[128:131]
	v_mfma_f32_16x16x32_bf16 v[132:135], v[112:115], v[180:183], v[132:135]
	v_mfma_f32_16x16x32_bf16 v[136:139], v[24:27], v[188:191], v[136:139]
	v_mfma_f32_16x16x32_bf16 v[140:143], v[112:115], v[188:191], v[140:143]
	v_mfma_f32_16x16x32_bf16 v[0:3], v[24:27], v[204:207], v[0:3]
	v_mfma_f32_16x16x32_bf16 v[4:7], v[112:115], v[204:207], v[4:7]
	v_mfma_f32_16x16x32_bf16 v[128:131], v[28:31], v[184:187], v[128:131]
	v_mfma_f32_16x16x32_bf16 v[132:135], v[116:119], v[184:187], v[132:135]
	v_mfma_f32_16x16x32_bf16 v[136:139], v[28:31], v[192:195], v[136:139]
	v_mfma_f32_16x16x32_bf16 v[140:143], v[116:119], v[192:195], v[140:143]
	v_mfma_f32_16x16x32_bf16 v[144:147], v[24:27], v[196:199], v[144:147]
	v_mfma_f32_16x16x32_bf16 v[160:163], v[112:115], v[196:199], v[160:163]
	v_mfma_f32_16x16x32_bf16 v[0:3], v[28:31], v[212:215], v[0:3]
	v_mfma_f32_16x16x32_bf16 v[4:7], v[116:119], v[212:215], v[4:7]
	v_mfma_f32_16x16x32_bf16 v[144:147], v[28:31], v[200:203], v[144:147]
	v_mfma_f32_16x16x32_bf16 v[160:163], v[116:119], v[200:203], v[160:163]
	s_setprio 0
	s_setprio 1
	v_mfma_f32_16x16x32_bf16 v[8:11], v[120:123], v[180:183], v[8:11]
	v_mfma_f32_16x16x32_bf16 v[12:15], v[164:167], v[180:183], v[12:15]
	v_mfma_f32_16x16x32_bf16 v[24:27], v[120:123], v[188:191], v[60:63]
	v_mfma_f32_16x16x32_bf16 v[28:31], v[164:167], v[188:191], v[100:103]
	v_mfma_f32_16x16x32_bf16 v[60:63], v[120:123], v[196:199], v[104:107]
	v_mfma_f32_16x16x32_bf16 v[100:103], v[164:167], v[196:199], v[108:111]
	v_mfma_f32_16x16x32_bf16 v[16:19], v[120:123], v[204:207], v[16:19]
	v_mfma_f32_16x16x32_bf16 v[20:23], v[164:167], v[204:207], v[20:23]
	v_mfma_f32_16x16x32_bf16 v[8:11], v[124:127], v[184:187], v[8:11]
	v_mfma_f32_16x16x32_bf16 v[12:15], v[176:179], v[184:187], v[12:15]
	v_mfma_f32_16x16x32_bf16 v[24:27], v[124:127], v[192:195], v[24:27]
	v_mfma_f32_16x16x32_bf16 v[28:31], v[176:179], v[192:195], v[28:31]
	v_mfma_f32_16x16x32_bf16 v[60:63], v[124:127], v[200:203], v[60:63]
	v_mfma_f32_16x16x32_bf16 v[100:103], v[176:179], v[200:203], v[100:103]
	v_mfma_f32_16x16x32_bf16 v[16:19], v[124:127], v[212:215], v[16:19]
	v_mfma_f32_16x16x32_bf16 v[20:23], v[176:179], v[212:215], v[20:23]
	s_setprio 0
	s_barrier
	ds_read_b128 v[104:107], v173
	ds_read_b128 v[108:111], v173 offset:1024
	ds_read_b128 v[112:115], v173 offset:2048
	ds_read_b128 v[116:119], v173 offset:3072
	ds_read_b128 v[120:123], v174
	ds_read_b128 v[124:127], v174 offset:1024
	ds_read_b128 v[164:167], v174 offset:2048
	ds_read_b128 v[176:179], v174 offset:3072
	s_add_u32 s36, s36, 0x10180
	s_addc_u32 s37, s37, 0
	s_mov_b32 m0, s64
	v_lshl_add_u64 v[168:169], s[36:37], 0, v[148:149]
	ds_read_b128 v[180:183], v175
	ds_read_b128 v[184:187], v175 offset:1024
	ds_read_b128 v[188:191], v175 offset:2048
	ds_read_b128 v[192:195], v175 offset:3072
	ds_read_b128 v[196:199], v175 offset:4096
	ds_read_b128 v[200:203], v175 offset:5120
	ds_read_b128 v[204:207], v175 offset:6144
	ds_read_b128 v[212:215], v175 offset:7168
	global_load_lds_dwordx4 v[168:169], off
	v_lshl_add_u64 v[168:169], s[36:37], 0, v[152:153]
	s_mov_b32 m0, s65
	s_nop 0
	global_load_lds_dwordx4 v[168:169], off
	s_waitcnt vmcnt(8)
	s_waitcnt lgkmcnt(0)
	s_barrier
	s_setprio 1
	s_waitcnt lgkmcnt(0)
	v_mfma_f32_16x16x32_bf16 v[64:67], v[104:107], v[180:183], v[64:67]
	v_mfma_f32_16x16x32_bf16 v[68:71], v[112:115], v[180:183], v[68:71]
	v_mfma_f32_16x16x32_bf16 v[72:75], v[104:107], v[188:191], v[72:75]
	v_mfma_f32_16x16x32_bf16 v[76:79], v[112:115], v[188:191], v[76:79]
	v_mfma_f32_16x16x32_bf16 v[80:83], v[104:107], v[196:199], v[80:83]
	v_mfma_f32_16x16x32_bf16 v[84:87], v[112:115], v[196:199], v[84:87]
	v_mfma_f32_16x16x32_bf16 v[88:91], v[104:107], v[204:207], v[88:91]
	v_mfma_f32_16x16x32_bf16 v[64:67], v[108:111], v[184:187], v[64:67]
	v_mfma_f32_16x16x32_bf16 v[68:71], v[116:119], v[184:187], v[68:71]
	v_mfma_f32_16x16x32_bf16 v[72:75], v[108:111], v[192:195], v[72:75]
	v_mfma_f32_16x16x32_bf16 v[76:79], v[116:119], v[192:195], v[76:79]
	v_mfma_f32_16x16x32_bf16 v[80:83], v[108:111], v[200:203], v[80:83]
	v_mfma_f32_16x16x32_bf16 v[84:87], v[116:119], v[200:203], v[84:87]
	v_mfma_f32_16x16x32_bf16 v[216:219], v[108:111], v[212:215], v[88:91]
	v_mfma_f32_16x16x32_bf16 v[88:91], v[112:115], v[204:207], v[92:95]
	v_mfma_f32_16x16x32_bf16 v[220:223], v[116:119], v[212:215], v[88:91]
	s_setprio 0
	s_setprio 1
	v_mfma_f32_16x16x32_bf16 v[88:91], v[120:123], v[180:183], v[96:99]
	v_mfma_f32_16x16x32_bf16 v[32:35], v[164:167], v[180:183], v[32:35]
	v_mfma_f32_16x16x32_bf16 v[36:39], v[120:123], v[188:191], v[36:39]
	v_mfma_f32_16x16x32_bf16 v[40:43], v[164:167], v[188:191], v[40:43]
	v_mfma_f32_16x16x32_bf16 v[44:47], v[120:123], v[196:199], v[44:47]
	v_mfma_f32_16x16x32_bf16 v[48:51], v[164:167], v[196:199], v[48:51]
	v_mfma_f32_16x16x32_bf16 v[52:55], v[120:123], v[204:207], v[52:55]
	v_mfma_f32_16x16x32_bf16 v[56:59], v[164:167], v[204:207], v[56:59]
	v_mfma_f32_16x16x32_bf16 v[96:99], v[124:127], v[184:187], v[88:91]
	v_mfma_f32_16x16x32_bf16 v[32:35], v[176:179], v[184:187], v[32:35]
	v_mfma_f32_16x16x32_bf16 v[36:39], v[124:127], v[192:195], v[36:39]
	v_mfma_f32_16x16x32_bf16 v[40:43], v[176:179], v[192:195], v[40:43]
	v_mfma_f32_16x16x32_bf16 v[44:47], v[124:127], v[200:203], v[44:47]
	v_mfma_f32_16x16x32_bf16 v[48:51], v[176:179], v[200:203], v[48:51]
	v_mfma_f32_16x16x32_bf16 v[52:55], v[124:127], v[212:215], v[52:55]
	v_mfma_f32_16x16x32_bf16 v[56:59], v[176:179], v[212:215], v[56:59]
	s_setprio 0
	s_barrier
	s_mov_b32 m0, s66
	v_lshl_add_u64 v[168:169], s[46:47], 0, v[150:151]
	s_add_u32 s36, s46, 0x10000
	ds_read_b128 v[88:91], v175 offset:16384
	ds_read_b128 v[92:95], v175 offset:17408
	ds_read_b128 v[180:183], v175 offset:18432
	ds_read_b128 v[184:187], v175 offset:19456
	ds_read_b128 v[188:191], v175 offset:20480
	ds_read_b128 v[192:195], v175 offset:21504
	ds_read_b128 v[196:199], v175 offset:22528
	ds_read_b128 v[200:203], v175 offset:23552
	global_load_lds_dwordx4 v[168:169], off
	v_lshl_add_u64 v[208:209], s[46:47], 0, v[154:155]
	s_mov_b32 m0, s67
	s_addc_u32 s37, s47, 0
	global_load_lds_dwordx4 v[208:209], off
	v_lshl_add_u64 v[204:205], s[36:37], 0, v[150:151]
	s_mov_b32 m0, s68
	v_lshl_add_u64 v[210:211], s[48:49], 0, v[148:149]
	global_load_lds_dwordx4 v[204:205], off
	v_lshl_add_u64 v[204:205], s[36:37], 0, v[154:155]
	s_mov_b32 m0, s69
	v_lshl_add_u64 v[252:253], s[48:49], 0, v[152:153]
	global_load_lds_dwordx4 v[204:205], off
	s_mov_b32 m0, s35
	s_nop 0
	global_load_lds_dwordx4 v[210:211], off
	s_mov_b32 m0, s51
	s_nop 0
	global_load_lds_dwordx4 v[252:253], off
	s_waitcnt vmcnt(8)
	s_waitcnt lgkmcnt(0)
	s_barrier
	s_setprio 1
	s_waitcnt lgkmcnt(0)
	v_mfma_f32_16x16x32_bf16 v[128:131], v[104:107], v[88:91], v[128:131]
	v_mfma_f32_16x16x32_bf16 v[204:207], v[108:111], v[92:95], v[128:131]
	v_mfma_f32_16x16x32_bf16 v[128:131], v[112:115], v[88:91], v[132:135]
	v_mfma_f32_16x16x32_bf16 v[212:215], v[116:119], v[92:95], v[128:131]
	v_mfma_f32_16x16x32_bf16 v[128:131], v[104:107], v[180:183], v[136:139]
	v_mfma_f32_16x16x32_bf16 v[224:227], v[108:111], v[184:187], v[128:131]
	v_mfma_f32_16x16x32_bf16 v[128:131], v[112:115], v[180:183], v[140:143]
	v_mfma_f32_16x16x32_bf16 v[228:231], v[116:119], v[184:187], v[128:131]
	v_mfma_f32_16x16x32_bf16 v[128:131], v[104:107], v[188:191], v[144:147]
	v_mfma_f32_16x16x32_bf16 v[0:3], v[104:107], v[196:199], v[0:3]
	v_mfma_f32_16x16x32_bf16 v[4:7], v[112:115], v[196:199], v[4:7]
	v_mfma_f32_16x16x32_bf16 v[144:147], v[108:111], v[192:195], v[128:131]
	v_mfma_f32_16x16x32_bf16 v[128:131], v[112:115], v[188:191], v[160:163]
	v_mfma_f32_16x16x32_bf16 v[0:3], v[108:111], v[200:203], v[0:3]
	v_mfma_f32_16x16x32_bf16 v[4:7], v[116:119], v[200:203], v[4:7]
	v_mfma_f32_16x16x32_bf16 v[160:163], v[116:119], v[192:195], v[128:131]
	s_setprio 0
	s_setprio 1
	v_mfma_f32_16x16x32_bf16 v[8:11], v[120:123], v[88:91], v[8:11]
	v_mfma_f32_16x16x32_bf16 v[104:107], v[124:127], v[92:95], v[8:11]
	v_mfma_f32_16x16x32_bf16 v[8:11], v[164:167], v[88:91], v[12:15]
	v_mfma_f32_16x16x32_bf16 v[116:119], v[176:179], v[92:95], v[8:11]
	v_mfma_f32_16x16x32_bf16 v[8:11], v[120:123], v[180:183], v[24:27]
	v_mfma_f32_16x16x32_bf16 v[232:235], v[124:127], v[184:187], v[8:11]
	v_mfma_f32_16x16x32_bf16 v[8:11], v[164:167], v[180:183], v[28:31]
	v_mfma_f32_16x16x32_bf16 v[180:183], v[176:179], v[184:187], v[8:11]
	v_mfma_f32_16x16x32_bf16 v[8:11], v[120:123], v[188:191], v[60:63]
	v_mfma_f32_16x16x32_bf16 v[184:187], v[124:127], v[192:195], v[8:11]
	v_mfma_f32_16x16x32_bf16 v[8:11], v[164:167], v[188:191], v[100:103]
	v_mfma_f32_16x16x32_bf16 v[188:191], v[176:179], v[192:195], v[8:11]
	v_mfma_f32_16x16x32_bf16 v[8:11], v[120:123], v[196:199], v[16:19]
	v_mfma_f32_16x16x32_bf16 v[120:123], v[124:127], v[200:203], v[8:11]
	v_mfma_f32_16x16x32_bf16 v[8:11], v[164:167], v[196:199], v[20:23]
	v_mfma_f32_16x16x32_bf16 v[124:127], v[176:179], v[200:203], v[8:11]
	s_setprio 0
	s_barrier
	s_nop 4
	ds_read_b128 v[8:11], v236
	ds_read_b128 v[12:15], v236 offset:1024
	ds_read_b128 v[16:19], v236 offset:2048
	ds_read_b128 v[20:23], v236 offset:3072
	ds_read_b128 v[164:167], v237
	ds_read_b128 v[176:179], v237 offset:1024
	ds_read_b128 v[192:195], v237 offset:2048
	ds_read_b128 v[196:199], v237 offset:3072
	s_add_u32 s36, s48, 0x10000
	s_addc_u32 s37, s49, 0
	s_mov_b32 m0, s52
	v_lshl_add_u64 v[88:89], s[36:37], 0, v[148:149]
	ds_read_b128 v[24:27], v175 offset:32768
	ds_read_b128 v[28:31], v175 offset:33792
	ds_read_b128 v[60:63], v175 offset:34816
	ds_read_b128 v[200:203], v175 offset:35840
	ds_read_b128 v[236:239], v175 offset:36864
	ds_read_b128 v[240:243], v175 offset:37888
	ds_read_b128 v[244:247], v175 offset:38912
	ds_read_b128 v[248:251], v175 offset:39936
	global_load_lds_dwordx4 v[88:89], off
	v_lshl_add_u64 v[88:89], s[36:37], 0, v[152:153]
	s_mov_b32 m0, s53
	s_nop 0
	global_load_lds_dwordx4 v[88:89], off
	s_waitcnt vmcnt(8)
	s_waitcnt lgkmcnt(0)
	s_barrier
	s_setprio 1
	s_waitcnt lgkmcnt(0)
	v_mfma_f32_16x16x32_bf16 v[64:67], v[8:11], v[24:27], v[64:67]
	v_mfma_f32_16x16x32_bf16 v[140:143], v[12:15], v[28:31], v[64:67]
	v_mfma_f32_16x16x32_bf16 v[64:67], v[16:19], v[24:27], v[68:71]
	v_mfma_f32_16x16x32_bf16 v[136:139], v[20:23], v[28:31], v[64:67]
	v_mfma_f32_16x16x32_bf16 v[64:67], v[8:11], v[60:63], v[72:75]
	v_mfma_f32_16x16x32_bf16 v[112:115], v[12:15], v[200:203], v[64:67]
	v_mfma_f32_16x16x32_bf16 v[64:67], v[16:19], v[60:63], v[76:79]
	v_mfma_f32_16x16x32_bf16 v[108:111], v[20:23], v[200:203], v[64:67]
	v_mfma_f32_16x16x32_bf16 v[64:67], v[8:11], v[236:239], v[80:83]
	v_mfma_f32_16x16x32_bf16 v[92:95], v[12:15], v[240:243], v[64:67]
	v_mfma_f32_16x16x32_bf16 v[64:67], v[16:19], v[236:239], v[84:87]
	v_mfma_f32_16x16x32_bf16 v[88:91], v[20:23], v[240:243], v[64:67]
	v_mfma_f32_16x16x32_bf16 v[64:67], v[8:11], v[244:247], v[216:219]
	v_mfma_f32_16x16x32_bf16 v[76:79], v[12:15], v[248:251], v[64:67]
	v_mfma_f32_16x16x32_bf16 v[64:67], v[16:19], v[244:247], v[220:223]
	v_mfma_f32_16x16x32_bf16 v[72:75], v[20:23], v[248:251], v[64:67]
	s_setprio 0
	s_setprio 1
	v_mfma_f32_16x16x32_bf16 v[64:67], v[164:167], v[24:27], v[96:99]
	v_mfma_f32_16x16x32_bf16 v[24:27], v[192:195], v[24:27], v[32:35]
	v_mfma_f32_16x16x32_bf16 v[128:131], v[196:199], v[28:31], v[24:27]
	v_mfma_f32_16x16x32_bf16 v[24:27], v[164:167], v[60:63], v[36:39]
	v_mfma_f32_16x16x32_bf16 v[100:103], v[176:179], v[200:203], v[24:27]
	v_mfma_f32_16x16x32_bf16 v[24:27], v[192:195], v[60:63], v[40:43]
	v_mfma_f32_16x16x32_bf16 v[96:99], v[196:199], v[200:203], v[24:27]
	v_mfma_f32_16x16x32_bf16 v[24:27], v[164:167], v[236:239], v[44:47]
	v_mfma_f32_16x16x32_bf16 v[84:87], v[176:179], v[240:243], v[24:27]
	v_mfma_f32_16x16x32_bf16 v[24:27], v[192:195], v[236:239], v[48:51]
	v_mfma_f32_16x16x32_bf16 v[80:83], v[196:199], v[240:243], v[24:27]
	v_mfma_f32_16x16x32_bf16 v[24:27], v[164:167], v[244:247], v[52:55]
	v_mfma_f32_16x16x32_bf16 v[68:71], v[176:179], v[248:251], v[24:27]
	v_mfma_f32_16x16x32_bf16 v[24:27], v[192:195], v[244:247], v[56:59]
	v_mfma_f32_16x16x32_bf16 v[132:135], v[176:179], v[28:31], v[64:67]
	v_mfma_f32_16x16x32_bf16 v[64:67], v[196:199], v[248:251], v[24:27]
	s_setprio 0
	s_barrier
	s_mov_b32 m0, s71
	s_nop 2
	v_lshl_add_u64 v[24:25], v[168:169], 0, s[4:5]
	s_add_u32 s36, s46, 0x10080
	ds_read_b128 v[32:35], v175 offset:49152
	ds_read_b128 v[36:39], v175 offset:50176
	ds_read_b128 v[200:203], v175 offset:51200
	ds_read_b128 v[216:219], v175 offset:52224
	ds_read_b128 v[220:223], v175 offset:53248
	ds_read_b128 v[236:239], v175 offset:54272
	ds_read_b128 v[240:243], v175 offset:55296
	ds_read_b128 v[244:247], v175 offset:56320
	global_load_lds_dwordx4 v[24:25], off
	v_lshl_add_u64 v[24:25], v[208:209], 0, s[4:5]
	s_mov_b32 m0, s19
	s_addc_u32 s37, s47, 0
	global_load_lds_dwordx4 v[24:25], off
	v_lshl_add_u64 v[24:25], s[36:37], 0, v[150:151]
	s_mov_b32 m0, s23
	s_nop 0
	global_load_lds_dwordx4 v[24:25], off
	v_lshl_add_u64 v[24:25], s[36:37], 0, v[154:155]
	s_mov_b32 m0, s40
	s_nop 0
	global_load_lds_dwordx4 v[24:25], off
	v_lshl_add_u64 v[24:25], v[210:211], 0, s[4:5]
	s_mov_b32 m0, s60
	s_nop 0
	global_load_lds_dwordx4 v[24:25], off
	v_lshl_add_u64 v[24:25], v[252:253], 0, s[4:5]
	s_mov_b32 m0, s61
	s_nop 0
	global_load_lds_dwordx4 v[24:25], off
	s_waitcnt vmcnt(8)
	s_waitcnt lgkmcnt(0)
	s_barrier
	s_setprio 1
	s_waitcnt lgkmcnt(0)
	v_mfma_f32_16x16x32_bf16 v[24:27], v[8:11], v[32:35], v[204:207]
	v_mfma_f32_16x16x32_bf16 v[60:63], v[12:15], v[36:39], v[24:27]
	v_mfma_f32_16x16x32_bf16 v[24:27], v[16:19], v[32:35], v[212:215]
	v_mfma_f32_16x16x32_bf16 v[56:59], v[20:23], v[36:39], v[24:27]
	v_mfma_f32_16x16x32_bf16 v[24:27], v[8:11], v[200:203], v[224:227]
	v_mfma_f32_16x16x32_bf16 v[44:47], v[12:15], v[216:219], v[24:27]
	v_mfma_f32_16x16x32_bf16 v[24:27], v[16:19], v[200:203], v[228:231]
	v_mfma_f32_16x16x32_bf16 v[40:43], v[20:23], v[216:219], v[24:27]
	v_mfma_f32_16x16x32_bf16 v[24:27], v[8:11], v[220:223], v[144:147]
	v_mfma_f32_16x16x32_bf16 v[0:3], v[8:11], v[240:243], v[0:3]
	v_mfma_f32_16x16x32_bf16 v[28:31], v[12:15], v[236:239], v[24:27]
	v_mfma_f32_16x16x32_bf16 v[24:27], v[16:19], v[220:223], v[160:163]
	v_mfma_f32_16x16x32_bf16 v[12:15], v[12:15], v[244:247], v[0:3]
	v_mfma_f32_16x16x32_bf16 v[0:3], v[16:19], v[240:243], v[4:7]
	v_mfma_f32_16x16x32_bf16 v[24:27], v[20:23], v[236:239], v[24:27]
	v_mfma_f32_16x16x32_bf16 v[8:11], v[20:23], v[244:247], v[0:3]
	s_setprio 0
	s_setprio 1
	v_mfma_f32_16x16x32_bf16 v[0:3], v[164:167], v[32:35], v[104:107]
	v_mfma_f32_16x16x32_bf16 v[52:55], v[176:179], v[36:39], v[0:3]
	v_mfma_f32_16x16x32_bf16 v[0:3], v[192:195], v[32:35], v[116:119]
	v_mfma_f32_16x16x32_bf16 v[48:51], v[196:199], v[36:39], v[0:3]
	v_mfma_f32_16x16x32_bf16 v[0:3], v[164:167], v[200:203], v[232:235]
	v_mfma_f32_16x16x32_bf16 v[36:39], v[176:179], v[216:219], v[0:3]
	v_mfma_f32_16x16x32_bf16 v[0:3], v[192:195], v[200:203], v[180:183]
	v_mfma_f32_16x16x32_bf16 v[32:35], v[196:199], v[216:219], v[0:3]
	v_mfma_f32_16x16x32_bf16 v[0:3], v[164:167], v[220:223], v[184:187]
	v_mfma_f32_16x16x32_bf16 v[20:23], v[176:179], v[236:239], v[0:3]
	v_mfma_f32_16x16x32_bf16 v[0:3], v[192:195], v[220:223], v[188:191]
	v_mfma_f32_16x16x32_bf16 v[16:19], v[196:199], v[236:239], v[0:3]
	v_mfma_f32_16x16x32_bf16 v[0:3], v[164:167], v[240:243], v[120:123]
	v_mfma_f32_16x16x32_bf16 v[4:7], v[176:179], v[244:247], v[0:3]
	v_mfma_f32_16x16x32_bf16 v[0:3], v[192:195], v[240:243], v[124:127]
	v_mfma_f32_16x16x32_bf16 v[0:3], v[196:199], v[244:247], v[0:3]
	s_setprio 0
	s_barrier
	s_andn2_b64 vcc, exec, s[8:9]
	s_cbranch_vccnz .LBB0_3163
	s_barrier
.LBB0_3163:
	s_lshl_b32 s19, s34, 8
	v_mov_b32_e32 v104, v170
	v_mov_b32_e32 v105, v171
	s_add_i32 s19, s19, s54
	s_andn2_b64 vcc, exec, s[6:7]
	v_add_u32_e32 v162, s19, v104
	s_lshl_b32 s19, s70, 8
	s_or_b32 s19, s19, s55
	v_lshl_add_u32 v104, v105, 3, s19
	v_ashrrev_i32_e32 v105, 31, v104
	v_lshlrev_b64 v[160:161], 1, v[104:105]
	v_ashrrev_i32_e32 v163, 31, v162
	v_lshl_add_u64 v[164:165], s[56:57], 0, v[160:161]
	v_lshlrev_b64 v[104:105], 12, v[162:163]
	v_lshl_add_u64 v[104:105], v[164:165], 0, v[104:105]
	global_load_dwordx4 v[176:179], v[104:105], off offset:2048
	v_lshl_add_u64 v[166:167], s[42:43], 0, v[160:161]
	v_lshlrev_b64 v[106:107], 11, v[162:163]
	v_lshl_add_u64 v[116:117], v[166:167], 0, v[106:107]
	global_load_dwordx4 v[180:183], v[116:117], off
	global_load_dwordx4 v[184:187], v[104:105], off offset:2304
	global_load_dwordx4 v[188:191], v[116:117], off offset:256
	v_add_u32_e32 v104, 16, v162
	v_add_u32_e32 v116, 32, v162
	v_add_u32_e32 v118, 48, v162
	v_ashrrev_i32_e32 v105, 31, v104
	v_ashrrev_i32_e32 v117, 31, v116
	v_ashrrev_i32_e32 v119, 31, v118
	v_lshlrev_b64 v[120:121], 12, v[104:105]
	v_lshlrev_b64 v[208:209], 11, v[104:105]
	v_lshlrev_b64 v[104:105], 12, v[116:117]
	v_lshlrev_b64 v[210:211], 11, v[116:117]
	v_lshlrev_b64 v[116:117], 12, v[118:119]
	v_lshl_add_u64 v[120:121], v[164:165], 0, v[120:121]
	v_lshlrev_b64 v[168:169], 11, v[118:119]
	v_lshl_add_u64 v[118:119], v[166:167], 0, v[208:209]
	global_load_dwordx4 v[192:195], v[120:121], off offset:2048
	global_load_dwordx4 v[196:199], v[118:119], off
	v_lshl_add_u64 v[106:107], s[42:43], 0, v[106:107]
	v_lshl_add_u64 v[104:105], v[164:165], 0, v[104:105]
	v_lshl_add_u64 v[122:123], v[166:167], 0, v[210:211]
	v_lshl_add_u64 v[116:117], v[164:165], 0, v[116:117]
	v_lshl_add_u64 v[224:225], v[166:167], 0, v[168:169]
	v_lshl_add_u64 v[226:227], v[106:107], 0, v[160:161]
	global_load_dwordx4 v[200:203], v[120:121], off offset:2304
	global_load_dwordx4 v[204:207], v[118:119], off offset:256
	global_load_dwordx4 v[212:215], v[104:105], off offset:2048
	global_load_dwordx4 v[216:219], v[104:105], off offset:2304
	global_load_dwordx4 v[220:223], v[122:123], off
	global_load_dwordx4 v[144:147], v[122:123], off offset:256
	global_load_dwordx4 v[124:127], v[116:117], off offset:2048
	s_nop 0
	global_load_dwordx4 v[116:119], v[116:117], off offset:2304
	s_nop 0
	global_load_dwordx4 v[120:123], v[224:225], off
	global_load_dwordx4 v[104:107], v[224:225], off offset:256
	s_mov_b64 s[6:7], -1
	s_waitcnt vmcnt(0)
	v_lshlrev_b32_e32 v163, 16, v176
	v_and_b32_e32 v176, 0xffff0000, v176
	v_lshlrev_b32_e32 v225, 16, v178
	v_lshlrev_b32_e32 v229, 16, v180
	v_and_b32_e32 v180, 0xffff0000, v180
	v_lshlrev_b32_e32 v231, 16, v182
	v_lshlrev_b32_e32 v224, 16, v177
	v_and_b32_e32 v177, 0xffff0000, v177
	v_and_b32_e32 v178, 0xffff0000, v178
	v_lshlrev_b32_e32 v228, 16, v179
	v_and_b32_e32 v179, 0xffff0000, v179
	v_lshlrev_b32_e32 v230, 16, v181
	v_and_b32_e32 v181, 0xffff0000, v181
	v_and_b32_e32 v182, 0xffff0000, v182
	v_lshlrev_b32_e32 v232, 16, v183
	v_and_b32_e32 v183, 0xffff0000, v183
	v_fmac_f32_e32 v229, v140, v163
	v_fmac_f32_e32 v180, v141, v176
	v_fmac_f32_e32 v231, v136, v225
	v_cvt_pk_bf16_f32 v136, v229, v180
	v_lshlrev_b32_e32 v233, 16, v184
	v_fmac_f32_e32 v230, v142, v224
	v_fmac_f32_e32 v181, v143, v177
	v_fmac_f32_e32 v182, v137, v178
	v_fmac_f32_e32 v232, v138, v228
	v_fmac_f32_e32 v183, v139, v179
	v_cvt_pk_bf16_f32 v137, v230, v181
	v_cvt_pk_bf16_f32 v138, v231, v182
	v_cvt_pk_bf16_f32 v139, v232, v183
	global_store_dwordx4 v[226:227], v[136:139], off
	v_and_b32_e32 v184, 0xffff0000, v184
	v_lshlrev_b32_e32 v234, 16, v185
	v_lshlrev_b32_e32 v136, 16, v188
	v_fmac_f32_e32 v136, v132, v233
	v_and_b32_e32 v132, 0xffff0000, v188
	v_fmac_f32_e32 v132, v133, v184
	v_lshlrev_b32_e32 v133, 16, v189
	v_and_b32_e32 v185, 0xffff0000, v185
	v_fmac_f32_e32 v133, v134, v234
	v_and_b32_e32 v134, 0xffff0000, v189
	v_lshlrev_b32_e32 v235, 16, v186
	v_and_b32_e32 v186, 0xffff0000, v186
	v_lshlrev_b32_e32 v236, 16, v187
	v_fmac_f32_e32 v134, v135, v185
	v_lshlrev_b32_e32 v135, 16, v190
	v_and_b32_e32 v137, 0xffff0000, v190
	v_lshlrev_b32_e32 v138, 16, v191
	v_and_b32_e32 v187, 0xffff0000, v187
	v_fmac_f32_e32 v135, v128, v235
	v_fmac_f32_e32 v137, v129, v186
	v_fmac_f32_e32 v138, v130, v236
	v_and_b32_e32 v139, 0xffff0000, v191
	v_cvt_pk_bf16_f32 v128, v136, v132
	v_cvt_pk_bf16_f32 v129, v133, v134
	v_cvt_pk_bf16_f32 v130, v135, v137
	v_fmac_f32_e32 v139, v131, v187
	v_cvt_pk_bf16_f32 v131, v138, v139
	global_store_dwordx4 v[226:227], v[128:131], off offset:256
	v_lshlrev_b32_e32 v138, 16, v196
	v_lshlrev_b32_e32 v132, 16, v193
	v_lshlrev_b32_e32 v130, 16, v192
	v_and_b32_e32 v131, 0xffff0000, v192
	v_fmac_f32_e32 v138, v112, v130
	v_and_b32_e32 v112, 0xffff0000, v196
	v_fmac_f32_e32 v112, v113, v131
	v_lshlrev_b32_e32 v113, 16, v197
	v_and_b32_e32 v133, 0xffff0000, v193
	v_fmac_f32_e32 v113, v114, v132
	v_and_b32_e32 v114, 0xffff0000, v197
	v_lshl_add_u64 v[128:129], s[42:43], 0, v[208:209]
	v_lshlrev_b32_e32 v134, 16, v194
	v_and_b32_e32 v135, 0xffff0000, v194
	v_fmac_f32_e32 v114, v115, v133
	v_lshlrev_b32_e32 v115, 16, v198
	v_and_b32_e32 v130, 0xffff0000, v198
	v_lshl_add_u64 v[128:129], v[128:129], 0, v[160:161]
	v_lshlrev_b32_e32 v136, 16, v195
	v_and_b32_e32 v137, 0xffff0000, v195
	v_fmac_f32_e32 v115, v108, v134
	v_fmac_f32_e32 v130, v109, v135
	v_lshlrev_b32_e32 v131, 16, v199
	v_and_b32_e32 v132, 0xffff0000, v199
	v_cvt_pk_bf16_f32 v108, v138, v112
	v_fmac_f32_e32 v131, v110, v136
	v_fmac_f32_e32 v132, v111, v137
	v_cvt_pk_bf16_f32 v109, v113, v114
	v_cvt_pk_bf16_f32 v110, v115, v130
	v_cvt_pk_bf16_f32 v111, v131, v132
	global_store_dwordx4 v[128:129], v[108:111], off
	v_lshlrev_b32_e32 v130, 16, v204
	v_lshlrev_b32_e32 v112, 16, v202
	v_lshlrev_b32_e32 v108, 16, v200
	v_and_b32_e32 v109, 0xffff0000, v200
	v_fmac_f32_e32 v130, v100, v108
	v_and_b32_e32 v100, 0xffff0000, v204
	v_lshlrev_b32_e32 v110, 16, v201
	v_fmac_f32_e32 v100, v101, v109
	v_lshlrev_b32_e32 v101, 16, v205
	v_and_b32_e32 v111, 0xffff0000, v201
	v_fmac_f32_e32 v101, v102, v110
	v_and_b32_e32 v102, 0xffff0000, v205
	v_and_b32_e32 v113, 0xffff0000, v202
	v_lshlrev_b32_e32 v114, 16, v203
	v_and_b32_e32 v115, 0xffff0000, v203
	v_fmac_f32_e32 v102, v103, v111
	v_lshlrev_b32_e32 v103, 16, v206
	v_and_b32_e32 v108, 0xffff0000, v206
	v_lshlrev_b32_e32 v109, 16, v207
	v_and_b32_e32 v110, 0xffff0000, v207
	v_fmac_f32_e32 v103, v96, v112
	v_fmac_f32_e32 v108, v97, v113
	v_fmac_f32_e32 v109, v98, v114
	v_fmac_f32_e32 v110, v99, v115
	v_cvt_pk_bf16_f32 v96, v130, v100
	v_cvt_pk_bf16_f32 v97, v101, v102
	v_cvt_pk_bf16_f32 v98, v103, v108
	v_cvt_pk_bf16_f32 v99, v109, v110
	global_store_dwordx4 v[128:129], v[96:99], off offset:256
	v_lshlrev_b32_e32 v110, 16, v220
	v_lshlrev_b32_e32 v100, 16, v213
	v_lshlrev_b32_e32 v98, 16, v212
	v_and_b32_e32 v99, 0xffff0000, v212
	v_fmac_f32_e32 v110, v92, v98
	v_and_b32_e32 v92, 0xffff0000, v220
	v_fmac_f32_e32 v92, v93, v99
	v_lshlrev_b32_e32 v93, 16, v221
	v_and_b32_e32 v101, 0xffff0000, v213
	v_fmac_f32_e32 v93, v94, v100
	v_and_b32_e32 v94, 0xffff0000, v221
	v_lshl_add_u64 v[96:97], s[42:43], 0, v[210:211]
	v_lshlrev_b32_e32 v102, 16, v214
	v_and_b32_e32 v103, 0xffff0000, v214
	v_fmac_f32_e32 v94, v95, v101
	v_lshlrev_b32_e32 v95, 16, v222
	v_and_b32_e32 v98, 0xffff0000, v222
	v_lshl_add_u64 v[96:97], v[96:97], 0, v[160:161]
	v_lshlrev_b32_e32 v108, 16, v215
	v_and_b32_e32 v109, 0xffff0000, v215
	v_fmac_f32_e32 v95, v88, v102
	v_fmac_f32_e32 v98, v89, v103
	v_lshlrev_b32_e32 v99, 16, v223
	v_and_b32_e32 v100, 0xffff0000, v223
	v_cvt_pk_bf16_f32 v88, v110, v92
	v_fmac_f32_e32 v99, v90, v108
	v_fmac_f32_e32 v100, v91, v109
	v_cvt_pk_bf16_f32 v89, v93, v94
	v_cvt_pk_bf16_f32 v90, v95, v98
	v_cvt_pk_bf16_f32 v91, v99, v100
	global_store_dwordx4 v[96:97], v[88:91], off
	v_lshlrev_b32_e32 v98, 16, v144
	v_lshlrev_b32_e32 v92, 16, v218
	v_lshlrev_b32_e32 v88, 16, v216
	v_and_b32_e32 v89, 0xffff0000, v216
	v_fmac_f32_e32 v98, v84, v88
	v_and_b32_e32 v84, 0xffff0000, v144
	v_lshlrev_b32_e32 v90, 16, v217
	v_fmac_f32_e32 v84, v85, v89
	v_lshlrev_b32_e32 v85, 16, v145
	v_and_b32_e32 v91, 0xffff0000, v217
	v_fmac_f32_e32 v85, v86, v90
	v_and_b32_e32 v86, 0xffff0000, v145
	v_and_b32_e32 v93, 0xffff0000, v218
	v_lshlrev_b32_e32 v94, 16, v219
	v_and_b32_e32 v95, 0xffff0000, v219
	v_fmac_f32_e32 v86, v87, v91
	v_lshlrev_b32_e32 v87, 16, v146
	v_and_b32_e32 v88, 0xffff0000, v146
	v_lshlrev_b32_e32 v89, 16, v147
	v_and_b32_e32 v90, 0xffff0000, v147
	v_fmac_f32_e32 v87, v80, v92
	v_fmac_f32_e32 v88, v81, v93
	v_fmac_f32_e32 v89, v82, v94
	v_fmac_f32_e32 v90, v83, v95
	v_cvt_pk_bf16_f32 v80, v98, v84
	v_cvt_pk_bf16_f32 v81, v85, v86
	v_cvt_pk_bf16_f32 v82, v87, v88
	v_cvt_pk_bf16_f32 v83, v89, v90
	global_store_dwordx4 v[96:97], v[80:83], off offset:256
	v_lshlrev_b32_e32 v90, 16, v120
	v_lshlrev_b32_e32 v84, 16, v125
	v_lshlrev_b32_e32 v82, 16, v124
	v_and_b32_e32 v83, 0xffff0000, v124
	v_fmac_f32_e32 v90, v76, v82
	v_and_b32_e32 v76, 0xffff0000, v120
	v_fmac_f32_e32 v76, v77, v83
	v_lshlrev_b32_e32 v77, 16, v121
	v_and_b32_e32 v85, 0xffff0000, v125
	v_fmac_f32_e32 v77, v78, v84
	v_and_b32_e32 v78, 0xffff0000, v121
	v_lshl_add_u64 v[80:81], s[42:43], 0, v[168:169]
	v_lshlrev_b32_e32 v86, 16, v126
	v_and_b32_e32 v87, 0xffff0000, v126
	v_fmac_f32_e32 v78, v79, v85
	v_lshlrev_b32_e32 v79, 16, v122
	v_and_b32_e32 v82, 0xffff0000, v122
	v_lshl_add_u64 v[80:81], v[80:81], 0, v[160:161]
	v_lshlrev_b32_e32 v88, 16, v127
	v_and_b32_e32 v89, 0xffff0000, v127
	v_fmac_f32_e32 v79, v72, v86
	v_fmac_f32_e32 v82, v73, v87
	v_lshlrev_b32_e32 v83, 16, v123
	v_and_b32_e32 v84, 0xffff0000, v123
	v_cvt_pk_bf16_f32 v72, v90, v76
	v_fmac_f32_e32 v83, v74, v88
	v_fmac_f32_e32 v84, v75, v89
	v_cvt_pk_bf16_f32 v73, v77, v78
	v_cvt_pk_bf16_f32 v74, v79, v82
	v_cvt_pk_bf16_f32 v75, v83, v84
	global_store_dwordx4 v[80:81], v[72:75], off
	v_lshlrev_b32_e32 v82, 16, v104
	v_lshlrev_b32_e32 v76, 16, v118
	v_lshlrev_b32_e32 v72, 16, v116
	v_and_b32_e32 v73, 0xffff0000, v116
	v_fmac_f32_e32 v82, v68, v72
	v_and_b32_e32 v68, 0xffff0000, v104
	v_lshlrev_b32_e32 v74, 16, v117
	v_fmac_f32_e32 v68, v69, v73
	v_lshlrev_b32_e32 v69, 16, v105
	v_and_b32_e32 v75, 0xffff0000, v117
	v_fmac_f32_e32 v69, v70, v74
	v_and_b32_e32 v70, 0xffff0000, v105
	v_fmac_f32_e32 v70, v71, v75
	v_lshlrev_b32_e32 v71, 16, v106
	v_and_b32_e32 v77, 0xffff0000, v118
	v_lshlrev_b32_e32 v78, 16, v119
	v_and_b32_e32 v79, 0xffff0000, v119
	v_fmac_f32_e32 v71, v64, v76
	v_and_b32_e32 v72, 0xffff0000, v106
	v_lshlrev_b32_e32 v73, 16, v107
	v_and_b32_e32 v74, 0xffff0000, v107
	v_cvt_pk_bf16_f32 v64, v82, v68
	v_fmac_f32_e32 v72, v65, v77
	v_fmac_f32_e32 v73, v66, v78
	v_fmac_f32_e32 v74, v67, v79
	v_cvt_pk_bf16_f32 v65, v69, v70
	v_cvt_pk_bf16_f32 v66, v71, v72
	v_cvt_pk_bf16_f32 v67, v73, v74
	global_store_dwordx4 v[80:81], v[64:67], off offset:256
	s_nop 1
	v_add_u32_e32 v64, 0x80, v162
	v_ashrrev_i32_e32 v65, 31, v64
	v_lshlrev_b64 v[66:67], 12, v[64:65]
	v_lshl_add_u64 v[66:67], v[164:165], 0, v[66:67]
	global_load_dwordx4 v[86:89], v[66:67], off offset:2048
	v_lshlrev_b64 v[130:131], 11, v[64:65]
	v_lshl_add_u64 v[64:65], v[166:167], 0, v[130:131]
	global_load_dwordx4 v[90:93], v[64:65], off
	global_load_dwordx4 v[94:97], v[66:67], off offset:2304
	global_load_dwordx4 v[98:101], v[64:65], off offset:256
	v_add_u32_e32 v64, 0x90, v162
	v_ashrrev_i32_e32 v65, 31, v64
	v_lshlrev_b64 v[66:67], 12, v[64:65]
	v_lshl_add_u64 v[66:67], v[164:165], 0, v[66:67]
	v_lshlrev_b64 v[132:133], 11, v[64:65]
	v_lshl_add_u64 v[64:65], v[166:167], 0, v[132:133]
	global_load_dwordx4 v[102:105], v[66:67], off offset:2048
	global_load_dwordx4 v[106:109], v[66:67], off offset:2304
	global_load_dwordx4 v[110:113], v[64:65], off
	global_load_dwordx4 v[114:117], v[64:65], off offset:256
	v_add_u32_e32 v64, 0xa0, v162
	v_ashrrev_i32_e32 v65, 31, v64
	v_lshlrev_b64 v[66:67], 12, v[64:65]
	v_lshl_add_u64 v[66:67], v[164:165], 0, v[66:67]
	v_lshlrev_b64 v[134:135], 11, v[64:65]
	v_lshl_add_u64 v[64:65], v[166:167], 0, v[134:135]
	global_load_dwordx4 v[118:121], v[66:67], off offset:2048
	global_load_dwordx4 v[122:125], v[66:67], off offset:2304
	global_load_dwordx4 v[126:129], v[64:65], off
	global_load_dwordx4 v[80:83], v[64:65], off offset:256
	v_add_u32_e32 v64, 0xb0, v162
	v_ashrrev_i32_e32 v65, 31, v64
	v_lshlrev_b64 v[66:67], 12, v[64:65]
	v_lshlrev_b64 v[84:85], 11, v[64:65]
	v_lshl_add_u64 v[66:67], v[164:165], 0, v[66:67]
	v_lshl_add_u64 v[64:65], v[166:167], 0, v[84:85]
	global_load_dwordx4 v[76:79], v[66:67], off offset:2048
	global_load_dwordx4 v[68:71], v[66:67], off offset:2304
	global_load_dwordx4 v[72:75], v[64:65], off
	s_nop 0
	global_load_dwordx4 v[64:67], v[64:65], off offset:256
	v_lshl_add_u64 v[130:131], s[42:43], 0, v[130:131]
	v_lshl_add_u64 v[130:131], v[130:131], 0, v[160:161]
	s_waitcnt vmcnt(15)
	v_lshlrev_b32_e32 v136, 16, v86
	s_waitcnt vmcnt(14)
	v_lshlrev_b32_e32 v140, 16, v90
	v_and_b32_e32 v86, 0xffff0000, v86
	v_fmac_f32_e32 v140, v60, v136
	v_and_b32_e32 v60, 0xffff0000, v90
	v_lshlrev_b32_e32 v137, 16, v87
	v_fmac_f32_e32 v60, v61, v86
	v_lshlrev_b32_e32 v61, 16, v91
	v_and_b32_e32 v87, 0xffff0000, v87
	v_fmac_f32_e32 v61, v62, v137
	v_and_b32_e32 v62, 0xffff0000, v91
	v_lshlrev_b32_e32 v138, 16, v88
	v_and_b32_e32 v88, 0xffff0000, v88
	v_fmac_f32_e32 v62, v63, v87
	v_lshlrev_b32_e32 v63, 16, v92
	v_and_b32_e32 v86, 0xffff0000, v92
	v_lshlrev_b32_e32 v139, 16, v89
	v_and_b32_e32 v89, 0xffff0000, v89
	v_fmac_f32_e32 v63, v56, v138
	v_fmac_f32_e32 v86, v57, v88
	v_lshlrev_b32_e32 v87, 16, v93
	v_and_b32_e32 v88, 0xffff0000, v93
	v_cvt_pk_bf16_f32 v56, v140, v60
	v_fmac_f32_e32 v87, v58, v139
	v_fmac_f32_e32 v88, v59, v89
	v_cvt_pk_bf16_f32 v57, v61, v62
	v_cvt_pk_bf16_f32 v58, v63, v86
	v_cvt_pk_bf16_f32 v59, v87, v88
	global_store_dwordx4 v[130:131], v[56:59], off
	s_waitcnt vmcnt(13)
	v_lshlrev_b32_e32 v86, 16, v98
	v_lshlrev_b32_e32 v60, 16, v96
	v_lshlrev_b32_e32 v56, 16, v94
	v_and_b32_e32 v57, 0xffff0000, v94
	v_fmac_f32_e32 v86, v52, v56
	v_and_b32_e32 v52, 0xffff0000, v98
	v_lshlrev_b32_e32 v58, 16, v95
	v_fmac_f32_e32 v52, v53, v57
	v_lshlrev_b32_e32 v53, 16, v99
	v_and_b32_e32 v59, 0xffff0000, v95
	v_fmac_f32_e32 v53, v54, v58
	v_and_b32_e32 v54, 0xffff0000, v99
	v_and_b32_e32 v61, 0xffff0000, v96
	v_lshlrev_b32_e32 v62, 16, v97
	v_and_b32_e32 v63, 0xffff0000, v97
	v_fmac_f32_e32 v54, v55, v59
	v_lshlrev_b32_e32 v55, 16, v100
	v_and_b32_e32 v56, 0xffff0000, v100
	v_lshlrev_b32_e32 v57, 16, v101
	v_and_b32_e32 v58, 0xffff0000, v101
	v_fmac_f32_e32 v55, v48, v60
	v_fmac_f32_e32 v56, v49, v61
	v_fmac_f32_e32 v57, v50, v62
	v_fmac_f32_e32 v58, v51, v63
	v_cvt_pk_bf16_f32 v48, v86, v52
	v_cvt_pk_bf16_f32 v49, v53, v54
	v_cvt_pk_bf16_f32 v50, v55, v56
	v_cvt_pk_bf16_f32 v51, v57, v58
	global_store_dwordx4 v[130:131], v[48:51], off offset:256
	s_waitcnt vmcnt(11)
	v_lshlrev_b32_e32 v58, 16, v110
	v_lshlrev_b32_e32 v52, 16, v103
	v_lshlrev_b32_e32 v50, 16, v102
	v_and_b32_e32 v51, 0xffff0000, v102
	v_fmac_f32_e32 v58, v44, v50
	v_and_b32_e32 v44, 0xffff0000, v110
	v_fmac_f32_e32 v44, v45, v51
	v_lshlrev_b32_e32 v45, 16, v111
	v_and_b32_e32 v53, 0xffff0000, v103
	v_fmac_f32_e32 v45, v46, v52
	v_and_b32_e32 v46, 0xffff0000, v111
	v_lshl_add_u64 v[48:49], s[42:43], 0, v[132:133]
	v_lshlrev_b32_e32 v54, 16, v104
	v_and_b32_e32 v55, 0xffff0000, v104
	v_fmac_f32_e32 v46, v47, v53
	v_lshlrev_b32_e32 v47, 16, v112
	v_and_b32_e32 v50, 0xffff0000, v112
	v_lshl_add_u64 v[48:49], v[48:49], 0, v[160:161]
	v_lshlrev_b32_e32 v56, 16, v105
	v_and_b32_e32 v57, 0xffff0000, v105
	v_fmac_f32_e32 v47, v40, v54
	v_fmac_f32_e32 v50, v41, v55
	v_lshlrev_b32_e32 v51, 16, v113
	v_and_b32_e32 v52, 0xffff0000, v113
	v_cvt_pk_bf16_f32 v40, v58, v44
	v_fmac_f32_e32 v51, v42, v56
	v_fmac_f32_e32 v52, v43, v57
	v_cvt_pk_bf16_f32 v41, v45, v46
	v_cvt_pk_bf16_f32 v42, v47, v50
	v_cvt_pk_bf16_f32 v43, v51, v52
	global_store_dwordx4 v[48:49], v[40:43], off
	s_waitcnt vmcnt(11)
	v_lshlrev_b32_e32 v50, 16, v114
	v_lshlrev_b32_e32 v44, 16, v108
	v_lshlrev_b32_e32 v40, 16, v106
	v_and_b32_e32 v41, 0xffff0000, v106
	v_fmac_f32_e32 v50, v36, v40
	v_and_b32_e32 v36, 0xffff0000, v114
	v_lshlrev_b32_e32 v42, 16, v107
	v_fmac_f32_e32 v36, v37, v41
	v_lshlrev_b32_e32 v37, 16, v115
	v_and_b32_e32 v43, 0xffff0000, v107
	v_fmac_f32_e32 v37, v38, v42
	v_and_b32_e32 v38, 0xffff0000, v115
	v_and_b32_e32 v45, 0xffff0000, v108
	v_lshlrev_b32_e32 v46, 16, v109
	v_and_b32_e32 v47, 0xffff0000, v109
	v_fmac_f32_e32 v38, v39, v43
	v_lshlrev_b32_e32 v39, 16, v116
	v_and_b32_e32 v40, 0xffff0000, v116
	v_lshlrev_b32_e32 v41, 16, v117
	v_and_b32_e32 v42, 0xffff0000, v117
	v_fmac_f32_e32 v39, v32, v44
	v_fmac_f32_e32 v40, v33, v45
	v_fmac_f32_e32 v41, v34, v46
	v_fmac_f32_e32 v42, v35, v47
	v_cvt_pk_bf16_f32 v32, v50, v36
	v_cvt_pk_bf16_f32 v33, v37, v38
	v_cvt_pk_bf16_f32 v34, v39, v40
	v_cvt_pk_bf16_f32 v35, v41, v42
	global_store_dwordx4 v[48:49], v[32:35], off offset:256
	s_waitcnt vmcnt(9)
	v_lshlrev_b32_e32 v42, 16, v126
	v_lshlrev_b32_e32 v36, 16, v119
	v_lshlrev_b32_e32 v34, 16, v118
	v_and_b32_e32 v35, 0xffff0000, v118
	v_fmac_f32_e32 v42, v28, v34
	v_and_b32_e32 v28, 0xffff0000, v126
	v_fmac_f32_e32 v28, v29, v35
	v_lshlrev_b32_e32 v29, 16, v127
	v_and_b32_e32 v37, 0xffff0000, v119
	v_fmac_f32_e32 v29, v30, v36
	v_and_b32_e32 v30, 0xffff0000, v127
	v_lshl_add_u64 v[32:33], s[42:43], 0, v[134:135]
	v_lshlrev_b32_e32 v38, 16, v120
	v_and_b32_e32 v39, 0xffff0000, v120
	v_fmac_f32_e32 v30, v31, v37
	v_lshlrev_b32_e32 v31, 16, v128
	v_and_b32_e32 v34, 0xffff0000, v128
	v_lshl_add_u64 v[32:33], v[32:33], 0, v[160:161]
	v_lshlrev_b32_e32 v40, 16, v121
	v_and_b32_e32 v41, 0xffff0000, v121
	v_fmac_f32_e32 v31, v24, v38
	v_fmac_f32_e32 v34, v25, v39
	v_lshlrev_b32_e32 v35, 16, v129
	v_and_b32_e32 v36, 0xffff0000, v129
	v_cvt_pk_bf16_f32 v24, v42, v28
	v_fmac_f32_e32 v35, v26, v40
	v_fmac_f32_e32 v36, v27, v41
	v_cvt_pk_bf16_f32 v25, v29, v30
	v_cvt_pk_bf16_f32 v26, v31, v34
	v_cvt_pk_bf16_f32 v27, v35, v36
	global_store_dwordx4 v[32:33], v[24:27], off
	s_waitcnt vmcnt(9)
	v_lshlrev_b32_e32 v34, 16, v80
	v_lshlrev_b32_e32 v28, 16, v124
	v_lshlrev_b32_e32 v24, 16, v122
	v_and_b32_e32 v25, 0xffff0000, v122
	v_fmac_f32_e32 v34, v20, v24
	v_and_b32_e32 v20, 0xffff0000, v80
	v_lshlrev_b32_e32 v26, 16, v123
	v_fmac_f32_e32 v20, v21, v25
	v_lshlrev_b32_e32 v21, 16, v81
	v_and_b32_e32 v27, 0xffff0000, v123
	v_fmac_f32_e32 v21, v22, v26
	v_and_b32_e32 v22, 0xffff0000, v81
	v_and_b32_e32 v29, 0xffff0000, v124
	v_lshlrev_b32_e32 v30, 16, v125
	v_and_b32_e32 v31, 0xffff0000, v125
	v_fmac_f32_e32 v22, v23, v27
	v_lshlrev_b32_e32 v23, 16, v82
	v_and_b32_e32 v24, 0xffff0000, v82
	v_lshlrev_b32_e32 v25, 16, v83
	v_and_b32_e32 v26, 0xffff0000, v83
	v_fmac_f32_e32 v23, v16, v28
	v_fmac_f32_e32 v24, v17, v29
	v_fmac_f32_e32 v25, v18, v30
	v_fmac_f32_e32 v26, v19, v31
	v_cvt_pk_bf16_f32 v16, v34, v20
	v_cvt_pk_bf16_f32 v17, v21, v22
	v_cvt_pk_bf16_f32 v18, v23, v24
	v_cvt_pk_bf16_f32 v19, v25, v26
	global_store_dwordx4 v[32:33], v[16:19], off offset:256
	s_waitcnt vmcnt(7)
	v_lshlrev_b32_e32 v26, 16, v72
	v_lshlrev_b32_e32 v20, 16, v77
	v_lshlrev_b32_e32 v18, 16, v76
	v_and_b32_e32 v19, 0xffff0000, v76
	v_fmac_f32_e32 v26, v12, v18
	v_and_b32_e32 v12, 0xffff0000, v72
	v_fmac_f32_e32 v12, v13, v19
	v_lshlrev_b32_e32 v13, 16, v73
	v_and_b32_e32 v21, 0xffff0000, v77
	v_fmac_f32_e32 v13, v14, v20
	v_and_b32_e32 v14, 0xffff0000, v73
	v_lshl_add_u64 v[16:17], s[42:43], 0, v[84:85]
	v_lshlrev_b32_e32 v22, 16, v78
	v_and_b32_e32 v23, 0xffff0000, v78
	v_fmac_f32_e32 v14, v15, v21
	v_lshlrev_b32_e32 v15, 16, v74
	v_and_b32_e32 v18, 0xffff0000, v74
	v_lshl_add_u64 v[16:17], v[16:17], 0, v[160:161]
	v_lshlrev_b32_e32 v24, 16, v79
	v_and_b32_e32 v25, 0xffff0000, v79
	v_fmac_f32_e32 v15, v8, v22
	v_fmac_f32_e32 v18, v9, v23
	v_lshlrev_b32_e32 v19, 16, v75
	v_and_b32_e32 v20, 0xffff0000, v75
	v_cvt_pk_bf16_f32 v8, v26, v12
	v_fmac_f32_e32 v19, v10, v24
	v_fmac_f32_e32 v20, v11, v25
	v_cvt_pk_bf16_f32 v9, v13, v14
	v_cvt_pk_bf16_f32 v10, v15, v18
	v_cvt_pk_bf16_f32 v11, v19, v20
	global_store_dwordx4 v[16:17], v[8:11], off
	s_waitcnt vmcnt(7)
	v_lshlrev_b32_e32 v18, 16, v64
	v_lshlrev_b32_e32 v12, 16, v70
	v_lshlrev_b32_e32 v8, 16, v68
	v_and_b32_e32 v9, 0xffff0000, v68
	v_fmac_f32_e32 v18, v4, v8
	v_and_b32_e32 v4, 0xffff0000, v64
	v_lshlrev_b32_e32 v10, 16, v69
	v_fmac_f32_e32 v4, v5, v9
	v_lshlrev_b32_e32 v5, 16, v65
	v_and_b32_e32 v11, 0xffff0000, v69
	v_fmac_f32_e32 v5, v6, v10
	v_and_b32_e32 v6, 0xffff0000, v65
	v_and_b32_e32 v13, 0xffff0000, v70
	v_lshlrev_b32_e32 v14, 16, v71
	v_and_b32_e32 v15, 0xffff0000, v71
	v_fmac_f32_e32 v6, v7, v11
	v_lshlrev_b32_e32 v7, 16, v66
	v_and_b32_e32 v8, 0xffff0000, v66
	v_lshlrev_b32_e32 v9, 16, v67
	v_and_b32_e32 v10, 0xffff0000, v67
	v_fmac_f32_e32 v7, v0, v12
	v_fmac_f32_e32 v8, v1, v13
	v_fmac_f32_e32 v9, v2, v14
	v_fmac_f32_e32 v10, v3, v15
	v_cvt_pk_bf16_f32 v0, v18, v4
	v_cvt_pk_bf16_f32 v1, v5, v6
	v_cvt_pk_bf16_f32 v2, v7, v8
	v_cvt_pk_bf16_f32 v3, v9, v10
	global_store_dwordx4 v[16:17], v[0:3], off offset:256
	s_mov_b32 s99, 1
	s_cbranch_vccnz .LBB0_3154
	s_andn2_b64 vcc, exec, s[0:1]
	s_cbranch_vccnz .LBB0_3153
	s_barrier
	s_branch .LBB0_3153
